# GEMM mainloops: LDS-DMA pieces issued with SGPR base + 32-bit VGPR offset (380 sites) instead of a per-piece 64-bit VALU address add
# baseline (speedup 1.0000x reference)
; #define PG8_STAGE(bufoff, gbase, voff) do { const char* _gb = (const char*)(gbase); asm volatile("" : "+s"(_gb));     \
;         _Pragma("unroll") for (int _i = 0; _i < 2; ++_i) \
;         __builtin_amdgcn_global_load_lds((const unsigned*)(_gb + (voff)[_i]), (LAS unsigned*)(lds + (bufoff) + ldsw + _i * 8192), 16, 0, 0); } while (0)
; #define PG8_WAIT_V(n) asm volatile("s_waitcnt vmcnt(" #n ")" ::: "memory")
; #define PG8_BAR __builtin_amdgcn_s_barrier()
; template <class Epi>
; __device__ __forceinline__ void gemm_phase(LAS unsigned char* lds, const int wid, const Gemm g, const Epi& E) {
;     ...
;     const char* cA = PG8_UA(cur); const char* cB = PG8_UB(cur);
;     PG8_STAGE(PG8_SB(0, 0), PG8_BP(cB, 0), voffB); PG8_STAGE(PG8_SB(0, 1), PG8_BP(cB, 0) + hstepB, voffB); PG8_STAGE(PG8_SA(0, 0), PG8_AP(cA, 0), voffA); PG8_STAGE(PG8_SA(0, 1), PG8_AP(cA, 0) + hstepA, voffA);
;     if (wr == 1) PG8_BAR;
;     PG8_WAIT_V(2); PG8_BAR;
;     PG8_STAGE(PG8_SB(1, 0), PG8_BP(cB, 1), voffB); PG8_STAGE(PG8_SA(1, 0), PG8_AP(cA, 1), voffA); PG8_STAGE(PG8_SB(1, 1), PG8_BP(cB, 1) + hstepB, voffB);
;     PG8_WAIT_V(6); PG8_BAR;
;     for (;;) {
;         const bool has_next = S.next(ui + 1, nxt);
;         const char* nA = has_next ? PG8_UA(nxt) : cA; const char* nB = has_next ? PG8_UB(nxt) : cB;
;         for (int t = 0; t < nt; t += 2) {
.LBB0_114:
	s_and_b32 s5, s33, 3
	s_lshl_b32 s56, s14, 6
	s_lshl_b32 s57, s5, 5
	s_cmp_lt_u32 s33, 4
	s_cselect_b64 s[10:11], -1, 0
	s_lshl_b32 s58, s5, 6
	s_add_u32 s12, s12, 0x9800000
	s_addc_u32 s13, s13, 0
	s_add_u32 s2, s34, 0x80
	s_addc_u32 s3, s35, 0
	s_waitcnt vmcnt(2)
	s_barrier
	s_add_i32 m0, s31, 0x18000
	s_nop 0
	global_load_lds_dwordx4 v146, s[2:3]
	s_add_i32 m0, s31, 0x1a000
	v_lshl_add_u64 v[2:3], s[2:3], 0, v[150:151]
	s_add_u32 s2, s38, 0x80
	s_addc_u32 s3, s39, 0
	s_add_i32 s59, s31, 0x8000
	global_load_lds_dwordx4 v[2:3], off
	s_mov_b32 m0, s59
	s_add_i32 s60, s31, 0xa000
	global_load_lds_dwordx4 v144, s[2:3]
	v_lshl_add_u64 v[2:3], s[2:3], 0, v[148:149]
	s_add_u32 s2, s34, 0x40080
	s_mov_b32 m0, s60
	s_addc_u32 s3, s35, 0
	global_load_lds_dwordx4 v[2:3], off
	s_add_i32 m0, s31, 0x1c000
	s_nop 0
	global_load_lds_dwordx4 v146, s[2:3]
	s_add_i32 m0, s31, 0x1e000
	v_xor_b32_e32 v1, 16, v162
	global_load_lds_dwordx4 v150, s[2:3]
	v_and_b32_e32 v2, 64, v162
	v_add_u32_e32 v2, 64, v2
	v_cmp_lt_i32_e32 vcc, v1, v2
	v_lshlrev_b32_e32 v3, 6, v163
	s_movk_i32 s2, 0x3c0
	v_cndmask_b32_e32 v1, v162, v1, vcc
	v_lshlrev_b32_e32 v164, 2, v1
	v_xor_b32_e32 v1, 32, v162
	v_cmp_lt_i32_e32 vcc, v1, v2
	v_and_b32_e32 v0, 0xfffffc00, v0
	v_lshl_add_u32 v2, s14, 13, v0
	v_cndmask_b32_e32 v1, v162, v1, vcc
	v_lshlrev_b32_e32 v165, 2, v1
	v_and_b32_e32 v1, 48, v163
	v_and_or_b32 v1, v3, s2, v1
	v_lshlrev_b32_e32 v3, 2, v163
	v_and_b32_e32 v3, 32, v3
	v_lshl_add_u32 v0, s5, 12, v0
	s_waitcnt vmcnt(6)
	v_bitop3_b32 v2, v1, v2, v3 bitop3:0xde
	v_bitop3_b32 v166, v1, v0, v3 bitop3:0xde
	s_add_i32 s63, 0, 0x10000
	s_add_i32 s64, 0, 0x14000
	s_waitcnt lgkmcnt(0)
	s_ashr_i32 s61, s46, 31
	v_mov_b64_e32 v[152:153], 0x500
	v_mov_b64_e32 v[154:155], 0x4ff
	s_movk_i32 s62, 0xa1
	v_add_u32_e32 v167, s63, v166
	v_add_u32_e32 v168, s64, v166
	v_add_u32_e32 v169, 0, v2
	s_mov_b64 s[14:15], 0x100
	s_movk_i32 s65, 0x1400
	s_mov_b32 s16, 0x3c800000
	s_mov_b32 s18, 0x358637bd
	s_mov_b32 s66, 0x800000
	v_mov_b32_e32 v170, 0x3e38aa3b
	s_barrier
	s_branch .LBB0_117

; #define PG8_STAGE(bufoff, gbase, voff) do { const char* _gb = (const char*)(gbase); asm volatile("" : "+s"(_gb));     \
;         _Pragma("unroll") for (int _i = 0; _i < 2; ++_i) \
;         __builtin_amdgcn_global_load_lds((const unsigned*)(_gb + (voff)[_i]), (LAS unsigned*)(lds + (bufoff) + ldsw + _i * 8192), 16, 0, 0); } while (0)
; #define PG8_LDA(dst, b, h) do { _Pragma("unroll") for (int m = 0; m < 4; ++m) _Pragma("unroll") for (int k = 0; k < 2; ++k) dst[m][k] = *(const LAS bf16x8*)(lds + PG8_SA(b, h) + aoff + m * 2048 + k * 1024); } while (0)
; #define PG8_LDB(dst, b, h) do { _Pragma("unroll") for (int n = 0; n < 2; ++n) _Pragma("unroll") for (int k = 0; k < 2; ++k) dst[n][k] = *(const LAS bf16x8*)(lds + PG8_SB(b, h) + boff + n * 2048 + k * 1024); } while (0)
; #define PG8_MMA(ai, bj, At, Bt) do { __builtin_amdgcn_s_setprio(1); _Pragma("unroll") for (int m = 0; m < 4; ++m) _Pragma("unroll") for (int n = 0; n < 2; ++n) _Pragma("unroll") for (int k = 0; k < 2; ++k) \
;         acc[ai][bj][m][n] = __builtin_amdgcn_mfma_f32_16x16x32_bf16(Bt[n][k], At[m][k], acc[ai][bj][m][n], 0, 0, 0); __builtin_amdgcn_s_setprio(0); } while (0)
; #define PG8_WAIT_V(n) asm volatile("s_waitcnt vmcnt(" #n ")" ::: "memory")
; #define PG8_WAIT_L(n) asm volatile("s_waitcnt lgkmcnt(" #n ")" ::: "memory")
; #define PG8_BAR __builtin_amdgcn_s_barrier()
; #define PG8_SCHED __builtin_amdgcn_sched_barrier(0)
; template <class Epi>
; __device__ __forceinline__ void gemm_phase(LAS unsigned char* lds, const int wid, const Gemm g, const Epi& E) {
;     ...
;             PG8_LDB(B0, 0, 0); PG8_LDB(B1, 0, 1); PG8_SCHED; PG8_LDA(At, 0, 0); PG8_STAGE(PG8_SA(1, 1), a1 + hstepA, voffA);
;             PG8_WAIT_V(8); PG8_WAIT_L(0); PG8_BAR; PG8_MMA(0, 0, At, B0); PG8_MMA(0, 1, At, B1); PG8_BAR; PG8_SCHED;
;             PG8_LDA(At, 0, 1); PG8_STAGE(PG8_SB(0, 0), b2, voffB); PG8_STAGE(PG8_SB(0, 1), b2 + hstepB, voffB); PG8_STAGE(PG8_SA(0, 0), a2, voffA);
;             PG8_WAIT_V(8); PG8_WAIT_L(0); PG8_BAR; PG8_MMA(1, 0, At, B0); PG8_MMA(1, 1, At, B1); PG8_BAR; PG8_SCHED;
.LBB0_120:
	ds_read_b128 v[128:131], v167
	ds_read_b128 v[132:135], v167 offset:1024
	ds_read_b128 v[136:139], v167 offset:2048
	ds_read_b128 v[140:143], v167 offset:3072
	ds_read_b128 v[156:159], v168
	ds_read_b128 v[172:175], v168 offset:1024
	ds_read_b128 v[176:179], v168 offset:2048
	ds_read_b128 v[180:183], v168 offset:3072
	s_add_u32 s38, s34, 0xfffc0080
	s_addc_u32 s39, s35, -1
	s_add_u32 s42, s72, 0xffffff80
	s_addc_u32 s43, s73, -1
	s_add_u32 s75, s34, 0xfffc0100
	s_addc_u32 s78, s35, -1
	s_add_i32 s80, s63, s47
	s_add_i32 m0, s31, 0xc000
	s_add_i32 s79, s31, 0xe000
	s_add_i32 s81, s80, 0x2000
	s_cmp_eq_u32 s74, 12
	s_cselect_b32 s41, s5, s39
	s_cselect_b32 s40, s25, s38
	s_cselect_b32 s77, s21, s43
	s_cselect_b32 s76, s67, s42
	s_cselect_b32 s39, s69, s78
	s_cselect_b32 s38, s68, s75
	s_mov_b64 s[42:43], s[34:35]
	ds_read_b128 v[184:187], v169
	ds_read_b128 v[188:191], v169 offset:1024
	ds_read_b128 v[192:195], v169 offset:2048
	ds_read_b128 v[196:199], v169 offset:3072
	ds_read_b128 v[200:203], v169 offset:4096
	ds_read_b128 v[206:209], v169 offset:5120
	ds_read_b128 v[210:213], v169 offset:6144
	ds_read_b128 v[214:217], v169 offset:7168
	s_nop 0
	global_load_lds_dwordx4 v144, s[42:43]
	s_mov_b32 m0, s79
	s_nop 0
	global_load_lds_dwordx4 v148, s[42:43]
	s_waitcnt vmcnt(8)
	s_waitcnt lgkmcnt(0)
	s_barrier
	s_setprio 1
	s_waitcnt lgkmcnt(0)
	v_mfma_f32_16x16x32_bf16 v[124:127], v[128:131], v[184:187], v[124:127]
	v_mfma_f32_16x16x32_bf16 v[120:123], v[136:139], v[184:187], v[120:123]
	v_mfma_f32_16x16x32_bf16 v[108:111], v[128:131], v[192:195], v[108:111]
	v_mfma_f32_16x16x32_bf16 v[104:107], v[136:139], v[192:195], v[104:107]
	v_mfma_f32_16x16x32_bf16 v[92:95], v[128:131], v[200:203], v[92:95]
	v_mfma_f32_16x16x32_bf16 v[88:91], v[136:139], v[200:203], v[88:91]
	v_mfma_f32_16x16x32_bf16 v[80:83], v[128:131], v[210:213], v[80:83]
	v_mfma_f32_16x16x32_bf16 v[72:75], v[136:139], v[210:213], v[72:75]
	v_mfma_f32_16x16x32_bf16 v[124:127], v[132:135], v[188:191], v[124:127]
	v_mfma_f32_16x16x32_bf16 v[120:123], v[140:143], v[188:191], v[120:123]
	v_mfma_f32_16x16x32_bf16 v[108:111], v[132:135], v[196:199], v[108:111]
	v_mfma_f32_16x16x32_bf16 v[104:107], v[140:143], v[196:199], v[104:107]
	v_mfma_f32_16x16x32_bf16 v[92:95], v[132:135], v[206:209], v[92:95]
	v_mfma_f32_16x16x32_bf16 v[88:91], v[140:143], v[206:209], v[88:91]
	v_mfma_f32_16x16x32_bf16 v[80:83], v[132:135], v[214:217], v[80:83]
	v_mfma_f32_16x16x32_bf16 v[72:75], v[140:143], v[214:217], v[72:75]
	s_setprio 0
	s_setprio 1
	v_mfma_f32_16x16x32_bf16 v[116:119], v[156:159], v[184:187], v[116:119]
	v_mfma_f32_16x16x32_bf16 v[112:115], v[176:179], v[184:187], v[112:115]
	v_mfma_f32_16x16x32_bf16 v[100:103], v[156:159], v[192:195], v[100:103]
	v_mfma_f32_16x16x32_bf16 v[96:99], v[176:179], v[192:195], v[96:99]
	v_mfma_f32_16x16x32_bf16 v[84:87], v[156:159], v[200:203], v[84:87]
	v_mfma_f32_16x16x32_bf16 v[76:79], v[176:179], v[200:203], v[76:79]
	v_mfma_f32_16x16x32_bf16 v[68:71], v[156:159], v[210:213], v[68:71]
	v_mfma_f32_16x16x32_bf16 v[64:67], v[176:179], v[210:213], v[64:67]
	v_mfma_f32_16x16x32_bf16 v[116:119], v[172:175], v[188:191], v[116:119]
	v_mfma_f32_16x16x32_bf16 v[112:115], v[180:183], v[188:191], v[112:115]
	v_mfma_f32_16x16x32_bf16 v[100:103], v[172:175], v[196:199], v[100:103]
	v_mfma_f32_16x16x32_bf16 v[96:99], v[180:183], v[196:199], v[96:99]
	v_mfma_f32_16x16x32_bf16 v[84:87], v[172:175], v[206:209], v[84:87]
	v_mfma_f32_16x16x32_bf16 v[76:79], v[180:183], v[206:209], v[76:79]
	v_mfma_f32_16x16x32_bf16 v[68:71], v[172:175], v[214:217], v[68:71]
	v_mfma_f32_16x16x32_bf16 v[64:67], v[180:183], v[214:217], v[64:67]
	s_setprio 0
	s_barrier
	s_mov_b64 s[42:43], s[76:77]
	s_mov_b32 m0, s80
	ds_read_b128 v[184:187], v169 offset:16384
	ds_read_b128 v[188:191], v169 offset:17408
	ds_read_b128 v[192:195], v169 offset:18432
	ds_read_b128 v[196:199], v169 offset:19456
	ds_read_b128 v[200:203], v169 offset:20480
	ds_read_b128 v[206:209], v169 offset:21504
	ds_read_b128 v[210:213], v169 offset:22528
	ds_read_b128 v[214:217], v169 offset:23552
	s_nop 0
	global_load_lds_dwordx4 v146, s[42:43]
	v_lshl_add_u64 v[160:161], s[42:43], 0, v[150:151]
	s_cselect_b32 s43, s71, s73
	s_cselect_b32 s42, s70, s72
	s_add_u32 s76, s76, 0x40000
	s_mov_b32 m0, s81
	s_addc_u32 s77, s77, 0
	s_add_i32 s75, s64, s47
	global_load_lds_dwordx4 v[160:161], off
	s_mov_b32 m0, s75
	s_nop 0
	global_load_lds_dwordx4 v146, s[76:77]
	v_lshl_add_u64 v[160:161], s[76:77], 0, v[150:151]
	s_add_i32 m0, s75, 0x2000
	s_mov_b64 s[76:77], s[40:41]
	global_load_lds_dwordx4 v[160:161], off
	s_mov_b32 m0, s31
	s_nop 0
	global_load_lds_dwordx4 v144, s[76:77]
	s_mov_b32 m0, s52
	s_nop 0
	global_load_lds_dwordx4 v148, s[76:77]
	s_waitcnt vmcnt(8)
	s_waitcnt lgkmcnt(0)
	s_barrier
; #define PG8_STAGE(bufoff, gbase, voff) do { const char* _gb = (const char*)(gbase); asm volatile("" : "+s"(_gb));     \
;         _Pragma("unroll") for (int _i = 0; _i < 2; ++_i) \
;         __builtin_amdgcn_global_load_lds((const unsigned*)(_gb + (voff)[_i]), (LAS unsigned*)(lds + (bufoff) + ldsw + _i * 8192), 16, 0, 0); } while (0)
; #define PG8_LDA(dst, b, h) do { _Pragma("unroll") for (int m = 0; m < 4; ++m) _Pragma("unroll") for (int k = 0; k < 2; ++k) dst[m][k] = *(const LAS bf16x8*)(lds + PG8_SA(b, h) + aoff + m * 2048 + k * 1024); } while (0)
; #define PG8_LDB(dst, b, h) do { _Pragma("unroll") for (int n = 0; n < 2; ++n) _Pragma("unroll") for (int k = 0; k < 2; ++k) dst[n][k] = *(const LAS bf16x8*)(lds + PG8_SB(b, h) + boff + n * 2048 + k * 1024); } while (0)
; #define PG8_MMA(ai, bj, At, Bt) do { __builtin_amdgcn_s_setprio(1); _Pragma("unroll") for (int m = 0; m < 4; ++m) _Pragma("unroll") for (int n = 0; n < 2; ++n) _Pragma("unroll") for (int k = 0; k < 2; ++k) \
;         acc[ai][bj][m][n] = __builtin_amdgcn_mfma_f32_16x16x32_bf16(Bt[n][k], At[m][k], acc[ai][bj][m][n], 0, 0, 0); __builtin_amdgcn_s_setprio(0); } while (0)
; #define PG8_WAIT_V(n) asm volatile("s_waitcnt vmcnt(" #n ")" ::: "memory")
; #define PG8_WAIT_L(n) asm volatile("s_waitcnt lgkmcnt(" #n ")" ::: "memory")
; #define PG8_BAR __builtin_amdgcn_s_barrier()
; #define PG8_SCHED __builtin_amdgcn_sched_barrier(0)
; template <class Epi>
; __device__ __forceinline__ void gemm_phase(LAS unsigned char* lds, const int wid, const Gemm g, const Epi& E) {
;     ...
;             PG8_WAIT_V(8); PG8_WAIT_L(0); PG8_BAR; PG8_MMA(1, 0, At, B0); PG8_MMA(1, 1, At, B1); PG8_BAR; PG8_SCHED;
;             PG8_LDB(B0, 1, 0); PG8_LDB(B1, 1, 1); PG8_SCHED; PG8_LDA(At, 1, 0); PG8_STAGE(PG8_SA(0, 1), a2 + hstepA, voffA);
;             PG8_WAIT_V(8); PG8_WAIT_L(0); PG8_BAR; PG8_MMA(0, 0, At, B0); PG8_MMA(0, 1, At, B1); PG8_BAR; PG8_SCHED;
	s_setprio 1
	s_waitcnt lgkmcnt(0)
	v_mfma_f32_16x16x32_bf16 v[60:63], v[128:131], v[184:187], v[60:63]
	v_mfma_f32_16x16x32_bf16 v[56:59], v[136:139], v[184:187], v[56:59]
	v_mfma_f32_16x16x32_bf16 v[48:51], v[128:131], v[192:195], v[48:51]
	v_mfma_f32_16x16x32_bf16 v[40:43], v[136:139], v[192:195], v[40:43]
	v_mfma_f32_16x16x32_bf16 v[28:31], v[128:131], v[200:203], v[28:31]
	v_mfma_f32_16x16x32_bf16 v[24:27], v[136:139], v[200:203], v[24:27]
	v_mfma_f32_16x16x32_bf16 v[16:19], v[128:131], v[210:213], v[16:19]
	v_mfma_f32_16x16x32_bf16 v[8:11], v[136:139], v[210:213], v[8:11]
	v_mfma_f32_16x16x32_bf16 v[60:63], v[132:135], v[188:191], v[60:63]
	v_mfma_f32_16x16x32_bf16 v[56:59], v[140:143], v[188:191], v[56:59]
	v_mfma_f32_16x16x32_bf16 v[48:51], v[132:135], v[196:199], v[48:51]
	v_mfma_f32_16x16x32_bf16 v[40:43], v[140:143], v[196:199], v[40:43]
	v_mfma_f32_16x16x32_bf16 v[28:31], v[132:135], v[206:209], v[28:31]
	v_mfma_f32_16x16x32_bf16 v[24:27], v[140:143], v[206:209], v[24:27]
	v_mfma_f32_16x16x32_bf16 v[16:19], v[132:135], v[214:217], v[16:19]
	v_mfma_f32_16x16x32_bf16 v[8:11], v[140:143], v[214:217], v[8:11]
	s_setprio 0
	s_setprio 1
	v_mfma_f32_16x16x32_bf16 v[52:55], v[156:159], v[184:187], v[52:55]
	v_mfma_f32_16x16x32_bf16 v[44:47], v[176:179], v[184:187], v[44:47]
	v_mfma_f32_16x16x32_bf16 v[36:39], v[156:159], v[192:195], v[36:39]
	v_mfma_f32_16x16x32_bf16 v[32:35], v[176:179], v[192:195], v[32:35]
	v_mfma_f32_16x16x32_bf16 v[20:23], v[156:159], v[200:203], v[20:23]
	v_mfma_f32_16x16x32_bf16 v[12:15], v[176:179], v[200:203], v[12:15]
	v_mfma_f32_16x16x32_bf16 v[4:7], v[156:159], v[210:213], v[4:7]
	v_mfma_f32_16x16x32_bf16 v[0:3], v[176:179], v[210:213], v[0:3]
	v_mfma_f32_16x16x32_bf16 v[52:55], v[172:175], v[188:191], v[52:55]
	v_mfma_f32_16x16x32_bf16 v[44:47], v[180:183], v[188:191], v[44:47]
	v_mfma_f32_16x16x32_bf16 v[36:39], v[172:175], v[196:199], v[36:39]
	v_mfma_f32_16x16x32_bf16 v[32:35], v[180:183], v[196:199], v[32:35]
	v_mfma_f32_16x16x32_bf16 v[20:23], v[172:175], v[206:209], v[20:23]
	v_mfma_f32_16x16x32_bf16 v[12:15], v[180:183], v[206:209], v[12:15]
	v_mfma_f32_16x16x32_bf16 v[4:7], v[172:175], v[214:217], v[4:7]
	v_mfma_f32_16x16x32_bf16 v[0:3], v[180:183], v[214:217], v[0:3]
	s_setprio 0
	s_barrier
	s_add_i32 s75, 0, 0x18000
	s_add_i32 s76, 0, 0x1c000
	v_add_u32_e32 v140, s75, v166
	v_add_u32_e32 v160, s76, v166
	ds_read_b128 v[128:131], v140
	ds_read_b128 v[132:135], v140 offset:1024
	ds_read_b128 v[136:139], v140 offset:2048
	ds_read_b128 v[140:143], v140 offset:3072
	ds_read_b128 v[156:159], v160
	ds_read_b128 v[172:175], v160 offset:1024
	ds_read_b128 v[176:179], v160 offset:2048
	ds_read_b128 v[180:183], v160 offset:3072
	s_add_u32 s40, s40, 0x40000
	s_addc_u32 s41, s41, 0
	s_mov_b32 m0, s53
	ds_read_b128 v[184:187], v169 offset:32768
	ds_read_b128 v[188:191], v169 offset:33792
	ds_read_b128 v[192:195], v169 offset:34816
	ds_read_b128 v[196:199], v169 offset:35840
	ds_read_b128 v[200:203], v169 offset:36864
	ds_read_b128 v[206:209], v169 offset:37888
	ds_read_b128 v[210:213], v169 offset:38912
	ds_read_b128 v[214:217], v169 offset:39936
	s_nop 0
	global_load_lds_dwordx4 v144, s[40:41]
	s_mov_b32 m0, s54
	s_nop 0
	global_load_lds_dwordx4 v148, s[40:41]
	s_waitcnt vmcnt(8)
	s_waitcnt lgkmcnt(0)
	s_barrier
	s_setprio 1
	s_waitcnt lgkmcnt(0)
	v_mfma_f32_16x16x32_bf16 v[124:127], v[128:131], v[184:187], v[124:127]
	v_mfma_f32_16x16x32_bf16 v[120:123], v[136:139], v[184:187], v[120:123]
	v_mfma_f32_16x16x32_bf16 v[108:111], v[128:131], v[192:195], v[108:111]
	v_mfma_f32_16x16x32_bf16 v[104:107], v[136:139], v[192:195], v[104:107]
	v_mfma_f32_16x16x32_bf16 v[92:95], v[128:131], v[200:203], v[92:95]
	v_mfma_f32_16x16x32_bf16 v[88:91], v[136:139], v[200:203], v[88:91]
	v_mfma_f32_16x16x32_bf16 v[80:83], v[128:131], v[210:213], v[80:83]
	v_mfma_f32_16x16x32_bf16 v[72:75], v[136:139], v[210:213], v[72:75]
	v_mfma_f32_16x16x32_bf16 v[124:127], v[132:135], v[188:191], v[124:127]
	v_mfma_f32_16x16x32_bf16 v[120:123], v[140:143], v[188:191], v[120:123]
	v_mfma_f32_16x16x32_bf16 v[108:111], v[132:135], v[196:199], v[108:111]
	v_mfma_f32_16x16x32_bf16 v[104:107], v[140:143], v[196:199], v[104:107]
	v_mfma_f32_16x16x32_bf16 v[92:95], v[132:135], v[206:209], v[92:95]
	v_mfma_f32_16x16x32_bf16 v[88:91], v[140:143], v[206:209], v[88:91]
	v_mfma_f32_16x16x32_bf16 v[80:83], v[132:135], v[214:217], v[80:83]
	v_mfma_f32_16x16x32_bf16 v[72:75], v[140:143], v[214:217], v[72:75]
	s_setprio 0
	s_setprio 1
	v_mfma_f32_16x16x32_bf16 v[116:119], v[156:159], v[184:187], v[116:119]
	v_mfma_f32_16x16x32_bf16 v[112:115], v[176:179], v[184:187], v[112:115]
	v_mfma_f32_16x16x32_bf16 v[100:103], v[156:159], v[192:195], v[100:103]
	v_mfma_f32_16x16x32_bf16 v[96:99], v[176:179], v[192:195], v[96:99]
	v_mfma_f32_16x16x32_bf16 v[84:87], v[156:159], v[200:203], v[84:87]
	v_mfma_f32_16x16x32_bf16 v[76:79], v[176:179], v[200:203], v[76:79]
	v_mfma_f32_16x16x32_bf16 v[68:71], v[156:159], v[210:213], v[68:71]
	v_mfma_f32_16x16x32_bf16 v[64:67], v[176:179], v[210:213], v[64:67]
	v_mfma_f32_16x16x32_bf16 v[116:119], v[172:175], v[188:191], v[116:119]
	v_mfma_f32_16x16x32_bf16 v[112:115], v[180:183], v[188:191], v[112:115]
	v_mfma_f32_16x16x32_bf16 v[100:103], v[172:175], v[196:199], v[100:103]
	v_mfma_f32_16x16x32_bf16 v[96:99], v[180:183], v[196:199], v[96:99]
	v_mfma_f32_16x16x32_bf16 v[84:87], v[172:175], v[206:209], v[84:87]
	v_mfma_f32_16x16x32_bf16 v[76:79], v[180:183], v[206:209], v[76:79]
	v_mfma_f32_16x16x32_bf16 v[68:71], v[172:175], v[214:217], v[68:71]
	v_mfma_f32_16x16x32_bf16 v[64:67], v[180:183], v[214:217], v[64:67]
	s_setprio 0
	s_barrier
; #define PG8_STAGE(bufoff, gbase, voff) do { const char* _gb = (const char*)(gbase); asm volatile("" : "+s"(_gb));     \
;         _Pragma("unroll") for (int _i = 0; _i < 2; ++_i) \
;         __builtin_amdgcn_global_load_lds((const unsigned*)(_gb + (voff)[_i]), (LAS unsigned*)(lds + (bufoff) + ldsw + _i * 8192), 16, 0, 0); } while (0)
; #define PG8_LDA(dst, b, h) do { _Pragma("unroll") for (int m = 0; m < 4; ++m) _Pragma("unroll") for (int k = 0; k < 2; ++k) dst[m][k] = *(const LAS bf16x8*)(lds + PG8_SA(b, h) + aoff + m * 2048 + k * 1024); } while (0)
; #define PG8_MMA(ai, bj, At, Bt) do { __builtin_amdgcn_s_setprio(1); _Pragma("unroll") for (int m = 0; m < 4; ++m) _Pragma("unroll") for (int n = 0; n < 2; ++n) _Pragma("unroll") for (int k = 0; k < 2; ++k) \
;         acc[ai][bj][m][n] = __builtin_amdgcn_mfma_f32_16x16x32_bf16(Bt[n][k], At[m][k], acc[ai][bj][m][n], 0, 0, 0); __builtin_amdgcn_s_setprio(0); } while (0)
; #define PG8_WAIT_V(n) asm volatile("s_waitcnt vmcnt(" #n ")" ::: "memory")
; #define PG8_WAIT_L(n) asm volatile("s_waitcnt lgkmcnt(" #n ")" ::: "memory")
; #define PG8_BAR __builtin_amdgcn_s_barrier()
; #define PG8_SCHED __builtin_amdgcn_sched_barrier(0)
; template <class Epi>
; __device__ __forceinline__ void gemm_phase(LAS unsigned char* lds, const int wid, const Gemm g, const Epi& E) {
;     ...
;             PG8_WAIT_V(8); PG8_WAIT_L(0); PG8_BAR; PG8_MMA(0, 0, At, B0); PG8_MMA(0, 1, At, B1); PG8_BAR; PG8_SCHED;
;             PG8_LDA(At, 1, 1); PG8_STAGE(PG8_SB(1, 0), b3, voffB); PG8_STAGE(PG8_SB(1, 1), b3 + hstepB, voffB); PG8_STAGE(PG8_SA(1, 0), a3, voffA);
;             PG8_WAIT_V(8); PG8_WAIT_L(0); PG8_BAR; PG8_MMA(1, 0, At, B0); PG8_MMA(1, 1, At, B1); PG8_BAR; PG8_SCHED;
;         }
;         if (wr == 0) PG8_BAR;
	s_mov_b64 s[40:41], s[42:43]
	s_add_i32 s75, s75, s47
	ds_read_b128 v[184:187], v169 offset:49152
	ds_read_b128 v[188:191], v169 offset:50176
	ds_read_b128 v[192:195], v169 offset:51200
	ds_read_b128 v[196:199], v169 offset:52224
	ds_read_b128 v[200:203], v169 offset:53248
	ds_read_b128 v[206:209], v169 offset:54272
	ds_read_b128 v[210:213], v169 offset:55296
	ds_read_b128 v[214:217], v169 offset:56320
	s_mov_b32 m0, s75
	s_nop 0
	global_load_lds_dwordx4 v146, s[40:41]
	s_add_i32 m0, s75, 0x2000
	v_lshl_add_u64 v[160:161], s[40:41], 0, v[150:151]
	s_add_u32 s40, s42, 0x40000
	s_addc_u32 s41, s43, 0
	s_add_i32 s42, s76, s47
	global_load_lds_dwordx4 v[160:161], off
	s_mov_b32 m0, s42
	s_nop 0
	global_load_lds_dwordx4 v146, s[40:41]
	s_add_i32 m0, s42, 0x2000
	s_nop 0
	global_load_lds_dwordx4 v150, s[40:41]
	s_mov_b32 m0, s59
	s_nop 0
	global_load_lds_dwordx4 v144, s[38:39]
	s_mov_b32 m0, s60
	s_nop 0
	global_load_lds_dwordx4 v148, s[38:39]
	s_waitcnt vmcnt(8)
	s_waitcnt lgkmcnt(0)
	s_barrier
	s_setprio 1
	s_waitcnt lgkmcnt(0)
	v_mfma_f32_16x16x32_bf16 v[60:63], v[128:131], v[184:187], v[60:63]
	v_mfma_f32_16x16x32_bf16 v[56:59], v[136:139], v[184:187], v[56:59]
	v_mfma_f32_16x16x32_bf16 v[48:51], v[128:131], v[192:195], v[48:51]
	v_mfma_f32_16x16x32_bf16 v[40:43], v[136:139], v[192:195], v[40:43]
	v_mfma_f32_16x16x32_bf16 v[28:31], v[128:131], v[200:203], v[28:31]
	v_mfma_f32_16x16x32_bf16 v[24:27], v[136:139], v[200:203], v[24:27]
	v_mfma_f32_16x16x32_bf16 v[16:19], v[128:131], v[210:213], v[16:19]
	v_mfma_f32_16x16x32_bf16 v[8:11], v[136:139], v[210:213], v[8:11]
	v_mfma_f32_16x16x32_bf16 v[60:63], v[132:135], v[188:191], v[60:63]
	v_mfma_f32_16x16x32_bf16 v[56:59], v[140:143], v[188:191], v[56:59]
	v_mfma_f32_16x16x32_bf16 v[48:51], v[132:135], v[196:199], v[48:51]
	v_mfma_f32_16x16x32_bf16 v[40:43], v[140:143], v[196:199], v[40:43]
	v_mfma_f32_16x16x32_bf16 v[28:31], v[132:135], v[206:209], v[28:31]
	v_mfma_f32_16x16x32_bf16 v[24:27], v[140:143], v[206:209], v[24:27]
	v_mfma_f32_16x16x32_bf16 v[16:19], v[132:135], v[214:217], v[16:19]
	v_mfma_f32_16x16x32_bf16 v[8:11], v[140:143], v[214:217], v[8:11]
	s_setprio 0
	s_setprio 1
	v_mfma_f32_16x16x32_bf16 v[52:55], v[156:159], v[184:187], v[52:55]
	v_mfma_f32_16x16x32_bf16 v[44:47], v[176:179], v[184:187], v[44:47]
	v_mfma_f32_16x16x32_bf16 v[36:39], v[156:159], v[192:195], v[36:39]
	v_mfma_f32_16x16x32_bf16 v[32:35], v[176:179], v[192:195], v[32:35]
	v_mfma_f32_16x16x32_bf16 v[20:23], v[156:159], v[200:203], v[20:23]
	v_mfma_f32_16x16x32_bf16 v[12:15], v[176:179], v[200:203], v[12:15]
	v_mfma_f32_16x16x32_bf16 v[4:7], v[156:159], v[210:213], v[4:7]
	v_mfma_f32_16x16x32_bf16 v[0:3], v[176:179], v[210:213], v[0:3]
	v_mfma_f32_16x16x32_bf16 v[52:55], v[172:175], v[188:191], v[52:55]
	v_mfma_f32_16x16x32_bf16 v[44:47], v[180:183], v[188:191], v[44:47]
	v_mfma_f32_16x16x32_bf16 v[36:39], v[172:175], v[196:199], v[36:39]
	v_mfma_f32_16x16x32_bf16 v[32:35], v[180:183], v[196:199], v[32:35]
	v_mfma_f32_16x16x32_bf16 v[20:23], v[172:175], v[206:209], v[20:23]
	v_mfma_f32_16x16x32_bf16 v[12:15], v[180:183], v[206:209], v[12:15]
	v_mfma_f32_16x16x32_bf16 v[4:7], v[172:175], v[214:217], v[4:7]
	v_mfma_f32_16x16x32_bf16 v[0:3], v[180:183], v[214:217], v[0:3]
	s_setprio 0
	s_barrier
	s_add_i32 s74, s74, 2
	s_add_u32 s72, s72, 0x100
	s_addc_u32 s73, s73, 0
	s_add_u32 s34, s34, 0x100
	s_addc_u32 s35, s35, 0
	s_cmp_gt_u32 s74, 13
	s_cbranch_scc0 .LBB0_120
	s_and_b64 vcc, exec, s[10:11]
	s_cbranch_vccz .LBB0_123
	s_barrier

; #define PG8_STAGE(bufoff, gbase, voff) do { const char* _gb = (const char*)(gbase); asm volatile("" : "+s"(_gb));     \
;         _Pragma("unroll") for (int _i = 0; _i < 2; ++_i) \
;         __builtin_amdgcn_global_load_lds((const unsigned*)(_gb + (voff)[_i]), (LAS unsigned*)(lds + (bufoff) + ldsw + _i * 8192), 16, 0, 0); } while (0)
; #define PG8_WAIT_V(n) asm volatile("s_waitcnt vmcnt(" #n ")" ::: "memory")
; #define PG8_BAR __builtin_amdgcn_s_barrier()
; template <class Epi>
; __device__ __forceinline__ void gemm_phase(LAS unsigned char* lds, const int wid, const Gemm g, const Epi& E) {
;     ...
;     const char* cA = PG8_UA(cur); const char* cB = PG8_UB(cur);
;     PG8_STAGE(PG8_SB(0, 0), PG8_BP(cB, 0), voffB); PG8_STAGE(PG8_SB(0, 1), PG8_BP(cB, 0) + hstepB, voffB); PG8_STAGE(PG8_SA(0, 0), PG8_AP(cA, 0), voffA); PG8_STAGE(PG8_SA(0, 1), PG8_AP(cA, 0) + hstepA, voffA);
;     if (wr == 1) PG8_BAR;
;     PG8_WAIT_V(2); PG8_BAR;
;     PG8_STAGE(PG8_SB(1, 0), PG8_BP(cB, 1), voffB); PG8_STAGE(PG8_SA(1, 0), PG8_AP(cA, 1), voffA); PG8_STAGE(PG8_SB(1, 1), PG8_BP(cB, 1) + hstepB, voffB);
;     PG8_WAIT_V(6); PG8_BAR;
;     for (;;) {
;         const bool has_next = S.next(ui + 1, nxt);
;         const char* nA = has_next ? PG8_UA(nxt) : cA; const char* nB = has_next ? PG8_UB(nxt) : cB;
;         for (int t = 0; t < nt; t += 2) {
.LBB0_339:
	s_lshl_b32 s10, s33, 5
	s_and_b32 s56, s10, 0x60
	s_lshl_b32 s55, s15, 6
	s_lshl_b32 s16, s15, 13
	s_lshr_b32 s17, s56, 3
	s_cmp_lt_u32 s33, 4
	s_cselect_b64 s[10:11], -1, 0
	s_add_u32 s12, s3, 0x5800000
	s_addc_u32 s13, s14, 0
	s_add_u32 s14, s38, 0x80
	s_addc_u32 s15, s39, 0
	s_waitcnt vmcnt(2)
	s_barrier
	s_add_i32 m0, s35, 0x18000
	s_nop 0
	global_load_lds_dwordx4 v132, s[14:15]
	s_add_i32 m0, s35, 0x1a000
	v_lshl_add_u64 v[0:1], s[14:15], 0, v[128:129]
	s_add_u32 s14, s40, 0x80
	s_addc_u32 s15, s41, 0
	s_add_i32 s57, s35, 0x8000
	global_load_lds_dwordx4 v[0:1], off
	s_mov_b32 m0, s57
	s_add_i32 s58, s35, 0xa000
	global_load_lds_dwordx4 v134, s[14:15]
	v_lshl_add_u64 v[0:1], s[14:15], 0, v[130:131]
	s_add_u32 s14, s38, 0x40080
	s_mov_b32 m0, s58
	s_addc_u32 s15, s39, 0
	global_load_lds_dwordx4 v[0:1], off
	s_add_i32 m0, s35, 0x1c000
	s_nop 0
	global_load_lds_dwordx4 v132, s[14:15]
	s_add_i32 m0, s35, 0x1e000
	s_sext_i32_i8 s63, s2
	global_load_lds_dwordx4 v128, s[14:15]
	v_and_b32_e32 v1, 48, v143
	v_lshlrev_b32_e32 v3, 6, v143
	s_movk_i32 s2, 0x3c0
	v_ashrrev_i32_e32 v0, 6, v143
	v_and_or_b32 v1, v3, s2, v1
	v_lshlrev_b32_e32 v3, 2, v143
	v_lshl_add_u32 v2, v0, 10, s16
	v_and_b32_e32 v3, 32, v3
	v_add_lshl_u32 v0, v0, s17, 10
	s_waitcnt vmcnt(6)
	v_bitop3_b32 v2, v1, v2, v3 bitop3:0xde
	v_bitop3_b32 v144, v1, v0, v3 bitop3:0xde
	s_add_i32 s61, 0, 0x10000
	s_add_i32 s62, 0, 0x14000
	s_mov_b32 s59, 0
	s_waitcnt lgkmcnt(0)
	s_ashr_i32 s60, s54, 31
	v_mov_b64_e32 v[136:137], 0x200
	v_mov_b64_e32 v[138:139], 0x1ff
	v_add_u32_e32 v145, s61, v144
	v_add_u32_e32 v146, s62, v144
	v_add_u32_e32 v147, 0, v2
	s_mov_b64 s[14:15], 0x20000
	s_mov_b64 s[16:17], 0x24000
	s_mov_b64 s[18:19], 0x28000
	s_mov_b64 s[20:21], 0x2c000
	s_barrier
	s_branch .LBB0_342

; #define PG8_STAGE(bufoff, gbase, voff) do { const char* _gb = (const char*)(gbase); asm volatile("" : "+s"(_gb));     \
;         _Pragma("unroll") for (int _i = 0; _i < 2; ++_i) \
;         __builtin_amdgcn_global_load_lds((const unsigned*)(_gb + (voff)[_i]), (LAS unsigned*)(lds + (bufoff) + ldsw + _i * 8192), 16, 0, 0); } while (0)
; #define PG8_LDA(dst, b, h) do { _Pragma("unroll") for (int m = 0; m < 4; ++m) _Pragma("unroll") for (int k = 0; k < 2; ++k) dst[m][k] = *(const LAS bf16x8*)(lds + PG8_SA(b, h) + aoff + m * 2048 + k * 1024); } while (0)
; #define PG8_LDB(dst, b, h) do { _Pragma("unroll") for (int n = 0; n < 2; ++n) _Pragma("unroll") for (int k = 0; k < 2; ++k) dst[n][k] = *(const LAS bf16x8*)(lds + PG8_SB(b, h) + boff + n * 2048 + k * 1024); } while (0)
; #define PG8_MMA(ai, bj, At, Bt) do { __builtin_amdgcn_s_setprio(1); _Pragma("unroll") for (int m = 0; m < 4; ++m) _Pragma("unroll") for (int n = 0; n < 2; ++n) _Pragma("unroll") for (int k = 0; k < 2; ++k) \
;         acc[ai][bj][m][n] = __builtin_amdgcn_mfma_f32_16x16x32_bf16(Bt[n][k], At[m][k], acc[ai][bj][m][n], 0, 0, 0); __builtin_amdgcn_s_setprio(0); } while (0)
; #define PG8_WAIT_V(n) asm volatile("s_waitcnt vmcnt(" #n ")" ::: "memory")
; #define PG8_WAIT_L(n) asm volatile("s_waitcnt lgkmcnt(" #n ")" ::: "memory")
; #define PG8_BAR __builtin_amdgcn_s_barrier()
; #define PG8_SCHED __builtin_amdgcn_sched_barrier(0)
; template <class Epi>
; __device__ __forceinline__ void gemm_phase(LAS unsigned char* lds, const int wid, const Gemm g, const Epi& E) {
;     ...
;             PG8_LDB(B0, 0, 0); PG8_LDB(B1, 0, 1); PG8_SCHED; PG8_LDA(At, 0, 0); PG8_STAGE(PG8_SA(1, 1), a1 + hstepA, voffA);
;             PG8_WAIT_V(8); PG8_WAIT_L(0); PG8_BAR; PG8_MMA(0, 0, At, B0); PG8_MMA(0, 1, At, B1); PG8_BAR; PG8_SCHED;
;             PG8_LDA(At, 0, 1); PG8_STAGE(PG8_SB(0, 0), b2, voffB); PG8_STAGE(PG8_SB(0, 1), b2 + hstepB, voffB); PG8_STAGE(PG8_SA(0, 0), a2, voffA);
;             PG8_WAIT_V(8); PG8_WAIT_L(0); PG8_BAR; PG8_MMA(1, 0, At, B0); PG8_MMA(1, 1, At, B1); PG8_BAR; PG8_SCHED;
.LBB0_349:
	ds_read_b128 v[148:151], v145
	ds_read_b128 v[152:155], v145 offset:1024
	ds_read_b128 v[156:159], v145 offset:2048
	ds_read_b128 v[160:163], v145 offset:3072
	ds_read_b128 v[164:167], v146
	ds_read_b128 v[168:171], v146 offset:1024
	ds_read_b128 v[172:175], v146 offset:2048
	ds_read_b128 v[176:179], v146 offset:3072
	s_add_u32 s40, s38, 0xfffc0080
	s_addc_u32 s41, s39, -1
	s_add_u32 s44, s70, 0xffffff80
	s_addc_u32 s45, s71, -1
	s_add_u32 s73, s38, 0xfffc0100
	s_addc_u32 s76, s39, -1
	s_add_i32 s78, s61, s23
	s_add_i32 m0, s35, 0xc000
	s_add_i32 s77, s35, 0xe000
	s_add_i32 s79, s78, 0x2000
	s_cmp_eq_u32 s72, 12
	s_cselect_b32 s43, s27, s41
	s_cselect_b32 s42, s64, s40
	s_cselect_b32 s75, s25, s45
	s_cselect_b32 s74, s65, s44
	s_cselect_b32 s41, s67, s76
	s_cselect_b32 s40, s66, s73
	s_mov_b64 s[44:45], s[38:39]
	ds_read_b128 v[180:183], v147
	ds_read_b128 v[184:187], v147 offset:1024
	ds_read_b128 v[188:191], v147 offset:2048
	ds_read_b128 v[192:195], v147 offset:3072
	ds_read_b128 v[196:199], v147 offset:4096
	ds_read_b128 v[200:203], v147 offset:5120
	ds_read_b128 v[206:209], v147 offset:6144
	ds_read_b128 v[210:213], v147 offset:7168
	s_nop 0
	global_load_lds_dwordx4 v134, s[44:45]
	s_mov_b32 m0, s77
	s_nop 0
	global_load_lds_dwordx4 v130, s[44:45]
	s_waitcnt vmcnt(8)
	s_waitcnt lgkmcnt(0)
	s_barrier
	s_setprio 1
	s_waitcnt lgkmcnt(0)
	v_mfma_f32_16x16x32_bf16 v[124:127], v[148:151], v[180:183], v[124:127]
	v_mfma_f32_16x16x32_bf16 v[120:123], v[156:159], v[180:183], v[120:123]
	v_mfma_f32_16x16x32_bf16 v[108:111], v[148:151], v[188:191], v[108:111]
	v_mfma_f32_16x16x32_bf16 v[104:107], v[156:159], v[188:191], v[104:107]
	v_mfma_f32_16x16x32_bf16 v[92:95], v[148:151], v[196:199], v[92:95]
	v_mfma_f32_16x16x32_bf16 v[88:91], v[156:159], v[196:199], v[88:91]
	v_mfma_f32_16x16x32_bf16 v[76:79], v[148:151], v[206:209], v[76:79]
	v_mfma_f32_16x16x32_bf16 v[72:75], v[156:159], v[206:209], v[72:75]
	v_mfma_f32_16x16x32_bf16 v[124:127], v[152:155], v[184:187], v[124:127]
	v_mfma_f32_16x16x32_bf16 v[120:123], v[160:163], v[184:187], v[120:123]
	v_mfma_f32_16x16x32_bf16 v[108:111], v[152:155], v[192:195], v[108:111]
	v_mfma_f32_16x16x32_bf16 v[104:107], v[160:163], v[192:195], v[104:107]
	v_mfma_f32_16x16x32_bf16 v[92:95], v[152:155], v[200:203], v[92:95]
	v_mfma_f32_16x16x32_bf16 v[88:91], v[160:163], v[200:203], v[88:91]
	v_mfma_f32_16x16x32_bf16 v[76:79], v[152:155], v[210:213], v[76:79]
	v_mfma_f32_16x16x32_bf16 v[72:75], v[160:163], v[210:213], v[72:75]
	s_setprio 0
	s_setprio 1
	v_mfma_f32_16x16x32_bf16 v[116:119], v[164:167], v[180:183], v[116:119]
	v_mfma_f32_16x16x32_bf16 v[112:115], v[172:175], v[180:183], v[112:115]
	v_mfma_f32_16x16x32_bf16 v[100:103], v[164:167], v[188:191], v[100:103]
	v_mfma_f32_16x16x32_bf16 v[96:99], v[172:175], v[188:191], v[96:99]
	v_mfma_f32_16x16x32_bf16 v[84:87], v[164:167], v[196:199], v[84:87]
	v_mfma_f32_16x16x32_bf16 v[80:83], v[172:175], v[196:199], v[80:83]
	v_mfma_f32_16x16x32_bf16 v[68:71], v[164:167], v[206:209], v[68:71]
	v_mfma_f32_16x16x32_bf16 v[64:67], v[172:175], v[206:209], v[64:67]
	v_mfma_f32_16x16x32_bf16 v[116:119], v[168:171], v[184:187], v[116:119]
	v_mfma_f32_16x16x32_bf16 v[112:115], v[176:179], v[184:187], v[112:115]
	v_mfma_f32_16x16x32_bf16 v[100:103], v[168:171], v[192:195], v[100:103]
	v_mfma_f32_16x16x32_bf16 v[96:99], v[176:179], v[192:195], v[96:99]
	v_mfma_f32_16x16x32_bf16 v[84:87], v[168:171], v[200:203], v[84:87]
	v_mfma_f32_16x16x32_bf16 v[80:83], v[176:179], v[200:203], v[80:83]
	v_mfma_f32_16x16x32_bf16 v[68:71], v[168:171], v[210:213], v[68:71]
	v_mfma_f32_16x16x32_bf16 v[64:67], v[176:179], v[210:213], v[64:67]
	s_setprio 0
	s_barrier
	s_mov_b64 s[44:45], s[74:75]
	s_mov_b32 m0, s78
	ds_read_b128 v[180:183], v147 offset:16384
	ds_read_b128 v[184:187], v147 offset:17408
	ds_read_b128 v[188:191], v147 offset:18432
	ds_read_b128 v[192:195], v147 offset:19456
	ds_read_b128 v[196:199], v147 offset:20480
	ds_read_b128 v[200:203], v147 offset:21504
	ds_read_b128 v[206:209], v147 offset:22528
	ds_read_b128 v[210:213], v147 offset:23552
	s_nop 0
	global_load_lds_dwordx4 v132, s[44:45]
	v_lshl_add_u64 v[140:141], s[44:45], 0, v[128:129]
	s_cselect_b32 s45, s69, s71
	s_cselect_b32 s44, s68, s70
	s_add_u32 s74, s74, 0x40000
	s_mov_b32 m0, s79
	s_addc_u32 s75, s75, 0
	s_add_i32 s73, s62, s23
	global_load_lds_dwordx4 v[140:141], off
	s_mov_b32 m0, s73
	s_nop 0
	global_load_lds_dwordx4 v132, s[74:75]
	v_lshl_add_u64 v[140:141], s[74:75], 0, v[128:129]
	s_add_i32 m0, s73, 0x2000
	s_mov_b64 s[74:75], s[42:43]
	global_load_lds_dwordx4 v[140:141], off
	s_mov_b32 m0, s35
	s_nop 0
	global_load_lds_dwordx4 v134, s[74:75]
	s_mov_b32 m0, s51
	s_nop 0
	global_load_lds_dwordx4 v130, s[74:75]
	s_waitcnt vmcnt(8)
	s_waitcnt lgkmcnt(0)
	s_barrier
; #define PG8_STAGE(bufoff, gbase, voff) do { const char* _gb = (const char*)(gbase); asm volatile("" : "+s"(_gb));     \
;         _Pragma("unroll") for (int _i = 0; _i < 2; ++_i) \
;         __builtin_amdgcn_global_load_lds((const unsigned*)(_gb + (voff)[_i]), (LAS unsigned*)(lds + (bufoff) + ldsw + _i * 8192), 16, 0, 0); } while (0)
; #define PG8_LDA(dst, b, h) do { _Pragma("unroll") for (int m = 0; m < 4; ++m) _Pragma("unroll") for (int k = 0; k < 2; ++k) dst[m][k] = *(const LAS bf16x8*)(lds + PG8_SA(b, h) + aoff + m * 2048 + k * 1024); } while (0)
; #define PG8_LDB(dst, b, h) do { _Pragma("unroll") for (int n = 0; n < 2; ++n) _Pragma("unroll") for (int k = 0; k < 2; ++k) dst[n][k] = *(const LAS bf16x8*)(lds + PG8_SB(b, h) + boff + n * 2048 + k * 1024); } while (0)
; #define PG8_MMA(ai, bj, At, Bt) do { __builtin_amdgcn_s_setprio(1); _Pragma("unroll") for (int m = 0; m < 4; ++m) _Pragma("unroll") for (int n = 0; n < 2; ++n) _Pragma("unroll") for (int k = 0; k < 2; ++k) \
;         acc[ai][bj][m][n] = __builtin_amdgcn_mfma_f32_16x16x32_bf16(Bt[n][k], At[m][k], acc[ai][bj][m][n], 0, 0, 0); __builtin_amdgcn_s_setprio(0); } while (0)
; #define PG8_WAIT_V(n) asm volatile("s_waitcnt vmcnt(" #n ")" ::: "memory")
; #define PG8_WAIT_L(n) asm volatile("s_waitcnt lgkmcnt(" #n ")" ::: "memory")
; #define PG8_BAR __builtin_amdgcn_s_barrier()
; #define PG8_SCHED __builtin_amdgcn_sched_barrier(0)
; template <class Epi>
; __device__ __forceinline__ void gemm_phase(LAS unsigned char* lds, const int wid, const Gemm g, const Epi& E) {
;     ...
;             PG8_WAIT_V(8); PG8_WAIT_L(0); PG8_BAR; PG8_MMA(1, 0, At, B0); PG8_MMA(1, 1, At, B1); PG8_BAR; PG8_SCHED;
;             PG8_LDB(B0, 1, 0); PG8_LDB(B1, 1, 1); PG8_SCHED; PG8_LDA(At, 1, 0); PG8_STAGE(PG8_SA(0, 1), a2 + hstepA, voffA);
;             PG8_WAIT_V(8); PG8_WAIT_L(0); PG8_BAR; PG8_MMA(0, 0, At, B0); PG8_MMA(0, 1, At, B1); PG8_BAR; PG8_SCHED;
	s_setprio 1
	s_waitcnt lgkmcnt(0)
	v_mfma_f32_16x16x32_bf16 v[60:63], v[148:151], v[180:183], v[60:63]
	v_mfma_f32_16x16x32_bf16 v[56:59], v[156:159], v[180:183], v[56:59]
	v_mfma_f32_16x16x32_bf16 v[44:47], v[148:151], v[188:191], v[44:47]
	v_mfma_f32_16x16x32_bf16 v[40:43], v[156:159], v[188:191], v[40:43]
	v_mfma_f32_16x16x32_bf16 v[28:31], v[148:151], v[196:199], v[28:31]
	v_mfma_f32_16x16x32_bf16 v[24:27], v[156:159], v[196:199], v[24:27]
	v_mfma_f32_16x16x32_bf16 v[12:15], v[148:151], v[206:209], v[12:15]
	v_mfma_f32_16x16x32_bf16 v[8:11], v[156:159], v[206:209], v[8:11]
	v_mfma_f32_16x16x32_bf16 v[60:63], v[152:155], v[184:187], v[60:63]
	v_mfma_f32_16x16x32_bf16 v[56:59], v[160:163], v[184:187], v[56:59]
	v_mfma_f32_16x16x32_bf16 v[44:47], v[152:155], v[192:195], v[44:47]
	v_mfma_f32_16x16x32_bf16 v[40:43], v[160:163], v[192:195], v[40:43]
	v_mfma_f32_16x16x32_bf16 v[28:31], v[152:155], v[200:203], v[28:31]
	v_mfma_f32_16x16x32_bf16 v[24:27], v[160:163], v[200:203], v[24:27]
	v_mfma_f32_16x16x32_bf16 v[12:15], v[152:155], v[210:213], v[12:15]
	v_mfma_f32_16x16x32_bf16 v[8:11], v[160:163], v[210:213], v[8:11]
	s_setprio 0
	s_setprio 1
	v_mfma_f32_16x16x32_bf16 v[52:55], v[164:167], v[180:183], v[52:55]
	v_mfma_f32_16x16x32_bf16 v[48:51], v[172:175], v[180:183], v[48:51]
	v_mfma_f32_16x16x32_bf16 v[36:39], v[164:167], v[188:191], v[36:39]
	v_mfma_f32_16x16x32_bf16 v[32:35], v[172:175], v[188:191], v[32:35]
	v_mfma_f32_16x16x32_bf16 v[20:23], v[164:167], v[196:199], v[20:23]
	v_mfma_f32_16x16x32_bf16 v[16:19], v[172:175], v[196:199], v[16:19]
	v_mfma_f32_16x16x32_bf16 v[4:7], v[164:167], v[206:209], v[4:7]
	v_mfma_f32_16x16x32_bf16 v[0:3], v[172:175], v[206:209], v[0:3]
	v_mfma_f32_16x16x32_bf16 v[52:55], v[168:171], v[184:187], v[52:55]
	v_mfma_f32_16x16x32_bf16 v[48:51], v[176:179], v[184:187], v[48:51]
	v_mfma_f32_16x16x32_bf16 v[36:39], v[168:171], v[192:195], v[36:39]
	v_mfma_f32_16x16x32_bf16 v[32:35], v[176:179], v[192:195], v[32:35]
	v_mfma_f32_16x16x32_bf16 v[20:23], v[168:171], v[200:203], v[20:23]
	v_mfma_f32_16x16x32_bf16 v[16:19], v[176:179], v[200:203], v[16:19]
	v_mfma_f32_16x16x32_bf16 v[4:7], v[168:171], v[210:213], v[4:7]
	v_mfma_f32_16x16x32_bf16 v[0:3], v[176:179], v[210:213], v[0:3]
	s_setprio 0
	s_barrier
	s_add_i32 s73, 0, 0x18000
	v_add_u32_e32 v140, s73, v144
	s_add_i32 s74, 0, 0x1c000
	ds_read_b128 v[148:151], v140
	ds_read_b128 v[152:155], v140 offset:1024
	ds_read_b128 v[156:159], v140 offset:2048
	ds_read_b128 v[160:163], v140 offset:3072
	v_add_u32_e32 v140, s74, v144
	ds_read_b128 v[164:167], v140
	ds_read_b128 v[168:171], v140 offset:1024
	ds_read_b128 v[172:175], v140 offset:2048
	ds_read_b128 v[176:179], v140 offset:3072
	s_add_u32 s42, s42, 0x40000
	s_addc_u32 s43, s43, 0
	s_mov_b32 m0, s52
	ds_read_b128 v[180:183], v147 offset:32768
	ds_read_b128 v[184:187], v147 offset:33792
	ds_read_b128 v[188:191], v147 offset:34816
	ds_read_b128 v[192:195], v147 offset:35840
	ds_read_b128 v[196:199], v147 offset:36864
	ds_read_b128 v[200:203], v147 offset:37888
	ds_read_b128 v[206:209], v147 offset:38912
	ds_read_b128 v[210:213], v147 offset:39936
	s_nop 0
	global_load_lds_dwordx4 v134, s[42:43]
	s_mov_b32 m0, s53
	s_nop 0
	global_load_lds_dwordx4 v130, s[42:43]
	s_waitcnt vmcnt(8)
	s_waitcnt lgkmcnt(0)
	s_barrier
	s_setprio 1
	s_waitcnt lgkmcnt(0)
	v_mfma_f32_16x16x32_bf16 v[124:127], v[148:151], v[180:183], v[124:127]
	v_mfma_f32_16x16x32_bf16 v[120:123], v[156:159], v[180:183], v[120:123]
	v_mfma_f32_16x16x32_bf16 v[108:111], v[148:151], v[188:191], v[108:111]
	v_mfma_f32_16x16x32_bf16 v[104:107], v[156:159], v[188:191], v[104:107]
	v_mfma_f32_16x16x32_bf16 v[92:95], v[148:151], v[196:199], v[92:95]
	v_mfma_f32_16x16x32_bf16 v[88:91], v[156:159], v[196:199], v[88:91]
	v_mfma_f32_16x16x32_bf16 v[76:79], v[148:151], v[206:209], v[76:79]
	v_mfma_f32_16x16x32_bf16 v[72:75], v[156:159], v[206:209], v[72:75]
	v_mfma_f32_16x16x32_bf16 v[124:127], v[152:155], v[184:187], v[124:127]
	v_mfma_f32_16x16x32_bf16 v[120:123], v[160:163], v[184:187], v[120:123]
	v_mfma_f32_16x16x32_bf16 v[108:111], v[152:155], v[192:195], v[108:111]
	v_mfma_f32_16x16x32_bf16 v[104:107], v[160:163], v[192:195], v[104:107]
	v_mfma_f32_16x16x32_bf16 v[92:95], v[152:155], v[200:203], v[92:95]
	v_mfma_f32_16x16x32_bf16 v[88:91], v[160:163], v[200:203], v[88:91]
	v_mfma_f32_16x16x32_bf16 v[76:79], v[152:155], v[210:213], v[76:79]
	v_mfma_f32_16x16x32_bf16 v[72:75], v[160:163], v[210:213], v[72:75]
	s_setprio 0
	s_setprio 1
	v_mfma_f32_16x16x32_bf16 v[116:119], v[164:167], v[180:183], v[116:119]
	v_mfma_f32_16x16x32_bf16 v[112:115], v[172:175], v[180:183], v[112:115]
	v_mfma_f32_16x16x32_bf16 v[100:103], v[164:167], v[188:191], v[100:103]
	v_mfma_f32_16x16x32_bf16 v[96:99], v[172:175], v[188:191], v[96:99]
	v_mfma_f32_16x16x32_bf16 v[84:87], v[164:167], v[196:199], v[84:87]
	v_mfma_f32_16x16x32_bf16 v[80:83], v[172:175], v[196:199], v[80:83]
	v_mfma_f32_16x16x32_bf16 v[68:71], v[164:167], v[206:209], v[68:71]
	v_mfma_f32_16x16x32_bf16 v[64:67], v[172:175], v[206:209], v[64:67]
	v_mfma_f32_16x16x32_bf16 v[116:119], v[168:171], v[184:187], v[116:119]
	v_mfma_f32_16x16x32_bf16 v[112:115], v[176:179], v[184:187], v[112:115]
	v_mfma_f32_16x16x32_bf16 v[100:103], v[168:171], v[192:195], v[100:103]
	v_mfma_f32_16x16x32_bf16 v[96:99], v[176:179], v[192:195], v[96:99]
	v_mfma_f32_16x16x32_bf16 v[84:87], v[168:171], v[200:203], v[84:87]
	v_mfma_f32_16x16x32_bf16 v[80:83], v[176:179], v[200:203], v[80:83]
	v_mfma_f32_16x16x32_bf16 v[68:71], v[168:171], v[210:213], v[68:71]
	v_mfma_f32_16x16x32_bf16 v[64:67], v[176:179], v[210:213], v[64:67]
	s_setprio 0
	s_barrier
; #define PG8_STAGE(bufoff, gbase, voff) do { const char* _gb = (const char*)(gbase); asm volatile("" : "+s"(_gb));     \
;         _Pragma("unroll") for (int _i = 0; _i < 2; ++_i) \
;         __builtin_amdgcn_global_load_lds((const unsigned*)(_gb + (voff)[_i]), (LAS unsigned*)(lds + (bufoff) + ldsw + _i * 8192), 16, 0, 0); } while (0)
; #define PG8_LDA(dst, b, h) do { _Pragma("unroll") for (int m = 0; m < 4; ++m) _Pragma("unroll") for (int k = 0; k < 2; ++k) dst[m][k] = *(const LAS bf16x8*)(lds + PG8_SA(b, h) + aoff + m * 2048 + k * 1024); } while (0)
; #define PG8_MMA(ai, bj, At, Bt) do { __builtin_amdgcn_s_setprio(1); _Pragma("unroll") for (int m = 0; m < 4; ++m) _Pragma("unroll") for (int n = 0; n < 2; ++n) _Pragma("unroll") for (int k = 0; k < 2; ++k) \
;         acc[ai][bj][m][n] = __builtin_amdgcn_mfma_f32_16x16x32_bf16(Bt[n][k], At[m][k], acc[ai][bj][m][n], 0, 0, 0); __builtin_amdgcn_s_setprio(0); } while (0)
; #define PG8_WAIT_V(n) asm volatile("s_waitcnt vmcnt(" #n ")" ::: "memory")
; #define PG8_WAIT_L(n) asm volatile("s_waitcnt lgkmcnt(" #n ")" ::: "memory")
; #define PG8_BAR __builtin_amdgcn_s_barrier()
; #define PG8_SCHED __builtin_amdgcn_sched_barrier(0)
; template <class Epi>
; __device__ __forceinline__ void gemm_phase(LAS unsigned char* lds, const int wid, const Gemm g, const Epi& E) {
;     ...
;             PG8_WAIT_V(8); PG8_WAIT_L(0); PG8_BAR; PG8_MMA(0, 0, At, B0); PG8_MMA(0, 1, At, B1); PG8_BAR; PG8_SCHED;
;             PG8_LDA(At, 1, 1); PG8_STAGE(PG8_SB(1, 0), b3, voffB); PG8_STAGE(PG8_SB(1, 1), b3 + hstepB, voffB); PG8_STAGE(PG8_SA(1, 0), a3, voffA);
;             PG8_WAIT_V(8); PG8_WAIT_L(0); PG8_BAR; PG8_MMA(1, 0, At, B0); PG8_MMA(1, 1, At, B1); PG8_BAR; PG8_SCHED;
;         }
;         if (wr == 0) PG8_BAR;
	s_mov_b64 s[42:43], s[44:45]
	s_add_i32 s73, s73, s23
	ds_read_b128 v[180:183], v147 offset:49152
	ds_read_b128 v[184:187], v147 offset:50176
	ds_read_b128 v[188:191], v147 offset:51200
	ds_read_b128 v[192:195], v147 offset:52224
	ds_read_b128 v[196:199], v147 offset:53248
	ds_read_b128 v[200:203], v147 offset:54272
	ds_read_b128 v[206:209], v147 offset:55296
	ds_read_b128 v[210:213], v147 offset:56320
	s_mov_b32 m0, s73
	s_nop 0
	global_load_lds_dwordx4 v132, s[42:43]
	s_add_i32 m0, s73, 0x2000
	v_lshl_add_u64 v[140:141], s[42:43], 0, v[128:129]
	s_add_u32 s42, s44, 0x40000
	s_addc_u32 s43, s45, 0
	s_add_i32 s44, s74, s23
	global_load_lds_dwordx4 v[140:141], off
	s_mov_b32 m0, s44
	s_nop 0
	global_load_lds_dwordx4 v132, s[42:43]
	s_add_i32 m0, s44, 0x2000
	s_nop 0
	global_load_lds_dwordx4 v128, s[42:43]
	s_mov_b32 m0, s57
	s_nop 0
	global_load_lds_dwordx4 v134, s[40:41]
	s_mov_b32 m0, s58
	s_nop 0
	global_load_lds_dwordx4 v130, s[40:41]
	s_waitcnt vmcnt(8)
	s_waitcnt lgkmcnt(0)
	s_barrier
	s_setprio 1
	s_waitcnt lgkmcnt(0)
	v_mfma_f32_16x16x32_bf16 v[60:63], v[148:151], v[180:183], v[60:63]
	v_mfma_f32_16x16x32_bf16 v[56:59], v[156:159], v[180:183], v[56:59]
	v_mfma_f32_16x16x32_bf16 v[44:47], v[148:151], v[188:191], v[44:47]
	v_mfma_f32_16x16x32_bf16 v[40:43], v[156:159], v[188:191], v[40:43]
	v_mfma_f32_16x16x32_bf16 v[28:31], v[148:151], v[196:199], v[28:31]
	v_mfma_f32_16x16x32_bf16 v[24:27], v[156:159], v[196:199], v[24:27]
	v_mfma_f32_16x16x32_bf16 v[12:15], v[148:151], v[206:209], v[12:15]
	v_mfma_f32_16x16x32_bf16 v[8:11], v[156:159], v[206:209], v[8:11]
	v_mfma_f32_16x16x32_bf16 v[60:63], v[152:155], v[184:187], v[60:63]
	v_mfma_f32_16x16x32_bf16 v[56:59], v[160:163], v[184:187], v[56:59]
	v_mfma_f32_16x16x32_bf16 v[44:47], v[152:155], v[192:195], v[44:47]
	v_mfma_f32_16x16x32_bf16 v[40:43], v[160:163], v[192:195], v[40:43]
	v_mfma_f32_16x16x32_bf16 v[28:31], v[152:155], v[200:203], v[28:31]
	v_mfma_f32_16x16x32_bf16 v[24:27], v[160:163], v[200:203], v[24:27]
	v_mfma_f32_16x16x32_bf16 v[12:15], v[152:155], v[210:213], v[12:15]
	v_mfma_f32_16x16x32_bf16 v[8:11], v[160:163], v[210:213], v[8:11]
	s_setprio 0
	s_setprio 1
	v_mfma_f32_16x16x32_bf16 v[52:55], v[164:167], v[180:183], v[52:55]
	v_mfma_f32_16x16x32_bf16 v[48:51], v[172:175], v[180:183], v[48:51]
	v_mfma_f32_16x16x32_bf16 v[36:39], v[164:167], v[188:191], v[36:39]
	v_mfma_f32_16x16x32_bf16 v[32:35], v[172:175], v[188:191], v[32:35]
	v_mfma_f32_16x16x32_bf16 v[20:23], v[164:167], v[196:199], v[20:23]
	v_mfma_f32_16x16x32_bf16 v[16:19], v[172:175], v[196:199], v[16:19]
	v_mfma_f32_16x16x32_bf16 v[4:7], v[164:167], v[206:209], v[4:7]
	v_mfma_f32_16x16x32_bf16 v[0:3], v[172:175], v[206:209], v[0:3]
	v_mfma_f32_16x16x32_bf16 v[52:55], v[168:171], v[184:187], v[52:55]
	v_mfma_f32_16x16x32_bf16 v[48:51], v[176:179], v[184:187], v[48:51]
	v_mfma_f32_16x16x32_bf16 v[36:39], v[168:171], v[192:195], v[36:39]
	v_mfma_f32_16x16x32_bf16 v[32:35], v[176:179], v[192:195], v[32:35]
	v_mfma_f32_16x16x32_bf16 v[20:23], v[168:171], v[200:203], v[20:23]
	v_mfma_f32_16x16x32_bf16 v[16:19], v[176:179], v[200:203], v[16:19]
	v_mfma_f32_16x16x32_bf16 v[4:7], v[168:171], v[210:213], v[4:7]
	v_mfma_f32_16x16x32_bf16 v[0:3], v[176:179], v[210:213], v[0:3]
	s_setprio 0
	s_barrier
	s_add_i32 s72, s72, 2
	s_add_u32 s70, s70, 0x100
	s_addc_u32 s71, s71, 0
	s_add_u32 s38, s38, 0x100
	s_addc_u32 s39, s39, 0
	s_cmp_gt_u32 s72, 13
	s_cbranch_scc0 .LBB0_349
	s_and_b64 vcc, exec, s[10:11]
	s_cbranch_vccz .LBB0_352
	s_barrier

; #define PG8_STAGE(bufoff, gbase, voff) do { const char* _gb = (const char*)(gbase); asm volatile("" : "+s"(_gb));     \
;         _Pragma("unroll") for (int _i = 0; _i < 2; ++_i) \
;         __builtin_amdgcn_global_load_lds((const unsigned*)(_gb + (voff)[_i]), (LAS unsigned*)(lds + (bufoff) + ldsw + _i * 8192), 16, 0, 0); } while (0)
; #define PG8_WAIT_V(n) asm volatile("s_waitcnt vmcnt(" #n ")" ::: "memory")
; #define PG8_BAR __builtin_amdgcn_s_barrier()
; template <class Epi>
; __device__ __forceinline__ void gemm_phase(LAS unsigned char* lds, const int wid, const Gemm g, const Epi& E) {
;     ...
;     const char* cA = PG8_UA(cur); const char* cB = PG8_UB(cur);
;     PG8_STAGE(PG8_SB(0, 0), PG8_BP(cB, 0), voffB); PG8_STAGE(PG8_SB(0, 1), PG8_BP(cB, 0) + hstepB, voffB); PG8_STAGE(PG8_SA(0, 0), PG8_AP(cA, 0), voffA); PG8_STAGE(PG8_SA(0, 1), PG8_AP(cA, 0) + hstepA, voffA);
;     if (wr == 1) PG8_BAR;
;     PG8_WAIT_V(2); PG8_BAR;
;     PG8_STAGE(PG8_SB(1, 0), PG8_BP(cB, 1), voffB); PG8_STAGE(PG8_SA(1, 0), PG8_AP(cA, 1), voffA); PG8_STAGE(PG8_SB(1, 1), PG8_BP(cB, 1) + hstepB, voffB);
;     PG8_WAIT_V(6); PG8_BAR;
;     for (;;) {
;         const bool has_next = S.next(ui + 1, nxt);
;         const char* nA = has_next ? PG8_UA(nxt) : cA; const char* nB = has_next ? PG8_UB(nxt) : cB;
;         for (int t = 0; t < nt; t += 2) {
.LBB0_475:
	s_lshl_b32 s8, s33, 5
	s_and_b32 s47, s8, 0x60
	s_lshl_b32 s46, s13, 6
	s_lshl_b32 s14, s13, 13
	s_lshr_b32 s15, s47, 3
	s_cmp_lt_u32 s33, 4
	s_cselect_b64 s[8:9], -1, 0
	s_add_u32 s10, s3, 0x9800000
	s_addc_u32 s11, s12, 0
	s_add_u32 s12, s24, 0x80
	s_addc_u32 s13, s25, 0
	s_waitcnt vmcnt(2)
	s_barrier
	s_add_i32 m0, s21, 0x18000
	s_nop 0
	global_load_lds_dwordx4 v132, s[12:13]
	s_add_i32 m0, s21, 0x1a000
	v_lshl_add_u64 v[0:1], s[12:13], 0, v[128:129]
	s_add_u32 s12, s26, 0x80
	s_addc_u32 s13, s27, 0
	s_add_i32 s48, s21, 0x8000
	global_load_lds_dwordx4 v[0:1], off
	s_mov_b32 m0, s48
	s_add_i32 s49, s21, 0xa000
	global_load_lds_dwordx4 v134, s[12:13]
	v_lshl_add_u64 v[0:1], s[12:13], 0, v[130:131]
	s_add_u32 s12, s24, 0x40080
	s_mov_b32 m0, s49
	s_addc_u32 s13, s25, 0
	global_load_lds_dwordx4 v[0:1], off
	s_add_i32 m0, s21, 0x1c000
	s_nop 0
	global_load_lds_dwordx4 v132, s[12:13]
	s_add_i32 m0, s21, 0x1e000
	s_sext_i32_i16 s55, s2
	global_load_lds_dwordx4 v128, s[12:13]
	v_and_b32_e32 v1, 48, v141
	v_lshlrev_b32_e32 v3, 6, v141
	s_movk_i32 s2, 0x3c0
	v_ashrrev_i32_e32 v0, 6, v141
	v_and_or_b32 v1, v3, s2, v1
	v_lshlrev_b32_e32 v3, 2, v141
	v_lshl_add_u32 v2, v0, 10, s14
	v_and_b32_e32 v3, 32, v3
	v_add_lshl_u32 v0, v0, s15, 10
	s_waitcnt vmcnt(6)
	v_bitop3_b32 v2, v1, v2, v3 bitop3:0xde
	v_bitop3_b32 v142, v1, v0, v3 bitop3:0xde
	s_add_i32 s52, 0, 0x10000
	s_add_i32 s53, 0, 0x14000
	s_mov_b32 s50, 0
	s_waitcnt lgkmcnt(0)
	s_ashr_i32 s51, s45, 31
	v_mov_b64_e32 v[136:137], 0xb00
	v_mov_b64_e32 v[138:139], 0xaff
	v_add_u32_e32 v143, s52, v142
	v_add_u32_e32 v144, s53, v142
	v_add_u32_e32 v145, 0, v2
	s_movk_i32 s54, 0x1600
	s_barrier
	s_branch .LBB0_478

; #define PG8_STAGE(bufoff, gbase, voff) do { const char* _gb = (const char*)(gbase); asm volatile("" : "+s"(_gb));     \
;         _Pragma("unroll") for (int _i = 0; _i < 2; ++_i) \
;         __builtin_amdgcn_global_load_lds((const unsigned*)(_gb + (voff)[_i]), (LAS unsigned*)(lds + (bufoff) + ldsw + _i * 8192), 16, 0, 0); } while (0)
; #define PG8_LDA(dst, b, h) do { _Pragma("unroll") for (int m = 0; m < 4; ++m) _Pragma("unroll") for (int k = 0; k < 2; ++k) dst[m][k] = *(const LAS bf16x8*)(lds + PG8_SA(b, h) + aoff + m * 2048 + k * 1024); } while (0)
; #define PG8_LDB(dst, b, h) do { _Pragma("unroll") for (int n = 0; n < 2; ++n) _Pragma("unroll") for (int k = 0; k < 2; ++k) dst[n][k] = *(const LAS bf16x8*)(lds + PG8_SB(b, h) + boff + n * 2048 + k * 1024); } while (0)
; #define PG8_MMA(ai, bj, At, Bt) do { __builtin_amdgcn_s_setprio(1); _Pragma("unroll") for (int m = 0; m < 4; ++m) _Pragma("unroll") for (int n = 0; n < 2; ++n) _Pragma("unroll") for (int k = 0; k < 2; ++k) \
;         acc[ai][bj][m][n] = __builtin_amdgcn_mfma_f32_16x16x32_bf16(Bt[n][k], At[m][k], acc[ai][bj][m][n], 0, 0, 0); __builtin_amdgcn_s_setprio(0); } while (0)
; #define PG8_WAIT_V(n) asm volatile("s_waitcnt vmcnt(" #n ")" ::: "memory")
; #define PG8_WAIT_L(n) asm volatile("s_waitcnt lgkmcnt(" #n ")" ::: "memory")
; #define PG8_BAR __builtin_amdgcn_s_barrier()
; #define PG8_SCHED __builtin_amdgcn_sched_barrier(0)
; template <class Epi>
; __device__ __forceinline__ void gemm_phase(LAS unsigned char* lds, const int wid, const Gemm g, const Epi& E) {
;     ...
;             PG8_LDB(B0, 0, 0); PG8_LDB(B1, 0, 1); PG8_SCHED; PG8_LDA(At, 0, 0); PG8_STAGE(PG8_SA(1, 1), a1 + hstepA, voffA);
;             PG8_WAIT_V(8); PG8_WAIT_L(0); PG8_BAR; PG8_MMA(0, 0, At, B0); PG8_MMA(0, 1, At, B1); PG8_BAR; PG8_SCHED;
;             PG8_LDA(At, 0, 1); PG8_STAGE(PG8_SB(0, 0), b2, voffB); PG8_STAGE(PG8_SB(0, 1), b2 + hstepB, voffB); PG8_STAGE(PG8_SA(0, 0), a2, voffA);
;             PG8_WAIT_V(8); PG8_WAIT_L(0); PG8_BAR; PG8_MMA(1, 0, At, B0); PG8_MMA(1, 1, At, B1); PG8_BAR; PG8_SCHED;
.LBB0_481:
	ds_read_b128 v[146:149], v143
	ds_read_b128 v[150:153], v143 offset:1024
	ds_read_b128 v[154:157], v143 offset:2048
	ds_read_b128 v[158:161], v143 offset:3072
	ds_read_b128 v[162:165], v144
	ds_read_b128 v[166:169], v144 offset:1024
	ds_read_b128 v[170:173], v144 offset:2048
	ds_read_b128 v[174:177], v144 offset:3072
	s_add_u32 s26, s24, 0xfffc0080
	s_addc_u32 s27, s25, -1
	s_add_u32 s30, s62, 0xffffff80
	s_addc_u32 s31, s63, -1
	s_add_u32 s65, s24, 0xfffc0100
	s_addc_u32 s68, s25, -1
	s_add_i32 s70, s52, s23
	s_add_i32 m0, s21, 0xc000
	s_add_i32 s69, s21, 0xe000
	s_add_i32 s71, s70, 0x2000
	s_cmp_eq_u32 s64, 12
	s_cselect_b32 s29, s15, s27
	s_cselect_b32 s28, s56, s26
	s_cselect_b32 s67, s13, s31
	s_cselect_b32 s66, s57, s30
	s_cselect_b32 s27, s59, s68
	s_cselect_b32 s26, s58, s65
	s_mov_b64 s[30:31], s[24:25]
	ds_read_b128 v[178:181], v145
	ds_read_b128 v[182:185], v145 offset:1024
	ds_read_b128 v[186:189], v145 offset:2048
	ds_read_b128 v[190:193], v145 offset:3072
	ds_read_b128 v[194:197], v145 offset:4096
	ds_read_b128 v[198:201], v145 offset:5120
	ds_read_b128 v[206:209], v145 offset:6144
	ds_read_b128 v[210:213], v145 offset:7168
	s_nop 0
	global_load_lds_dwordx4 v134, s[30:31]
	s_mov_b32 m0, s69
	s_nop 0
	global_load_lds_dwordx4 v130, s[30:31]
	s_waitcnt vmcnt(8)
	s_waitcnt lgkmcnt(0)
	s_barrier
	s_setprio 1
	s_waitcnt lgkmcnt(0)
	v_mfma_f32_16x16x32_bf16 v[124:127], v[146:149], v[178:181], v[124:127]
	v_mfma_f32_16x16x32_bf16 v[120:123], v[154:157], v[178:181], v[120:123]
	v_mfma_f32_16x16x32_bf16 v[108:111], v[146:149], v[186:189], v[108:111]
	v_mfma_f32_16x16x32_bf16 v[104:107], v[154:157], v[186:189], v[104:107]
	v_mfma_f32_16x16x32_bf16 v[92:95], v[146:149], v[194:197], v[92:95]
	v_mfma_f32_16x16x32_bf16 v[88:91], v[154:157], v[194:197], v[88:91]
	v_mfma_f32_16x16x32_bf16 v[76:79], v[146:149], v[206:209], v[76:79]
	v_mfma_f32_16x16x32_bf16 v[72:75], v[154:157], v[206:209], v[72:75]
	v_mfma_f32_16x16x32_bf16 v[124:127], v[150:153], v[182:185], v[124:127]
	v_mfma_f32_16x16x32_bf16 v[120:123], v[158:161], v[182:185], v[120:123]
	v_mfma_f32_16x16x32_bf16 v[108:111], v[150:153], v[190:193], v[108:111]
	v_mfma_f32_16x16x32_bf16 v[104:107], v[158:161], v[190:193], v[104:107]
	v_mfma_f32_16x16x32_bf16 v[92:95], v[150:153], v[198:201], v[92:95]
	v_mfma_f32_16x16x32_bf16 v[88:91], v[158:161], v[198:201], v[88:91]
	v_mfma_f32_16x16x32_bf16 v[76:79], v[150:153], v[210:213], v[76:79]
	v_mfma_f32_16x16x32_bf16 v[72:75], v[158:161], v[210:213], v[72:75]
	s_setprio 0
	s_setprio 1
	v_mfma_f32_16x16x32_bf16 v[116:119], v[162:165], v[178:181], v[116:119]
	v_mfma_f32_16x16x32_bf16 v[112:115], v[170:173], v[178:181], v[112:115]
	v_mfma_f32_16x16x32_bf16 v[100:103], v[162:165], v[186:189], v[100:103]
	v_mfma_f32_16x16x32_bf16 v[96:99], v[170:173], v[186:189], v[96:99]
	v_mfma_f32_16x16x32_bf16 v[84:87], v[162:165], v[194:197], v[84:87]
	v_mfma_f32_16x16x32_bf16 v[80:83], v[170:173], v[194:197], v[80:83]
	v_mfma_f32_16x16x32_bf16 v[68:71], v[162:165], v[206:209], v[68:71]
	v_mfma_f32_16x16x32_bf16 v[64:67], v[170:173], v[206:209], v[64:67]
	v_mfma_f32_16x16x32_bf16 v[116:119], v[166:169], v[182:185], v[116:119]
	v_mfma_f32_16x16x32_bf16 v[112:115], v[174:177], v[182:185], v[112:115]
	v_mfma_f32_16x16x32_bf16 v[100:103], v[166:169], v[190:193], v[100:103]
	v_mfma_f32_16x16x32_bf16 v[96:99], v[174:177], v[190:193], v[96:99]
	v_mfma_f32_16x16x32_bf16 v[84:87], v[166:169], v[198:201], v[84:87]
	v_mfma_f32_16x16x32_bf16 v[80:83], v[174:177], v[198:201], v[80:83]
	v_mfma_f32_16x16x32_bf16 v[68:71], v[166:169], v[210:213], v[68:71]
	v_mfma_f32_16x16x32_bf16 v[64:67], v[174:177], v[210:213], v[64:67]
	s_setprio 0
	s_barrier
	s_mov_b64 s[30:31], s[66:67]
	s_mov_b32 m0, s70
	ds_read_b128 v[178:181], v145 offset:16384
	ds_read_b128 v[182:185], v145 offset:17408
	ds_read_b128 v[186:189], v145 offset:18432
	ds_read_b128 v[190:193], v145 offset:19456
	ds_read_b128 v[194:197], v145 offset:20480
	ds_read_b128 v[198:201], v145 offset:21504
	ds_read_b128 v[206:209], v145 offset:22528
	ds_read_b128 v[210:213], v145 offset:23552
	s_nop 0
	global_load_lds_dwordx4 v132, s[30:31]
	v_lshl_add_u64 v[202:203], s[30:31], 0, v[128:129]
	s_cselect_b32 s31, s61, s63
	s_cselect_b32 s30, s60, s62
	s_add_u32 s66, s66, 0x40000
	s_mov_b32 m0, s71
	s_addc_u32 s67, s67, 0
	s_add_i32 s65, s53, s23
	global_load_lds_dwordx4 v[202:203], off
	s_mov_b32 m0, s65
	s_nop 0
	global_load_lds_dwordx4 v132, s[66:67]
	v_lshl_add_u64 v[202:203], s[66:67], 0, v[128:129]
	s_add_i32 m0, s65, 0x2000
	s_mov_b64 s[66:67], s[28:29]
	global_load_lds_dwordx4 v[202:203], off
	s_mov_b32 m0, s21
	s_nop 0
	global_load_lds_dwordx4 v134, s[66:67]
	s_mov_b32 m0, s42
	s_nop 0
	global_load_lds_dwordx4 v130, s[66:67]
	s_waitcnt vmcnt(8)
	s_waitcnt lgkmcnt(0)
	s_barrier
; #define PG8_STAGE(bufoff, gbase, voff) do { const char* _gb = (const char*)(gbase); asm volatile("" : "+s"(_gb));     \
;         _Pragma("unroll") for (int _i = 0; _i < 2; ++_i) \
;         __builtin_amdgcn_global_load_lds((const unsigned*)(_gb + (voff)[_i]), (LAS unsigned*)(lds + (bufoff) + ldsw + _i * 8192), 16, 0, 0); } while (0)
; #define PG8_LDA(dst, b, h) do { _Pragma("unroll") for (int m = 0; m < 4; ++m) _Pragma("unroll") for (int k = 0; k < 2; ++k) dst[m][k] = *(const LAS bf16x8*)(lds + PG8_SA(b, h) + aoff + m * 2048 + k * 1024); } while (0)
; #define PG8_LDB(dst, b, h) do { _Pragma("unroll") for (int n = 0; n < 2; ++n) _Pragma("unroll") for (int k = 0; k < 2; ++k) dst[n][k] = *(const LAS bf16x8*)(lds + PG8_SB(b, h) + boff + n * 2048 + k * 1024); } while (0)
; #define PG8_MMA(ai, bj, At, Bt) do { __builtin_amdgcn_s_setprio(1); _Pragma("unroll") for (int m = 0; m < 4; ++m) _Pragma("unroll") for (int n = 0; n < 2; ++n) _Pragma("unroll") for (int k = 0; k < 2; ++k) \
;         acc[ai][bj][m][n] = __builtin_amdgcn_mfma_f32_16x16x32_bf16(Bt[n][k], At[m][k], acc[ai][bj][m][n], 0, 0, 0); __builtin_amdgcn_s_setprio(0); } while (0)
; #define PG8_WAIT_V(n) asm volatile("s_waitcnt vmcnt(" #n ")" ::: "memory")
; #define PG8_WAIT_L(n) asm volatile("s_waitcnt lgkmcnt(" #n ")" ::: "memory")
; #define PG8_BAR __builtin_amdgcn_s_barrier()
; #define PG8_SCHED __builtin_amdgcn_sched_barrier(0)
; template <class Epi>
; __device__ __forceinline__ void gemm_phase(LAS unsigned char* lds, const int wid, const Gemm g, const Epi& E) {
;     ...
;             PG8_WAIT_V(8); PG8_WAIT_L(0); PG8_BAR; PG8_MMA(1, 0, At, B0); PG8_MMA(1, 1, At, B1); PG8_BAR; PG8_SCHED;
;             PG8_LDB(B0, 1, 0); PG8_LDB(B1, 1, 1); PG8_SCHED; PG8_LDA(At, 1, 0); PG8_STAGE(PG8_SA(0, 1), a2 + hstepA, voffA);
;             PG8_WAIT_V(8); PG8_WAIT_L(0); PG8_BAR; PG8_MMA(0, 0, At, B0); PG8_MMA(0, 1, At, B1); PG8_BAR; PG8_SCHED;
	s_setprio 1
	s_waitcnt lgkmcnt(0)
	v_mfma_f32_16x16x32_bf16 v[60:63], v[146:149], v[178:181], v[60:63]
	v_mfma_f32_16x16x32_bf16 v[56:59], v[154:157], v[178:181], v[56:59]
	v_mfma_f32_16x16x32_bf16 v[44:47], v[146:149], v[186:189], v[44:47]
	v_mfma_f32_16x16x32_bf16 v[40:43], v[154:157], v[186:189], v[40:43]
	v_mfma_f32_16x16x32_bf16 v[28:31], v[146:149], v[194:197], v[28:31]
	v_mfma_f32_16x16x32_bf16 v[24:27], v[154:157], v[194:197], v[24:27]
	v_mfma_f32_16x16x32_bf16 v[12:15], v[146:149], v[206:209], v[12:15]
	v_mfma_f32_16x16x32_bf16 v[8:11], v[154:157], v[206:209], v[8:11]
	v_mfma_f32_16x16x32_bf16 v[60:63], v[150:153], v[182:185], v[60:63]
	v_mfma_f32_16x16x32_bf16 v[56:59], v[158:161], v[182:185], v[56:59]
	v_mfma_f32_16x16x32_bf16 v[44:47], v[150:153], v[190:193], v[44:47]
	v_mfma_f32_16x16x32_bf16 v[40:43], v[158:161], v[190:193], v[40:43]
	v_mfma_f32_16x16x32_bf16 v[28:31], v[150:153], v[198:201], v[28:31]
	v_mfma_f32_16x16x32_bf16 v[24:27], v[158:161], v[198:201], v[24:27]
	v_mfma_f32_16x16x32_bf16 v[12:15], v[150:153], v[210:213], v[12:15]
	v_mfma_f32_16x16x32_bf16 v[8:11], v[158:161], v[210:213], v[8:11]
	s_setprio 0
	s_setprio 1
	v_mfma_f32_16x16x32_bf16 v[52:55], v[162:165], v[178:181], v[52:55]
	v_mfma_f32_16x16x32_bf16 v[48:51], v[170:173], v[178:181], v[48:51]
	v_mfma_f32_16x16x32_bf16 v[36:39], v[162:165], v[186:189], v[36:39]
	v_mfma_f32_16x16x32_bf16 v[32:35], v[170:173], v[186:189], v[32:35]
	v_mfma_f32_16x16x32_bf16 v[20:23], v[162:165], v[194:197], v[20:23]
	v_mfma_f32_16x16x32_bf16 v[16:19], v[170:173], v[194:197], v[16:19]
	v_mfma_f32_16x16x32_bf16 v[4:7], v[162:165], v[206:209], v[4:7]
	v_mfma_f32_16x16x32_bf16 v[0:3], v[170:173], v[206:209], v[0:3]
	v_mfma_f32_16x16x32_bf16 v[52:55], v[166:169], v[182:185], v[52:55]
	v_mfma_f32_16x16x32_bf16 v[48:51], v[174:177], v[182:185], v[48:51]
	v_mfma_f32_16x16x32_bf16 v[36:39], v[166:169], v[190:193], v[36:39]
	v_mfma_f32_16x16x32_bf16 v[32:35], v[174:177], v[190:193], v[32:35]
	v_mfma_f32_16x16x32_bf16 v[20:23], v[166:169], v[198:201], v[20:23]
	v_mfma_f32_16x16x32_bf16 v[16:19], v[174:177], v[198:201], v[16:19]
	v_mfma_f32_16x16x32_bf16 v[4:7], v[166:169], v[210:213], v[4:7]
	v_mfma_f32_16x16x32_bf16 v[0:3], v[174:177], v[210:213], v[0:3]
	s_setprio 0
	s_barrier
	s_add_i32 s65, 0, 0x18000
	s_add_i32 s66, 0, 0x1c000
	v_add_u32_e32 v158, s65, v142
	v_add_u32_e32 v174, s66, v142
	ds_read_b128 v[146:149], v158
	ds_read_b128 v[150:153], v158 offset:1024
	ds_read_b128 v[154:157], v158 offset:2048
	ds_read_b128 v[158:161], v158 offset:3072
	ds_read_b128 v[162:165], v174
	ds_read_b128 v[166:169], v174 offset:1024
	ds_read_b128 v[170:173], v174 offset:2048
	ds_read_b128 v[174:177], v174 offset:3072
	s_add_u32 s28, s28, 0x40000
	s_addc_u32 s29, s29, 0
	s_mov_b32 m0, s43
	ds_read_b128 v[178:181], v145 offset:32768
	ds_read_b128 v[182:185], v145 offset:33792
	ds_read_b128 v[186:189], v145 offset:34816
	ds_read_b128 v[190:193], v145 offset:35840
	ds_read_b128 v[194:197], v145 offset:36864
	ds_read_b128 v[198:201], v145 offset:37888
	ds_read_b128 v[206:209], v145 offset:38912
	ds_read_b128 v[210:213], v145 offset:39936
	s_nop 0
	global_load_lds_dwordx4 v134, s[28:29]
	s_mov_b32 m0, s44
	s_nop 0
	global_load_lds_dwordx4 v130, s[28:29]
	s_waitcnt vmcnt(8)
	s_waitcnt lgkmcnt(0)
	s_barrier
	s_setprio 1
	s_waitcnt lgkmcnt(0)
	v_mfma_f32_16x16x32_bf16 v[124:127], v[146:149], v[178:181], v[124:127]
	v_mfma_f32_16x16x32_bf16 v[120:123], v[154:157], v[178:181], v[120:123]
	v_mfma_f32_16x16x32_bf16 v[108:111], v[146:149], v[186:189], v[108:111]
	v_mfma_f32_16x16x32_bf16 v[104:107], v[154:157], v[186:189], v[104:107]
	v_mfma_f32_16x16x32_bf16 v[92:95], v[146:149], v[194:197], v[92:95]
	v_mfma_f32_16x16x32_bf16 v[88:91], v[154:157], v[194:197], v[88:91]
	v_mfma_f32_16x16x32_bf16 v[76:79], v[146:149], v[206:209], v[76:79]
	v_mfma_f32_16x16x32_bf16 v[72:75], v[154:157], v[206:209], v[72:75]
	v_mfma_f32_16x16x32_bf16 v[124:127], v[150:153], v[182:185], v[124:127]
	v_mfma_f32_16x16x32_bf16 v[120:123], v[158:161], v[182:185], v[120:123]
	v_mfma_f32_16x16x32_bf16 v[108:111], v[150:153], v[190:193], v[108:111]
	v_mfma_f32_16x16x32_bf16 v[104:107], v[158:161], v[190:193], v[104:107]
	v_mfma_f32_16x16x32_bf16 v[92:95], v[150:153], v[198:201], v[92:95]
	v_mfma_f32_16x16x32_bf16 v[88:91], v[158:161], v[198:201], v[88:91]
	v_mfma_f32_16x16x32_bf16 v[76:79], v[150:153], v[210:213], v[76:79]
	v_mfma_f32_16x16x32_bf16 v[72:75], v[158:161], v[210:213], v[72:75]
	s_setprio 0
	s_setprio 1
	v_mfma_f32_16x16x32_bf16 v[116:119], v[162:165], v[178:181], v[116:119]
	v_mfma_f32_16x16x32_bf16 v[112:115], v[170:173], v[178:181], v[112:115]
	v_mfma_f32_16x16x32_bf16 v[100:103], v[162:165], v[186:189], v[100:103]
	v_mfma_f32_16x16x32_bf16 v[96:99], v[170:173], v[186:189], v[96:99]
	v_mfma_f32_16x16x32_bf16 v[84:87], v[162:165], v[194:197], v[84:87]
	v_mfma_f32_16x16x32_bf16 v[80:83], v[170:173], v[194:197], v[80:83]
	v_mfma_f32_16x16x32_bf16 v[68:71], v[162:165], v[206:209], v[68:71]
	v_mfma_f32_16x16x32_bf16 v[64:67], v[170:173], v[206:209], v[64:67]
	v_mfma_f32_16x16x32_bf16 v[116:119], v[166:169], v[182:185], v[116:119]
	v_mfma_f32_16x16x32_bf16 v[112:115], v[174:177], v[182:185], v[112:115]
	v_mfma_f32_16x16x32_bf16 v[100:103], v[166:169], v[190:193], v[100:103]
	v_mfma_f32_16x16x32_bf16 v[96:99], v[174:177], v[190:193], v[96:99]
	v_mfma_f32_16x16x32_bf16 v[84:87], v[166:169], v[198:201], v[84:87]
	v_mfma_f32_16x16x32_bf16 v[80:83], v[174:177], v[198:201], v[80:83]
	v_mfma_f32_16x16x32_bf16 v[68:71], v[166:169], v[210:213], v[68:71]
	v_mfma_f32_16x16x32_bf16 v[64:67], v[174:177], v[210:213], v[64:67]
	s_setprio 0
	s_barrier
; #define PG8_STAGE(bufoff, gbase, voff) do { const char* _gb = (const char*)(gbase); asm volatile("" : "+s"(_gb));     \
;         _Pragma("unroll") for (int _i = 0; _i < 2; ++_i) \
;         __builtin_amdgcn_global_load_lds((const unsigned*)(_gb + (voff)[_i]), (LAS unsigned*)(lds + (bufoff) + ldsw + _i * 8192), 16, 0, 0); } while (0)
; #define PG8_LDA(dst, b, h) do { _Pragma("unroll") for (int m = 0; m < 4; ++m) _Pragma("unroll") for (int k = 0; k < 2; ++k) dst[m][k] = *(const LAS bf16x8*)(lds + PG8_SA(b, h) + aoff + m * 2048 + k * 1024); } while (0)
; #define PG8_MMA(ai, bj, At, Bt) do { __builtin_amdgcn_s_setprio(1); _Pragma("unroll") for (int m = 0; m < 4; ++m) _Pragma("unroll") for (int n = 0; n < 2; ++n) _Pragma("unroll") for (int k = 0; k < 2; ++k) \
;         acc[ai][bj][m][n] = __builtin_amdgcn_mfma_f32_16x16x32_bf16(Bt[n][k], At[m][k], acc[ai][bj][m][n], 0, 0, 0); __builtin_amdgcn_s_setprio(0); } while (0)
; #define PG8_WAIT_V(n) asm volatile("s_waitcnt vmcnt(" #n ")" ::: "memory")
; #define PG8_WAIT_L(n) asm volatile("s_waitcnt lgkmcnt(" #n ")" ::: "memory")
; #define PG8_BAR __builtin_amdgcn_s_barrier()
; #define PG8_SCHED __builtin_amdgcn_sched_barrier(0)
; template <class Epi>
; __device__ __forceinline__ void gemm_phase(LAS unsigned char* lds, const int wid, const Gemm g, const Epi& E) {
;     ...
;             PG8_WAIT_V(8); PG8_WAIT_L(0); PG8_BAR; PG8_MMA(0, 0, At, B0); PG8_MMA(0, 1, At, B1); PG8_BAR; PG8_SCHED;
;             PG8_LDA(At, 1, 1); PG8_STAGE(PG8_SB(1, 0), b3, voffB); PG8_STAGE(PG8_SB(1, 1), b3 + hstepB, voffB); PG8_STAGE(PG8_SA(1, 0), a3, voffA);
;             PG8_WAIT_V(8); PG8_WAIT_L(0); PG8_BAR; PG8_MMA(1, 0, At, B0); PG8_MMA(1, 1, At, B1); PG8_BAR; PG8_SCHED;
;         }
;         if (wr == 0) PG8_BAR;
	s_mov_b64 s[28:29], s[30:31]
	s_add_i32 s65, s65, s23
	ds_read_b128 v[178:181], v145 offset:49152
	ds_read_b128 v[182:185], v145 offset:50176
	ds_read_b128 v[186:189], v145 offset:51200
	ds_read_b128 v[190:193], v145 offset:52224
	ds_read_b128 v[194:197], v145 offset:53248
	ds_read_b128 v[198:201], v145 offset:54272
	ds_read_b128 v[206:209], v145 offset:55296
	ds_read_b128 v[210:213], v145 offset:56320
	s_mov_b32 m0, s65
	s_nop 0
	global_load_lds_dwordx4 v132, s[28:29]
	s_add_i32 m0, s65, 0x2000
	v_lshl_add_u64 v[202:203], s[28:29], 0, v[128:129]
	s_add_u32 s28, s30, 0x40000
	s_addc_u32 s29, s31, 0
	s_add_i32 s30, s66, s23
	global_load_lds_dwordx4 v[202:203], off
	s_mov_b32 m0, s30
	s_nop 0
	global_load_lds_dwordx4 v132, s[28:29]
	s_add_i32 m0, s30, 0x2000
	s_nop 0
	global_load_lds_dwordx4 v128, s[28:29]
	s_mov_b32 m0, s48
	s_nop 0
	global_load_lds_dwordx4 v134, s[26:27]
	s_mov_b32 m0, s49
	s_nop 0
	global_load_lds_dwordx4 v130, s[26:27]
	s_waitcnt vmcnt(8)
	s_waitcnt lgkmcnt(0)
	s_barrier
	s_setprio 1
	s_waitcnt lgkmcnt(0)
	v_mfma_f32_16x16x32_bf16 v[60:63], v[146:149], v[178:181], v[60:63]
	v_mfma_f32_16x16x32_bf16 v[56:59], v[154:157], v[178:181], v[56:59]
	v_mfma_f32_16x16x32_bf16 v[44:47], v[146:149], v[186:189], v[44:47]
	v_mfma_f32_16x16x32_bf16 v[40:43], v[154:157], v[186:189], v[40:43]
	v_mfma_f32_16x16x32_bf16 v[28:31], v[146:149], v[194:197], v[28:31]
	v_mfma_f32_16x16x32_bf16 v[24:27], v[154:157], v[194:197], v[24:27]
	v_mfma_f32_16x16x32_bf16 v[12:15], v[146:149], v[206:209], v[12:15]
	v_mfma_f32_16x16x32_bf16 v[8:11], v[154:157], v[206:209], v[8:11]
	v_mfma_f32_16x16x32_bf16 v[60:63], v[150:153], v[182:185], v[60:63]
	v_mfma_f32_16x16x32_bf16 v[56:59], v[158:161], v[182:185], v[56:59]
	v_mfma_f32_16x16x32_bf16 v[44:47], v[150:153], v[190:193], v[44:47]
	v_mfma_f32_16x16x32_bf16 v[40:43], v[158:161], v[190:193], v[40:43]
	v_mfma_f32_16x16x32_bf16 v[28:31], v[150:153], v[198:201], v[28:31]
	v_mfma_f32_16x16x32_bf16 v[24:27], v[158:161], v[198:201], v[24:27]
	v_mfma_f32_16x16x32_bf16 v[12:15], v[150:153], v[210:213], v[12:15]
	v_mfma_f32_16x16x32_bf16 v[8:11], v[158:161], v[210:213], v[8:11]
	s_setprio 0
	s_setprio 1
	v_mfma_f32_16x16x32_bf16 v[52:55], v[162:165], v[178:181], v[52:55]
	v_mfma_f32_16x16x32_bf16 v[48:51], v[170:173], v[178:181], v[48:51]
	v_mfma_f32_16x16x32_bf16 v[36:39], v[162:165], v[186:189], v[36:39]
	v_mfma_f32_16x16x32_bf16 v[32:35], v[170:173], v[186:189], v[32:35]
	v_mfma_f32_16x16x32_bf16 v[20:23], v[162:165], v[194:197], v[20:23]
	v_mfma_f32_16x16x32_bf16 v[16:19], v[170:173], v[194:197], v[16:19]
	v_mfma_f32_16x16x32_bf16 v[4:7], v[162:165], v[206:209], v[4:7]
	v_mfma_f32_16x16x32_bf16 v[0:3], v[170:173], v[206:209], v[0:3]
	v_mfma_f32_16x16x32_bf16 v[52:55], v[166:169], v[182:185], v[52:55]
	v_mfma_f32_16x16x32_bf16 v[48:51], v[174:177], v[182:185], v[48:51]
	v_mfma_f32_16x16x32_bf16 v[36:39], v[166:169], v[190:193], v[36:39]
	v_mfma_f32_16x16x32_bf16 v[32:35], v[174:177], v[190:193], v[32:35]
	v_mfma_f32_16x16x32_bf16 v[20:23], v[166:169], v[198:201], v[20:23]
	v_mfma_f32_16x16x32_bf16 v[16:19], v[174:177], v[198:201], v[16:19]
	v_mfma_f32_16x16x32_bf16 v[4:7], v[166:169], v[210:213], v[4:7]
	v_mfma_f32_16x16x32_bf16 v[0:3], v[174:177], v[210:213], v[0:3]
	s_setprio 0
	s_barrier
	s_add_i32 s64, s64, 2
	s_add_u32 s62, s62, 0x100
	s_addc_u32 s63, s63, 0
	s_add_u32 s24, s24, 0x100
	s_addc_u32 s25, s25, 0
	s_cmp_gt_u32 s64, 13
	s_cbranch_scc0 .LBB0_481
	s_and_b64 vcc, exec, s[8:9]
	s_cbranch_vccz .LBB0_484
	s_barrier

; #define PG8_STAGE(bufoff, gbase, voff) do { const char* _gb = (const char*)(gbase); asm volatile("" : "+s"(_gb));     \
;         _Pragma("unroll") for (int _i = 0; _i < 2; ++_i) \
;         __builtin_amdgcn_global_load_lds((const unsigned*)(_gb + (voff)[_i]), (LAS unsigned*)(lds + (bufoff) + ldsw + _i * 8192), 16, 0, 0); } while (0)
; #define PG8_WAIT_V(n) asm volatile("s_waitcnt vmcnt(" #n ")" ::: "memory")
; #define PG8_BAR __builtin_amdgcn_s_barrier()
; template <class Epi>
; __device__ __forceinline__ void gemm_phase(LAS unsigned char* lds, const int wid, const Gemm g, const Epi& E) {
;     ...
;     const char* cA = PG8_UA(cur); const char* cB = PG8_UB(cur);
;     PG8_STAGE(PG8_SB(0, 0), PG8_BP(cB, 0), voffB); PG8_STAGE(PG8_SB(0, 1), PG8_BP(cB, 0) + hstepB, voffB); PG8_STAGE(PG8_SA(0, 0), PG8_AP(cA, 0), voffA); PG8_STAGE(PG8_SA(0, 1), PG8_AP(cA, 0) + hstepA, voffA);
;     if (wr == 1) PG8_BAR;
;     PG8_WAIT_V(2); PG8_BAR;
;     PG8_STAGE(PG8_SB(1, 0), PG8_BP(cB, 1), voffB); PG8_STAGE(PG8_SA(1, 0), PG8_AP(cA, 1), voffA); PG8_STAGE(PG8_SB(1, 1), PG8_BP(cB, 1) + hstepB, voffB);
;     PG8_WAIT_V(6); PG8_BAR;
;     for (;;) {
;         const bool has_next = S.next(ui + 1, nxt);
;         const char* nA = has_next ? PG8_UA(nxt) : cA; const char* nB = has_next ? PG8_UB(nxt) : cB;
;         for (int t = 0; t < nt; t += 2) {
.LBB0_541:
	s_lshl_b32 s2, s33, 5
	s_and_b32 s51, s2, 0x60
	s_lshl_b32 s50, s10, 6
	s_lshl_b32 s4, s10, 13
	s_lshr_b32 s5, s51, 3
	s_cmp_lt_u32 s33, 4
	s_cselect_b64 s[10:11], -1, 0
	s_add_u32 s12, s12, 0x5800000
	s_addc_u32 s13, s13, 0
	s_add_u32 s14, s14, 0x5800000
	s_addc_u32 s15, s15, 0
	s_add_u32 s2, s28, 0x80
	s_addc_u32 s3, s29, 0
	s_waitcnt vmcnt(2)
	s_barrier
	s_add_i32 m0, s45, 0x18000
	s_nop 0
	global_load_lds_dwordx4 v132, s[2:3]
	s_add_i32 m0, s45, 0x1a000
	v_lshl_add_u64 v[0:1], s[2:3], 0, v[128:129]
	s_add_u32 s2, s30, 0x80
	s_addc_u32 s3, s31, 0
	s_add_i32 s52, s45, 0x8000
	global_load_lds_dwordx4 v[0:1], off
	s_mov_b32 m0, s52
	s_add_i32 s53, s45, 0xa000
	global_load_lds_dwordx4 v134, s[2:3]
	v_lshl_add_u64 v[0:1], s[2:3], 0, v[130:131]
	s_add_u32 s2, s28, 0xb0080
	s_mov_b32 m0, s53
	s_addc_u32 s3, s29, 0
	global_load_lds_dwordx4 v[0:1], off
	s_add_i32 m0, s45, 0x1c000
	s_nop 0
	global_load_lds_dwordx4 v132, s[2:3]
	s_add_i32 m0, s45, 0x1e000
	v_lshlrev_b32_e32 v3, 6, v147
	global_load_lds_dwordx4 v128, s[2:3]
	v_and_b32_e32 v1, 48, v147
	s_movk_i32 s2, 0x3c0
	v_ashrrev_i32_e32 v0, 6, v147
	v_and_or_b32 v1, v3, s2, v1
	v_lshlrev_b32_e32 v3, 2, v147
	v_lshl_add_u32 v2, v0, 10, s4
	v_and_b32_e32 v3, 32, v3
	v_add_lshl_u32 v0, v0, s5, 10
	s_waitcnt vmcnt(6)
	v_bitop3_b32 v2, v1, v2, v3 bitop3:0xde
	v_bitop3_b32 v148, v1, v0, v3 bitop3:0xde
	s_add_i32 s56, 0, 0x10000
	s_add_i32 s57, 0, 0x14000
	s_sext_i32_i8 s61, s16
	s_mov_b32 s54, 0
	s_waitcnt lgkmcnt(0)
	s_ashr_i32 s55, s49, 31
	v_mov_b64_e32 v[136:137], 0x200
	v_mov_b64_e32 v[138:139], 0x1ff
	v_add_u32_e32 v149, s56, v148
	v_add_u32_e32 v150, s57, v148
	v_add_u32_e32 v151, 0, v2
	s_mov_b64 s[16:17], 0x40000
	s_mov_b64 s[18:19], 0x48000
	s_mov_b64 s[20:21], 0x50000
	s_mov_b64 s[24:25], 0x58000
	s_barrier
	s_branch .LBB0_544

; #define PG8_STAGE(bufoff, gbase, voff) do { const char* _gb = (const char*)(gbase); asm volatile("" : "+s"(_gb));     \
;         _Pragma("unroll") for (int _i = 0; _i < 2; ++_i) \
;         __builtin_amdgcn_global_load_lds((const unsigned*)(_gb + (voff)[_i]), (LAS unsigned*)(lds + (bufoff) + ldsw + _i * 8192), 16, 0, 0); } while (0)
; #define PG8_LDA(dst, b, h) do { _Pragma("unroll") for (int m = 0; m < 4; ++m) _Pragma("unroll") for (int k = 0; k < 2; ++k) dst[m][k] = *(const LAS bf16x8*)(lds + PG8_SA(b, h) + aoff + m * 2048 + k * 1024); } while (0)
; #define PG8_LDB(dst, b, h) do { _Pragma("unroll") for (int n = 0; n < 2; ++n) _Pragma("unroll") for (int k = 0; k < 2; ++k) dst[n][k] = *(const LAS bf16x8*)(lds + PG8_SB(b, h) + boff + n * 2048 + k * 1024); } while (0)
; #define PG8_MMA(ai, bj, At, Bt) do { __builtin_amdgcn_s_setprio(1); _Pragma("unroll") for (int m = 0; m < 4; ++m) _Pragma("unroll") for (int n = 0; n < 2; ++n) _Pragma("unroll") for (int k = 0; k < 2; ++k) \
;         acc[ai][bj][m][n] = __builtin_amdgcn_mfma_f32_16x16x32_bf16(Bt[n][k], At[m][k], acc[ai][bj][m][n], 0, 0, 0); __builtin_amdgcn_s_setprio(0); } while (0)
; #define PG8_WAIT_V(n) asm volatile("s_waitcnt vmcnt(" #n ")" ::: "memory")
; #define PG8_WAIT_L(n) asm volatile("s_waitcnt lgkmcnt(" #n ")" ::: "memory")
; #define PG8_BAR __builtin_amdgcn_s_barrier()
; #define PG8_SCHED __builtin_amdgcn_sched_barrier(0)
; template <class Epi>
; __device__ __forceinline__ void gemm_phase(LAS unsigned char* lds, const int wid, const Gemm g, const Epi& E) {
;     ...
;             PG8_LDB(B0, 0, 0); PG8_LDB(B1, 0, 1); PG8_SCHED; PG8_LDA(At, 0, 0); PG8_STAGE(PG8_SA(1, 1), a1 + hstepA, voffA);
;             PG8_WAIT_V(8); PG8_WAIT_L(0); PG8_BAR; PG8_MMA(0, 0, At, B0); PG8_MMA(0, 1, At, B1); PG8_BAR; PG8_SCHED;
;             PG8_LDA(At, 0, 1); PG8_STAGE(PG8_SB(0, 0), b2, voffB); PG8_STAGE(PG8_SB(0, 1), b2 + hstepB, voffB); PG8_STAGE(PG8_SA(0, 0), a2, voffA);
;             PG8_WAIT_V(8); PG8_WAIT_L(0); PG8_BAR; PG8_MMA(1, 0, At, B0); PG8_MMA(1, 1, At, B1); PG8_BAR; PG8_SCHED;
.LBB0_555:
	ds_read_b128 v[140:143], v149
	ds_read_b128 v[152:155], v149 offset:1024
	ds_read_b128 v[156:159], v149 offset:2048
	ds_read_b128 v[160:163], v149 offset:3072
	ds_read_b128 v[164:167], v150
	ds_read_b128 v[168:171], v150 offset:1024
	ds_read_b128 v[172:175], v150 offset:2048
	ds_read_b128 v[176:179], v150 offset:3072
	s_add_u32 s30, s28, 0xfff50080
	s_addc_u32 s31, s29, -1
	s_add_u32 s38, s66, 0xffffff80
	s_addc_u32 s39, s67, -1
	s_add_u32 s69, s28, 0xfff50100
	s_addc_u32 s72, s29, -1
	s_add_i32 s74, s56, s23
	s_add_i32 m0, s45, 0xc000
	s_add_i32 s73, s45, 0xe000
	s_add_i32 s75, s74, 0x2000
	s_cmp_eq_u32 s68, 40
	s_cselect_b32 s35, s5, s31
	s_cselect_b32 s34, s4, s30
	s_cselect_b32 s71, s27, s39
	s_cselect_b32 s70, s26, s38
	s_cselect_b32 s31, s63, s72
	s_cselect_b32 s30, s62, s69
	s_mov_b64 s[38:39], s[28:29]
	ds_read_b128 v[180:183], v151
	ds_read_b128 v[184:187], v151 offset:1024
	ds_read_b128 v[188:191], v151 offset:2048
	ds_read_b128 v[192:195], v151 offset:3072
	ds_read_b128 v[196:199], v151 offset:4096
	ds_read_b128 v[200:203], v151 offset:5120
	ds_read_b128 v[206:209], v151 offset:6144
	ds_read_b128 v[210:213], v151 offset:7168
	s_nop 0
	global_load_lds_dwordx4 v134, s[38:39]
	s_mov_b32 m0, s73
	s_nop 0
	global_load_lds_dwordx4 v130, s[38:39]
	s_waitcnt vmcnt(8)
	s_waitcnt lgkmcnt(0)
	s_barrier
	s_setprio 1
	s_waitcnt lgkmcnt(0)
	v_mfma_f32_16x16x32_bf16 v[124:127], v[140:143], v[180:183], v[124:127]
	v_mfma_f32_16x16x32_bf16 v[120:123], v[156:159], v[180:183], v[120:123]
	v_mfma_f32_16x16x32_bf16 v[108:111], v[140:143], v[188:191], v[108:111]
	v_mfma_f32_16x16x32_bf16 v[104:107], v[156:159], v[188:191], v[104:107]
	v_mfma_f32_16x16x32_bf16 v[92:95], v[140:143], v[196:199], v[92:95]
	v_mfma_f32_16x16x32_bf16 v[88:91], v[156:159], v[196:199], v[88:91]
	v_mfma_f32_16x16x32_bf16 v[76:79], v[140:143], v[206:209], v[76:79]
	v_mfma_f32_16x16x32_bf16 v[72:75], v[156:159], v[206:209], v[72:75]
	v_mfma_f32_16x16x32_bf16 v[124:127], v[152:155], v[184:187], v[124:127]
	v_mfma_f32_16x16x32_bf16 v[120:123], v[160:163], v[184:187], v[120:123]
	v_mfma_f32_16x16x32_bf16 v[108:111], v[152:155], v[192:195], v[108:111]
	v_mfma_f32_16x16x32_bf16 v[104:107], v[160:163], v[192:195], v[104:107]
	v_mfma_f32_16x16x32_bf16 v[92:95], v[152:155], v[200:203], v[92:95]
	v_mfma_f32_16x16x32_bf16 v[88:91], v[160:163], v[200:203], v[88:91]
	v_mfma_f32_16x16x32_bf16 v[76:79], v[152:155], v[210:213], v[76:79]
	v_mfma_f32_16x16x32_bf16 v[72:75], v[160:163], v[210:213], v[72:75]
	s_setprio 0
	s_setprio 1
	v_mfma_f32_16x16x32_bf16 v[116:119], v[164:167], v[180:183], v[116:119]
	v_mfma_f32_16x16x32_bf16 v[112:115], v[172:175], v[180:183], v[112:115]
	v_mfma_f32_16x16x32_bf16 v[100:103], v[164:167], v[188:191], v[100:103]
	v_mfma_f32_16x16x32_bf16 v[96:99], v[172:175], v[188:191], v[96:99]
	v_mfma_f32_16x16x32_bf16 v[84:87], v[164:167], v[196:199], v[84:87]
	v_mfma_f32_16x16x32_bf16 v[80:83], v[172:175], v[196:199], v[80:83]
	v_mfma_f32_16x16x32_bf16 v[68:71], v[164:167], v[206:209], v[68:71]
	v_mfma_f32_16x16x32_bf16 v[64:67], v[172:175], v[206:209], v[64:67]
	v_mfma_f32_16x16x32_bf16 v[116:119], v[168:171], v[184:187], v[116:119]
	v_mfma_f32_16x16x32_bf16 v[112:115], v[176:179], v[184:187], v[112:115]
	v_mfma_f32_16x16x32_bf16 v[100:103], v[168:171], v[192:195], v[100:103]
	v_mfma_f32_16x16x32_bf16 v[96:99], v[176:179], v[192:195], v[96:99]
	v_mfma_f32_16x16x32_bf16 v[84:87], v[168:171], v[200:203], v[84:87]
	v_mfma_f32_16x16x32_bf16 v[80:83], v[176:179], v[200:203], v[80:83]
	v_mfma_f32_16x16x32_bf16 v[68:71], v[168:171], v[210:213], v[68:71]
	v_mfma_f32_16x16x32_bf16 v[64:67], v[176:179], v[210:213], v[64:67]
	s_setprio 0
	s_barrier
	s_mov_b64 s[38:39], s[70:71]
	s_mov_b32 m0, s74
	ds_read_b128 v[180:183], v151 offset:16384
	ds_read_b128 v[184:187], v151 offset:17408
	ds_read_b128 v[188:191], v151 offset:18432
	ds_read_b128 v[192:195], v151 offset:19456
	ds_read_b128 v[196:199], v151 offset:20480
	ds_read_b128 v[200:203], v151 offset:21504
	ds_read_b128 v[206:209], v151 offset:22528
	ds_read_b128 v[210:213], v151 offset:23552
	s_nop 0
	global_load_lds_dwordx4 v132, s[38:39]
	v_lshl_add_u64 v[144:145], s[38:39], 0, v[128:129]
	s_cselect_b32 s39, s65, s67
	s_cselect_b32 s38, s64, s66
	s_add_u32 s70, s70, 0xb0000
	s_mov_b32 m0, s75
	s_addc_u32 s71, s71, 0
	s_add_i32 s69, s57, s23
	global_load_lds_dwordx4 v[144:145], off
	s_mov_b32 m0, s69
	s_nop 0
	global_load_lds_dwordx4 v132, s[70:71]
	v_lshl_add_u64 v[144:145], s[70:71], 0, v[128:129]
	s_add_i32 m0, s69, 0x2000
	s_mov_b64 s[70:71], s[34:35]
	global_load_lds_dwordx4 v[144:145], off
	s_mov_b32 m0, s45
	s_nop 0
	global_load_lds_dwordx4 v134, s[70:71]
	s_mov_b32 m0, s46
	s_nop 0
	global_load_lds_dwordx4 v130, s[70:71]
	s_waitcnt vmcnt(8)
	s_waitcnt lgkmcnt(0)
	s_barrier
; #define PG8_STAGE(bufoff, gbase, voff) do { const char* _gb = (const char*)(gbase); asm volatile("" : "+s"(_gb));     \
;         _Pragma("unroll") for (int _i = 0; _i < 2; ++_i) \
;         __builtin_amdgcn_global_load_lds((const unsigned*)(_gb + (voff)[_i]), (LAS unsigned*)(lds + (bufoff) + ldsw + _i * 8192), 16, 0, 0); } while (0)
; #define PG8_LDA(dst, b, h) do { _Pragma("unroll") for (int m = 0; m < 4; ++m) _Pragma("unroll") for (int k = 0; k < 2; ++k) dst[m][k] = *(const LAS bf16x8*)(lds + PG8_SA(b, h) + aoff + m * 2048 + k * 1024); } while (0)
; #define PG8_LDB(dst, b, h) do { _Pragma("unroll") for (int n = 0; n < 2; ++n) _Pragma("unroll") for (int k = 0; k < 2; ++k) dst[n][k] = *(const LAS bf16x8*)(lds + PG8_SB(b, h) + boff + n * 2048 + k * 1024); } while (0)
; #define PG8_MMA(ai, bj, At, Bt) do { __builtin_amdgcn_s_setprio(1); _Pragma("unroll") for (int m = 0; m < 4; ++m) _Pragma("unroll") for (int n = 0; n < 2; ++n) _Pragma("unroll") for (int k = 0; k < 2; ++k) \
;         acc[ai][bj][m][n] = __builtin_amdgcn_mfma_f32_16x16x32_bf16(Bt[n][k], At[m][k], acc[ai][bj][m][n], 0, 0, 0); __builtin_amdgcn_s_setprio(0); } while (0)
; #define PG8_WAIT_V(n) asm volatile("s_waitcnt vmcnt(" #n ")" ::: "memory")
; #define PG8_WAIT_L(n) asm volatile("s_waitcnt lgkmcnt(" #n ")" ::: "memory")
; #define PG8_BAR __builtin_amdgcn_s_barrier()
; #define PG8_SCHED __builtin_amdgcn_sched_barrier(0)
; template <class Epi>
; __device__ __forceinline__ void gemm_phase(LAS unsigned char* lds, const int wid, const Gemm g, const Epi& E) {
;     ...
;             PG8_WAIT_V(8); PG8_WAIT_L(0); PG8_BAR; PG8_MMA(1, 0, At, B0); PG8_MMA(1, 1, At, B1); PG8_BAR; PG8_SCHED;
;             PG8_LDB(B0, 1, 0); PG8_LDB(B1, 1, 1); PG8_SCHED; PG8_LDA(At, 1, 0); PG8_STAGE(PG8_SA(0, 1), a2 + hstepA, voffA);
;             PG8_WAIT_V(8); PG8_WAIT_L(0); PG8_BAR; PG8_MMA(0, 0, At, B0); PG8_MMA(0, 1, At, B1); PG8_BAR; PG8_SCHED;
	s_setprio 1
	s_waitcnt lgkmcnt(0)
	v_mfma_f32_16x16x32_bf16 v[60:63], v[140:143], v[180:183], v[60:63]
	v_mfma_f32_16x16x32_bf16 v[56:59], v[156:159], v[180:183], v[56:59]
	v_mfma_f32_16x16x32_bf16 v[44:47], v[140:143], v[188:191], v[44:47]
	v_mfma_f32_16x16x32_bf16 v[40:43], v[156:159], v[188:191], v[40:43]
	v_mfma_f32_16x16x32_bf16 v[28:31], v[140:143], v[196:199], v[28:31]
	v_mfma_f32_16x16x32_bf16 v[24:27], v[156:159], v[196:199], v[24:27]
	v_mfma_f32_16x16x32_bf16 v[12:15], v[140:143], v[206:209], v[12:15]
	v_mfma_f32_16x16x32_bf16 v[8:11], v[156:159], v[206:209], v[8:11]
	v_mfma_f32_16x16x32_bf16 v[60:63], v[152:155], v[184:187], v[60:63]
	v_mfma_f32_16x16x32_bf16 v[56:59], v[160:163], v[184:187], v[56:59]
	v_mfma_f32_16x16x32_bf16 v[44:47], v[152:155], v[192:195], v[44:47]
	v_mfma_f32_16x16x32_bf16 v[40:43], v[160:163], v[192:195], v[40:43]
	v_mfma_f32_16x16x32_bf16 v[28:31], v[152:155], v[200:203], v[28:31]
	v_mfma_f32_16x16x32_bf16 v[24:27], v[160:163], v[200:203], v[24:27]
	v_mfma_f32_16x16x32_bf16 v[12:15], v[152:155], v[210:213], v[12:15]
	v_mfma_f32_16x16x32_bf16 v[8:11], v[160:163], v[210:213], v[8:11]
	s_setprio 0
	s_setprio 1
	v_mfma_f32_16x16x32_bf16 v[52:55], v[164:167], v[180:183], v[52:55]
	v_mfma_f32_16x16x32_bf16 v[48:51], v[172:175], v[180:183], v[48:51]
	v_mfma_f32_16x16x32_bf16 v[36:39], v[164:167], v[188:191], v[36:39]
	v_mfma_f32_16x16x32_bf16 v[32:35], v[172:175], v[188:191], v[32:35]
	v_mfma_f32_16x16x32_bf16 v[20:23], v[164:167], v[196:199], v[20:23]
	v_mfma_f32_16x16x32_bf16 v[16:19], v[172:175], v[196:199], v[16:19]
	v_mfma_f32_16x16x32_bf16 v[4:7], v[164:167], v[206:209], v[4:7]
	v_mfma_f32_16x16x32_bf16 v[0:3], v[172:175], v[206:209], v[0:3]
	v_mfma_f32_16x16x32_bf16 v[52:55], v[168:171], v[184:187], v[52:55]
	v_mfma_f32_16x16x32_bf16 v[48:51], v[176:179], v[184:187], v[48:51]
	v_mfma_f32_16x16x32_bf16 v[36:39], v[168:171], v[192:195], v[36:39]
	v_mfma_f32_16x16x32_bf16 v[32:35], v[176:179], v[192:195], v[32:35]
	v_mfma_f32_16x16x32_bf16 v[20:23], v[168:171], v[200:203], v[20:23]
	v_mfma_f32_16x16x32_bf16 v[16:19], v[176:179], v[200:203], v[16:19]
	v_mfma_f32_16x16x32_bf16 v[4:7], v[168:171], v[210:213], v[4:7]
	v_mfma_f32_16x16x32_bf16 v[0:3], v[176:179], v[210:213], v[0:3]
	s_setprio 0
	s_barrier
	s_add_i32 s69, 0, 0x18000
	v_add_u32_e32 v144, s69, v148
	s_add_i32 s70, 0, 0x1c000
	ds_read_b128 v[140:143], v144
	ds_read_b128 v[152:155], v144 offset:1024
	ds_read_b128 v[156:159], v144 offset:2048
	ds_read_b128 v[160:163], v144 offset:3072
	v_add_u32_e32 v144, s70, v148
	ds_read_b128 v[164:167], v144
	ds_read_b128 v[168:171], v144 offset:1024
	ds_read_b128 v[172:175], v144 offset:2048
	ds_read_b128 v[176:179], v144 offset:3072
	s_add_u32 s34, s34, 0xb0000
	s_addc_u32 s35, s35, 0
	s_mov_b32 m0, s47
	ds_read_b128 v[180:183], v151 offset:32768
	ds_read_b128 v[184:187], v151 offset:33792
	ds_read_b128 v[188:191], v151 offset:34816
	ds_read_b128 v[192:195], v151 offset:35840
	ds_read_b128 v[196:199], v151 offset:36864
	ds_read_b128 v[200:203], v151 offset:37888
	ds_read_b128 v[206:209], v151 offset:38912
	ds_read_b128 v[210:213], v151 offset:39936
	s_nop 0
	global_load_lds_dwordx4 v134, s[34:35]
	s_mov_b32 m0, s48
	s_nop 0
	global_load_lds_dwordx4 v130, s[34:35]
	s_waitcnt vmcnt(8)
	s_waitcnt lgkmcnt(0)
	s_barrier
	s_setprio 1
	s_waitcnt lgkmcnt(0)
	v_mfma_f32_16x16x32_bf16 v[124:127], v[140:143], v[180:183], v[124:127]
	v_mfma_f32_16x16x32_bf16 v[120:123], v[156:159], v[180:183], v[120:123]
	v_mfma_f32_16x16x32_bf16 v[108:111], v[140:143], v[188:191], v[108:111]
	v_mfma_f32_16x16x32_bf16 v[104:107], v[156:159], v[188:191], v[104:107]
	v_mfma_f32_16x16x32_bf16 v[92:95], v[140:143], v[196:199], v[92:95]
	v_mfma_f32_16x16x32_bf16 v[88:91], v[156:159], v[196:199], v[88:91]
	v_mfma_f32_16x16x32_bf16 v[76:79], v[140:143], v[206:209], v[76:79]
	v_mfma_f32_16x16x32_bf16 v[72:75], v[156:159], v[206:209], v[72:75]
	v_mfma_f32_16x16x32_bf16 v[124:127], v[152:155], v[184:187], v[124:127]
	v_mfma_f32_16x16x32_bf16 v[120:123], v[160:163], v[184:187], v[120:123]
	v_mfma_f32_16x16x32_bf16 v[108:111], v[152:155], v[192:195], v[108:111]
	v_mfma_f32_16x16x32_bf16 v[104:107], v[160:163], v[192:195], v[104:107]
	v_mfma_f32_16x16x32_bf16 v[92:95], v[152:155], v[200:203], v[92:95]
	v_mfma_f32_16x16x32_bf16 v[88:91], v[160:163], v[200:203], v[88:91]
	v_mfma_f32_16x16x32_bf16 v[76:79], v[152:155], v[210:213], v[76:79]
	v_mfma_f32_16x16x32_bf16 v[72:75], v[160:163], v[210:213], v[72:75]
	s_setprio 0
	s_setprio 1
	v_mfma_f32_16x16x32_bf16 v[116:119], v[164:167], v[180:183], v[116:119]
	v_mfma_f32_16x16x32_bf16 v[112:115], v[172:175], v[180:183], v[112:115]
	v_mfma_f32_16x16x32_bf16 v[100:103], v[164:167], v[188:191], v[100:103]
	v_mfma_f32_16x16x32_bf16 v[96:99], v[172:175], v[188:191], v[96:99]
	v_mfma_f32_16x16x32_bf16 v[84:87], v[164:167], v[196:199], v[84:87]
	v_mfma_f32_16x16x32_bf16 v[80:83], v[172:175], v[196:199], v[80:83]
	v_mfma_f32_16x16x32_bf16 v[68:71], v[164:167], v[206:209], v[68:71]
	v_mfma_f32_16x16x32_bf16 v[64:67], v[172:175], v[206:209], v[64:67]
	v_mfma_f32_16x16x32_bf16 v[116:119], v[168:171], v[184:187], v[116:119]
	v_mfma_f32_16x16x32_bf16 v[112:115], v[176:179], v[184:187], v[112:115]
	v_mfma_f32_16x16x32_bf16 v[100:103], v[168:171], v[192:195], v[100:103]
	v_mfma_f32_16x16x32_bf16 v[96:99], v[176:179], v[192:195], v[96:99]
	v_mfma_f32_16x16x32_bf16 v[84:87], v[168:171], v[200:203], v[84:87]
	v_mfma_f32_16x16x32_bf16 v[80:83], v[176:179], v[200:203], v[80:83]
	v_mfma_f32_16x16x32_bf16 v[68:71], v[168:171], v[210:213], v[68:71]
	v_mfma_f32_16x16x32_bf16 v[64:67], v[176:179], v[210:213], v[64:67]
	s_setprio 0
	s_barrier
; #define PG8_STAGE(bufoff, gbase, voff) do { const char* _gb = (const char*)(gbase); asm volatile("" : "+s"(_gb));     \
;         _Pragma("unroll") for (int _i = 0; _i < 2; ++_i) \
;         __builtin_amdgcn_global_load_lds((const unsigned*)(_gb + (voff)[_i]), (LAS unsigned*)(lds + (bufoff) + ldsw + _i * 8192), 16, 0, 0); } while (0)
; #define PG8_LDA(dst, b, h) do { _Pragma("unroll") for (int m = 0; m < 4; ++m) _Pragma("unroll") for (int k = 0; k < 2; ++k) dst[m][k] = *(const LAS bf16x8*)(lds + PG8_SA(b, h) + aoff + m * 2048 + k * 1024); } while (0)
; #define PG8_MMA(ai, bj, At, Bt) do { __builtin_amdgcn_s_setprio(1); _Pragma("unroll") for (int m = 0; m < 4; ++m) _Pragma("unroll") for (int n = 0; n < 2; ++n) _Pragma("unroll") for (int k = 0; k < 2; ++k) \
;         acc[ai][bj][m][n] = __builtin_amdgcn_mfma_f32_16x16x32_bf16(Bt[n][k], At[m][k], acc[ai][bj][m][n], 0, 0, 0); __builtin_amdgcn_s_setprio(0); } while (0)
; #define PG8_WAIT_V(n) asm volatile("s_waitcnt vmcnt(" #n ")" ::: "memory")
; #define PG8_WAIT_L(n) asm volatile("s_waitcnt lgkmcnt(" #n ")" ::: "memory")
; #define PG8_BAR __builtin_amdgcn_s_barrier()
; #define PG8_SCHED __builtin_amdgcn_sched_barrier(0)
; template <class Epi>
; __device__ __forceinline__ void gemm_phase(LAS unsigned char* lds, const int wid, const Gemm g, const Epi& E) {
;     ...
;             PG8_WAIT_V(8); PG8_WAIT_L(0); PG8_BAR; PG8_MMA(0, 0, At, B0); PG8_MMA(0, 1, At, B1); PG8_BAR; PG8_SCHED;
;             PG8_LDA(At, 1, 1); PG8_STAGE(PG8_SB(1, 0), b3, voffB); PG8_STAGE(PG8_SB(1, 1), b3 + hstepB, voffB); PG8_STAGE(PG8_SA(1, 0), a3, voffA);
;             PG8_WAIT_V(8); PG8_WAIT_L(0); PG8_BAR; PG8_MMA(1, 0, At, B0); PG8_MMA(1, 1, At, B1); PG8_BAR; PG8_SCHED;
;         }
;         if (wr == 0) PG8_BAR;
	s_mov_b64 s[34:35], s[38:39]
	s_add_i32 s69, s69, s23
	ds_read_b128 v[180:183], v151 offset:49152
	ds_read_b128 v[184:187], v151 offset:50176
	ds_read_b128 v[188:191], v151 offset:51200
	ds_read_b128 v[192:195], v151 offset:52224
	ds_read_b128 v[196:199], v151 offset:53248
	ds_read_b128 v[200:203], v151 offset:54272
	ds_read_b128 v[206:209], v151 offset:55296
	ds_read_b128 v[210:213], v151 offset:56320
	s_mov_b32 m0, s69
	s_nop 0
	global_load_lds_dwordx4 v132, s[34:35]
	s_add_i32 m0, s69, 0x2000
	v_lshl_add_u64 v[144:145], s[34:35], 0, v[128:129]
	s_add_u32 s34, s38, 0xb0000
	s_addc_u32 s35, s39, 0
	s_add_i32 s38, s70, s23
	global_load_lds_dwordx4 v[144:145], off
	s_mov_b32 m0, s38
	s_nop 0
	global_load_lds_dwordx4 v132, s[34:35]
	s_add_i32 m0, s38, 0x2000
	s_nop 0
	global_load_lds_dwordx4 v128, s[34:35]
	s_mov_b32 m0, s52
	s_nop 0
	global_load_lds_dwordx4 v134, s[30:31]
	s_mov_b32 m0, s53
	s_nop 0
	global_load_lds_dwordx4 v130, s[30:31]
	s_waitcnt vmcnt(8)
	s_waitcnt lgkmcnt(0)
	s_barrier
	s_setprio 1
	s_waitcnt lgkmcnt(0)
	v_mfma_f32_16x16x32_bf16 v[60:63], v[140:143], v[180:183], v[60:63]
	v_mfma_f32_16x16x32_bf16 v[56:59], v[156:159], v[180:183], v[56:59]
	v_mfma_f32_16x16x32_bf16 v[44:47], v[140:143], v[188:191], v[44:47]
	v_mfma_f32_16x16x32_bf16 v[40:43], v[156:159], v[188:191], v[40:43]
	v_mfma_f32_16x16x32_bf16 v[28:31], v[140:143], v[196:199], v[28:31]
	v_mfma_f32_16x16x32_bf16 v[24:27], v[156:159], v[196:199], v[24:27]
	v_mfma_f32_16x16x32_bf16 v[12:15], v[140:143], v[206:209], v[12:15]
	v_mfma_f32_16x16x32_bf16 v[8:11], v[156:159], v[206:209], v[8:11]
	v_mfma_f32_16x16x32_bf16 v[60:63], v[152:155], v[184:187], v[60:63]
	v_mfma_f32_16x16x32_bf16 v[56:59], v[160:163], v[184:187], v[56:59]
	v_mfma_f32_16x16x32_bf16 v[44:47], v[152:155], v[192:195], v[44:47]
	v_mfma_f32_16x16x32_bf16 v[40:43], v[160:163], v[192:195], v[40:43]
	v_mfma_f32_16x16x32_bf16 v[28:31], v[152:155], v[200:203], v[28:31]
	v_mfma_f32_16x16x32_bf16 v[24:27], v[160:163], v[200:203], v[24:27]
	v_mfma_f32_16x16x32_bf16 v[12:15], v[152:155], v[210:213], v[12:15]
	v_mfma_f32_16x16x32_bf16 v[8:11], v[160:163], v[210:213], v[8:11]
	s_setprio 0
	s_setprio 1
	v_mfma_f32_16x16x32_bf16 v[52:55], v[164:167], v[180:183], v[52:55]
	v_mfma_f32_16x16x32_bf16 v[48:51], v[172:175], v[180:183], v[48:51]
	v_mfma_f32_16x16x32_bf16 v[36:39], v[164:167], v[188:191], v[36:39]
	v_mfma_f32_16x16x32_bf16 v[32:35], v[172:175], v[188:191], v[32:35]
	v_mfma_f32_16x16x32_bf16 v[20:23], v[164:167], v[196:199], v[20:23]
	v_mfma_f32_16x16x32_bf16 v[16:19], v[172:175], v[196:199], v[16:19]
	v_mfma_f32_16x16x32_bf16 v[4:7], v[164:167], v[206:209], v[4:7]
	v_mfma_f32_16x16x32_bf16 v[0:3], v[172:175], v[206:209], v[0:3]
	v_mfma_f32_16x16x32_bf16 v[52:55], v[168:171], v[184:187], v[52:55]
	v_mfma_f32_16x16x32_bf16 v[48:51], v[176:179], v[184:187], v[48:51]
	v_mfma_f32_16x16x32_bf16 v[36:39], v[168:171], v[192:195], v[36:39]
	v_mfma_f32_16x16x32_bf16 v[32:35], v[176:179], v[192:195], v[32:35]
	v_mfma_f32_16x16x32_bf16 v[20:23], v[168:171], v[200:203], v[20:23]
	v_mfma_f32_16x16x32_bf16 v[16:19], v[176:179], v[200:203], v[16:19]
	v_mfma_f32_16x16x32_bf16 v[4:7], v[168:171], v[210:213], v[4:7]
	v_mfma_f32_16x16x32_bf16 v[0:3], v[176:179], v[210:213], v[0:3]
	s_setprio 0
	s_barrier
	s_add_i32 s68, s68, 2
	s_add_u32 s66, s66, 0x100
	s_addc_u32 s67, s67, 0
	s_add_u32 s28, s28, 0x100
	s_addc_u32 s29, s29, 0
	s_cmp_gt_u32 s68, 41
	s_cbranch_scc0 .LBB0_555
	s_and_b64 vcc, exec, s[10:11]
	s_cbranch_vccz .LBB0_558
	s_barrier

; #define PG8_STAGE(bufoff, gbase, voff) do { const char* _gb = (const char*)(gbase); asm volatile("" : "+s"(_gb));     \
;         _Pragma("unroll") for (int _i = 0; _i < 2; ++_i) \
;         __builtin_amdgcn_global_load_lds((const unsigned*)(_gb + (voff)[_i]), (LAS unsigned*)(lds + (bufoff) + ldsw + _i * 8192), 16, 0, 0); } while (0)
; #define PG8_WAIT_V(n) asm volatile("s_waitcnt vmcnt(" #n ")" ::: "memory")
; #define PG8_BAR __builtin_amdgcn_s_barrier()
; template <class Epi>
; __device__ __forceinline__ void gemm_phase(LAS unsigned char* lds, const int wid, const Gemm g, const Epi& E) {
;     ...
;     const char* cA = PG8_UA(cur); const char* cB = PG8_UB(cur);
;     PG8_STAGE(PG8_SB(0, 0), PG8_BP(cB, 0), voffB); PG8_STAGE(PG8_SB(0, 1), PG8_BP(cB, 0) + hstepB, voffB); PG8_STAGE(PG8_SA(0, 0), PG8_AP(cA, 0), voffA); PG8_STAGE(PG8_SA(0, 1), PG8_AP(cA, 0) + hstepA, voffA);
;     if (wr == 1) PG8_BAR;
;     PG8_WAIT_V(2); PG8_BAR;
;     PG8_STAGE(PG8_SB(1, 0), PG8_BP(cB, 1), voffB); PG8_STAGE(PG8_SA(1, 0), PG8_AP(cA, 1), voffA); PG8_STAGE(PG8_SB(1, 1), PG8_BP(cB, 1) + hstepB, voffB);
;     PG8_WAIT_V(6); PG8_BAR;
;     for (;;) {
;         const bool has_next = S.next(ui + 1, nxt);
;         const char* nA = has_next ? PG8_UA(nxt) : cA; const char* nB = has_next ? PG8_UB(nxt) : cB;
;         for (int t = 0; t < nt; t += 2) {
.LBB0_819:
	s_add_u32 s73, s4, 0x9800000
	s_addc_u32 s74, s5, 0
	s_add_u32 s18, s6, 0x1d800000
	s_addc_u32 s19, s7, 0
	s_add_u32 s4, s50, 0x80
	s_addc_u32 s5, s51, 0
	s_waitcnt vmcnt(2)
	s_barrier
	s_add_i32 m0, s21, 0x18000
	s_nop 0
	global_load_lds_dwordx4 v130, s[4:5]
	s_add_i32 m0, s21, 0x1a000
	v_lshl_add_u64 v[0:1], s[4:5], 0, v[134:135]
	s_add_u32 s4, s52, 0x80
	s_addc_u32 s5, s53, 0
	s_add_i32 s75, s21, 0x8000
	global_load_lds_dwordx4 v[0:1], off
	s_mov_b32 m0, s75
	s_add_i32 s76, s21, 0xa000
	global_load_lds_dwordx4 v128, s[4:5]
	v_lshl_add_u64 v[0:1], s[4:5], 0, v[132:133]
	s_add_u32 s4, s50, 0x40080
	s_mov_b32 m0, s76
	s_addc_u32 s5, s51, 0
	global_load_lds_dwordx4 v[0:1], off
	s_add_i32 m0, s21, 0x1c000
	s_nop 0
	global_load_lds_dwordx4 v130, s[4:5]
	s_add_i32 m0, s21, 0x1e000
	v_ashrrev_i32_e32 v2, 6, v155
	global_load_lds_dwordx4 v134, s[4:5]
	v_and_b32_e32 v0, 15, v155
	v_or_b32_e32 v1, s62, v0
	v_lshlrev_b32_e32 v3, 6, v1
	v_and_b32_e32 v4, 48, v155
	s_movk_i32 s4, 0x3c0
	v_lshlrev_b32_e32 v1, 2, v1
	v_and_or_b32 v3, v3, s4, v4
	v_lshl_add_u32 v5, v2, 10, s57
	v_and_b32_e32 v1, 32, v1
	v_bitop3_b32 v1, v3, v5, v1 bitop3:0xde
	v_lshlrev_b32_e32 v3, 2, v155
	v_lshl_or_b32 v0, v0, 6, v4
	v_add_lshl_u32 v2, v2, s56, 10
	v_and_b32_e32 v3, 32, v3
	s_waitcnt vmcnt(6)
	v_bitop3_b32 v156, v0, v2, v3 bitop3:0xde
	s_add_i32 s78, 0, 0x10000
	s_add_i32 s79, 0, 0x14000
	s_waitcnt lgkmcnt(0)
	s_ashr_i32 s77, s60, 31
	v_mov_b64_e32 v[136:137], 0x400
	v_mov_b64_e32 v[138:139], 0x3ff
	v_add_u32_e32 v157, s78, v156
	v_add_u32_e32 v158, s79, v156
	v_add_u32_e32 v159, 0, v1
	s_movk_i32 s80, 0xa0
	s_movk_i32 s81, 0xffbf
	s_mov_b64 s[24:25], 0x20000
	s_mov_b64 s[26:27], 0x24000
	s_mov_b64 s[28:29], 0x28000
	s_mov_b64 s[30:31], 0x2c000
	s_mov_b32 s82, 0x40000
	s_mov_b64 s[34:35], 0x48000
	s_mov_b32 s83, 0x48000
	s_mov_b64 s[38:39], 0x50000
	s_mov_b32 s84, 0x50000
	s_mov_b64 s[40:41], 0x58000
	s_barrier
	s_branch .LBB0_822

; #define PG8_STAGE(bufoff, gbase, voff) do { const char* _gb = (const char*)(gbase); asm volatile("" : "+s"(_gb));     \
;         _Pragma("unroll") for (int _i = 0; _i < 2; ++_i) \
;         __builtin_amdgcn_global_load_lds((const unsigned*)(_gb + (voff)[_i]), (LAS unsigned*)(lds + (bufoff) + ldsw + _i * 8192), 16, 0, 0); } while (0)
; #define PG8_LDA(dst, b, h) do { _Pragma("unroll") for (int m = 0; m < 4; ++m) _Pragma("unroll") for (int k = 0; k < 2; ++k) dst[m][k] = *(const LAS bf16x8*)(lds + PG8_SA(b, h) + aoff + m * 2048 + k * 1024); } while (0)
; #define PG8_LDB(dst, b, h) do { _Pragma("unroll") for (int n = 0; n < 2; ++n) _Pragma("unroll") for (int k = 0; k < 2; ++k) dst[n][k] = *(const LAS bf16x8*)(lds + PG8_SB(b, h) + boff + n * 2048 + k * 1024); } while (0)
; #define PG8_MMA(ai, bj, At, Bt) do { __builtin_amdgcn_s_setprio(1); _Pragma("unroll") for (int m = 0; m < 4; ++m) _Pragma("unroll") for (int n = 0; n < 2; ++n) _Pragma("unroll") for (int k = 0; k < 2; ++k) \
;         acc[ai][bj][m][n] = __builtin_amdgcn_mfma_f32_16x16x32_bf16(Bt[n][k], At[m][k], acc[ai][bj][m][n], 0, 0, 0); __builtin_amdgcn_s_setprio(0); } while (0)
; #define PG8_WAIT_V(n) asm volatile("s_waitcnt vmcnt(" #n ")" ::: "memory")
; #define PG8_WAIT_L(n) asm volatile("s_waitcnt lgkmcnt(" #n ")" ::: "memory")
; #define PG8_BAR __builtin_amdgcn_s_barrier()
; #define PG8_SCHED __builtin_amdgcn_sched_barrier(0)
; template <class Epi>
; __device__ __forceinline__ void gemm_phase(LAS unsigned char* lds, const int wid, const Gemm g, const Epi& E) {
;     ...
;             PG8_LDB(B0, 0, 0); PG8_LDB(B1, 0, 1); PG8_SCHED; PG8_LDA(At, 0, 0); PG8_STAGE(PG8_SA(1, 1), a1 + hstepA, voffA);
;             PG8_WAIT_V(8); PG8_WAIT_L(0); PG8_BAR; PG8_MMA(0, 0, At, B0); PG8_MMA(0, 1, At, B1); PG8_BAR; PG8_SCHED;
;             PG8_LDA(At, 0, 1); PG8_STAGE(PG8_SB(0, 0), b2, voffB); PG8_STAGE(PG8_SB(0, 1), b2 + hstepB, voffB); PG8_STAGE(PG8_SA(0, 0), a2, voffA);
;             PG8_WAIT_V(8); PG8_WAIT_L(0); PG8_BAR; PG8_MMA(1, 0, At, B0); PG8_MMA(1, 1, At, B1); PG8_BAR; PG8_SCHED;
.LBB0_831:
	ds_read_b128 v[140:143], v157
	ds_read_b128 v[144:147], v157 offset:1024
	ds_read_b128 v[148:151], v157 offset:2048
	ds_read_b128 v[160:163], v157 offset:3072
	ds_read_b128 v[164:167], v158
	ds_read_b128 v[168:171], v158 offset:1024
	ds_read_b128 v[172:175], v158 offset:2048
	ds_read_b128 v[176:179], v158 offset:3072
	s_add_u32 s50, s6, 0xfffc0080
	s_addc_u32 s51, s7, -1
	s_add_u32 s54, s88, 0xffffff80
	s_addc_u32 s55, s89, -1
	s_add_u32 s91, s6, 0xfffc0100
	s_addc_u32 s94, s7, -1
	s_add_i32 s96, s78, s61
	s_add_i32 m0, s21, 0xc000
	s_add_i32 s95, s21, 0xe000
	s_add_i32 s97, s96, 0x2000
	s_cmp_eq_u32 s90, 12
	s_cselect_b32 s53, s47, s51
	s_cselect_b32 s52, s46, s50
	s_cselect_b32 s93, s9, s55
	s_cselect_b32 s92, s43, s54
	s_cselect_b32 s51, s85, s94
	s_cselect_b32 s50, s45, s91
	s_mov_b64 s[54:55], s[6:7]
	ds_read_b128 v[180:183], v159
	ds_read_b128 v[184:187], v159 offset:1024
	ds_read_b128 v[188:191], v159 offset:2048
	ds_read_b128 v[192:195], v159 offset:3072
	ds_read_b128 v[196:199], v159 offset:4096
	ds_read_b128 v[200:203], v159 offset:5120
	ds_read_b128 v[206:209], v159 offset:6144
	ds_read_b128 v[210:213], v159 offset:7168
	s_nop 0
	global_load_lds_dwordx4 v128, s[54:55]
	s_mov_b32 m0, s95
	s_nop 0
	global_load_lds_dwordx4 v132, s[54:55]
	s_waitcnt vmcnt(8)
	s_waitcnt lgkmcnt(0)
	s_barrier
	s_setprio 1
	s_waitcnt lgkmcnt(0)
	v_mfma_f32_16x16x32_bf16 v[124:127], v[140:143], v[180:183], v[124:127]
	v_mfma_f32_16x16x32_bf16 v[120:123], v[148:151], v[180:183], v[120:123]
	v_mfma_f32_16x16x32_bf16 v[116:119], v[140:143], v[188:191], v[116:119]
	v_mfma_f32_16x16x32_bf16 v[112:115], v[148:151], v[188:191], v[112:115]
	v_mfma_f32_16x16x32_bf16 v[100:103], v[140:143], v[196:199], v[100:103]
	v_mfma_f32_16x16x32_bf16 v[96:99], v[148:151], v[196:199], v[96:99]
	v_mfma_f32_16x16x32_bf16 v[84:87], v[140:143], v[206:209], v[84:87]
	v_mfma_f32_16x16x32_bf16 v[80:83], v[148:151], v[206:209], v[80:83]
	v_mfma_f32_16x16x32_bf16 v[124:127], v[144:147], v[184:187], v[124:127]
	v_mfma_f32_16x16x32_bf16 v[120:123], v[160:163], v[184:187], v[120:123]
	v_mfma_f32_16x16x32_bf16 v[116:119], v[144:147], v[192:195], v[116:119]
	v_mfma_f32_16x16x32_bf16 v[112:115], v[160:163], v[192:195], v[112:115]
	v_mfma_f32_16x16x32_bf16 v[100:103], v[144:147], v[200:203], v[100:103]
	v_mfma_f32_16x16x32_bf16 v[96:99], v[160:163], v[200:203], v[96:99]
	v_mfma_f32_16x16x32_bf16 v[84:87], v[144:147], v[210:213], v[84:87]
	v_mfma_f32_16x16x32_bf16 v[80:83], v[160:163], v[210:213], v[80:83]
	s_setprio 0
	s_setprio 1
	v_mfma_f32_16x16x32_bf16 v[108:111], v[164:167], v[180:183], v[108:111]
	v_mfma_f32_16x16x32_bf16 v[104:107], v[172:175], v[180:183], v[104:107]
	v_mfma_f32_16x16x32_bf16 v[92:95], v[164:167], v[188:191], v[92:95]
	v_mfma_f32_16x16x32_bf16 v[88:91], v[172:175], v[188:191], v[88:91]
	v_mfma_f32_16x16x32_bf16 v[76:79], v[164:167], v[196:199], v[76:79]
	v_mfma_f32_16x16x32_bf16 v[72:75], v[172:175], v[196:199], v[72:75]
	v_mfma_f32_16x16x32_bf16 v[68:71], v[164:167], v[206:209], v[68:71]
	v_mfma_f32_16x16x32_bf16 v[64:67], v[172:175], v[206:209], v[64:67]
	v_mfma_f32_16x16x32_bf16 v[108:111], v[168:171], v[184:187], v[108:111]
	v_mfma_f32_16x16x32_bf16 v[104:107], v[176:179], v[184:187], v[104:107]
	v_mfma_f32_16x16x32_bf16 v[92:95], v[168:171], v[192:195], v[92:95]
	v_mfma_f32_16x16x32_bf16 v[88:91], v[176:179], v[192:195], v[88:91]
	v_mfma_f32_16x16x32_bf16 v[76:79], v[168:171], v[200:203], v[76:79]
	v_mfma_f32_16x16x32_bf16 v[72:75], v[176:179], v[200:203], v[72:75]
	v_mfma_f32_16x16x32_bf16 v[68:71], v[168:171], v[210:213], v[68:71]
	v_mfma_f32_16x16x32_bf16 v[64:67], v[176:179], v[210:213], v[64:67]
	s_setprio 0
	s_barrier
	s_mov_b64 s[54:55], s[92:93]
	s_mov_b32 m0, s96
	ds_read_b128 v[180:183], v159 offset:16384
	ds_read_b128 v[184:187], v159 offset:17408
	ds_read_b128 v[188:191], v159 offset:18432
	ds_read_b128 v[192:195], v159 offset:19456
	ds_read_b128 v[196:199], v159 offset:20480
	ds_read_b128 v[200:203], v159 offset:21504
	ds_read_b128 v[206:209], v159 offset:22528
	ds_read_b128 v[210:213], v159 offset:23552
	s_nop 0
	global_load_lds_dwordx4 v130, s[54:55]
	v_lshl_add_u64 v[152:153], s[54:55], 0, v[134:135]
	s_cselect_b32 s55, s87, s89
	s_cselect_b32 s54, s86, s88
	s_add_u32 s92, s92, 0x40000
	s_mov_b32 m0, s97
	s_addc_u32 s93, s93, 0
	s_add_i32 s91, s79, s61
	global_load_lds_dwordx4 v[152:153], off
	s_mov_b32 m0, s91
	s_nop 0
	global_load_lds_dwordx4 v130, s[92:93]
	v_lshl_add_u64 v[152:153], s[92:93], 0, v[134:135]
	s_add_i32 m0, s91, 0x2000
	s_mov_b64 s[92:93], s[52:53]
	global_load_lds_dwordx4 v[152:153], off
	s_mov_b32 m0, s21
	s_nop 0
	global_load_lds_dwordx4 v128, s[92:93]
	s_mov_b32 m0, s69
	s_nop 0
	global_load_lds_dwordx4 v132, s[92:93]
	s_waitcnt vmcnt(8)
	s_waitcnt lgkmcnt(0)
	s_barrier
; #define PG8_STAGE(bufoff, gbase, voff) do { const char* _gb = (const char*)(gbase); asm volatile("" : "+s"(_gb));     \
;         _Pragma("unroll") for (int _i = 0; _i < 2; ++_i) \
;         __builtin_amdgcn_global_load_lds((const unsigned*)(_gb + (voff)[_i]), (LAS unsigned*)(lds + (bufoff) + ldsw + _i * 8192), 16, 0, 0); } while (0)
; #define PG8_LDA(dst, b, h) do { _Pragma("unroll") for (int m = 0; m < 4; ++m) _Pragma("unroll") for (int k = 0; k < 2; ++k) dst[m][k] = *(const LAS bf16x8*)(lds + PG8_SA(b, h) + aoff + m * 2048 + k * 1024); } while (0)
; #define PG8_LDB(dst, b, h) do { _Pragma("unroll") for (int n = 0; n < 2; ++n) _Pragma("unroll") for (int k = 0; k < 2; ++k) dst[n][k] = *(const LAS bf16x8*)(lds + PG8_SB(b, h) + boff + n * 2048 + k * 1024); } while (0)
; #define PG8_MMA(ai, bj, At, Bt) do { __builtin_amdgcn_s_setprio(1); _Pragma("unroll") for (int m = 0; m < 4; ++m) _Pragma("unroll") for (int n = 0; n < 2; ++n) _Pragma("unroll") for (int k = 0; k < 2; ++k) \
;         acc[ai][bj][m][n] = __builtin_amdgcn_mfma_f32_16x16x32_bf16(Bt[n][k], At[m][k], acc[ai][bj][m][n], 0, 0, 0); __builtin_amdgcn_s_setprio(0); } while (0)
; #define PG8_WAIT_V(n) asm volatile("s_waitcnt vmcnt(" #n ")" ::: "memory")
; #define PG8_WAIT_L(n) asm volatile("s_waitcnt lgkmcnt(" #n ")" ::: "memory")
; #define PG8_BAR __builtin_amdgcn_s_barrier()
; #define PG8_SCHED __builtin_amdgcn_sched_barrier(0)
; template <class Epi>
; __device__ __forceinline__ void gemm_phase(LAS unsigned char* lds, const int wid, const Gemm g, const Epi& E) {
;     ...
;             PG8_WAIT_V(8); PG8_WAIT_L(0); PG8_BAR; PG8_MMA(1, 0, At, B0); PG8_MMA(1, 1, At, B1); PG8_BAR; PG8_SCHED;
;             PG8_LDB(B0, 1, 0); PG8_LDB(B1, 1, 1); PG8_SCHED; PG8_LDA(At, 1, 0); PG8_STAGE(PG8_SA(0, 1), a2 + hstepA, voffA);
;             PG8_WAIT_V(8); PG8_WAIT_L(0); PG8_BAR; PG8_MMA(0, 0, At, B0); PG8_MMA(0, 1, At, B1); PG8_BAR; PG8_SCHED;
	s_setprio 1
	s_waitcnt lgkmcnt(0)
	v_mfma_f32_16x16x32_bf16 v[60:63], v[140:143], v[180:183], v[60:63]
	v_mfma_f32_16x16x32_bf16 v[56:59], v[148:151], v[180:183], v[56:59]
	v_mfma_f32_16x16x32_bf16 v[52:55], v[140:143], v[188:191], v[52:55]
	v_mfma_f32_16x16x32_bf16 v[48:51], v[148:151], v[188:191], v[48:51]
	v_mfma_f32_16x16x32_bf16 v[36:39], v[140:143], v[196:199], v[36:39]
	v_mfma_f32_16x16x32_bf16 v[32:35], v[148:151], v[196:199], v[32:35]
	v_mfma_f32_16x16x32_bf16 v[20:23], v[140:143], v[206:209], v[20:23]
	v_mfma_f32_16x16x32_bf16 v[16:19], v[148:151], v[206:209], v[16:19]
	v_mfma_f32_16x16x32_bf16 v[60:63], v[144:147], v[184:187], v[60:63]
	v_mfma_f32_16x16x32_bf16 v[56:59], v[160:163], v[184:187], v[56:59]
	v_mfma_f32_16x16x32_bf16 v[52:55], v[144:147], v[192:195], v[52:55]
	v_mfma_f32_16x16x32_bf16 v[48:51], v[160:163], v[192:195], v[48:51]
	v_mfma_f32_16x16x32_bf16 v[36:39], v[144:147], v[200:203], v[36:39]
	v_mfma_f32_16x16x32_bf16 v[32:35], v[160:163], v[200:203], v[32:35]
	v_mfma_f32_16x16x32_bf16 v[20:23], v[144:147], v[210:213], v[20:23]
	v_mfma_f32_16x16x32_bf16 v[16:19], v[160:163], v[210:213], v[16:19]
	s_setprio 0
	s_setprio 1
	v_mfma_f32_16x16x32_bf16 v[44:47], v[164:167], v[180:183], v[44:47]
	v_mfma_f32_16x16x32_bf16 v[40:43], v[172:175], v[180:183], v[40:43]
	v_mfma_f32_16x16x32_bf16 v[28:31], v[164:167], v[188:191], v[28:31]
	v_mfma_f32_16x16x32_bf16 v[24:27], v[172:175], v[188:191], v[24:27]
	v_mfma_f32_16x16x32_bf16 v[12:15], v[164:167], v[196:199], v[12:15]
	v_mfma_f32_16x16x32_bf16 v[8:11], v[172:175], v[196:199], v[8:11]
	v_mfma_f32_16x16x32_bf16 v[4:7], v[164:167], v[206:209], v[4:7]
	v_mfma_f32_16x16x32_bf16 v[0:3], v[172:175], v[206:209], v[0:3]
	v_mfma_f32_16x16x32_bf16 v[44:47], v[168:171], v[184:187], v[44:47]
	v_mfma_f32_16x16x32_bf16 v[40:43], v[176:179], v[184:187], v[40:43]
	v_mfma_f32_16x16x32_bf16 v[28:31], v[168:171], v[192:195], v[28:31]
	v_mfma_f32_16x16x32_bf16 v[24:27], v[176:179], v[192:195], v[24:27]
	v_mfma_f32_16x16x32_bf16 v[12:15], v[168:171], v[200:203], v[12:15]
	v_mfma_f32_16x16x32_bf16 v[8:11], v[176:179], v[200:203], v[8:11]
	v_mfma_f32_16x16x32_bf16 v[4:7], v[168:171], v[210:213], v[4:7]
	v_mfma_f32_16x16x32_bf16 v[0:3], v[176:179], v[210:213], v[0:3]
	s_setprio 0
	s_barrier
	s_add_i32 s91, 0, 0x18000
	v_add_u32_e32 v152, s91, v156
	s_add_i32 s92, 0, 0x1c000
	ds_read_b128 v[140:143], v152
	ds_read_b128 v[144:147], v152 offset:1024
	ds_read_b128 v[148:151], v152 offset:2048
	ds_read_b128 v[160:163], v152 offset:3072
	v_add_u32_e32 v152, s92, v156
	ds_read_b128 v[164:167], v152
	ds_read_b128 v[168:171], v152 offset:1024
	ds_read_b128 v[172:175], v152 offset:2048
	ds_read_b128 v[176:179], v152 offset:3072
	s_add_u32 s52, s52, 0x40000
	s_addc_u32 s53, s53, 0
	s_mov_b32 m0, s70
	ds_read_b128 v[180:183], v159 offset:32768
	ds_read_b128 v[184:187], v159 offset:33792
	ds_read_b128 v[188:191], v159 offset:34816
	ds_read_b128 v[192:195], v159 offset:35840
	ds_read_b128 v[196:199], v159 offset:36864
	ds_read_b128 v[200:203], v159 offset:37888
	ds_read_b128 v[206:209], v159 offset:38912
	ds_read_b128 v[210:213], v159 offset:39936
	s_nop 0
	global_load_lds_dwordx4 v128, s[52:53]
	s_mov_b32 m0, s71
	s_nop 0
	global_load_lds_dwordx4 v132, s[52:53]
	s_waitcnt vmcnt(8)
	s_waitcnt lgkmcnt(0)
	s_barrier
	s_setprio 1
	s_waitcnt lgkmcnt(0)
	v_mfma_f32_16x16x32_bf16 v[124:127], v[140:143], v[180:183], v[124:127]
	v_mfma_f32_16x16x32_bf16 v[120:123], v[148:151], v[180:183], v[120:123]
	v_mfma_f32_16x16x32_bf16 v[116:119], v[140:143], v[188:191], v[116:119]
	v_mfma_f32_16x16x32_bf16 v[112:115], v[148:151], v[188:191], v[112:115]
	v_mfma_f32_16x16x32_bf16 v[100:103], v[140:143], v[196:199], v[100:103]
	v_mfma_f32_16x16x32_bf16 v[96:99], v[148:151], v[196:199], v[96:99]
	v_mfma_f32_16x16x32_bf16 v[84:87], v[140:143], v[206:209], v[84:87]
	v_mfma_f32_16x16x32_bf16 v[80:83], v[148:151], v[206:209], v[80:83]
	v_mfma_f32_16x16x32_bf16 v[124:127], v[144:147], v[184:187], v[124:127]
	v_mfma_f32_16x16x32_bf16 v[120:123], v[160:163], v[184:187], v[120:123]
	v_mfma_f32_16x16x32_bf16 v[116:119], v[144:147], v[192:195], v[116:119]
	v_mfma_f32_16x16x32_bf16 v[112:115], v[160:163], v[192:195], v[112:115]
	v_mfma_f32_16x16x32_bf16 v[100:103], v[144:147], v[200:203], v[100:103]
	v_mfma_f32_16x16x32_bf16 v[96:99], v[160:163], v[200:203], v[96:99]
	v_mfma_f32_16x16x32_bf16 v[84:87], v[144:147], v[210:213], v[84:87]
	v_mfma_f32_16x16x32_bf16 v[80:83], v[160:163], v[210:213], v[80:83]
	s_setprio 0
	s_setprio 1
	v_mfma_f32_16x16x32_bf16 v[108:111], v[164:167], v[180:183], v[108:111]
	v_mfma_f32_16x16x32_bf16 v[104:107], v[172:175], v[180:183], v[104:107]
	v_mfma_f32_16x16x32_bf16 v[92:95], v[164:167], v[188:191], v[92:95]
	v_mfma_f32_16x16x32_bf16 v[88:91], v[172:175], v[188:191], v[88:91]
	v_mfma_f32_16x16x32_bf16 v[76:79], v[164:167], v[196:199], v[76:79]
	v_mfma_f32_16x16x32_bf16 v[72:75], v[172:175], v[196:199], v[72:75]
	v_mfma_f32_16x16x32_bf16 v[68:71], v[164:167], v[206:209], v[68:71]
	v_mfma_f32_16x16x32_bf16 v[64:67], v[172:175], v[206:209], v[64:67]
	v_mfma_f32_16x16x32_bf16 v[108:111], v[168:171], v[184:187], v[108:111]
	v_mfma_f32_16x16x32_bf16 v[104:107], v[176:179], v[184:187], v[104:107]
	v_mfma_f32_16x16x32_bf16 v[92:95], v[168:171], v[192:195], v[92:95]
	v_mfma_f32_16x16x32_bf16 v[88:91], v[176:179], v[192:195], v[88:91]
	v_mfma_f32_16x16x32_bf16 v[76:79], v[168:171], v[200:203], v[76:79]
	v_mfma_f32_16x16x32_bf16 v[72:75], v[176:179], v[200:203], v[72:75]
	v_mfma_f32_16x16x32_bf16 v[68:71], v[168:171], v[210:213], v[68:71]
	v_mfma_f32_16x16x32_bf16 v[64:67], v[176:179], v[210:213], v[64:67]
	s_setprio 0
	s_barrier
; #define PG8_STAGE(bufoff, gbase, voff) do { const char* _gb = (const char*)(gbase); asm volatile("" : "+s"(_gb));     \
;         _Pragma("unroll") for (int _i = 0; _i < 2; ++_i) \
;         __builtin_amdgcn_global_load_lds((const unsigned*)(_gb + (voff)[_i]), (LAS unsigned*)(lds + (bufoff) + ldsw + _i * 8192), 16, 0, 0); } while (0)
; #define PG8_LDA(dst, b, h) do { _Pragma("unroll") for (int m = 0; m < 4; ++m) _Pragma("unroll") for (int k = 0; k < 2; ++k) dst[m][k] = *(const LAS bf16x8*)(lds + PG8_SA(b, h) + aoff + m * 2048 + k * 1024); } while (0)
; #define PG8_MMA(ai, bj, At, Bt) do { __builtin_amdgcn_s_setprio(1); _Pragma("unroll") for (int m = 0; m < 4; ++m) _Pragma("unroll") for (int n = 0; n < 2; ++n) _Pragma("unroll") for (int k = 0; k < 2; ++k) \
;         acc[ai][bj][m][n] = __builtin_amdgcn_mfma_f32_16x16x32_bf16(Bt[n][k], At[m][k], acc[ai][bj][m][n], 0, 0, 0); __builtin_amdgcn_s_setprio(0); } while (0)
; #define PG8_WAIT_V(n) asm volatile("s_waitcnt vmcnt(" #n ")" ::: "memory")
; #define PG8_WAIT_L(n) asm volatile("s_waitcnt lgkmcnt(" #n ")" ::: "memory")
; #define PG8_BAR __builtin_amdgcn_s_barrier()
; #define PG8_SCHED __builtin_amdgcn_sched_barrier(0)
; template <class Epi>
; __device__ __forceinline__ void gemm_phase(LAS unsigned char* lds, const int wid, const Gemm g, const Epi& E) {
;     ...
;             PG8_WAIT_V(8); PG8_WAIT_L(0); PG8_BAR; PG8_MMA(0, 0, At, B0); PG8_MMA(0, 1, At, B1); PG8_BAR; PG8_SCHED;
;             PG8_LDA(At, 1, 1); PG8_STAGE(PG8_SB(1, 0), b3, voffB); PG8_STAGE(PG8_SB(1, 1), b3 + hstepB, voffB); PG8_STAGE(PG8_SA(1, 0), a3, voffA);
;             PG8_WAIT_V(8); PG8_WAIT_L(0); PG8_BAR; PG8_MMA(1, 0, At, B0); PG8_MMA(1, 1, At, B1); PG8_BAR; PG8_SCHED;
;         }
;         if (wr == 0) PG8_BAR;
	s_mov_b64 s[52:53], s[54:55]
	s_add_i32 s91, s91, s61
	ds_read_b128 v[180:183], v159 offset:49152
	ds_read_b128 v[184:187], v159 offset:50176
	ds_read_b128 v[188:191], v159 offset:51200
	ds_read_b128 v[192:195], v159 offset:52224
	ds_read_b128 v[196:199], v159 offset:53248
	ds_read_b128 v[200:203], v159 offset:54272
	ds_read_b128 v[206:209], v159 offset:55296
	ds_read_b128 v[210:213], v159 offset:56320
	s_mov_b32 m0, s91
	s_nop 0
	global_load_lds_dwordx4 v130, s[52:53]
	s_add_i32 m0, s91, 0x2000
	v_lshl_add_u64 v[152:153], s[52:53], 0, v[134:135]
	s_add_u32 s52, s54, 0x40000
	s_addc_u32 s53, s55, 0
	s_add_i32 s54, s92, s61
	global_load_lds_dwordx4 v[152:153], off
	s_mov_b32 m0, s54
	s_nop 0
	global_load_lds_dwordx4 v130, s[52:53]
	s_add_i32 m0, s54, 0x2000
	s_nop 0
	global_load_lds_dwordx4 v134, s[52:53]
	s_mov_b32 m0, s75
	s_nop 0
	global_load_lds_dwordx4 v128, s[50:51]
	s_mov_b32 m0, s76
	s_nop 0
	global_load_lds_dwordx4 v132, s[50:51]
	s_waitcnt vmcnt(8)
	s_waitcnt lgkmcnt(0)
	s_barrier
	s_setprio 1
	s_waitcnt lgkmcnt(0)
	v_mfma_f32_16x16x32_bf16 v[60:63], v[140:143], v[180:183], v[60:63]
	v_mfma_f32_16x16x32_bf16 v[56:59], v[148:151], v[180:183], v[56:59]
	v_mfma_f32_16x16x32_bf16 v[52:55], v[140:143], v[188:191], v[52:55]
	v_mfma_f32_16x16x32_bf16 v[48:51], v[148:151], v[188:191], v[48:51]
	v_mfma_f32_16x16x32_bf16 v[36:39], v[140:143], v[196:199], v[36:39]
	v_mfma_f32_16x16x32_bf16 v[32:35], v[148:151], v[196:199], v[32:35]
	v_mfma_f32_16x16x32_bf16 v[20:23], v[140:143], v[206:209], v[20:23]
	v_mfma_f32_16x16x32_bf16 v[16:19], v[148:151], v[206:209], v[16:19]
	v_mfma_f32_16x16x32_bf16 v[60:63], v[144:147], v[184:187], v[60:63]
	v_mfma_f32_16x16x32_bf16 v[56:59], v[160:163], v[184:187], v[56:59]
	v_mfma_f32_16x16x32_bf16 v[52:55], v[144:147], v[192:195], v[52:55]
	v_mfma_f32_16x16x32_bf16 v[48:51], v[160:163], v[192:195], v[48:51]
	v_mfma_f32_16x16x32_bf16 v[36:39], v[144:147], v[200:203], v[36:39]
	v_mfma_f32_16x16x32_bf16 v[32:35], v[160:163], v[200:203], v[32:35]
	v_mfma_f32_16x16x32_bf16 v[20:23], v[144:147], v[210:213], v[20:23]
	v_mfma_f32_16x16x32_bf16 v[16:19], v[160:163], v[210:213], v[16:19]
	s_setprio 0
	s_setprio 1
	v_mfma_f32_16x16x32_bf16 v[44:47], v[164:167], v[180:183], v[44:47]
	v_mfma_f32_16x16x32_bf16 v[40:43], v[172:175], v[180:183], v[40:43]
	v_mfma_f32_16x16x32_bf16 v[28:31], v[164:167], v[188:191], v[28:31]
	v_mfma_f32_16x16x32_bf16 v[24:27], v[172:175], v[188:191], v[24:27]
	v_mfma_f32_16x16x32_bf16 v[12:15], v[164:167], v[196:199], v[12:15]
	v_mfma_f32_16x16x32_bf16 v[8:11], v[172:175], v[196:199], v[8:11]
	v_mfma_f32_16x16x32_bf16 v[4:7], v[164:167], v[206:209], v[4:7]
	v_mfma_f32_16x16x32_bf16 v[0:3], v[172:175], v[206:209], v[0:3]
	v_mfma_f32_16x16x32_bf16 v[44:47], v[168:171], v[184:187], v[44:47]
	v_mfma_f32_16x16x32_bf16 v[40:43], v[176:179], v[184:187], v[40:43]
	v_mfma_f32_16x16x32_bf16 v[28:31], v[168:171], v[192:195], v[28:31]
	v_mfma_f32_16x16x32_bf16 v[24:27], v[176:179], v[192:195], v[24:27]
	v_mfma_f32_16x16x32_bf16 v[12:15], v[168:171], v[200:203], v[12:15]
	v_mfma_f32_16x16x32_bf16 v[8:11], v[176:179], v[200:203], v[8:11]
	v_mfma_f32_16x16x32_bf16 v[4:7], v[168:171], v[210:213], v[4:7]
	v_mfma_f32_16x16x32_bf16 v[0:3], v[176:179], v[210:213], v[0:3]
	s_setprio 0
	s_barrier
	s_add_i32 s90, s90, 2
	s_add_u32 s88, s88, 0x100
	s_addc_u32 s89, s89, 0
	s_add_u32 s6, s6, 0x100
	s_addc_u32 s7, s7, 0
	s_cmp_gt_u32 s90, 13
	s_cbranch_scc0 .LBB0_831
	s_and_b64 vcc, exec, s[12:13]
	s_cbranch_vccz .LBB0_834
	s_barrier

; #define PG8_STAGE(bufoff, gbase, voff) do { const char* _gb = (const char*)(gbase); asm volatile("" : "+s"(_gb));     \
;         _Pragma("unroll") for (int _i = 0; _i < 2; ++_i) \
;         __builtin_amdgcn_global_load_lds((const unsigned*)(_gb + (voff)[_i]), (LAS unsigned*)(lds + (bufoff) + ldsw + _i * 8192), 16, 0, 0); } while (0)
; #define PG8_WAIT_V(n) asm volatile("s_waitcnt vmcnt(" #n ")" ::: "memory")
; #define PG8_BAR __builtin_amdgcn_s_barrier()
; template <class Epi>
; __device__ __forceinline__ void gemm_phase(LAS unsigned char* lds, const int wid, const Gemm g, const Epi& E) {
;     ...
;     const char* cA = PG8_UA(cur); const char* cB = PG8_UB(cur);
;     PG8_STAGE(PG8_SB(0, 0), PG8_BP(cB, 0), voffB); PG8_STAGE(PG8_SB(0, 1), PG8_BP(cB, 0) + hstepB, voffB); PG8_STAGE(PG8_SA(0, 0), PG8_AP(cA, 0), voffA); PG8_STAGE(PG8_SA(0, 1), PG8_AP(cA, 0) + hstepA, voffA);
;     if (wr == 1) PG8_BAR;
;     PG8_WAIT_V(2); PG8_BAR;
;     PG8_STAGE(PG8_SB(1, 0), PG8_BP(cB, 1), voffB); PG8_STAGE(PG8_SA(1, 0), PG8_AP(cA, 1), voffA); PG8_STAGE(PG8_SB(1, 1), PG8_BP(cB, 1) + hstepB, voffB);
;     PG8_WAIT_V(6); PG8_BAR;
;     for (;;) {
;         const bool has_next = S.next(ui + 1, nxt);
;         const char* nA = has_next ? PG8_UA(nxt) : cA; const char* nB = has_next ? PG8_UB(nxt) : cB;
;         for (int t = 0; t < nt; t += 2) {
.LBB0_944:
	s_add_u32 s73, s6, 0x9800000
	s_addc_u32 s74, s7, 0
	s_sub_i32 s4, 0, s21
	s_sub_u32 s5, s16, s20
	s_subb_u32 s6, s17, 0
	s_add_u32 s5, s5, 0
	s_addc_u32 s6, s6, s4
	s_add_u32 s4, s5, 0xf6800000
	s_addc_u32 s5, s6, -1
	s_ashr_i64 s[14:15], s[4:5], 1
	s_add_u32 s16, s24, 0x1d800000
	s_addc_u32 s17, s25, 0
	s_add_u32 s4, s50, 0x80
	s_addc_u32 s5, s51, 0
	s_waitcnt vmcnt(2)
	s_barrier
	s_add_i32 m0, s10, 0x18000
	s_nop 0
	global_load_lds_dwordx4 v130, s[4:5]
	s_add_i32 m0, s10, 0x1a000
	v_lshl_add_u64 v[0:1], s[4:5], 0, v[134:135]
	s_add_u32 s4, s52, 0x880
	s_addc_u32 s5, s53, 0
	s_add_i32 s75, s10, 0x8000
	global_load_lds_dwordx4 v[0:1], off
	s_mov_b32 m0, s75
	s_add_i32 s76, s10, 0xa000
	global_load_lds_dwordx4 v128, s[4:5]
	v_lshl_add_u64 v[0:1], s[4:5], 0, v[132:133]
	s_add_u32 s4, s50, 0x80080
	s_mov_b32 m0, s76
	s_addc_u32 s5, s51, 0
	global_load_lds_dwordx4 v[0:1], off
	s_add_i32 m0, s10, 0x1c000
	s_nop 0
	global_load_lds_dwordx4 v130, s[4:5]
	s_add_i32 m0, s10, 0x1e000
	v_ashrrev_i32_e32 v2, 6, v155
	global_load_lds_dwordx4 v134, s[4:5]
	v_and_b32_e32 v0, 15, v155
	v_or_b32_e32 v1, s62, v0
	v_lshlrev_b32_e32 v3, 6, v1
	v_and_b32_e32 v4, 48, v155
	s_movk_i32 s4, 0x3c0
	v_lshlrev_b32_e32 v1, 2, v1
	v_and_or_b32 v3, v3, s4, v4
	v_lshl_add_u32 v5, v2, 10, s57
	v_and_b32_e32 v1, 32, v1
	v_bitop3_b32 v1, v3, v5, v1 bitop3:0xde
	v_lshlrev_b32_e32 v3, 2, v155
	v_lshl_or_b32 v0, v0, 6, v4
	v_add_lshl_u32 v2, v2, s56, 10
	v_and_b32_e32 v3, 32, v3
	s_waitcnt vmcnt(6)
	v_bitop3_b32 v156, v0, v2, v3 bitop3:0xde
	s_add_i32 s80, 0, 0x10000
	s_add_i32 s81, 0, 0x14000
	s_ashr_i32 s77, s60, 31
	v_mov_b64_e32 v[136:137], 0x300
	v_mov_b64_e32 v[138:139], 0x2ff
	s_movk_i32 s0, 0x61
	s_movk_i32 s79, 0x800
	v_add_u32_e32 v157, s80, v156
	v_add_u32_e32 v158, s81, v156
	v_add_u32_e32 v159, 0, v1
	s_mov_b64 s[20:21], 0x40000
	s_movk_i32 s82, 0xa0
	s_movk_i32 s83, 0xffbf
	s_mov_b64 s[24:25], 0x20000
	s_mov_b64 s[26:27], 0x24000
	s_mov_b64 s[28:29], 0x28000
	s_mov_b64 s[30:31], 0x2c000
	s_mov_b32 s84, 0x40000
	s_mov_b64 s[34:35], 0x48000
	s_mov_b32 s85, 0x48000
	s_mov_b64 s[38:39], 0x50000
	s_mov_b32 s86, 0x50000
	s_mov_b64 s[40:41], 0x58000
	s_barrier
	s_branch .LBB0_947

; #define PG8_STAGE(bufoff, gbase, voff) do { const char* _gb = (const char*)(gbase); asm volatile("" : "+s"(_gb));     \
;         _Pragma("unroll") for (int _i = 0; _i < 2; ++_i) \
;         __builtin_amdgcn_global_load_lds((const unsigned*)(_gb + (voff)[_i]), (LAS unsigned*)(lds + (bufoff) + ldsw + _i * 8192), 16, 0, 0); } while (0)
; #define PG8_LDA(dst, b, h) do { _Pragma("unroll") for (int m = 0; m < 4; ++m) _Pragma("unroll") for (int k = 0; k < 2; ++k) dst[m][k] = *(const LAS bf16x8*)(lds + PG8_SA(b, h) + aoff + m * 2048 + k * 1024); } while (0)
; #define PG8_LDB(dst, b, h) do { _Pragma("unroll") for (int n = 0; n < 2; ++n) _Pragma("unroll") for (int k = 0; k < 2; ++k) dst[n][k] = *(const LAS bf16x8*)(lds + PG8_SB(b, h) + boff + n * 2048 + k * 1024); } while (0)
; #define PG8_MMA(ai, bj, At, Bt) do { __builtin_amdgcn_s_setprio(1); _Pragma("unroll") for (int m = 0; m < 4; ++m) _Pragma("unroll") for (int n = 0; n < 2; ++n) _Pragma("unroll") for (int k = 0; k < 2; ++k) \
;         acc[ai][bj][m][n] = __builtin_amdgcn_mfma_f32_16x16x32_bf16(Bt[n][k], At[m][k], acc[ai][bj][m][n], 0, 0, 0); __builtin_amdgcn_s_setprio(0); } while (0)
; #define PG8_WAIT_V(n) asm volatile("s_waitcnt vmcnt(" #n ")" ::: "memory")
; #define PG8_WAIT_L(n) asm volatile("s_waitcnt lgkmcnt(" #n ")" ::: "memory")
; template <class Epi>
; __device__ __forceinline__ void gemm_phase(LAS unsigned char* lds, const int wid, const Gemm g, const Epi& E) {
;     ...
;         for (int t = 0; t < nt; t += 2) {
;             const bool last = (t == nt - 2);
;             const char* a1 = PG8_AP(cA, t + 1);
;             const char* a2 = last ? PG8_AP(nA, 0) : PG8_AP(cA, t + 2); const char* b2 = last ? PG8_BP(nB, 0) : PG8_BP(cB, t + 2);
;             const char* a3 = last ? PG8_AP(nA, 1) : PG8_AP(cA, t + 3); const char* b3 = last ? PG8_BP(nB, 1) : PG8_BP(cB, t + 3);
;             PG8_LDB(B0, 0, 0); PG8_LDB(B1, 0, 1); PG8_SCHED; PG8_LDA(At, 0, 0); PG8_STAGE(PG8_SA(1, 1), a1 + hstepA, voffA);
;             PG8_WAIT_V(8); PG8_WAIT_L(0); PG8_BAR; PG8_MMA(0, 0, At, B0); PG8_MMA(0, 1, At, B1); PG8_BAR; PG8_SCHED;
;             PG8_LDA(At, 0, 1); PG8_STAGE(PG8_SB(0, 0), b2, voffB); PG8_STAGE(PG8_SB(0, 1), b2 + hstepB, voffB); PG8_STAGE(PG8_SA(0, 0), a2, voffA);
;             PG8_WAIT_V(8); PG8_WAIT_L(0); PG8_BAR; PG8_MMA(1, 0, At, B0); PG8_MMA(1, 1, At, B1); PG8_BAR; PG8_SCHED;
.LBB0_952:
	s_add_i32 s92, s92, 2
	s_cmp_lt_u32 s92, 16
	s_cselect_b32 s54, 0, -1
	s_cselect_b32 s55, s79, 0xfffff800
	s_cmp_lt_u32 s92, 14
	s_cselect_b32 s57, s79, 0xfffff800
	s_cselect_b32 s56, 0, -1
	s_add_u32 s57, s57, s6
	s_addc_u32 s56, s56, s7
	s_add_u32 s57, s52, s57
	s_addc_u32 s56, s53, s56
	s_add_u32 s93, s57, 0x100
	s_addc_u32 s56, s56, 0
	s_add_u32 s57, s50, s6
	s_addc_u32 s58, s51, s7
	s_add_u32 s94, s57, 0x100
	s_addc_u32 s95, s58, 0
	s_cmp_lt_u32 s92, 13
	s_cselect_b32 s96, s79, 0xfffff800
	s_cselect_b32 s59, 0, -1
	s_add_u32 s96, s96, s6
	s_addc_u32 s59, s59, s7
	s_add_u32 s96, s52, s96
	s_addc_u32 s59, s53, s59
	s_add_u32 s96, s96, 0x180
	s_addc_u32 s97, s59, 0
	ds_read_b128 v[140:143], v157
	ds_read_b128 v[144:147], v157 offset:1024
	ds_read_b128 v[148:151], v157 offset:2048
	ds_read_b128 v[160:163], v157 offset:3072
	ds_read_b128 v[164:167], v158
	ds_read_b128 v[168:171], v158 offset:1024
	ds_read_b128 v[172:175], v158 offset:2048
	ds_read_b128 v[176:179], v158 offset:3072
	s_add_u32 vcc_lo, s57, 0x180
	s_addc_u32 vcc_hi, s58, 0
	s_add_u32 s55, s55, s6
	s_addc_u32 s54, s54, s7
	s_add_u32 s55, s52, s55
	s_addc_u32 s54, s53, s54
	s_add_u32 s58, s55, 0x40080
	s_addc_u32 s59, s54, 0
	s_add_i32 s11, s80, s61
	s_add_i32 m0, s10, 0xc000
	s_add_i32 s19, s10, 0xe000
	s_add_i32 s78, s11, 0x2000
	s_cmpk_eq_i32 s6, 0xf00
	s_cselect_b32 s57, s87, s56
	s_cselect_b32 s56, s45, s93
	s_cselect_b32 s95, s9, s95
	s_cselect_b32 s94, s43, s94
	s_cselect_b32 s55, s89, s97
	s_cselect_b32 s54, s88, s96
	ds_read_b128 v[180:183], v159
	ds_read_b128 v[184:187], v159 offset:1024
	ds_read_b128 v[188:191], v159 offset:2048
	ds_read_b128 v[192:195], v159 offset:3072
	ds_read_b128 v[196:199], v159 offset:4096
	ds_read_b128 v[200:203], v159 offset:5120
	ds_read_b128 v[206:209], v159 offset:6144
	ds_read_b128 v[210:213], v159 offset:7168
	s_nop 0
	global_load_lds_dwordx4 v128, s[58:59]
	s_mov_b32 m0, s19
	s_nop 0
	global_load_lds_dwordx4 v132, s[58:59]
	s_waitcnt vmcnt(8)
	s_waitcnt lgkmcnt(0)
	s_barrier
	s_setprio 1
	s_waitcnt lgkmcnt(0)
	v_mfma_f32_16x16x32_bf16 v[124:127], v[140:143], v[180:183], v[124:127]
	v_mfma_f32_16x16x32_bf16 v[120:123], v[148:151], v[180:183], v[120:123]
	v_mfma_f32_16x16x32_bf16 v[116:119], v[140:143], v[188:191], v[116:119]
	v_mfma_f32_16x16x32_bf16 v[112:115], v[148:151], v[188:191], v[112:115]
	v_mfma_f32_16x16x32_bf16 v[100:103], v[140:143], v[196:199], v[100:103]
	v_mfma_f32_16x16x32_bf16 v[96:99], v[148:151], v[196:199], v[96:99]
	v_mfma_f32_16x16x32_bf16 v[84:87], v[140:143], v[206:209], v[84:87]
	v_mfma_f32_16x16x32_bf16 v[80:83], v[148:151], v[206:209], v[80:83]
	v_mfma_f32_16x16x32_bf16 v[124:127], v[144:147], v[184:187], v[124:127]
	v_mfma_f32_16x16x32_bf16 v[120:123], v[160:163], v[184:187], v[120:123]
	v_mfma_f32_16x16x32_bf16 v[116:119], v[144:147], v[192:195], v[116:119]
	v_mfma_f32_16x16x32_bf16 v[112:115], v[160:163], v[192:195], v[112:115]
	v_mfma_f32_16x16x32_bf16 v[100:103], v[144:147], v[200:203], v[100:103]
	v_mfma_f32_16x16x32_bf16 v[96:99], v[160:163], v[200:203], v[96:99]
	v_mfma_f32_16x16x32_bf16 v[84:87], v[144:147], v[210:213], v[84:87]
	v_mfma_f32_16x16x32_bf16 v[80:83], v[160:163], v[210:213], v[80:83]
	s_setprio 0
	s_setprio 1
	v_mfma_f32_16x16x32_bf16 v[108:111], v[164:167], v[180:183], v[108:111]
	v_mfma_f32_16x16x32_bf16 v[104:107], v[172:175], v[180:183], v[104:107]
	v_mfma_f32_16x16x32_bf16 v[92:95], v[164:167], v[188:191], v[92:95]
	v_mfma_f32_16x16x32_bf16 v[88:91], v[172:175], v[188:191], v[88:91]
	v_mfma_f32_16x16x32_bf16 v[76:79], v[164:167], v[196:199], v[76:79]
	v_mfma_f32_16x16x32_bf16 v[72:75], v[172:175], v[196:199], v[72:75]
	v_mfma_f32_16x16x32_bf16 v[68:71], v[164:167], v[206:209], v[68:71]
	v_mfma_f32_16x16x32_bf16 v[64:67], v[172:175], v[206:209], v[64:67]
	v_mfma_f32_16x16x32_bf16 v[108:111], v[168:171], v[184:187], v[108:111]
	v_mfma_f32_16x16x32_bf16 v[104:107], v[176:179], v[184:187], v[104:107]
	v_mfma_f32_16x16x32_bf16 v[92:95], v[168:171], v[192:195], v[92:95]
	v_mfma_f32_16x16x32_bf16 v[88:91], v[176:179], v[192:195], v[88:91]
	v_mfma_f32_16x16x32_bf16 v[76:79], v[168:171], v[200:203], v[76:79]
	v_mfma_f32_16x16x32_bf16 v[72:75], v[176:179], v[200:203], v[72:75]
	v_mfma_f32_16x16x32_bf16 v[68:71], v[168:171], v[210:213], v[68:71]
	v_mfma_f32_16x16x32_bf16 v[64:67], v[176:179], v[210:213], v[64:67]
	s_setprio 0
	s_barrier
	s_mov_b64 s[58:59], s[94:95]
	s_mov_b32 m0, s11
	ds_read_b128 v[180:183], v159 offset:16384
	ds_read_b128 v[184:187], v159 offset:17408
	ds_read_b128 v[188:191], v159 offset:18432
	ds_read_b128 v[192:195], v159 offset:19456
	ds_read_b128 v[196:199], v159 offset:20480
	ds_read_b128 v[200:203], v159 offset:21504
	ds_read_b128 v[206:209], v159 offset:22528
	ds_read_b128 v[210:213], v159 offset:23552
	s_nop 0
	global_load_lds_dwordx4 v130, s[58:59]
	v_lshl_add_u64 v[152:153], s[58:59], 0, v[134:135]
	s_cselect_b32 s59, s91, vcc_hi
	s_cselect_b32 s58, s90, vcc_lo
	s_add_u32 s94, s94, 0x80000
	s_mov_b32 m0, s78
	s_addc_u32 s95, s95, 0
	s_add_i32 s1, s81, s61
	global_load_lds_dwordx4 v[152:153], off
	s_mov_b32 m0, s1
	s_nop 0
	global_load_lds_dwordx4 v130, s[94:95]
	v_lshl_add_u64 v[152:153], s[94:95], 0, v[134:135]
	s_add_i32 m0, s1, 0x2000
	s_mov_b64 s[94:95], s[56:57]
	global_load_lds_dwordx4 v[152:153], off
	s_mov_b32 m0, s10
	s_nop 0
	global_load_lds_dwordx4 v128, s[94:95]
	s_mov_b32 m0, s69
	s_nop 0
	global_load_lds_dwordx4 v132, s[94:95]
	s_waitcnt vmcnt(8)
	s_waitcnt lgkmcnt(0)
	s_barrier
; #define PG8_STAGE(bufoff, gbase, voff) do { const char* _gb = (const char*)(gbase); asm volatile("" : "+s"(_gb));     \
;         _Pragma("unroll") for (int _i = 0; _i < 2; ++_i) \
;         __builtin_amdgcn_global_load_lds((const unsigned*)(_gb + (voff)[_i]), (LAS unsigned*)(lds + (bufoff) + ldsw + _i * 8192), 16, 0, 0); } while (0)
; #define PG8_LDA(dst, b, h) do { _Pragma("unroll") for (int m = 0; m < 4; ++m) _Pragma("unroll") for (int k = 0; k < 2; ++k) dst[m][k] = *(const LAS bf16x8*)(lds + PG8_SA(b, h) + aoff + m * 2048 + k * 1024); } while (0)
; #define PG8_LDB(dst, b, h) do { _Pragma("unroll") for (int n = 0; n < 2; ++n) _Pragma("unroll") for (int k = 0; k < 2; ++k) dst[n][k] = *(const LAS bf16x8*)(lds + PG8_SB(b, h) + boff + n * 2048 + k * 1024); } while (0)
; #define PG8_MMA(ai, bj, At, Bt) do { __builtin_amdgcn_s_setprio(1); _Pragma("unroll") for (int m = 0; m < 4; ++m) _Pragma("unroll") for (int n = 0; n < 2; ++n) _Pragma("unroll") for (int k = 0; k < 2; ++k) \
;         acc[ai][bj][m][n] = __builtin_amdgcn_mfma_f32_16x16x32_bf16(Bt[n][k], At[m][k], acc[ai][bj][m][n], 0, 0, 0); __builtin_amdgcn_s_setprio(0); } while (0)
; #define PG8_WAIT_V(n) asm volatile("s_waitcnt vmcnt(" #n ")" ::: "memory")
; #define PG8_WAIT_L(n) asm volatile("s_waitcnt lgkmcnt(" #n ")" ::: "memory")
; #define PG8_BAR __builtin_amdgcn_s_barrier()
; #define PG8_SCHED __builtin_amdgcn_sched_barrier(0)
; template <class Epi>
; __device__ __forceinline__ void gemm_phase(LAS unsigned char* lds, const int wid, const Gemm g, const Epi& E) {
;     ...
;             PG8_WAIT_V(8); PG8_WAIT_L(0); PG8_BAR; PG8_MMA(1, 0, At, B0); PG8_MMA(1, 1, At, B1); PG8_BAR; PG8_SCHED;
;             PG8_LDB(B0, 1, 0); PG8_LDB(B1, 1, 1); PG8_SCHED; PG8_LDA(At, 1, 0); PG8_STAGE(PG8_SA(0, 1), a2 + hstepA, voffA);
;             PG8_WAIT_V(8); PG8_WAIT_L(0); PG8_BAR; PG8_MMA(0, 0, At, B0); PG8_MMA(0, 1, At, B1); PG8_BAR; PG8_SCHED;
	s_setprio 1
	s_waitcnt lgkmcnt(0)
	v_mfma_f32_16x16x32_bf16 v[60:63], v[140:143], v[180:183], v[60:63]
	v_mfma_f32_16x16x32_bf16 v[56:59], v[148:151], v[180:183], v[56:59]
	v_mfma_f32_16x16x32_bf16 v[52:55], v[140:143], v[188:191], v[52:55]
	v_mfma_f32_16x16x32_bf16 v[48:51], v[148:151], v[188:191], v[48:51]
	v_mfma_f32_16x16x32_bf16 v[36:39], v[140:143], v[196:199], v[36:39]
	v_mfma_f32_16x16x32_bf16 v[32:35], v[148:151], v[196:199], v[32:35]
	v_mfma_f32_16x16x32_bf16 v[20:23], v[140:143], v[206:209], v[20:23]
	v_mfma_f32_16x16x32_bf16 v[16:19], v[148:151], v[206:209], v[16:19]
	v_mfma_f32_16x16x32_bf16 v[60:63], v[144:147], v[184:187], v[60:63]
	v_mfma_f32_16x16x32_bf16 v[56:59], v[160:163], v[184:187], v[56:59]
	v_mfma_f32_16x16x32_bf16 v[52:55], v[144:147], v[192:195], v[52:55]
	v_mfma_f32_16x16x32_bf16 v[48:51], v[160:163], v[192:195], v[48:51]
	v_mfma_f32_16x16x32_bf16 v[36:39], v[144:147], v[200:203], v[36:39]
	v_mfma_f32_16x16x32_bf16 v[32:35], v[160:163], v[200:203], v[32:35]
	v_mfma_f32_16x16x32_bf16 v[20:23], v[144:147], v[210:213], v[20:23]
	v_mfma_f32_16x16x32_bf16 v[16:19], v[160:163], v[210:213], v[16:19]
	s_setprio 0
	s_setprio 1
	v_mfma_f32_16x16x32_bf16 v[44:47], v[164:167], v[180:183], v[44:47]
	v_mfma_f32_16x16x32_bf16 v[40:43], v[172:175], v[180:183], v[40:43]
	v_mfma_f32_16x16x32_bf16 v[28:31], v[164:167], v[188:191], v[28:31]
	v_mfma_f32_16x16x32_bf16 v[24:27], v[172:175], v[188:191], v[24:27]
	v_mfma_f32_16x16x32_bf16 v[12:15], v[164:167], v[196:199], v[12:15]
	v_mfma_f32_16x16x32_bf16 v[8:11], v[172:175], v[196:199], v[8:11]
	v_mfma_f32_16x16x32_bf16 v[4:7], v[164:167], v[206:209], v[4:7]
	v_mfma_f32_16x16x32_bf16 v[0:3], v[172:175], v[206:209], v[0:3]
	v_mfma_f32_16x16x32_bf16 v[44:47], v[168:171], v[184:187], v[44:47]
	v_mfma_f32_16x16x32_bf16 v[40:43], v[176:179], v[184:187], v[40:43]
	v_mfma_f32_16x16x32_bf16 v[28:31], v[168:171], v[192:195], v[28:31]
	v_mfma_f32_16x16x32_bf16 v[24:27], v[176:179], v[192:195], v[24:27]
	v_mfma_f32_16x16x32_bf16 v[12:15], v[168:171], v[200:203], v[12:15]
	v_mfma_f32_16x16x32_bf16 v[8:11], v[176:179], v[200:203], v[8:11]
	v_mfma_f32_16x16x32_bf16 v[4:7], v[168:171], v[210:213], v[4:7]
	v_mfma_f32_16x16x32_bf16 v[0:3], v[176:179], v[210:213], v[0:3]
	s_setprio 0
	s_barrier
	s_add_i32 s1, 0, 0x18000
	v_add_u32_e32 v152, s1, v156
	s_add_i32 s11, 0, 0x1c000
	ds_read_b128 v[140:143], v152
	ds_read_b128 v[144:147], v152 offset:1024
	ds_read_b128 v[148:151], v152 offset:2048
	ds_read_b128 v[160:163], v152 offset:3072
	v_add_u32_e32 v152, s11, v156
	ds_read_b128 v[164:167], v152
	ds_read_b128 v[168:171], v152 offset:1024
	ds_read_b128 v[172:175], v152 offset:2048
	ds_read_b128 v[176:179], v152 offset:3072
	s_add_u32 s56, s56, 0x40000
	s_addc_u32 s57, s57, 0
	s_mov_b32 m0, s70
	ds_read_b128 v[180:183], v159 offset:32768
	ds_read_b128 v[184:187], v159 offset:33792
	ds_read_b128 v[188:191], v159 offset:34816
	ds_read_b128 v[192:195], v159 offset:35840
	ds_read_b128 v[196:199], v159 offset:36864
	ds_read_b128 v[200:203], v159 offset:37888
	ds_read_b128 v[206:209], v159 offset:38912
	ds_read_b128 v[210:213], v159 offset:39936
	s_nop 0
	global_load_lds_dwordx4 v128, s[56:57]
	s_mov_b32 m0, s71
	s_nop 0
	global_load_lds_dwordx4 v132, s[56:57]
	s_waitcnt vmcnt(8)
	s_waitcnt lgkmcnt(0)
	s_barrier
	s_setprio 1
	s_waitcnt lgkmcnt(0)
	v_mfma_f32_16x16x32_bf16 v[124:127], v[140:143], v[180:183], v[124:127]
	v_mfma_f32_16x16x32_bf16 v[120:123], v[148:151], v[180:183], v[120:123]
	v_mfma_f32_16x16x32_bf16 v[116:119], v[140:143], v[188:191], v[116:119]
	v_mfma_f32_16x16x32_bf16 v[112:115], v[148:151], v[188:191], v[112:115]
	v_mfma_f32_16x16x32_bf16 v[100:103], v[140:143], v[196:199], v[100:103]
	v_mfma_f32_16x16x32_bf16 v[96:99], v[148:151], v[196:199], v[96:99]
	v_mfma_f32_16x16x32_bf16 v[84:87], v[140:143], v[206:209], v[84:87]
	v_mfma_f32_16x16x32_bf16 v[80:83], v[148:151], v[206:209], v[80:83]
	v_mfma_f32_16x16x32_bf16 v[124:127], v[144:147], v[184:187], v[124:127]
	v_mfma_f32_16x16x32_bf16 v[120:123], v[160:163], v[184:187], v[120:123]
	v_mfma_f32_16x16x32_bf16 v[116:119], v[144:147], v[192:195], v[116:119]
	v_mfma_f32_16x16x32_bf16 v[112:115], v[160:163], v[192:195], v[112:115]
	v_mfma_f32_16x16x32_bf16 v[100:103], v[144:147], v[200:203], v[100:103]
	v_mfma_f32_16x16x32_bf16 v[96:99], v[160:163], v[200:203], v[96:99]
	v_mfma_f32_16x16x32_bf16 v[84:87], v[144:147], v[210:213], v[84:87]
	v_mfma_f32_16x16x32_bf16 v[80:83], v[160:163], v[210:213], v[80:83]
	s_setprio 0
	s_setprio 1
	v_mfma_f32_16x16x32_bf16 v[108:111], v[164:167], v[180:183], v[108:111]
	v_mfma_f32_16x16x32_bf16 v[104:107], v[172:175], v[180:183], v[104:107]
	v_mfma_f32_16x16x32_bf16 v[92:95], v[164:167], v[188:191], v[92:95]
	v_mfma_f32_16x16x32_bf16 v[88:91], v[172:175], v[188:191], v[88:91]
	v_mfma_f32_16x16x32_bf16 v[76:79], v[164:167], v[196:199], v[76:79]
	v_mfma_f32_16x16x32_bf16 v[72:75], v[172:175], v[196:199], v[72:75]
	v_mfma_f32_16x16x32_bf16 v[68:71], v[164:167], v[206:209], v[68:71]
	v_mfma_f32_16x16x32_bf16 v[64:67], v[172:175], v[206:209], v[64:67]
	v_mfma_f32_16x16x32_bf16 v[108:111], v[168:171], v[184:187], v[108:111]
	v_mfma_f32_16x16x32_bf16 v[104:107], v[176:179], v[184:187], v[104:107]
	v_mfma_f32_16x16x32_bf16 v[92:95], v[168:171], v[192:195], v[92:95]
	v_mfma_f32_16x16x32_bf16 v[88:91], v[176:179], v[192:195], v[88:91]
	v_mfma_f32_16x16x32_bf16 v[76:79], v[168:171], v[200:203], v[76:79]
	v_mfma_f32_16x16x32_bf16 v[72:75], v[176:179], v[200:203], v[72:75]
	v_mfma_f32_16x16x32_bf16 v[68:71], v[168:171], v[210:213], v[68:71]
	v_mfma_f32_16x16x32_bf16 v[64:67], v[176:179], v[210:213], v[64:67]
	s_setprio 0
	s_barrier
; #define PG8_STAGE(bufoff, gbase, voff) do { const char* _gb = (const char*)(gbase); asm volatile("" : "+s"(_gb));     \
;         _Pragma("unroll") for (int _i = 0; _i < 2; ++_i) \
;         __builtin_amdgcn_global_load_lds((const unsigned*)(_gb + (voff)[_i]), (LAS unsigned*)(lds + (bufoff) + ldsw + _i * 8192), 16, 0, 0); } while (0)
; #define PG8_LDA(dst, b, h) do { _Pragma("unroll") for (int m = 0; m < 4; ++m) _Pragma("unroll") for (int k = 0; k < 2; ++k) dst[m][k] = *(const LAS bf16x8*)(lds + PG8_SA(b, h) + aoff + m * 2048 + k * 1024); } while (0)
; #define PG8_MMA(ai, bj, At, Bt) do { __builtin_amdgcn_s_setprio(1); _Pragma("unroll") for (int m = 0; m < 4; ++m) _Pragma("unroll") for (int n = 0; n < 2; ++n) _Pragma("unroll") for (int k = 0; k < 2; ++k) \
;         acc[ai][bj][m][n] = __builtin_amdgcn_mfma_f32_16x16x32_bf16(Bt[n][k], At[m][k], acc[ai][bj][m][n], 0, 0, 0); __builtin_amdgcn_s_setprio(0); } while (0)
; #define PG8_WAIT_V(n) asm volatile("s_waitcnt vmcnt(" #n ")" ::: "memory")
; #define PG8_WAIT_L(n) asm volatile("s_waitcnt lgkmcnt(" #n ")" ::: "memory")
; #define PG8_BAR __builtin_amdgcn_s_barrier()
; #define PG8_SCHED __builtin_amdgcn_sched_barrier(0)
; template <class Epi>
; __device__ __forceinline__ void gemm_phase(LAS unsigned char* lds, const int wid, const Gemm g, const Epi& E) {
;     ...
;             PG8_WAIT_V(8); PG8_WAIT_L(0); PG8_BAR; PG8_MMA(0, 0, At, B0); PG8_MMA(0, 1, At, B1); PG8_BAR; PG8_SCHED;
;             PG8_LDA(At, 1, 1); PG8_STAGE(PG8_SB(1, 0), b3, voffB); PG8_STAGE(PG8_SB(1, 1), b3 + hstepB, voffB); PG8_STAGE(PG8_SA(1, 0), a3, voffA);
;             PG8_WAIT_V(8); PG8_WAIT_L(0); PG8_BAR; PG8_MMA(1, 0, At, B0); PG8_MMA(1, 1, At, B1); PG8_BAR; PG8_SCHED;
;         }
;         if (wr == 0) PG8_BAR;
	s_mov_b64 s[56:57], s[58:59]
	s_add_i32 s1, s1, s61
	ds_read_b128 v[180:183], v159 offset:49152
	ds_read_b128 v[184:187], v159 offset:50176
	ds_read_b128 v[188:191], v159 offset:51200
	ds_read_b128 v[192:195], v159 offset:52224
	ds_read_b128 v[196:199], v159 offset:53248
	ds_read_b128 v[200:203], v159 offset:54272
	ds_read_b128 v[206:209], v159 offset:55296
	ds_read_b128 v[210:213], v159 offset:56320
	s_mov_b32 m0, s1
	s_nop 0
	global_load_lds_dwordx4 v130, s[56:57]
	s_add_i32 m0, s1, 0x2000
	v_lshl_add_u64 v[152:153], s[56:57], 0, v[134:135]
	s_add_u32 s56, s58, 0x80000
	s_addc_u32 s57, s59, 0
	s_add_i32 s1, s11, s61
	global_load_lds_dwordx4 v[152:153], off
	s_mov_b32 m0, s1
	s_nop 0
	global_load_lds_dwordx4 v130, s[56:57]
	s_add_i32 m0, s1, 0x2000
	s_nop 0
	global_load_lds_dwordx4 v134, s[56:57]
	s_mov_b32 m0, s75
	s_nop 0
	global_load_lds_dwordx4 v128, s[54:55]
	s_mov_b32 m0, s76
	s_nop 0
	global_load_lds_dwordx4 v132, s[54:55]
	s_waitcnt vmcnt(8)
	s_waitcnt lgkmcnt(0)
	s_barrier
	s_setprio 1
	s_waitcnt lgkmcnt(0)
	v_mfma_f32_16x16x32_bf16 v[60:63], v[140:143], v[180:183], v[60:63]
	v_mfma_f32_16x16x32_bf16 v[56:59], v[148:151], v[180:183], v[56:59]
	v_mfma_f32_16x16x32_bf16 v[52:55], v[140:143], v[188:191], v[52:55]
	v_mfma_f32_16x16x32_bf16 v[48:51], v[148:151], v[188:191], v[48:51]
	v_mfma_f32_16x16x32_bf16 v[36:39], v[140:143], v[196:199], v[36:39]
	v_mfma_f32_16x16x32_bf16 v[32:35], v[148:151], v[196:199], v[32:35]
	v_mfma_f32_16x16x32_bf16 v[20:23], v[140:143], v[206:209], v[20:23]
	v_mfma_f32_16x16x32_bf16 v[16:19], v[148:151], v[206:209], v[16:19]
	v_mfma_f32_16x16x32_bf16 v[60:63], v[144:147], v[184:187], v[60:63]
	v_mfma_f32_16x16x32_bf16 v[56:59], v[160:163], v[184:187], v[56:59]
	v_mfma_f32_16x16x32_bf16 v[52:55], v[144:147], v[192:195], v[52:55]
	v_mfma_f32_16x16x32_bf16 v[48:51], v[160:163], v[192:195], v[48:51]
	v_mfma_f32_16x16x32_bf16 v[36:39], v[144:147], v[200:203], v[36:39]
	v_mfma_f32_16x16x32_bf16 v[32:35], v[160:163], v[200:203], v[32:35]
	v_mfma_f32_16x16x32_bf16 v[20:23], v[144:147], v[210:213], v[20:23]
	v_mfma_f32_16x16x32_bf16 v[16:19], v[160:163], v[210:213], v[16:19]
	s_setprio 0
	s_setprio 1
	v_mfma_f32_16x16x32_bf16 v[44:47], v[164:167], v[180:183], v[44:47]
	v_mfma_f32_16x16x32_bf16 v[40:43], v[172:175], v[180:183], v[40:43]
	v_mfma_f32_16x16x32_bf16 v[28:31], v[164:167], v[188:191], v[28:31]
	v_mfma_f32_16x16x32_bf16 v[24:27], v[172:175], v[188:191], v[24:27]
	v_mfma_f32_16x16x32_bf16 v[12:15], v[164:167], v[196:199], v[12:15]
	v_mfma_f32_16x16x32_bf16 v[8:11], v[172:175], v[196:199], v[8:11]
	v_mfma_f32_16x16x32_bf16 v[4:7], v[164:167], v[206:209], v[4:7]
	v_mfma_f32_16x16x32_bf16 v[0:3], v[172:175], v[206:209], v[0:3]
	v_mfma_f32_16x16x32_bf16 v[44:47], v[168:171], v[184:187], v[44:47]
	v_mfma_f32_16x16x32_bf16 v[40:43], v[176:179], v[184:187], v[40:43]
	v_mfma_f32_16x16x32_bf16 v[28:31], v[168:171], v[192:195], v[28:31]
	v_mfma_f32_16x16x32_bf16 v[24:27], v[176:179], v[192:195], v[24:27]
	v_mfma_f32_16x16x32_bf16 v[12:15], v[168:171], v[200:203], v[12:15]
	v_mfma_f32_16x16x32_bf16 v[8:11], v[176:179], v[200:203], v[8:11]
	v_mfma_f32_16x16x32_bf16 v[4:7], v[168:171], v[210:213], v[4:7]
	v_mfma_f32_16x16x32_bf16 v[0:3], v[176:179], v[210:213], v[0:3]
	s_setprio 0
	s_barrier
	s_add_u32 s6, s6, 0x100
	s_addc_u32 s7, s7, 0
	s_cmp_gt_u32 s92, 29
	s_cbranch_scc0 .LBB0_952
	s_and_b64 vcc, exec, s[12:13]
	s_cbranch_vccz .LBB0_955
	s_barrier

; #define PG8_STAGE(bufoff, gbase, voff) do { const char* _gb = (const char*)(gbase); asm volatile("" : "+s"(_gb));     \
;         _Pragma("unroll") for (int _i = 0; _i < 2; ++_i) \
;         __builtin_amdgcn_global_load_lds((const unsigned*)(_gb + (voff)[_i]), (LAS unsigned*)(lds + (bufoff) + ldsw + _i * 8192), 16, 0, 0); } while (0)
; #define PG8_WAIT_V(n) asm volatile("s_waitcnt vmcnt(" #n ")" ::: "memory")
; #define PG8_BAR __builtin_amdgcn_s_barrier()
; template <class Epi>
; __device__ __forceinline__ void gemm_phase(LAS unsigned char* lds, const int wid, const Gemm g, const Epi& E) {
;     ...
;     const char* cA = PG8_UA(cur); const char* cB = PG8_UB(cur);
;     PG8_STAGE(PG8_SB(0, 0), PG8_BP(cB, 0), voffB); PG8_STAGE(PG8_SB(0, 1), PG8_BP(cB, 0) + hstepB, voffB); PG8_STAGE(PG8_SA(0, 0), PG8_AP(cA, 0), voffA); PG8_STAGE(PG8_SA(0, 1), PG8_AP(cA, 0) + hstepA, voffA);
;     if (wr == 1) PG8_BAR;
;     PG8_WAIT_V(2); PG8_BAR;
;     PG8_STAGE(PG8_SB(1, 0), PG8_BP(cB, 1), voffB); PG8_STAGE(PG8_SA(1, 0), PG8_AP(cA, 1), voffA); PG8_STAGE(PG8_SB(1, 1), PG8_BP(cB, 1) + hstepB, voffB);
;     PG8_WAIT_V(6); PG8_BAR;
;     for (;;) {
;         const bool has_next = S.next(ui + 1, nxt);
;         const char* nA = has_next ? PG8_UA(nxt) : cA; const char* nB = has_next ? PG8_UB(nxt) : cB;
;         for (int t = 0; t < nt; t += 2) {
.LBB0_1113:
	s_lshl_b32 s1, s33, 5
	s_and_b32 s58, s1, 0x60
	s_lshl_b32 s57, s14, 6
	s_lshl_b32 s0, s14, 13
	s_lshr_b32 s1, s58, 3
	s_cmp_lt_u32 s33, 4
	s_cselect_b64 s[14:15], -1, 0
	s_add_u32 s59, s18, 0x15800000
	s_addc_u32 s60, s19, 0
	s_add_u32 s2, s40, 0x80
	s_addc_u32 s3, s41, 0
	s_waitcnt vmcnt(2)
	s_barrier
	s_add_i32 m0, s52, 0x18000
	s_nop 0
	global_load_lds_dwordx4 v138, s[2:3]
	s_add_i32 m0, s52, 0x1a000
	v_lshl_add_u64 v[0:1], s[2:3], 0, v[142:143]
	s_add_u32 s2, s42, 0x80
	s_addc_u32 s3, s43, 0
	s_add_i32 s61, s52, 0x8000
	global_load_lds_dwordx4 v[0:1], off
	s_mov_b32 m0, s61
	s_add_i32 s62, s52, 0xa000
	global_load_lds_dwordx4 v136, s[2:3]
	v_lshl_add_u64 v[0:1], s[2:3], 0, v[140:141]
	s_add_u32 s2, s40, 0x18080
	s_mov_b32 m0, s62
	s_addc_u32 s3, s41, 0
	global_load_lds_dwordx4 v[0:1], off
	s_add_i32 m0, s52, 0x1c000
	s_nop 0
	global_load_lds_dwordx4 v138, s[2:3]
	s_add_i32 m0, s52, 0x1e000
	v_lshlrev_b32_e32 v3, 6, v161
	global_load_lds_dwordx4 v142, s[2:3]
	v_ashrrev_i32_e32 v0, 6, v161
	v_and_b32_e32 v1, 48, v161
	v_lshl_add_u32 v2, v0, 10, s0
	s_movk_i32 s0, 0x3c0
	v_and_or_b32 v1, v3, s0, v1
	v_lshlrev_b32_e32 v3, 2, v161
	s_waitcnt lgkmcnt(0)
	s_ashr_i32 s63, s46, 31
	v_and_b32_e32 v3, 32, v3
	v_add_lshl_u32 v0, v0, s1, 10
	s_waitcnt vmcnt(6)
	s_add_u32 s18, s18, 0x11800000
	v_bitop3_b32 v2, v1, v2, v3 bitop3:0xde
	v_bitop3_b32 v162, v1, v0, v3 bitop3:0xde
	s_addc_u32 s19, s19, 0
	s_add_i32 s64, 0, 0x10000
	s_add_i32 s65, 0, 0x14000
	s_mov_b64 s[16:17], 0x80
	v_mov_b64_e32 v[144:145], 0x400
	v_mov_b64_e32 v[146:147], 0x3ff
	v_add_u32_e32 v163, s64, v162
	v_add_u32_e32 v164, s65, v162
	v_add_u32_e32 v165, 0, v2
	s_movk_i32 s66, 0xa0
	s_brev_b32 s67, 64
	s_mov_b64 s[20:21], 0x24000
	s_mov_b64 s[24:25], 0x28000
	s_mov_b64 s[26:27], 0x2c000
	v_mov_b32_e32 v166, 0x3f1b4598
	s_barrier
	s_branch .LBB0_1116

; #define PG8_STAGE(bufoff, gbase, voff) do { const char* _gb = (const char*)(gbase); asm volatile("" : "+s"(_gb));     \
;         _Pragma("unroll") for (int _i = 0; _i < 2; ++_i) \
;         __builtin_amdgcn_global_load_lds((const unsigned*)(_gb + (voff)[_i]), (LAS unsigned*)(lds + (bufoff) + ldsw + _i * 8192), 16, 0, 0); } while (0)
; #define PG8_LDA(dst, b, h) do { _Pragma("unroll") for (int m = 0; m < 4; ++m) _Pragma("unroll") for (int k = 0; k < 2; ++k) dst[m][k] = *(const LAS bf16x8*)(lds + PG8_SA(b, h) + aoff + m * 2048 + k * 1024); } while (0)
; #define PG8_LDB(dst, b, h) do { _Pragma("unroll") for (int n = 0; n < 2; ++n) _Pragma("unroll") for (int k = 0; k < 2; ++k) dst[n][k] = *(const LAS bf16x8*)(lds + PG8_SB(b, h) + boff + n * 2048 + k * 1024); } while (0)
; #define PG8_MMA(ai, bj, At, Bt) do { __builtin_amdgcn_s_setprio(1); _Pragma("unroll") for (int m = 0; m < 4; ++m) _Pragma("unroll") for (int n = 0; n < 2; ++n) _Pragma("unroll") for (int k = 0; k < 2; ++k) \
;         acc[ai][bj][m][n] = __builtin_amdgcn_mfma_f32_16x16x32_bf16(Bt[n][k], At[m][k], acc[ai][bj][m][n], 0, 0, 0); __builtin_amdgcn_s_setprio(0); } while (0)
; #define PG8_WAIT_V(n) asm volatile("s_waitcnt vmcnt(" #n ")" ::: "memory")
; #define PG8_WAIT_L(n) asm volatile("s_waitcnt lgkmcnt(" #n ")" ::: "memory")
; #define PG8_BAR __builtin_amdgcn_s_barrier()
; #define PG8_SCHED __builtin_amdgcn_sched_barrier(0)
; template <class Epi>
; __device__ __forceinline__ void gemm_phase(LAS unsigned char* lds, const int wid, const Gemm g, const Epi& E) {
;     ...
;             PG8_LDB(B0, 0, 0); PG8_LDB(B1, 0, 1); PG8_SCHED; PG8_LDA(At, 0, 0); PG8_STAGE(PG8_SA(1, 1), a1 + hstepA, voffA);
;             PG8_WAIT_V(8); PG8_WAIT_L(0); PG8_BAR; PG8_MMA(0, 0, At, B0); PG8_MMA(0, 1, At, B1); PG8_BAR; PG8_SCHED;
;             PG8_LDA(At, 0, 1); PG8_STAGE(PG8_SB(0, 0), b2, voffB); PG8_STAGE(PG8_SB(0, 1), b2 + hstepB, voffB); PG8_STAGE(PG8_SA(0, 0), a2, voffA);
;             PG8_WAIT_V(8); PG8_WAIT_L(0); PG8_BAR; PG8_MMA(1, 0, At, B0); PG8_MMA(1, 1, At, B1); PG8_BAR; PG8_SCHED;
.LBB0_1125:
	ds_read_b128 v[104:107], v163
	ds_read_b128 v[108:111], v163 offset:1024
	ds_read_b128 v[148:151], v163 offset:2048
	ds_read_b128 v[152:155], v163 offset:3072
	ds_read_b128 v[156:159], v164
	ds_read_b128 v[168:171], v164 offset:1024
	ds_read_b128 v[172:175], v164 offset:2048
	ds_read_b128 v[176:179], v164 offset:3072
	s_add_u32 s0, s4, 0xfffe0080
	s_addc_u32 s1, s5, -1
	s_add_u32 s40, s74, 0xffffff80
	s_addc_u32 s41, s75, -1
	s_add_u32 s44, s4, 0xfffe0100
	s_addc_u32 s45, s5, -1
	s_add_i32 s80, s64, s47
	s_add_i32 m0, s52, 0xc000
	s_add_i32 s77, s52, 0xe000
	s_add_i32 s81, s80, 0x2000
	s_cmp_eq_u32 s76, 2
	s_cselect_b32 s43, s29, s1
	s_cselect_b32 s42, s39, s0
	s_cselect_b32 s79, s31, s41
	s_cselect_b32 s78, s30, s40
	s_cselect_b32 s41, s71, s45
	s_cselect_b32 s40, s70, s44
	s_mov_b64 s[44:45], s[4:5]
	ds_read_b128 v[180:183], v165
	ds_read_b128 v[184:187], v165 offset:1024
	ds_read_b128 v[188:191], v165 offset:2048
	ds_read_b128 v[192:195], v165 offset:3072
	ds_read_b128 v[196:199], v165 offset:4096
	ds_read_b128 v[200:203], v165 offset:5120
	ds_read_b128 v[206:209], v165 offset:6144
	ds_read_b128 v[210:213], v165 offset:7168
	s_nop 0
	global_load_lds_dwordx4 v136, s[44:45]
	s_mov_b32 m0, s77
	s_nop 0
	global_load_lds_dwordx4 v140, s[44:45]
	s_waitcnt vmcnt(8)
	s_waitcnt lgkmcnt(0)
	s_barrier
	s_setprio 1
	s_waitcnt lgkmcnt(0)
	v_mfma_f32_16x16x32_bf16 v[132:135], v[104:107], v[180:183], v[132:135]
	v_mfma_f32_16x16x32_bf16 v[128:131], v[148:151], v[180:183], v[128:131]
	v_mfma_f32_16x16x32_bf16 v[124:127], v[104:107], v[188:191], v[124:127]
	v_mfma_f32_16x16x32_bf16 v[120:123], v[148:151], v[188:191], v[120:123]
	v_mfma_f32_16x16x32_bf16 v[116:119], v[104:107], v[196:199], v[116:119]
	v_mfma_f32_16x16x32_bf16 v[112:115], v[148:151], v[196:199], v[112:115]
	v_mfma_f32_16x16x32_bf16 v[100:103], v[104:107], v[206:209], v[100:103]
	v_mfma_f32_16x16x32_bf16 v[96:99], v[148:151], v[206:209], v[96:99]
	v_mfma_f32_16x16x32_bf16 v[132:135], v[108:111], v[184:187], v[132:135]
	v_mfma_f32_16x16x32_bf16 v[128:131], v[152:155], v[184:187], v[128:131]
	v_mfma_f32_16x16x32_bf16 v[124:127], v[108:111], v[192:195], v[124:127]
	v_mfma_f32_16x16x32_bf16 v[120:123], v[152:155], v[192:195], v[120:123]
	v_mfma_f32_16x16x32_bf16 v[116:119], v[108:111], v[200:203], v[116:119]
	v_mfma_f32_16x16x32_bf16 v[112:115], v[152:155], v[200:203], v[112:115]
	v_mfma_f32_16x16x32_bf16 v[100:103], v[108:111], v[210:213], v[100:103]
	v_mfma_f32_16x16x32_bf16 v[96:99], v[152:155], v[210:213], v[96:99]
	s_setprio 0
	s_setprio 1
	v_mfma_f32_16x16x32_bf16 v[60:63], v[156:159], v[180:183], v[60:63]
	v_mfma_f32_16x16x32_bf16 v[56:59], v[172:175], v[180:183], v[56:59]
	v_mfma_f32_16x16x32_bf16 v[52:55], v[156:159], v[188:191], v[52:55]
	v_mfma_f32_16x16x32_bf16 v[48:51], v[172:175], v[188:191], v[48:51]
	v_mfma_f32_16x16x32_bf16 v[44:47], v[156:159], v[196:199], v[44:47]
	v_mfma_f32_16x16x32_bf16 v[40:43], v[172:175], v[196:199], v[40:43]
	v_mfma_f32_16x16x32_bf16 v[36:39], v[156:159], v[206:209], v[36:39]
	v_mfma_f32_16x16x32_bf16 v[32:35], v[172:175], v[206:209], v[32:35]
	v_mfma_f32_16x16x32_bf16 v[60:63], v[168:171], v[184:187], v[60:63]
	v_mfma_f32_16x16x32_bf16 v[56:59], v[176:179], v[184:187], v[56:59]
	v_mfma_f32_16x16x32_bf16 v[52:55], v[168:171], v[192:195], v[52:55]
	v_mfma_f32_16x16x32_bf16 v[48:51], v[176:179], v[192:195], v[48:51]
	v_mfma_f32_16x16x32_bf16 v[44:47], v[168:171], v[200:203], v[44:47]
	v_mfma_f32_16x16x32_bf16 v[40:43], v[176:179], v[200:203], v[40:43]
	v_mfma_f32_16x16x32_bf16 v[36:39], v[168:171], v[210:213], v[36:39]
	v_mfma_f32_16x16x32_bf16 v[32:35], v[176:179], v[210:213], v[32:35]
	s_setprio 0
	s_barrier
	s_mov_b64 s[44:45], s[78:79]
	s_mov_b32 m0, s80
	ds_read_b128 v[180:183], v165 offset:16384
	ds_read_b128 v[184:187], v165 offset:17408
	ds_read_b128 v[188:191], v165 offset:18432
	ds_read_b128 v[192:195], v165 offset:19456
	ds_read_b128 v[196:199], v165 offset:20480
	ds_read_b128 v[200:203], v165 offset:21504
	ds_read_b128 v[206:209], v165 offset:22528
	ds_read_b128 v[210:213], v165 offset:23552
	s_nop 0
	global_load_lds_dwordx4 v138, s[44:45]
	v_lshl_add_u64 v[204:205], s[44:45], 0, v[142:143]
	s_cselect_b32 s45, s73, s75
	s_cselect_b32 s44, s72, s74
	s_add_u32 s78, s78, 0x18000
	s_mov_b32 m0, s81
	s_addc_u32 s79, s79, 0
	s_add_i32 s0, s65, s47
	global_load_lds_dwordx4 v[204:205], off
	s_mov_b32 m0, s0
	s_nop 0
	global_load_lds_dwordx4 v138, s[78:79]
	v_lshl_add_u64 v[204:205], s[78:79], 0, v[142:143]
	s_add_i32 m0, s0, 0x2000
	s_mov_b64 s[78:79], s[42:43]
	global_load_lds_dwordx4 v[204:205], off
	s_mov_b32 m0, s52
	s_nop 0
	global_load_lds_dwordx4 v136, s[78:79]
	s_mov_b32 m0, s53
	s_nop 0
	global_load_lds_dwordx4 v140, s[78:79]
	s_waitcnt vmcnt(8)
	s_waitcnt lgkmcnt(0)
	s_barrier
; #define PG8_STAGE(bufoff, gbase, voff) do { const char* _gb = (const char*)(gbase); asm volatile("" : "+s"(_gb));     \
;         _Pragma("unroll") for (int _i = 0; _i < 2; ++_i) \
;         __builtin_amdgcn_global_load_lds((const unsigned*)(_gb + (voff)[_i]), (LAS unsigned*)(lds + (bufoff) + ldsw + _i * 8192), 16, 0, 0); } while (0)
; #define PG8_LDA(dst, b, h) do { _Pragma("unroll") for (int m = 0; m < 4; ++m) _Pragma("unroll") for (int k = 0; k < 2; ++k) dst[m][k] = *(const LAS bf16x8*)(lds + PG8_SA(b, h) + aoff + m * 2048 + k * 1024); } while (0)
; #define PG8_LDB(dst, b, h) do { _Pragma("unroll") for (int n = 0; n < 2; ++n) _Pragma("unroll") for (int k = 0; k < 2; ++k) dst[n][k] = *(const LAS bf16x8*)(lds + PG8_SB(b, h) + boff + n * 2048 + k * 1024); } while (0)
; #define PG8_MMA(ai, bj, At, Bt) do { __builtin_amdgcn_s_setprio(1); _Pragma("unroll") for (int m = 0; m < 4; ++m) _Pragma("unroll") for (int n = 0; n < 2; ++n) _Pragma("unroll") for (int k = 0; k < 2; ++k) \
;         acc[ai][bj][m][n] = __builtin_amdgcn_mfma_f32_16x16x32_bf16(Bt[n][k], At[m][k], acc[ai][bj][m][n], 0, 0, 0); __builtin_amdgcn_s_setprio(0); } while (0)
; #define PG8_WAIT_V(n) asm volatile("s_waitcnt vmcnt(" #n ")" ::: "memory")
; #define PG8_WAIT_L(n) asm volatile("s_waitcnt lgkmcnt(" #n ")" ::: "memory")
; #define PG8_BAR __builtin_amdgcn_s_barrier()
; #define PG8_SCHED __builtin_amdgcn_sched_barrier(0)
; template <class Epi>
; __device__ __forceinline__ void gemm_phase(LAS unsigned char* lds, const int wid, const Gemm g, const Epi& E) {
;     ...
;             PG8_WAIT_V(8); PG8_WAIT_L(0); PG8_BAR; PG8_MMA(1, 0, At, B0); PG8_MMA(1, 1, At, B1); PG8_BAR; PG8_SCHED;
;             PG8_LDB(B0, 1, 0); PG8_LDB(B1, 1, 1); PG8_SCHED; PG8_LDA(At, 1, 0); PG8_STAGE(PG8_SA(0, 1), a2 + hstepA, voffA);
;             PG8_WAIT_V(8); PG8_WAIT_L(0); PG8_BAR; PG8_MMA(0, 0, At, B0); PG8_MMA(0, 1, At, B1); PG8_BAR; PG8_SCHED;
	s_setprio 1
	s_waitcnt lgkmcnt(0)
	v_mfma_f32_16x16x32_bf16 v[92:95], v[104:107], v[180:183], v[92:95]
	v_mfma_f32_16x16x32_bf16 v[88:91], v[148:151], v[180:183], v[88:91]
	v_mfma_f32_16x16x32_bf16 v[84:87], v[104:107], v[188:191], v[84:87]
	v_mfma_f32_16x16x32_bf16 v[80:83], v[148:151], v[188:191], v[80:83]
	v_mfma_f32_16x16x32_bf16 v[76:79], v[104:107], v[196:199], v[76:79]
	v_mfma_f32_16x16x32_bf16 v[72:75], v[148:151], v[196:199], v[72:75]
	v_mfma_f32_16x16x32_bf16 v[68:71], v[104:107], v[206:209], v[68:71]
	v_mfma_f32_16x16x32_bf16 v[64:67], v[148:151], v[206:209], v[64:67]
	v_mfma_f32_16x16x32_bf16 v[92:95], v[108:111], v[184:187], v[92:95]
	v_mfma_f32_16x16x32_bf16 v[88:91], v[152:155], v[184:187], v[88:91]
	v_mfma_f32_16x16x32_bf16 v[84:87], v[108:111], v[192:195], v[84:87]
	v_mfma_f32_16x16x32_bf16 v[80:83], v[152:155], v[192:195], v[80:83]
	v_mfma_f32_16x16x32_bf16 v[76:79], v[108:111], v[200:203], v[76:79]
	v_mfma_f32_16x16x32_bf16 v[72:75], v[152:155], v[200:203], v[72:75]
	v_mfma_f32_16x16x32_bf16 v[68:71], v[108:111], v[210:213], v[68:71]
	v_mfma_f32_16x16x32_bf16 v[64:67], v[152:155], v[210:213], v[64:67]
	s_setprio 0
	s_setprio 1
	v_mfma_f32_16x16x32_bf16 v[28:31], v[156:159], v[180:183], v[28:31]
	v_mfma_f32_16x16x32_bf16 v[24:27], v[172:175], v[180:183], v[24:27]
	v_mfma_f32_16x16x32_bf16 v[20:23], v[156:159], v[188:191], v[20:23]
	v_mfma_f32_16x16x32_bf16 v[16:19], v[172:175], v[188:191], v[16:19]
	v_mfma_f32_16x16x32_bf16 v[12:15], v[156:159], v[196:199], v[12:15]
	v_mfma_f32_16x16x32_bf16 v[8:11], v[172:175], v[196:199], v[8:11]
	v_mfma_f32_16x16x32_bf16 v[4:7], v[156:159], v[206:209], v[4:7]
	v_mfma_f32_16x16x32_bf16 v[0:3], v[172:175], v[206:209], v[0:3]
	v_mfma_f32_16x16x32_bf16 v[28:31], v[168:171], v[184:187], v[28:31]
	v_mfma_f32_16x16x32_bf16 v[24:27], v[176:179], v[184:187], v[24:27]
	v_mfma_f32_16x16x32_bf16 v[20:23], v[168:171], v[192:195], v[20:23]
	v_mfma_f32_16x16x32_bf16 v[16:19], v[176:179], v[192:195], v[16:19]
	v_mfma_f32_16x16x32_bf16 v[12:15], v[168:171], v[200:203], v[12:15]
	v_mfma_f32_16x16x32_bf16 v[8:11], v[176:179], v[200:203], v[8:11]
	v_mfma_f32_16x16x32_bf16 v[4:7], v[168:171], v[210:213], v[4:7]
	v_mfma_f32_16x16x32_bf16 v[0:3], v[176:179], v[210:213], v[0:3]
	s_setprio 0
	s_barrier
	s_add_i32 s0, 0, 0x18000
	s_add_i32 s1, 0, 0x1c000
	v_add_u32_e32 v152, s0, v162
	v_add_u32_e32 v167, s1, v162
	ds_read_b128 v[104:107], v152
	ds_read_b128 v[108:111], v152 offset:1024
	ds_read_b128 v[148:151], v152 offset:2048
	ds_read_b128 v[152:155], v152 offset:3072
	ds_read_b128 v[156:159], v167
	ds_read_b128 v[168:171], v167 offset:1024
	ds_read_b128 v[172:175], v167 offset:2048
	ds_read_b128 v[176:179], v167 offset:3072
	s_add_u32 s42, s42, 0x20000
	s_addc_u32 s43, s43, 0
	s_mov_b32 m0, s54
	ds_read_b128 v[180:183], v165 offset:32768
	ds_read_b128 v[184:187], v165 offset:33792
	ds_read_b128 v[188:191], v165 offset:34816
	ds_read_b128 v[192:195], v165 offset:35840
	ds_read_b128 v[196:199], v165 offset:36864
	ds_read_b128 v[200:203], v165 offset:37888
	ds_read_b128 v[206:209], v165 offset:38912
	ds_read_b128 v[210:213], v165 offset:39936
	s_nop 0
	global_load_lds_dwordx4 v136, s[42:43]
	s_mov_b32 m0, s55
	s_nop 0
	global_load_lds_dwordx4 v140, s[42:43]
	s_waitcnt vmcnt(8)
	s_waitcnt lgkmcnt(0)
	s_barrier
	s_setprio 1
	s_waitcnt lgkmcnt(0)
	v_mfma_f32_16x16x32_bf16 v[132:135], v[104:107], v[180:183], v[132:135]
	v_mfma_f32_16x16x32_bf16 v[128:131], v[148:151], v[180:183], v[128:131]
	v_mfma_f32_16x16x32_bf16 v[124:127], v[104:107], v[188:191], v[124:127]
	v_mfma_f32_16x16x32_bf16 v[120:123], v[148:151], v[188:191], v[120:123]
	v_mfma_f32_16x16x32_bf16 v[116:119], v[104:107], v[196:199], v[116:119]
	v_mfma_f32_16x16x32_bf16 v[112:115], v[148:151], v[196:199], v[112:115]
	v_mfma_f32_16x16x32_bf16 v[100:103], v[104:107], v[206:209], v[100:103]
	v_mfma_f32_16x16x32_bf16 v[96:99], v[148:151], v[206:209], v[96:99]
	v_mfma_f32_16x16x32_bf16 v[132:135], v[108:111], v[184:187], v[132:135]
	v_mfma_f32_16x16x32_bf16 v[128:131], v[152:155], v[184:187], v[128:131]
	v_mfma_f32_16x16x32_bf16 v[124:127], v[108:111], v[192:195], v[124:127]
	v_mfma_f32_16x16x32_bf16 v[120:123], v[152:155], v[192:195], v[120:123]
	v_mfma_f32_16x16x32_bf16 v[116:119], v[108:111], v[200:203], v[116:119]
	v_mfma_f32_16x16x32_bf16 v[112:115], v[152:155], v[200:203], v[112:115]
	v_mfma_f32_16x16x32_bf16 v[100:103], v[108:111], v[210:213], v[100:103]
	v_mfma_f32_16x16x32_bf16 v[96:99], v[152:155], v[210:213], v[96:99]
	s_setprio 0
	s_setprio 1
	v_mfma_f32_16x16x32_bf16 v[60:63], v[156:159], v[180:183], v[60:63]
	v_mfma_f32_16x16x32_bf16 v[56:59], v[172:175], v[180:183], v[56:59]
	v_mfma_f32_16x16x32_bf16 v[52:55], v[156:159], v[188:191], v[52:55]
	v_mfma_f32_16x16x32_bf16 v[48:51], v[172:175], v[188:191], v[48:51]
	v_mfma_f32_16x16x32_bf16 v[44:47], v[156:159], v[196:199], v[44:47]
	v_mfma_f32_16x16x32_bf16 v[40:43], v[172:175], v[196:199], v[40:43]
	v_mfma_f32_16x16x32_bf16 v[36:39], v[156:159], v[206:209], v[36:39]
	v_mfma_f32_16x16x32_bf16 v[32:35], v[172:175], v[206:209], v[32:35]
	v_mfma_f32_16x16x32_bf16 v[60:63], v[168:171], v[184:187], v[60:63]
	v_mfma_f32_16x16x32_bf16 v[56:59], v[176:179], v[184:187], v[56:59]
	v_mfma_f32_16x16x32_bf16 v[52:55], v[168:171], v[192:195], v[52:55]
	v_mfma_f32_16x16x32_bf16 v[48:51], v[176:179], v[192:195], v[48:51]
	v_mfma_f32_16x16x32_bf16 v[44:47], v[168:171], v[200:203], v[44:47]
	v_mfma_f32_16x16x32_bf16 v[40:43], v[176:179], v[200:203], v[40:43]
	v_mfma_f32_16x16x32_bf16 v[36:39], v[168:171], v[210:213], v[36:39]
	v_mfma_f32_16x16x32_bf16 v[32:35], v[176:179], v[210:213], v[32:35]
	s_setprio 0
	s_barrier
; #define PG8_STAGE(bufoff, gbase, voff) do { const char* _gb = (const char*)(gbase); asm volatile("" : "+s"(_gb));     \
;         _Pragma("unroll") for (int _i = 0; _i < 2; ++_i) \
;         __builtin_amdgcn_global_load_lds((const unsigned*)(_gb + (voff)[_i]), (LAS unsigned*)(lds + (bufoff) + ldsw + _i * 8192), 16, 0, 0); } while (0)
; #define PG8_LDA(dst, b, h) do { _Pragma("unroll") for (int m = 0; m < 4; ++m) _Pragma("unroll") for (int k = 0; k < 2; ++k) dst[m][k] = *(const LAS bf16x8*)(lds + PG8_SA(b, h) + aoff + m * 2048 + k * 1024); } while (0)
; #define PG8_MMA(ai, bj, At, Bt) do { __builtin_amdgcn_s_setprio(1); _Pragma("unroll") for (int m = 0; m < 4; ++m) _Pragma("unroll") for (int n = 0; n < 2; ++n) _Pragma("unroll") for (int k = 0; k < 2; ++k) \
;         acc[ai][bj][m][n] = __builtin_amdgcn_mfma_f32_16x16x32_bf16(Bt[n][k], At[m][k], acc[ai][bj][m][n], 0, 0, 0); __builtin_amdgcn_s_setprio(0); } while (0)
; #define PG8_WAIT_V(n) asm volatile("s_waitcnt vmcnt(" #n ")" ::: "memory")
; #define PG8_WAIT_L(n) asm volatile("s_waitcnt lgkmcnt(" #n ")" ::: "memory")
; #define PG8_BAR __builtin_amdgcn_s_barrier()
; #define PG8_SCHED __builtin_amdgcn_sched_barrier(0)
; template <class Epi>
; __device__ __forceinline__ void gemm_phase(LAS unsigned char* lds, const int wid, const Gemm g, const Epi& E) {
;     ...
;             PG8_WAIT_V(8); PG8_WAIT_L(0); PG8_BAR; PG8_MMA(0, 0, At, B0); PG8_MMA(0, 1, At, B1); PG8_BAR; PG8_SCHED;
;             PG8_LDA(At, 1, 1); PG8_STAGE(PG8_SB(1, 0), b3, voffB); PG8_STAGE(PG8_SB(1, 1), b3 + hstepB, voffB); PG8_STAGE(PG8_SA(1, 0), a3, voffA);
;             PG8_WAIT_V(8); PG8_WAIT_L(0); PG8_BAR; PG8_MMA(1, 0, At, B0); PG8_MMA(1, 1, At, B1); PG8_BAR; PG8_SCHED;
;         }
;         if (wr == 0) PG8_BAR;
	s_mov_b64 s[42:43], s[44:45]
	s_add_i32 s0, s0, s47
	ds_read_b128 v[180:183], v165 offset:49152
	ds_read_b128 v[184:187], v165 offset:50176
	ds_read_b128 v[188:191], v165 offset:51200
	ds_read_b128 v[192:195], v165 offset:52224
	ds_read_b128 v[196:199], v165 offset:53248
	ds_read_b128 v[200:203], v165 offset:54272
	ds_read_b128 v[206:209], v165 offset:55296
	ds_read_b128 v[210:213], v165 offset:56320
	s_mov_b32 m0, s0
	s_nop 0
	global_load_lds_dwordx4 v138, s[42:43]
	s_add_i32 m0, s0, 0x2000
	v_lshl_add_u64 v[204:205], s[42:43], 0, v[142:143]
	s_add_u32 s42, s44, 0x18000
	s_addc_u32 s43, s45, 0
	s_add_i32 s0, s1, s47
	global_load_lds_dwordx4 v[204:205], off
	s_mov_b32 m0, s0
	s_nop 0
	global_load_lds_dwordx4 v138, s[42:43]
	s_add_i32 m0, s0, 0x2000
	s_nop 0
	global_load_lds_dwordx4 v142, s[42:43]
	s_mov_b32 m0, s61
	s_nop 0
	global_load_lds_dwordx4 v136, s[40:41]
	s_mov_b32 m0, s62
	s_nop 0
	global_load_lds_dwordx4 v140, s[40:41]
	s_waitcnt vmcnt(8)
	s_waitcnt lgkmcnt(0)
	s_barrier
	s_setprio 1
	s_waitcnt lgkmcnt(0)
	v_mfma_f32_16x16x32_bf16 v[92:95], v[104:107], v[180:183], v[92:95]
	v_mfma_f32_16x16x32_bf16 v[88:91], v[148:151], v[180:183], v[88:91]
	v_mfma_f32_16x16x32_bf16 v[84:87], v[104:107], v[188:191], v[84:87]
	v_mfma_f32_16x16x32_bf16 v[80:83], v[148:151], v[188:191], v[80:83]
	v_mfma_f32_16x16x32_bf16 v[76:79], v[104:107], v[196:199], v[76:79]
	v_mfma_f32_16x16x32_bf16 v[72:75], v[148:151], v[196:199], v[72:75]
	v_mfma_f32_16x16x32_bf16 v[68:71], v[104:107], v[206:209], v[68:71]
	v_mfma_f32_16x16x32_bf16 v[64:67], v[148:151], v[206:209], v[64:67]
	v_mfma_f32_16x16x32_bf16 v[92:95], v[108:111], v[184:187], v[92:95]
	v_mfma_f32_16x16x32_bf16 v[88:91], v[152:155], v[184:187], v[88:91]
	v_mfma_f32_16x16x32_bf16 v[84:87], v[108:111], v[192:195], v[84:87]
	v_mfma_f32_16x16x32_bf16 v[80:83], v[152:155], v[192:195], v[80:83]
	v_mfma_f32_16x16x32_bf16 v[76:79], v[108:111], v[200:203], v[76:79]
	v_mfma_f32_16x16x32_bf16 v[72:75], v[152:155], v[200:203], v[72:75]
	v_mfma_f32_16x16x32_bf16 v[68:71], v[108:111], v[210:213], v[68:71]
	v_mfma_f32_16x16x32_bf16 v[64:67], v[152:155], v[210:213], v[64:67]
	s_setprio 0
	s_setprio 1
	v_mfma_f32_16x16x32_bf16 v[28:31], v[156:159], v[180:183], v[28:31]
	v_mfma_f32_16x16x32_bf16 v[24:27], v[172:175], v[180:183], v[24:27]
	v_mfma_f32_16x16x32_bf16 v[20:23], v[156:159], v[188:191], v[20:23]
	v_mfma_f32_16x16x32_bf16 v[16:19], v[172:175], v[188:191], v[16:19]
	v_mfma_f32_16x16x32_bf16 v[12:15], v[156:159], v[196:199], v[12:15]
	v_mfma_f32_16x16x32_bf16 v[8:11], v[172:175], v[196:199], v[8:11]
	v_mfma_f32_16x16x32_bf16 v[4:7], v[156:159], v[206:209], v[4:7]
	v_mfma_f32_16x16x32_bf16 v[0:3], v[172:175], v[206:209], v[0:3]
	v_mfma_f32_16x16x32_bf16 v[28:31], v[168:171], v[184:187], v[28:31]
	v_mfma_f32_16x16x32_bf16 v[24:27], v[176:179], v[184:187], v[24:27]
	v_mfma_f32_16x16x32_bf16 v[20:23], v[168:171], v[192:195], v[20:23]
	v_mfma_f32_16x16x32_bf16 v[16:19], v[176:179], v[192:195], v[16:19]
	v_mfma_f32_16x16x32_bf16 v[12:15], v[168:171], v[200:203], v[12:15]
	v_mfma_f32_16x16x32_bf16 v[8:11], v[176:179], v[200:203], v[8:11]
	v_mfma_f32_16x16x32_bf16 v[4:7], v[168:171], v[210:213], v[4:7]
	v_mfma_f32_16x16x32_bf16 v[0:3], v[176:179], v[210:213], v[0:3]
	s_setprio 0
	s_barrier
	s_add_i32 s76, s76, 2
	s_add_u32 s74, s74, 0x100
	s_addc_u32 s75, s75, 0
	s_add_u32 s4, s4, 0x100
	s_addc_u32 s5, s5, 0
	s_cmp_gt_u32 s76, 3
	s_cbranch_scc0 .LBB0_1125
	s_and_b64 vcc, exec, s[14:15]
	s_cbranch_vccz .LBB0_1128
	s_barrier

; #define PG8_STAGE(bufoff, gbase, voff) do { const char* _gb = (const char*)(gbase); asm volatile("" : "+s"(_gb));     \
;         _Pragma("unroll") for (int _i = 0; _i < 2; ++_i) \
;         __builtin_amdgcn_global_load_lds((const unsigned*)(_gb + (voff)[_i]), (LAS unsigned*)(lds + (bufoff) + ldsw + _i * 8192), 16, 0, 0); } while (0)
; #define PG8_WAIT_V(n) asm volatile("s_waitcnt vmcnt(" #n ")" ::: "memory")
; #define PG8_BAR __builtin_amdgcn_s_barrier()
; template <class Epi>
; __device__ __forceinline__ void gemm_phase(LAS unsigned char* lds, const int wid, const Gemm g, const Epi& E) {
;     ...
;     const char* cA = PG8_UA(cur); const char* cB = PG8_UB(cur);
;     PG8_STAGE(PG8_SB(0, 0), PG8_BP(cB, 0), voffB); PG8_STAGE(PG8_SB(0, 1), PG8_BP(cB, 0) + hstepB, voffB); PG8_STAGE(PG8_SA(0, 0), PG8_AP(cA, 0), voffA); PG8_STAGE(PG8_SA(0, 1), PG8_AP(cA, 0) + hstepA, voffA);
;     if (wr == 1) PG8_BAR;
;     PG8_WAIT_V(2); PG8_BAR;
;     PG8_STAGE(PG8_SB(1, 0), PG8_BP(cB, 1), voffB); PG8_STAGE(PG8_SA(1, 0), PG8_AP(cA, 1), voffA); PG8_STAGE(PG8_SB(1, 1), PG8_BP(cB, 1) + hstepB, voffB);
;     PG8_WAIT_V(6); PG8_BAR;
;     for (;;) {
;         const bool has_next = S.next(ui + 1, nxt);
;         const char* nA = has_next ? PG8_UA(nxt) : cA; const char* nB = has_next ? PG8_UB(nxt) : cB;
.LBB0_1318:
	s_and_b32 s70, s33, 3
	s_lshl_b32 s71, s3, 6
	s_cmp_lt_u32 s33, 4
	s_cselect_b64 s[14:15], -1, 0
	s_add_u32 s16, s18, 0x1700000
	s_addc_u32 s17, s19, 0
	s_add_u32 s18, s20, 0x100000
	s_addc_u32 s19, s21, 0
	s_add_u32 s20, s24, 0x15800000
	s_addc_u32 s21, s25, 0
	s_add_u32 s24, s38, 0x80
	s_addc_u32 s25, s39, 0
	s_waitcnt vmcnt(2)
	s_barrier
	s_add_i32 m0, s65, 0x18000
	s_nop 0
	global_load_lds_dwordx4 v132, s[24:25]
	s_add_i32 m0, s65, 0x1a000
	v_lshl_add_u64 v[2:3], s[24:25], 0, v[128:129]
	s_add_u32 s24, s40, 0x80
	s_addc_u32 s25, s41, 0
	s_add_i32 s72, s65, 0x8000
	global_load_lds_dwordx4 v[2:3], off
	s_mov_b32 m0, s72
	s_add_i32 s73, s65, 0xa000
	global_load_lds_dwordx4 v134, s[24:25]
	v_lshl_add_u64 v[2:3], s[24:25], 0, v[130:131]
	s_add_u32 s24, s38, 0x10080
	s_mov_b32 m0, s73
	s_addc_u32 s25, s39, 0
	global_load_lds_dwordx4 v[2:3], off
	s_add_i32 m0, s65, 0x1c000
	s_nop 0
	global_load_lds_dwordx4 v132, s[24:25]
	s_add_i32 m0, s65, 0x1e000
	v_xor_b32_e32 v1, 16, v152
	global_load_lds_dwordx4 v128, s[24:25]
	v_and_b32_e32 v2, 64, v152
	v_add_u32_e32 v2, 64, v2
	v_cmp_lt_i32_e32 vcc, v1, v2
	v_lshlrev_b32_e32 v3, 6, v153
	s_movk_i32 s0, 0x3c0
	v_cndmask_b32_e32 v1, v152, v1, vcc
	v_lshlrev_b32_e32 v154, 2, v1
	v_xor_b32_e32 v1, 32, v152
	v_cmp_lt_i32_e32 vcc, v1, v2
	v_and_b32_e32 v0, 0xfffffc00, v0
	v_lshl_add_u32 v2, s3, 13, v0
	v_cndmask_b32_e32 v1, v152, v1, vcc
	v_lshlrev_b32_e32 v155, 2, v1
	v_and_b32_e32 v1, 48, v153
	v_and_or_b32 v1, v3, s0, v1
	v_lshlrev_b32_e32 v3, 2, v153
	v_and_b32_e32 v3, 32, v3
	v_lshl_add_u32 v0, s70, 12, v0
	s_waitcnt vmcnt(6)
	v_bitop3_b32 v2, v1, v2, v3 bitop3:0xde
	v_bitop3_b32 v156, v1, v0, v3 bitop3:0xde
	s_add_i32 s76, 0, 0x10000
	s_add_i32 s77, 0, 0x14000
	s_sext_i32_i8 s35, s2
	s_mov_b32 s74, 0
	s_waitcnt lgkmcnt(0)
	s_ashr_i32 s75, s69, 31
	v_mov_b64_e32 v[136:137], 0x200
	v_mov_b64_e32 v[138:139], 0x1ff
	v_add_u32_e32 v157, s76, v156
	v_add_u32_e32 v158, s77, v156
	v_add_u32_e32 v159, 0, v2
	v_mov_b32_e32 v160, 0x3a27c5ac
	s_mov_b32 s78, 0x800000
	s_barrier
	s_branch .LBB0_1321

; #define PG8_STAGE(bufoff, gbase, voff) do { const char* _gb = (const char*)(gbase); asm volatile("" : "+s"(_gb));     \
;         _Pragma("unroll") for (int _i = 0; _i < 2; ++_i) \
;         __builtin_amdgcn_global_load_lds((const unsigned*)(_gb + (voff)[_i]), (LAS unsigned*)(lds + (bufoff) + ldsw + _i * 8192), 16, 0, 0); } while (0)
; #define PG8_LDA(dst, b, h) do { _Pragma("unroll") for (int m = 0; m < 4; ++m) _Pragma("unroll") for (int k = 0; k < 2; ++k) dst[m][k] = *(const LAS bf16x8*)(lds + PG8_SA(b, h) + aoff + m * 2048 + k * 1024); } while (0)
; #define PG8_LDB(dst, b, h) do { _Pragma("unroll") for (int n = 0; n < 2; ++n) _Pragma("unroll") for (int k = 0; k < 2; ++k) dst[n][k] = *(const LAS bf16x8*)(lds + PG8_SB(b, h) + boff + n * 2048 + k * 1024); } while (0)
; #define PG8_MMA(ai, bj, At, Bt) do { __builtin_amdgcn_s_setprio(1); _Pragma("unroll") for (int m = 0; m < 4; ++m) _Pragma("unroll") for (int n = 0; n < 2; ++n) _Pragma("unroll") for (int k = 0; k < 2; ++k) \
;         acc[ai][bj][m][n] = __builtin_amdgcn_mfma_f32_16x16x32_bf16(Bt[n][k], At[m][k], acc[ai][bj][m][n], 0, 0, 0); __builtin_amdgcn_s_setprio(0); } while (0)
; #define PG8_WAIT_V(n) asm volatile("s_waitcnt vmcnt(" #n ")" ::: "memory")
; #define PG8_WAIT_L(n) asm volatile("s_waitcnt lgkmcnt(" #n ")" ::: "memory")
; #define PG8_BAR __builtin_amdgcn_s_barrier()
; template <class Epi>
; __device__ __forceinline__ void gemm_phase(LAS unsigned char* lds, const int wid, const Gemm g, const Epi& E) {
;     ...
;             const bool last = (t == nt - 2);
;             const char* a1 = PG8_AP(cA, t + 1);
;             const char* a2 = last ? PG8_AP(nA, 0) : PG8_AP(cA, t + 2); const char* b2 = last ? PG8_BP(nB, 0) : PG8_BP(cB, t + 2);
;             const char* a3 = last ? PG8_AP(nA, 1) : PG8_AP(cA, t + 3); const char* b3 = last ? PG8_BP(nB, 1) : PG8_BP(cB, t + 3);
;             PG8_LDB(B0, 0, 0); PG8_LDB(B1, 0, 1); PG8_SCHED; PG8_LDA(At, 0, 0); PG8_STAGE(PG8_SA(1, 1), a1 + hstepA, voffA);
;             PG8_WAIT_V(8); PG8_WAIT_L(0); PG8_BAR; PG8_MMA(0, 0, At, B0); PG8_MMA(0, 1, At, B1); PG8_BAR; PG8_SCHED;
;             PG8_LDA(At, 0, 1); PG8_STAGE(PG8_SB(0, 0), b2, voffB); PG8_STAGE(PG8_SB(0, 1), b2 + hstepB, voffB); PG8_STAGE(PG8_SA(0, 0), a2, voffA);
;             PG8_WAIT_V(8); PG8_WAIT_L(0); PG8_BAR; PG8_MMA(1, 0, At, B0); PG8_MMA(1, 1, At, B1); PG8_BAR; PG8_SCHED;
.LBB0_1328:
	s_add_u32 s0, s40, s46
	s_addc_u32 s1, s41, 0
	s_add_u32 s47, s0, 0x100
	s_addc_u32 s50, s1, 0
	s_and_b64 s[48:49], s[44:45], exec
	s_cselect_b32 s53, s27, s50
	s_cselect_b32 s52, s79, s47
	s_add_u32 s48, s38, s46
	s_addc_u32 s49, s39, 0
	s_add_u32 s50, s48, 0x100
	s_addc_u32 s51, s49, 0
	s_and_b64 s[46:47], s[44:45], exec
	s_cselect_b32 s55, s25, s51
	s_cselect_b32 s54, s80, s50
	s_add_u32 s50, s0, 0x180
	s_addc_u32 s51, s1, 0
	s_and_b64 s[46:47], s[44:45], exec
	s_cselect_b32 s46, s81, s50
	s_cselect_b32 s47, s82, s51
	s_add_u32 s48, s48, 0x180
	s_addc_u32 s49, s49, 0
	s_add_u32 s58, s0, 0x20080
	s_addc_u32 s59, s1, 0
	s_add_i32 s94, s76, s23
	s_add_i32 m0, s65, 0xc000
	s_add_i32 s0, s65, 0xe000
	s_add_i32 s91, s94, 0x2000
	ds_read_b128 v[140:143], v157
	ds_read_b128 v[144:147], v157 offset:1024
	ds_read_b128 v[148:151], v157 offset:2048
	ds_read_b128 v[162:165], v157 offset:3072
	ds_read_b128 v[166:169], v158
	ds_read_b128 v[170:173], v158 offset:1024
	ds_read_b128 v[174:177], v158 offset:2048
	ds_read_b128 v[178:181], v158 offset:3072
	s_add_u32 s56, s54, 0x10000
	s_addc_u32 s57, s55, 0
	s_add_i32 s90, s77, s23
	s_add_i32 s89, s90, 0x2000
	s_add_i32 s88, 0, 0x18000
	s_add_i32 s87, 0, 0x1c000
	s_add_u32 s50, s52, 0x20000
	s_addc_u32 s51, s53, 0
	s_and_b64 s[44:45], s[44:45], exec
	s_cselect_b32 s49, s84, s49
	s_cselect_b32 s48, s83, s48
	s_add_i32 s86, s88, s23
	s_add_i32 s85, s86, 0x2000
	s_add_u32 s44, s48, 0x10000
	s_addc_u32 s45, s49, 0
	s_add_i32 s93, s87, s23
	s_add_i32 s92, s93, 0x2000
	ds_read_b128 v[182:185], v159
	ds_read_b128 v[186:189], v159 offset:1024
	ds_read_b128 v[190:193], v159 offset:2048
	ds_read_b128 v[194:197], v159 offset:3072
	ds_read_b128 v[198:201], v159 offset:4096
	ds_read_b128 v[206:209], v159 offset:5120
	ds_read_b128 v[210:213], v159 offset:6144
	ds_read_b128 v[214:217], v159 offset:7168
	s_nop 0
	global_load_lds_dwordx4 v134, s[58:59]
	s_mov_b32 m0, s0
	s_nop 0
	global_load_lds_dwordx4 v130, s[58:59]
	s_waitcnt vmcnt(8)
	s_waitcnt lgkmcnt(0)
	s_barrier
	s_setprio 1
	s_waitcnt lgkmcnt(0)
	v_mfma_f32_16x16x32_bf16 v[124:127], v[140:143], v[182:185], v[124:127]
	v_mfma_f32_16x16x32_bf16 v[120:123], v[148:151], v[182:185], v[120:123]
	v_mfma_f32_16x16x32_bf16 v[108:111], v[140:143], v[190:193], v[108:111]
	v_mfma_f32_16x16x32_bf16 v[104:107], v[148:151], v[190:193], v[104:107]
	v_mfma_f32_16x16x32_bf16 v[92:95], v[140:143], v[198:201], v[92:95]
	v_mfma_f32_16x16x32_bf16 v[88:91], v[148:151], v[198:201], v[88:91]
	v_mfma_f32_16x16x32_bf16 v[76:79], v[140:143], v[210:213], v[76:79]
	v_mfma_f32_16x16x32_bf16 v[72:75], v[148:151], v[210:213], v[72:75]
	v_mfma_f32_16x16x32_bf16 v[124:127], v[144:147], v[186:189], v[124:127]
	v_mfma_f32_16x16x32_bf16 v[120:123], v[162:165], v[186:189], v[120:123]
	v_mfma_f32_16x16x32_bf16 v[108:111], v[144:147], v[194:197], v[108:111]
	v_mfma_f32_16x16x32_bf16 v[104:107], v[162:165], v[194:197], v[104:107]
	v_mfma_f32_16x16x32_bf16 v[92:95], v[144:147], v[206:209], v[92:95]
	v_mfma_f32_16x16x32_bf16 v[88:91], v[162:165], v[206:209], v[88:91]
	v_mfma_f32_16x16x32_bf16 v[76:79], v[144:147], v[214:217], v[76:79]
	v_mfma_f32_16x16x32_bf16 v[72:75], v[162:165], v[214:217], v[72:75]
	s_setprio 0
	s_setprio 1
	v_mfma_f32_16x16x32_bf16 v[116:119], v[166:169], v[182:185], v[116:119]
	v_mfma_f32_16x16x32_bf16 v[112:115], v[174:177], v[182:185], v[112:115]
	v_mfma_f32_16x16x32_bf16 v[100:103], v[166:169], v[190:193], v[100:103]
	v_mfma_f32_16x16x32_bf16 v[96:99], v[174:177], v[190:193], v[96:99]
	v_mfma_f32_16x16x32_bf16 v[84:87], v[166:169], v[198:201], v[84:87]
	v_mfma_f32_16x16x32_bf16 v[80:83], v[174:177], v[198:201], v[80:83]
	v_mfma_f32_16x16x32_bf16 v[68:71], v[166:169], v[210:213], v[68:71]
	v_mfma_f32_16x16x32_bf16 v[64:67], v[174:177], v[210:213], v[64:67]
	v_mfma_f32_16x16x32_bf16 v[116:119], v[170:173], v[186:189], v[116:119]
	v_mfma_f32_16x16x32_bf16 v[112:115], v[178:181], v[186:189], v[112:115]
	v_mfma_f32_16x16x32_bf16 v[100:103], v[170:173], v[194:197], v[100:103]
	v_mfma_f32_16x16x32_bf16 v[96:99], v[178:181], v[194:197], v[96:99]
	v_mfma_f32_16x16x32_bf16 v[84:87], v[170:173], v[206:209], v[84:87]
	v_mfma_f32_16x16x32_bf16 v[80:83], v[178:181], v[206:209], v[80:83]
	v_mfma_f32_16x16x32_bf16 v[68:71], v[170:173], v[214:217], v[68:71]
	v_mfma_f32_16x16x32_bf16 v[64:67], v[178:181], v[214:217], v[64:67]
	s_setprio 0
	s_barrier
	s_mov_b32 m0, s94
	ds_read_b128 v[182:185], v159 offset:16384
	ds_read_b128 v[186:189], v159 offset:17408
	ds_read_b128 v[190:193], v159 offset:18432
	ds_read_b128 v[194:197], v159 offset:19456
	ds_read_b128 v[198:201], v159 offset:20480
	ds_read_b128 v[206:209], v159 offset:21504
	ds_read_b128 v[210:213], v159 offset:22528
	ds_read_b128 v[214:217], v159 offset:23552
	s_nop 0
	global_load_lds_dwordx4 v132, s[54:55]
	s_mov_b32 m0, s91
	s_nop 0
	global_load_lds_dwordx4 v128, s[54:55]
	s_mov_b32 m0, s90
	s_nop 0
	global_load_lds_dwordx4 v132, s[56:57]
	s_mov_b32 m0, s89
	s_nop 0
	global_load_lds_dwordx4 v128, s[56:57]
	s_mov_b32 m0, s65
	s_nop 0
	global_load_lds_dwordx4 v134, s[52:53]
	s_mov_b32 m0, s66
	s_nop 0
	global_load_lds_dwordx4 v130, s[52:53]
	s_waitcnt vmcnt(8)
	s_waitcnt lgkmcnt(0)
	s_barrier
; #define PG8_STAGE(bufoff, gbase, voff) do { const char* _gb = (const char*)(gbase); asm volatile("" : "+s"(_gb));     \
;         _Pragma("unroll") for (int _i = 0; _i < 2; ++_i) \
;         __builtin_amdgcn_global_load_lds((const unsigned*)(_gb + (voff)[_i]), (LAS unsigned*)(lds + (bufoff) + ldsw + _i * 8192), 16, 0, 0); } while (0)
; #define PG8_LDA(dst, b, h) do { _Pragma("unroll") for (int m = 0; m < 4; ++m) _Pragma("unroll") for (int k = 0; k < 2; ++k) dst[m][k] = *(const LAS bf16x8*)(lds + PG8_SA(b, h) + aoff + m * 2048 + k * 1024); } while (0)
; #define PG8_LDB(dst, b, h) do { _Pragma("unroll") for (int n = 0; n < 2; ++n) _Pragma("unroll") for (int k = 0; k < 2; ++k) dst[n][k] = *(const LAS bf16x8*)(lds + PG8_SB(b, h) + boff + n * 2048 + k * 1024); } while (0)
; #define PG8_MMA(ai, bj, At, Bt) do { __builtin_amdgcn_s_setprio(1); _Pragma("unroll") for (int m = 0; m < 4; ++m) _Pragma("unroll") for (int n = 0; n < 2; ++n) _Pragma("unroll") for (int k = 0; k < 2; ++k) \
;         acc[ai][bj][m][n] = __builtin_amdgcn_mfma_f32_16x16x32_bf16(Bt[n][k], At[m][k], acc[ai][bj][m][n], 0, 0, 0); __builtin_amdgcn_s_setprio(0); } while (0)
; #define PG8_WAIT_V(n) asm volatile("s_waitcnt vmcnt(" #n ")" ::: "memory")
; #define PG8_WAIT_L(n) asm volatile("s_waitcnt lgkmcnt(" #n ")" ::: "memory")
; #define PG8_BAR __builtin_amdgcn_s_barrier()
; #define PG8_SCHED __builtin_amdgcn_sched_barrier(0)
; template <class Epi>
; __device__ __forceinline__ void gemm_phase(LAS unsigned char* lds, const int wid, const Gemm g, const Epi& E) {
;     ...
;             PG8_WAIT_V(8); PG8_WAIT_L(0); PG8_BAR; PG8_MMA(1, 0, At, B0); PG8_MMA(1, 1, At, B1); PG8_BAR; PG8_SCHED;
;             PG8_LDB(B0, 1, 0); PG8_LDB(B1, 1, 1); PG8_SCHED; PG8_LDA(At, 1, 0); PG8_STAGE(PG8_SA(0, 1), a2 + hstepA, voffA);
;             PG8_WAIT_V(8); PG8_WAIT_L(0); PG8_BAR; PG8_MMA(0, 0, At, B0); PG8_MMA(0, 1, At, B1); PG8_BAR; PG8_SCHED;
	s_setprio 1
	s_waitcnt lgkmcnt(0)
	v_mfma_f32_16x16x32_bf16 v[60:63], v[140:143], v[182:185], v[60:63]
	v_mfma_f32_16x16x32_bf16 v[56:59], v[148:151], v[182:185], v[56:59]
	v_mfma_f32_16x16x32_bf16 v[44:47], v[140:143], v[190:193], v[44:47]
	v_mfma_f32_16x16x32_bf16 v[40:43], v[148:151], v[190:193], v[40:43]
	v_mfma_f32_16x16x32_bf16 v[28:31], v[140:143], v[198:201], v[28:31]
	v_mfma_f32_16x16x32_bf16 v[24:27], v[148:151], v[198:201], v[24:27]
	v_mfma_f32_16x16x32_bf16 v[12:15], v[140:143], v[210:213], v[12:15]
	v_mfma_f32_16x16x32_bf16 v[8:11], v[148:151], v[210:213], v[8:11]
	v_mfma_f32_16x16x32_bf16 v[60:63], v[144:147], v[186:189], v[60:63]
	v_mfma_f32_16x16x32_bf16 v[56:59], v[162:165], v[186:189], v[56:59]
	v_mfma_f32_16x16x32_bf16 v[44:47], v[144:147], v[194:197], v[44:47]
	v_mfma_f32_16x16x32_bf16 v[40:43], v[162:165], v[194:197], v[40:43]
	v_mfma_f32_16x16x32_bf16 v[28:31], v[144:147], v[206:209], v[28:31]
	v_mfma_f32_16x16x32_bf16 v[24:27], v[162:165], v[206:209], v[24:27]
	v_mfma_f32_16x16x32_bf16 v[12:15], v[144:147], v[214:217], v[12:15]
	v_mfma_f32_16x16x32_bf16 v[8:11], v[162:165], v[214:217], v[8:11]
	s_setprio 0
	s_setprio 1
	v_mfma_f32_16x16x32_bf16 v[52:55], v[166:169], v[182:185], v[52:55]
	v_mfma_f32_16x16x32_bf16 v[48:51], v[174:177], v[182:185], v[48:51]
	v_mfma_f32_16x16x32_bf16 v[36:39], v[166:169], v[190:193], v[36:39]
	v_mfma_f32_16x16x32_bf16 v[32:35], v[174:177], v[190:193], v[32:35]
	v_mfma_f32_16x16x32_bf16 v[20:23], v[166:169], v[198:201], v[20:23]
	v_mfma_f32_16x16x32_bf16 v[16:19], v[174:177], v[198:201], v[16:19]
	v_mfma_f32_16x16x32_bf16 v[4:7], v[166:169], v[210:213], v[4:7]
	v_mfma_f32_16x16x32_bf16 v[0:3], v[174:177], v[210:213], v[0:3]
	v_mfma_f32_16x16x32_bf16 v[52:55], v[170:173], v[186:189], v[52:55]
	v_mfma_f32_16x16x32_bf16 v[48:51], v[178:181], v[186:189], v[48:51]
	v_mfma_f32_16x16x32_bf16 v[36:39], v[170:173], v[194:197], v[36:39]
	v_mfma_f32_16x16x32_bf16 v[32:35], v[178:181], v[194:197], v[32:35]
	v_mfma_f32_16x16x32_bf16 v[20:23], v[170:173], v[206:209], v[20:23]
	v_mfma_f32_16x16x32_bf16 v[16:19], v[178:181], v[206:209], v[16:19]
	v_mfma_f32_16x16x32_bf16 v[4:7], v[170:173], v[214:217], v[4:7]
	v_mfma_f32_16x16x32_bf16 v[0:3], v[178:181], v[214:217], v[0:3]
	s_setprio 0
	s_barrier
	v_add_u32_e32 v161, s88, v156
	ds_read_b128 v[140:143], v161
	ds_read_b128 v[144:147], v161 offset:1024
	ds_read_b128 v[148:151], v161 offset:2048
	ds_read_b128 v[162:165], v161 offset:3072
	v_add_u32_e32 v161, s87, v156
	ds_read_b128 v[166:169], v161
	ds_read_b128 v[170:173], v161 offset:1024
	ds_read_b128 v[174:177], v161 offset:2048
	ds_read_b128 v[178:181], v161 offset:3072
	s_mov_b32 m0, s67
	ds_read_b128 v[182:185], v159 offset:32768
	ds_read_b128 v[186:189], v159 offset:33792
	ds_read_b128 v[190:193], v159 offset:34816
	ds_read_b128 v[194:197], v159 offset:35840
	ds_read_b128 v[198:201], v159 offset:36864
	ds_read_b128 v[206:209], v159 offset:37888
	ds_read_b128 v[210:213], v159 offset:38912
	ds_read_b128 v[214:217], v159 offset:39936
	s_nop 0
	global_load_lds_dwordx4 v134, s[50:51]
	s_mov_b32 m0, s68
	s_nop 0
	global_load_lds_dwordx4 v130, s[50:51]
	s_waitcnt vmcnt(8)
	s_waitcnt lgkmcnt(0)
	s_barrier
	s_setprio 1
	s_waitcnt lgkmcnt(0)
	v_mfma_f32_16x16x32_bf16 v[124:127], v[140:143], v[182:185], v[124:127]
	v_mfma_f32_16x16x32_bf16 v[120:123], v[148:151], v[182:185], v[120:123]
	v_mfma_f32_16x16x32_bf16 v[108:111], v[140:143], v[190:193], v[108:111]
	v_mfma_f32_16x16x32_bf16 v[104:107], v[148:151], v[190:193], v[104:107]
	v_mfma_f32_16x16x32_bf16 v[92:95], v[140:143], v[198:201], v[92:95]
	v_mfma_f32_16x16x32_bf16 v[88:91], v[148:151], v[198:201], v[88:91]
	v_mfma_f32_16x16x32_bf16 v[76:79], v[140:143], v[210:213], v[76:79]
	v_mfma_f32_16x16x32_bf16 v[72:75], v[148:151], v[210:213], v[72:75]
	v_mfma_f32_16x16x32_bf16 v[124:127], v[144:147], v[186:189], v[124:127]
	v_mfma_f32_16x16x32_bf16 v[120:123], v[162:165], v[186:189], v[120:123]
	v_mfma_f32_16x16x32_bf16 v[108:111], v[144:147], v[194:197], v[108:111]
	v_mfma_f32_16x16x32_bf16 v[104:107], v[162:165], v[194:197], v[104:107]
	v_mfma_f32_16x16x32_bf16 v[92:95], v[144:147], v[206:209], v[92:95]
	v_mfma_f32_16x16x32_bf16 v[88:91], v[162:165], v[206:209], v[88:91]
	v_mfma_f32_16x16x32_bf16 v[76:79], v[144:147], v[214:217], v[76:79]
	v_mfma_f32_16x16x32_bf16 v[72:75], v[162:165], v[214:217], v[72:75]
	s_setprio 0
	s_setprio 1
	v_mfma_f32_16x16x32_bf16 v[116:119], v[166:169], v[182:185], v[116:119]
	v_mfma_f32_16x16x32_bf16 v[112:115], v[174:177], v[182:185], v[112:115]
	v_mfma_f32_16x16x32_bf16 v[100:103], v[166:169], v[190:193], v[100:103]
	v_mfma_f32_16x16x32_bf16 v[96:99], v[174:177], v[190:193], v[96:99]
	v_mfma_f32_16x16x32_bf16 v[84:87], v[166:169], v[198:201], v[84:87]
	v_mfma_f32_16x16x32_bf16 v[80:83], v[174:177], v[198:201], v[80:83]
	v_mfma_f32_16x16x32_bf16 v[68:71], v[166:169], v[210:213], v[68:71]
	v_mfma_f32_16x16x32_bf16 v[64:67], v[174:177], v[210:213], v[64:67]
	v_mfma_f32_16x16x32_bf16 v[116:119], v[170:173], v[186:189], v[116:119]
	v_mfma_f32_16x16x32_bf16 v[112:115], v[178:181], v[186:189], v[112:115]
	v_mfma_f32_16x16x32_bf16 v[100:103], v[170:173], v[194:197], v[100:103]
	v_mfma_f32_16x16x32_bf16 v[96:99], v[178:181], v[194:197], v[96:99]
	v_mfma_f32_16x16x32_bf16 v[84:87], v[170:173], v[206:209], v[84:87]
	v_mfma_f32_16x16x32_bf16 v[80:83], v[178:181], v[206:209], v[80:83]
	v_mfma_f32_16x16x32_bf16 v[68:71], v[170:173], v[214:217], v[68:71]
	v_mfma_f32_16x16x32_bf16 v[64:67], v[178:181], v[214:217], v[64:67]
	s_setprio 0
	s_barrier
; #define PG8_STAGE(bufoff, gbase, voff) do { const char* _gb = (const char*)(gbase); asm volatile("" : "+s"(_gb));     \
;         _Pragma("unroll") for (int _i = 0; _i < 2; ++_i) \
;         __builtin_amdgcn_global_load_lds((const unsigned*)(_gb + (voff)[_i]), (LAS unsigned*)(lds + (bufoff) + ldsw + _i * 8192), 16, 0, 0); } while (0)
; #define PG8_LDA(dst, b, h) do { _Pragma("unroll") for (int m = 0; m < 4; ++m) _Pragma("unroll") for (int k = 0; k < 2; ++k) dst[m][k] = *(const LAS bf16x8*)(lds + PG8_SA(b, h) + aoff + m * 2048 + k * 1024); } while (0)
; #define PG8_MMA(ai, bj, At, Bt) do { __builtin_amdgcn_s_setprio(1); _Pragma("unroll") for (int m = 0; m < 4; ++m) _Pragma("unroll") for (int n = 0; n < 2; ++n) _Pragma("unroll") for (int k = 0; k < 2; ++k) \
;         acc[ai][bj][m][n] = __builtin_amdgcn_mfma_f32_16x16x32_bf16(Bt[n][k], At[m][k], acc[ai][bj][m][n], 0, 0, 0); __builtin_amdgcn_s_setprio(0); } while (0)
; #define PG8_WAIT_V(n) asm volatile("s_waitcnt vmcnt(" #n ")" ::: "memory")
; #define PG8_WAIT_L(n) asm volatile("s_waitcnt lgkmcnt(" #n ")" ::: "memory")
; #define PG8_BAR __builtin_amdgcn_s_barrier()
; #define PG8_SCHED __builtin_amdgcn_sched_barrier(0)
; template <class Epi>
; __device__ __forceinline__ void gemm_phase(LAS unsigned char* lds, const int wid, const Gemm g, const Epi& E) {
;     ...
;             PG8_WAIT_V(8); PG8_WAIT_L(0); PG8_BAR; PG8_MMA(0, 0, At, B0); PG8_MMA(0, 1, At, B1); PG8_BAR; PG8_SCHED;
;             PG8_LDA(At, 1, 1); PG8_STAGE(PG8_SB(1, 0), b3, voffB); PG8_STAGE(PG8_SB(1, 1), b3 + hstepB, voffB); PG8_STAGE(PG8_SA(1, 0), a3, voffA);
;             PG8_WAIT_V(8); PG8_WAIT_L(0); PG8_BAR; PG8_MMA(1, 0, At, B0); PG8_MMA(1, 1, At, B1); PG8_BAR; PG8_SCHED;
;         }
;         if (wr == 0) PG8_BAR;
	s_mov_b32 m0, s86
	ds_read_b128 v[182:185], v159 offset:49152
	ds_read_b128 v[186:189], v159 offset:50176
	ds_read_b128 v[190:193], v159 offset:51200
	ds_read_b128 v[194:197], v159 offset:52224
	ds_read_b128 v[198:201], v159 offset:53248
	ds_read_b128 v[206:209], v159 offset:54272
	ds_read_b128 v[210:213], v159 offset:55296
	ds_read_b128 v[214:217], v159 offset:56320
	s_nop 0
	global_load_lds_dwordx4 v132, s[48:49]
	s_mov_b32 m0, s85
	s_nop 0
	global_load_lds_dwordx4 v128, s[48:49]
	s_mov_b32 m0, s93
	s_nop 0
	global_load_lds_dwordx4 v132, s[44:45]
	s_mov_b32 m0, s92
	s_nop 0
	global_load_lds_dwordx4 v128, s[44:45]
	s_mov_b32 m0, s72
	s_nop 0
	global_load_lds_dwordx4 v134, s[46:47]
	s_mov_b32 m0, s73
	s_nop 0
	global_load_lds_dwordx4 v130, s[46:47]
	s_waitcnt vmcnt(8)
	s_waitcnt lgkmcnt(0)
	s_barrier
	s_setprio 1
	s_waitcnt lgkmcnt(0)
	v_mfma_f32_16x16x32_bf16 v[60:63], v[140:143], v[182:185], v[60:63]
	v_mfma_f32_16x16x32_bf16 v[56:59], v[148:151], v[182:185], v[56:59]
	v_mfma_f32_16x16x32_bf16 v[44:47], v[140:143], v[190:193], v[44:47]
	v_mfma_f32_16x16x32_bf16 v[40:43], v[148:151], v[190:193], v[40:43]
	v_mfma_f32_16x16x32_bf16 v[28:31], v[140:143], v[198:201], v[28:31]
	v_mfma_f32_16x16x32_bf16 v[24:27], v[148:151], v[198:201], v[24:27]
	v_mfma_f32_16x16x32_bf16 v[12:15], v[140:143], v[210:213], v[12:15]
	v_mfma_f32_16x16x32_bf16 v[8:11], v[148:151], v[210:213], v[8:11]
	v_mfma_f32_16x16x32_bf16 v[60:63], v[144:147], v[186:189], v[60:63]
	v_mfma_f32_16x16x32_bf16 v[56:59], v[162:165], v[186:189], v[56:59]
	v_mfma_f32_16x16x32_bf16 v[44:47], v[144:147], v[194:197], v[44:47]
	v_mfma_f32_16x16x32_bf16 v[40:43], v[162:165], v[194:197], v[40:43]
	v_mfma_f32_16x16x32_bf16 v[28:31], v[144:147], v[206:209], v[28:31]
	v_mfma_f32_16x16x32_bf16 v[24:27], v[162:165], v[206:209], v[24:27]
	v_mfma_f32_16x16x32_bf16 v[12:15], v[144:147], v[214:217], v[12:15]
	v_mfma_f32_16x16x32_bf16 v[8:11], v[162:165], v[214:217], v[8:11]
	s_setprio 0
	s_setprio 1
	v_mfma_f32_16x16x32_bf16 v[52:55], v[166:169], v[182:185], v[52:55]
	v_mfma_f32_16x16x32_bf16 v[48:51], v[174:177], v[182:185], v[48:51]
	v_mfma_f32_16x16x32_bf16 v[36:39], v[166:169], v[190:193], v[36:39]
	v_mfma_f32_16x16x32_bf16 v[32:35], v[174:177], v[190:193], v[32:35]
	v_mfma_f32_16x16x32_bf16 v[20:23], v[166:169], v[198:201], v[20:23]
	v_mfma_f32_16x16x32_bf16 v[16:19], v[174:177], v[198:201], v[16:19]
	v_mfma_f32_16x16x32_bf16 v[4:7], v[166:169], v[210:213], v[4:7]
	v_mfma_f32_16x16x32_bf16 v[0:3], v[174:177], v[210:213], v[0:3]
	v_mfma_f32_16x16x32_bf16 v[52:55], v[170:173], v[186:189], v[52:55]
	v_mfma_f32_16x16x32_bf16 v[48:51], v[178:181], v[186:189], v[48:51]
	v_mfma_f32_16x16x32_bf16 v[36:39], v[170:173], v[194:197], v[36:39]
	v_mfma_f32_16x16x32_bf16 v[32:35], v[178:181], v[194:197], v[32:35]
	v_mfma_f32_16x16x32_bf16 v[20:23], v[170:173], v[206:209], v[20:23]
	v_mfma_f32_16x16x32_bf16 v[16:19], v[178:181], v[206:209], v[16:19]
	v_mfma_f32_16x16x32_bf16 v[4:7], v[170:173], v[214:217], v[4:7]
	v_mfma_f32_16x16x32_bf16 v[0:3], v[178:181], v[214:217], v[0:3]
	s_setprio 0
	s_barrier
	s_movk_i32 s46, 0x100
	s_andn2_b64 vcc, exec, s[42:43]
	s_mov_b64 s[44:45], -1
	s_mov_b64 s[42:43], 0
	s_cbranch_vccz .LBB0_1328
	s_and_b64 vcc, exec, s[14:15]
	s_cbranch_vccz .LBB0_1331
	s_barrier

; #define PG8_STAGE(bufoff, gbase, voff) do { const char* _gb = (const char*)(gbase); asm volatile("" : "+s"(_gb));     \
;         _Pragma("unroll") for (int _i = 0; _i < 2; ++_i) \
;         __builtin_amdgcn_global_load_lds((const unsigned*)(_gb + (voff)[_i]), (LAS unsigned*)(lds + (bufoff) + ldsw + _i * 8192), 16, 0, 0); } while (0)
; #define PG8_WAIT_V(n) asm volatile("s_waitcnt vmcnt(" #n ")" ::: "memory")
; #define PG8_BAR __builtin_amdgcn_s_barrier()
; template <class Epi>
; __device__ __forceinline__ void gemm_phase(LAS unsigned char* lds, const int wid, const Gemm g, const Epi& E) {
;     ...
;     const char* cA = PG8_UA(cur); const char* cB = PG8_UB(cur);
;     PG8_STAGE(PG8_SB(0, 0), PG8_BP(cB, 0), voffB); PG8_STAGE(PG8_SB(0, 1), PG8_BP(cB, 0) + hstepB, voffB); PG8_STAGE(PG8_SA(0, 0), PG8_AP(cA, 0), voffA); PG8_STAGE(PG8_SA(0, 1), PG8_AP(cA, 0) + hstepA, voffA);
;     if (wr == 1) PG8_BAR;
;     PG8_WAIT_V(2); PG8_BAR;
;     PG8_STAGE(PG8_SB(1, 0), PG8_BP(cB, 1), voffB); PG8_STAGE(PG8_SA(1, 0), PG8_AP(cA, 1), voffA); PG8_STAGE(PG8_SB(1, 1), PG8_BP(cB, 1) + hstepB, voffB);
;     PG8_WAIT_V(6); PG8_BAR;
;     for (;;) {
;         const bool has_next = S.next(ui + 1, nxt);
;         const char* nA = has_next ? PG8_UA(nxt) : cA; const char* nB = has_next ? PG8_UB(nxt) : cB;
.LBB0_1388:
	s_lshl_b32 s1, s33, 5
	s_and_b32 s56, s1, 0x60
	s_lshl_b32 s55, s12, 6
	s_lshl_b32 s0, s12, 13
	s_lshr_b32 s1, s56, 3
	s_cmp_lt_u32 s33, 4
	s_cselect_b64 s[10:11], -1, 0
	s_add_u32 s12, s3, 0x5800000
	s_addc_u32 s13, s13, 0
	s_add_u32 s14, s14, 0x5800000
	s_addc_u32 s15, s15, 0
	s_add_u32 s16, s38, 0x80
	s_addc_u32 s17, s39, 0
	s_waitcnt vmcnt(2)
	s_barrier
	s_add_i32 m0, s35, 0x18000
	s_nop 0
	global_load_lds_dwordx4 v132, s[16:17]
	s_add_i32 m0, s35, 0x1a000
	v_lshl_add_u64 v[0:1], s[16:17], 0, v[128:129]
	s_add_u32 s16, s40, 0x80
	s_addc_u32 s17, s41, 0
	s_add_i32 s57, s35, 0x8000
	global_load_lds_dwordx4 v[0:1], off
	s_mov_b32 m0, s57
	s_add_i32 s58, s35, 0xa000
	global_load_lds_dwordx4 v134, s[16:17]
	v_lshl_add_u64 v[0:1], s[16:17], 0, v[130:131]
	s_add_u32 s16, s38, 0x40080
	s_mov_b32 m0, s58
	s_addc_u32 s17, s39, 0
	global_load_lds_dwordx4 v[0:1], off
	s_add_i32 m0, s35, 0x1c000
	s_nop 0
	global_load_lds_dwordx4 v132, s[16:17]
	s_add_i32 m0, s35, 0x1e000
	v_lshlrev_b32_e32 v3, 6, v147
	global_load_lds_dwordx4 v128, s[16:17]
	v_ashrrev_i32_e32 v0, 6, v147
	v_and_b32_e32 v1, 48, v147
	v_lshl_add_u32 v2, v0, 10, s0
	s_movk_i32 s0, 0x3c0
	v_and_or_b32 v1, v3, s0, v1
	v_lshlrev_b32_e32 v3, 2, v147
	v_and_b32_e32 v3, 32, v3
	v_add_lshl_u32 v0, v0, s1, 10
	s_waitcnt vmcnt(6)
	v_bitop3_b32 v2, v1, v2, v3 bitop3:0xde
	v_bitop3_b32 v148, v1, v0, v3 bitop3:0xde
	s_add_i32 s61, 0, 0x10000
	s_add_i32 s62, 0, 0x14000
	s_sext_i32_i8 s63, s2
	s_mov_b32 s59, 0
	s_waitcnt lgkmcnt(0)
	s_ashr_i32 s60, s54, 31
	v_mov_b64_e32 v[136:137], 0x200
	v_mov_b64_e32 v[138:139], 0x1ff
	v_add_u32_e32 v149, s61, v148
	v_add_u32_e32 v150, s62, v148
	v_add_u32_e32 v151, 0, v2
	s_mov_b64 s[16:17], 0x48000
	s_mov_b64 s[18:19], 0x50000
	s_mov_b64 s[20:21], 0x58000
	s_barrier
	s_branch .LBB0_1391

; #define PG8_STAGE(bufoff, gbase, voff) do { const char* _gb = (const char*)(gbase); asm volatile("" : "+s"(_gb));     \
;         _Pragma("unroll") for (int _i = 0; _i < 2; ++_i) \
;         __builtin_amdgcn_global_load_lds((const unsigned*)(_gb + (voff)[_i]), (LAS unsigned*)(lds + (bufoff) + ldsw + _i * 8192), 16, 0, 0); } while (0)
; #define PG8_LDA(dst, b, h) do { _Pragma("unroll") for (int m = 0; m < 4; ++m) _Pragma("unroll") for (int k = 0; k < 2; ++k) dst[m][k] = *(const LAS bf16x8*)(lds + PG8_SA(b, h) + aoff + m * 2048 + k * 1024); } while (0)
; #define PG8_LDB(dst, b, h) do { _Pragma("unroll") for (int n = 0; n < 2; ++n) _Pragma("unroll") for (int k = 0; k < 2; ++k) dst[n][k] = *(const LAS bf16x8*)(lds + PG8_SB(b, h) + boff + n * 2048 + k * 1024); } while (0)
; #define PG8_MMA(ai, bj, At, Bt) do { __builtin_amdgcn_s_setprio(1); _Pragma("unroll") for (int m = 0; m < 4; ++m) _Pragma("unroll") for (int n = 0; n < 2; ++n) _Pragma("unroll") for (int k = 0; k < 2; ++k) \
;         acc[ai][bj][m][n] = __builtin_amdgcn_mfma_f32_16x16x32_bf16(Bt[n][k], At[m][k], acc[ai][bj][m][n], 0, 0, 0); __builtin_amdgcn_s_setprio(0); } while (0)
; #define PG8_WAIT_V(n) asm volatile("s_waitcnt vmcnt(" #n ")" ::: "memory")
; #define PG8_WAIT_L(n) asm volatile("s_waitcnt lgkmcnt(" #n ")" ::: "memory")
; #define PG8_BAR __builtin_amdgcn_s_barrier()
; template <class Epi>
; __device__ __forceinline__ void gemm_phase(LAS unsigned char* lds, const int wid, const Gemm g, const Epi& E) {
;     ...
;             const bool last = (t == nt - 2);
;             const char* a1 = PG8_AP(cA, t + 1);
;             const char* a2 = last ? PG8_AP(nA, 0) : PG8_AP(cA, t + 2); const char* b2 = last ? PG8_BP(nB, 0) : PG8_BP(cB, t + 2);
;             const char* a3 = last ? PG8_AP(nA, 1) : PG8_AP(cA, t + 3); const char* b3 = last ? PG8_BP(nB, 1) : PG8_BP(cB, t + 3);
;             PG8_LDB(B0, 0, 0); PG8_LDB(B1, 0, 1); PG8_SCHED; PG8_LDA(At, 0, 0); PG8_STAGE(PG8_SA(1, 1), a1 + hstepA, voffA);
;             PG8_WAIT_V(8); PG8_WAIT_L(0); PG8_BAR; PG8_MMA(0, 0, At, B0); PG8_MMA(0, 1, At, B1); PG8_BAR; PG8_SCHED;
;             PG8_LDA(At, 0, 1); PG8_STAGE(PG8_SB(0, 0), b2, voffB); PG8_STAGE(PG8_SB(0, 1), b2 + hstepB, voffB); PG8_STAGE(PG8_SA(0, 0), a2, voffA);
;             PG8_WAIT_V(8); PG8_WAIT_L(0); PG8_BAR; PG8_MMA(1, 0, At, B0); PG8_MMA(1, 1, At, B1); PG8_BAR; PG8_SCHED;
.LBB0_1398:
	ds_read_b128 v[140:143], v149
	ds_read_b128 v[152:155], v149 offset:1024
	ds_read_b128 v[156:159], v149 offset:2048
	ds_read_b128 v[160:163], v149 offset:3072
	ds_read_b128 v[164:167], v150
	ds_read_b128 v[168:171], v150 offset:1024
	ds_read_b128 v[172:175], v150 offset:2048
	ds_read_b128 v[176:179], v150 offset:3072
	s_add_u32 s0, s38, 0xfffc0080
	s_addc_u32 s1, s39, -1
	s_add_u32 s40, s70, 0xffffff80
	s_addc_u32 s41, s71, -1
	s_add_u32 s44, s38, 0xfffc0100
	s_addc_u32 s45, s39, -1
	s_add_i32 s76, s61, s23
	s_add_i32 m0, s35, 0xc000
	s_add_i32 s73, s35, 0xe000
	s_add_i32 s77, s76, 0x2000
	s_cmp_eq_u32 s72, 12
	s_cselect_b32 s43, s27, s1
	s_cselect_b32 s42, s64, s0
	s_cselect_b32 s75, s25, s41
	s_cselect_b32 s74, s65, s40
	s_cselect_b32 s41, s67, s45
	s_cselect_b32 s40, s66, s44
	s_mov_b64 s[44:45], s[38:39]
	ds_read_b128 v[180:183], v151
	ds_read_b128 v[184:187], v151 offset:1024
	ds_read_b128 v[188:191], v151 offset:2048
	ds_read_b128 v[192:195], v151 offset:3072
	ds_read_b128 v[196:199], v151 offset:4096
	ds_read_b128 v[200:203], v151 offset:5120
	ds_read_b128 v[206:209], v151 offset:6144
	ds_read_b128 v[210:213], v151 offset:7168
	s_nop 0
	global_load_lds_dwordx4 v134, s[44:45]
	s_mov_b32 m0, s73
	s_nop 0
	global_load_lds_dwordx4 v130, s[44:45]
	s_waitcnt vmcnt(8)
	s_waitcnt lgkmcnt(0)
	s_barrier
	s_setprio 1
	s_waitcnt lgkmcnt(0)
	v_mfma_f32_16x16x32_bf16 v[124:127], v[140:143], v[180:183], v[124:127]
	v_mfma_f32_16x16x32_bf16 v[120:123], v[156:159], v[180:183], v[120:123]
	v_mfma_f32_16x16x32_bf16 v[108:111], v[140:143], v[188:191], v[108:111]
	v_mfma_f32_16x16x32_bf16 v[104:107], v[156:159], v[188:191], v[104:107]
	v_mfma_f32_16x16x32_bf16 v[92:95], v[140:143], v[196:199], v[92:95]
	v_mfma_f32_16x16x32_bf16 v[88:91], v[156:159], v[196:199], v[88:91]
	v_mfma_f32_16x16x32_bf16 v[76:79], v[140:143], v[206:209], v[76:79]
	v_mfma_f32_16x16x32_bf16 v[72:75], v[156:159], v[206:209], v[72:75]
	v_mfma_f32_16x16x32_bf16 v[124:127], v[152:155], v[184:187], v[124:127]
	v_mfma_f32_16x16x32_bf16 v[120:123], v[160:163], v[184:187], v[120:123]
	v_mfma_f32_16x16x32_bf16 v[108:111], v[152:155], v[192:195], v[108:111]
	v_mfma_f32_16x16x32_bf16 v[104:107], v[160:163], v[192:195], v[104:107]
	v_mfma_f32_16x16x32_bf16 v[92:95], v[152:155], v[200:203], v[92:95]
	v_mfma_f32_16x16x32_bf16 v[88:91], v[160:163], v[200:203], v[88:91]
	v_mfma_f32_16x16x32_bf16 v[76:79], v[152:155], v[210:213], v[76:79]
	v_mfma_f32_16x16x32_bf16 v[72:75], v[160:163], v[210:213], v[72:75]
	s_setprio 0
	s_setprio 1
	v_mfma_f32_16x16x32_bf16 v[116:119], v[164:167], v[180:183], v[116:119]
	v_mfma_f32_16x16x32_bf16 v[112:115], v[172:175], v[180:183], v[112:115]
	v_mfma_f32_16x16x32_bf16 v[100:103], v[164:167], v[188:191], v[100:103]
	v_mfma_f32_16x16x32_bf16 v[96:99], v[172:175], v[188:191], v[96:99]
	v_mfma_f32_16x16x32_bf16 v[84:87], v[164:167], v[196:199], v[84:87]
	v_mfma_f32_16x16x32_bf16 v[80:83], v[172:175], v[196:199], v[80:83]
	v_mfma_f32_16x16x32_bf16 v[68:71], v[164:167], v[206:209], v[68:71]
	v_mfma_f32_16x16x32_bf16 v[64:67], v[172:175], v[206:209], v[64:67]
	v_mfma_f32_16x16x32_bf16 v[116:119], v[168:171], v[184:187], v[116:119]
	v_mfma_f32_16x16x32_bf16 v[112:115], v[176:179], v[184:187], v[112:115]
	v_mfma_f32_16x16x32_bf16 v[100:103], v[168:171], v[192:195], v[100:103]
	v_mfma_f32_16x16x32_bf16 v[96:99], v[176:179], v[192:195], v[96:99]
	v_mfma_f32_16x16x32_bf16 v[84:87], v[168:171], v[200:203], v[84:87]
	v_mfma_f32_16x16x32_bf16 v[80:83], v[176:179], v[200:203], v[80:83]
	v_mfma_f32_16x16x32_bf16 v[68:71], v[168:171], v[210:213], v[68:71]
	v_mfma_f32_16x16x32_bf16 v[64:67], v[176:179], v[210:213], v[64:67]
	s_setprio 0
	s_barrier
	s_mov_b64 s[44:45], s[74:75]
	s_mov_b32 m0, s76
	ds_read_b128 v[180:183], v151 offset:16384
	ds_read_b128 v[184:187], v151 offset:17408
	ds_read_b128 v[188:191], v151 offset:18432
	ds_read_b128 v[192:195], v151 offset:19456
	ds_read_b128 v[196:199], v151 offset:20480
	ds_read_b128 v[200:203], v151 offset:21504
	ds_read_b128 v[206:209], v151 offset:22528
	ds_read_b128 v[210:213], v151 offset:23552
	s_nop 0
	global_load_lds_dwordx4 v132, s[44:45]
	v_lshl_add_u64 v[144:145], s[44:45], 0, v[128:129]
	s_cselect_b32 s45, s69, s71
	s_cselect_b32 s44, s68, s70
	s_add_u32 s74, s74, 0x40000
	s_mov_b32 m0, s77
	s_addc_u32 s75, s75, 0
	s_add_i32 s0, s62, s23
	global_load_lds_dwordx4 v[144:145], off
	s_mov_b32 m0, s0
	s_nop 0
	global_load_lds_dwordx4 v132, s[74:75]
	v_lshl_add_u64 v[144:145], s[74:75], 0, v[128:129]
	s_add_i32 m0, s0, 0x2000
	s_mov_b64 s[74:75], s[42:43]
	global_load_lds_dwordx4 v[144:145], off
	s_mov_b32 m0, s35
	s_nop 0
	global_load_lds_dwordx4 v134, s[74:75]
	s_mov_b32 m0, s51
	s_nop 0
	global_load_lds_dwordx4 v130, s[74:75]
	s_waitcnt vmcnt(8)
	s_waitcnt lgkmcnt(0)
	s_barrier
; #define PG8_STAGE(bufoff, gbase, voff) do { const char* _gb = (const char*)(gbase); asm volatile("" : "+s"(_gb));     \
;         _Pragma("unroll") for (int _i = 0; _i < 2; ++_i) \
;         __builtin_amdgcn_global_load_lds((const unsigned*)(_gb + (voff)[_i]), (LAS unsigned*)(lds + (bufoff) + ldsw + _i * 8192), 16, 0, 0); } while (0)
; #define PG8_LDA(dst, b, h) do { _Pragma("unroll") for (int m = 0; m < 4; ++m) _Pragma("unroll") for (int k = 0; k < 2; ++k) dst[m][k] = *(const LAS bf16x8*)(lds + PG8_SA(b, h) + aoff + m * 2048 + k * 1024); } while (0)
; #define PG8_LDB(dst, b, h) do { _Pragma("unroll") for (int n = 0; n < 2; ++n) _Pragma("unroll") for (int k = 0; k < 2; ++k) dst[n][k] = *(const LAS bf16x8*)(lds + PG8_SB(b, h) + boff + n * 2048 + k * 1024); } while (0)
; #define PG8_MMA(ai, bj, At, Bt) do { __builtin_amdgcn_s_setprio(1); _Pragma("unroll") for (int m = 0; m < 4; ++m) _Pragma("unroll") for (int n = 0; n < 2; ++n) _Pragma("unroll") for (int k = 0; k < 2; ++k) \
;         acc[ai][bj][m][n] = __builtin_amdgcn_mfma_f32_16x16x32_bf16(Bt[n][k], At[m][k], acc[ai][bj][m][n], 0, 0, 0); __builtin_amdgcn_s_setprio(0); } while (0)
; #define PG8_WAIT_V(n) asm volatile("s_waitcnt vmcnt(" #n ")" ::: "memory")
; #define PG8_WAIT_L(n) asm volatile("s_waitcnt lgkmcnt(" #n ")" ::: "memory")
; #define PG8_BAR __builtin_amdgcn_s_barrier()
; #define PG8_SCHED __builtin_amdgcn_sched_barrier(0)
; template <class Epi>
; __device__ __forceinline__ void gemm_phase(LAS unsigned char* lds, const int wid, const Gemm g, const Epi& E) {
;     ...
;             PG8_WAIT_V(8); PG8_WAIT_L(0); PG8_BAR; PG8_MMA(1, 0, At, B0); PG8_MMA(1, 1, At, B1); PG8_BAR; PG8_SCHED;
;             PG8_LDB(B0, 1, 0); PG8_LDB(B1, 1, 1); PG8_SCHED; PG8_LDA(At, 1, 0); PG8_STAGE(PG8_SA(0, 1), a2 + hstepA, voffA);
;             PG8_WAIT_V(8); PG8_WAIT_L(0); PG8_BAR; PG8_MMA(0, 0, At, B0); PG8_MMA(0, 1, At, B1); PG8_BAR; PG8_SCHED;
	s_setprio 1
	s_waitcnt lgkmcnt(0)
	v_mfma_f32_16x16x32_bf16 v[60:63], v[140:143], v[180:183], v[60:63]
	v_mfma_f32_16x16x32_bf16 v[56:59], v[156:159], v[180:183], v[56:59]
	v_mfma_f32_16x16x32_bf16 v[44:47], v[140:143], v[188:191], v[44:47]
	v_mfma_f32_16x16x32_bf16 v[40:43], v[156:159], v[188:191], v[40:43]
	v_mfma_f32_16x16x32_bf16 v[28:31], v[140:143], v[196:199], v[28:31]
	v_mfma_f32_16x16x32_bf16 v[24:27], v[156:159], v[196:199], v[24:27]
	v_mfma_f32_16x16x32_bf16 v[12:15], v[140:143], v[206:209], v[12:15]
	v_mfma_f32_16x16x32_bf16 v[8:11], v[156:159], v[206:209], v[8:11]
	v_mfma_f32_16x16x32_bf16 v[60:63], v[152:155], v[184:187], v[60:63]
	v_mfma_f32_16x16x32_bf16 v[56:59], v[160:163], v[184:187], v[56:59]
	v_mfma_f32_16x16x32_bf16 v[44:47], v[152:155], v[192:195], v[44:47]
	v_mfma_f32_16x16x32_bf16 v[40:43], v[160:163], v[192:195], v[40:43]
	v_mfma_f32_16x16x32_bf16 v[28:31], v[152:155], v[200:203], v[28:31]
	v_mfma_f32_16x16x32_bf16 v[24:27], v[160:163], v[200:203], v[24:27]
	v_mfma_f32_16x16x32_bf16 v[12:15], v[152:155], v[210:213], v[12:15]
	v_mfma_f32_16x16x32_bf16 v[8:11], v[160:163], v[210:213], v[8:11]
	s_setprio 0
	s_setprio 1
	v_mfma_f32_16x16x32_bf16 v[52:55], v[164:167], v[180:183], v[52:55]
	v_mfma_f32_16x16x32_bf16 v[48:51], v[172:175], v[180:183], v[48:51]
	v_mfma_f32_16x16x32_bf16 v[36:39], v[164:167], v[188:191], v[36:39]
	v_mfma_f32_16x16x32_bf16 v[32:35], v[172:175], v[188:191], v[32:35]
	v_mfma_f32_16x16x32_bf16 v[20:23], v[164:167], v[196:199], v[20:23]
	v_mfma_f32_16x16x32_bf16 v[16:19], v[172:175], v[196:199], v[16:19]
	v_mfma_f32_16x16x32_bf16 v[4:7], v[164:167], v[206:209], v[4:7]
	v_mfma_f32_16x16x32_bf16 v[0:3], v[172:175], v[206:209], v[0:3]
	v_mfma_f32_16x16x32_bf16 v[52:55], v[168:171], v[184:187], v[52:55]
	v_mfma_f32_16x16x32_bf16 v[48:51], v[176:179], v[184:187], v[48:51]
	v_mfma_f32_16x16x32_bf16 v[36:39], v[168:171], v[192:195], v[36:39]
	v_mfma_f32_16x16x32_bf16 v[32:35], v[176:179], v[192:195], v[32:35]
	v_mfma_f32_16x16x32_bf16 v[20:23], v[168:171], v[200:203], v[20:23]
	v_mfma_f32_16x16x32_bf16 v[16:19], v[176:179], v[200:203], v[16:19]
	v_mfma_f32_16x16x32_bf16 v[4:7], v[168:171], v[210:213], v[4:7]
	v_mfma_f32_16x16x32_bf16 v[0:3], v[176:179], v[210:213], v[0:3]
	s_setprio 0
	s_barrier
	s_add_i32 s0, 0, 0x18000
	v_add_u32_e32 v144, s0, v148
	s_add_i32 s1, 0, 0x1c000
	ds_read_b128 v[140:143], v144
	ds_read_b128 v[152:155], v144 offset:1024
	ds_read_b128 v[156:159], v144 offset:2048
	ds_read_b128 v[160:163], v144 offset:3072
	v_add_u32_e32 v144, s1, v148
	ds_read_b128 v[164:167], v144
	ds_read_b128 v[168:171], v144 offset:1024
	ds_read_b128 v[172:175], v144 offset:2048
	ds_read_b128 v[176:179], v144 offset:3072
	s_add_u32 s42, s42, 0x40000
	s_addc_u32 s43, s43, 0
	s_mov_b32 m0, s52
	ds_read_b128 v[180:183], v151 offset:32768
	ds_read_b128 v[184:187], v151 offset:33792
	ds_read_b128 v[188:191], v151 offset:34816
	ds_read_b128 v[192:195], v151 offset:35840
	ds_read_b128 v[196:199], v151 offset:36864
	ds_read_b128 v[200:203], v151 offset:37888
	ds_read_b128 v[206:209], v151 offset:38912
	ds_read_b128 v[210:213], v151 offset:39936
	s_nop 0
	global_load_lds_dwordx4 v134, s[42:43]
	s_mov_b32 m0, s53
	s_nop 0
	global_load_lds_dwordx4 v130, s[42:43]
	s_waitcnt vmcnt(8)
	s_waitcnt lgkmcnt(0)
	s_barrier
	s_setprio 1
	s_waitcnt lgkmcnt(0)
	v_mfma_f32_16x16x32_bf16 v[124:127], v[140:143], v[180:183], v[124:127]
	v_mfma_f32_16x16x32_bf16 v[120:123], v[156:159], v[180:183], v[120:123]
	v_mfma_f32_16x16x32_bf16 v[108:111], v[140:143], v[188:191], v[108:111]
	v_mfma_f32_16x16x32_bf16 v[104:107], v[156:159], v[188:191], v[104:107]
	v_mfma_f32_16x16x32_bf16 v[92:95], v[140:143], v[196:199], v[92:95]
	v_mfma_f32_16x16x32_bf16 v[88:91], v[156:159], v[196:199], v[88:91]
	v_mfma_f32_16x16x32_bf16 v[76:79], v[140:143], v[206:209], v[76:79]
	v_mfma_f32_16x16x32_bf16 v[72:75], v[156:159], v[206:209], v[72:75]
	v_mfma_f32_16x16x32_bf16 v[124:127], v[152:155], v[184:187], v[124:127]
	v_mfma_f32_16x16x32_bf16 v[120:123], v[160:163], v[184:187], v[120:123]
	v_mfma_f32_16x16x32_bf16 v[108:111], v[152:155], v[192:195], v[108:111]
	v_mfma_f32_16x16x32_bf16 v[104:107], v[160:163], v[192:195], v[104:107]
	v_mfma_f32_16x16x32_bf16 v[92:95], v[152:155], v[200:203], v[92:95]
	v_mfma_f32_16x16x32_bf16 v[88:91], v[160:163], v[200:203], v[88:91]
	v_mfma_f32_16x16x32_bf16 v[76:79], v[152:155], v[210:213], v[76:79]
	v_mfma_f32_16x16x32_bf16 v[72:75], v[160:163], v[210:213], v[72:75]
	s_setprio 0
	s_setprio 1
	v_mfma_f32_16x16x32_bf16 v[116:119], v[164:167], v[180:183], v[116:119]
	v_mfma_f32_16x16x32_bf16 v[112:115], v[172:175], v[180:183], v[112:115]
	v_mfma_f32_16x16x32_bf16 v[100:103], v[164:167], v[188:191], v[100:103]
	v_mfma_f32_16x16x32_bf16 v[96:99], v[172:175], v[188:191], v[96:99]
	v_mfma_f32_16x16x32_bf16 v[84:87], v[164:167], v[196:199], v[84:87]
	v_mfma_f32_16x16x32_bf16 v[80:83], v[172:175], v[196:199], v[80:83]
	v_mfma_f32_16x16x32_bf16 v[68:71], v[164:167], v[206:209], v[68:71]
	v_mfma_f32_16x16x32_bf16 v[64:67], v[172:175], v[206:209], v[64:67]
	v_mfma_f32_16x16x32_bf16 v[116:119], v[168:171], v[184:187], v[116:119]
	v_mfma_f32_16x16x32_bf16 v[112:115], v[176:179], v[184:187], v[112:115]
	v_mfma_f32_16x16x32_bf16 v[100:103], v[168:171], v[192:195], v[100:103]
	v_mfma_f32_16x16x32_bf16 v[96:99], v[176:179], v[192:195], v[96:99]
	v_mfma_f32_16x16x32_bf16 v[84:87], v[168:171], v[200:203], v[84:87]
	v_mfma_f32_16x16x32_bf16 v[80:83], v[176:179], v[200:203], v[80:83]
	v_mfma_f32_16x16x32_bf16 v[68:71], v[168:171], v[210:213], v[68:71]
	v_mfma_f32_16x16x32_bf16 v[64:67], v[176:179], v[210:213], v[64:67]
	s_setprio 0
	s_barrier
; #define PG8_STAGE(bufoff, gbase, voff) do { const char* _gb = (const char*)(gbase); asm volatile("" : "+s"(_gb));     \
;         _Pragma("unroll") for (int _i = 0; _i < 2; ++_i) \
;         __builtin_amdgcn_global_load_lds((const unsigned*)(_gb + (voff)[_i]), (LAS unsigned*)(lds + (bufoff) + ldsw + _i * 8192), 16, 0, 0); } while (0)
; #define PG8_LDA(dst, b, h) do { _Pragma("unroll") for (int m = 0; m < 4; ++m) _Pragma("unroll") for (int k = 0; k < 2; ++k) dst[m][k] = *(const LAS bf16x8*)(lds + PG8_SA(b, h) + aoff + m * 2048 + k * 1024); } while (0)
; #define PG8_MMA(ai, bj, At, Bt) do { __builtin_amdgcn_s_setprio(1); _Pragma("unroll") for (int m = 0; m < 4; ++m) _Pragma("unroll") for (int n = 0; n < 2; ++n) _Pragma("unroll") for (int k = 0; k < 2; ++k) \
;         acc[ai][bj][m][n] = __builtin_amdgcn_mfma_f32_16x16x32_bf16(Bt[n][k], At[m][k], acc[ai][bj][m][n], 0, 0, 0); __builtin_amdgcn_s_setprio(0); } while (0)
; #define PG8_WAIT_V(n) asm volatile("s_waitcnt vmcnt(" #n ")" ::: "memory")
; #define PG8_WAIT_L(n) asm volatile("s_waitcnt lgkmcnt(" #n ")" ::: "memory")
; #define PG8_BAR __builtin_amdgcn_s_barrier()
; #define PG8_SCHED __builtin_amdgcn_sched_barrier(0)
; template <class Epi>
; __device__ __forceinline__ void gemm_phase(LAS unsigned char* lds, const int wid, const Gemm g, const Epi& E) {
;     ...
;             PG8_WAIT_V(8); PG8_WAIT_L(0); PG8_BAR; PG8_MMA(0, 0, At, B0); PG8_MMA(0, 1, At, B1); PG8_BAR; PG8_SCHED;
;             PG8_LDA(At, 1, 1); PG8_STAGE(PG8_SB(1, 0), b3, voffB); PG8_STAGE(PG8_SB(1, 1), b3 + hstepB, voffB); PG8_STAGE(PG8_SA(1, 0), a3, voffA);
;             PG8_WAIT_V(8); PG8_WAIT_L(0); PG8_BAR; PG8_MMA(1, 0, At, B0); PG8_MMA(1, 1, At, B1); PG8_BAR; PG8_SCHED;
;         }
;         if (wr == 0) PG8_BAR;
	s_mov_b64 s[42:43], s[44:45]
	s_add_i32 s0, s0, s23
	ds_read_b128 v[180:183], v151 offset:49152
	ds_read_b128 v[184:187], v151 offset:50176
	ds_read_b128 v[188:191], v151 offset:51200
	ds_read_b128 v[192:195], v151 offset:52224
	ds_read_b128 v[196:199], v151 offset:53248
	ds_read_b128 v[200:203], v151 offset:54272
	ds_read_b128 v[206:209], v151 offset:55296
	ds_read_b128 v[210:213], v151 offset:56320
	s_mov_b32 m0, s0
	s_nop 0
	global_load_lds_dwordx4 v132, s[42:43]
	s_add_i32 m0, s0, 0x2000
	v_lshl_add_u64 v[144:145], s[42:43], 0, v[128:129]
	s_add_u32 s42, s44, 0x40000
	s_addc_u32 s43, s45, 0
	s_add_i32 s0, s1, s23
	global_load_lds_dwordx4 v[144:145], off
	s_mov_b32 m0, s0
	s_nop 0
	global_load_lds_dwordx4 v132, s[42:43]
	s_add_i32 m0, s0, 0x2000
	s_nop 0
	global_load_lds_dwordx4 v128, s[42:43]
	s_mov_b32 m0, s57
	s_nop 0
	global_load_lds_dwordx4 v134, s[40:41]
	s_mov_b32 m0, s58
	s_nop 0
	global_load_lds_dwordx4 v130, s[40:41]
	s_waitcnt vmcnt(8)
	s_waitcnt lgkmcnt(0)
	s_barrier
	s_setprio 1
	s_waitcnt lgkmcnt(0)
	v_mfma_f32_16x16x32_bf16 v[60:63], v[140:143], v[180:183], v[60:63]
	v_mfma_f32_16x16x32_bf16 v[56:59], v[156:159], v[180:183], v[56:59]
	v_mfma_f32_16x16x32_bf16 v[44:47], v[140:143], v[188:191], v[44:47]
	v_mfma_f32_16x16x32_bf16 v[40:43], v[156:159], v[188:191], v[40:43]
	v_mfma_f32_16x16x32_bf16 v[28:31], v[140:143], v[196:199], v[28:31]
	v_mfma_f32_16x16x32_bf16 v[24:27], v[156:159], v[196:199], v[24:27]
	v_mfma_f32_16x16x32_bf16 v[12:15], v[140:143], v[206:209], v[12:15]
	v_mfma_f32_16x16x32_bf16 v[8:11], v[156:159], v[206:209], v[8:11]
	v_mfma_f32_16x16x32_bf16 v[60:63], v[152:155], v[184:187], v[60:63]
	v_mfma_f32_16x16x32_bf16 v[56:59], v[160:163], v[184:187], v[56:59]
	v_mfma_f32_16x16x32_bf16 v[44:47], v[152:155], v[192:195], v[44:47]
	v_mfma_f32_16x16x32_bf16 v[40:43], v[160:163], v[192:195], v[40:43]
	v_mfma_f32_16x16x32_bf16 v[28:31], v[152:155], v[200:203], v[28:31]
	v_mfma_f32_16x16x32_bf16 v[24:27], v[160:163], v[200:203], v[24:27]
	v_mfma_f32_16x16x32_bf16 v[12:15], v[152:155], v[210:213], v[12:15]
	v_mfma_f32_16x16x32_bf16 v[8:11], v[160:163], v[210:213], v[8:11]
	s_setprio 0
	s_setprio 1
	v_mfma_f32_16x16x32_bf16 v[52:55], v[164:167], v[180:183], v[52:55]
	v_mfma_f32_16x16x32_bf16 v[48:51], v[172:175], v[180:183], v[48:51]
	v_mfma_f32_16x16x32_bf16 v[36:39], v[164:167], v[188:191], v[36:39]
	v_mfma_f32_16x16x32_bf16 v[32:35], v[172:175], v[188:191], v[32:35]
	v_mfma_f32_16x16x32_bf16 v[20:23], v[164:167], v[196:199], v[20:23]
	v_mfma_f32_16x16x32_bf16 v[16:19], v[172:175], v[196:199], v[16:19]
	v_mfma_f32_16x16x32_bf16 v[4:7], v[164:167], v[206:209], v[4:7]
	v_mfma_f32_16x16x32_bf16 v[0:3], v[172:175], v[206:209], v[0:3]
	v_mfma_f32_16x16x32_bf16 v[52:55], v[168:171], v[184:187], v[52:55]
	v_mfma_f32_16x16x32_bf16 v[48:51], v[176:179], v[184:187], v[48:51]
	v_mfma_f32_16x16x32_bf16 v[36:39], v[168:171], v[192:195], v[36:39]
	v_mfma_f32_16x16x32_bf16 v[32:35], v[176:179], v[192:195], v[32:35]
	v_mfma_f32_16x16x32_bf16 v[20:23], v[168:171], v[200:203], v[20:23]
	v_mfma_f32_16x16x32_bf16 v[16:19], v[176:179], v[200:203], v[16:19]
	v_mfma_f32_16x16x32_bf16 v[4:7], v[168:171], v[210:213], v[4:7]
	v_mfma_f32_16x16x32_bf16 v[0:3], v[176:179], v[210:213], v[0:3]
	s_setprio 0
	s_barrier
	s_add_i32 s72, s72, 2
	s_add_u32 s70, s70, 0x100
	s_addc_u32 s71, s71, 0
	s_add_u32 s38, s38, 0x100
	s_addc_u32 s39, s39, 0
	s_cmp_gt_u32 s72, 13
	s_cbranch_scc0 .LBB0_1398
	s_and_b64 vcc, exec, s[10:11]
	s_cbranch_vccz .LBB0_1401
	s_barrier

; #define PG8_STAGE(bufoff, gbase, voff) do { const char* _gb = (const char*)(gbase); asm volatile("" : "+s"(_gb));     \
;         _Pragma("unroll") for (int _i = 0; _i < 2; ++_i) \
;         __builtin_amdgcn_global_load_lds((const unsigned*)(_gb + (voff)[_i]), (LAS unsigned*)(lds + (bufoff) + ldsw + _i * 8192), 16, 0, 0); } while (0)
; #define PG8_WAIT_V(n) asm volatile("s_waitcnt vmcnt(" #n ")" ::: "memory")
; #define PG8_BAR __builtin_amdgcn_s_barrier()
; template <class Epi>
; __device__ __forceinline__ void gemm_phase(LAS unsigned char* lds, const int wid, const Gemm g, const Epi& E) {
;     ...
;     const char* cA = PG8_UA(cur); const char* cB = PG8_UB(cur);
;     PG8_STAGE(PG8_SB(0, 0), PG8_BP(cB, 0), voffB); PG8_STAGE(PG8_SB(0, 1), PG8_BP(cB, 0) + hstepB, voffB); PG8_STAGE(PG8_SA(0, 0), PG8_AP(cA, 0), voffA); PG8_STAGE(PG8_SA(0, 1), PG8_AP(cA, 0) + hstepA, voffA);
;     if (wr == 1) PG8_BAR;
;     PG8_WAIT_V(2); PG8_BAR;
;     PG8_STAGE(PG8_SB(1, 0), PG8_BP(cB, 1), voffB); PG8_STAGE(PG8_SA(1, 0), PG8_AP(cA, 1), voffA); PG8_STAGE(PG8_SB(1, 1), PG8_BP(cB, 1) + hstepB, voffB);
;     PG8_WAIT_V(6); PG8_BAR;
;     for (;;) {
;         const bool has_next = S.next(ui + 1, nxt);
;         const char* nA = has_next ? PG8_UA(nxt) : cA; const char* nB = has_next ? PG8_UB(nxt) : cB;
.LBB0_1524:
	s_lshl_b32 s1, s33, 5
	s_and_b32 s47, s1, 0x60
	s_lshl_b32 s46, s13, 6
	s_lshl_b32 s0, s13, 13
	s_lshr_b32 s1, s47, 3
	s_cmp_lt_u32 s33, 4
	s_cselect_b64 s[8:9], -1, 0
	s_add_u32 s10, s3, 0x9800000
	s_addc_u32 s11, s12, 0
	s_add_u32 s12, s24, 0x80
	s_addc_u32 s13, s25, 0
	s_waitcnt vmcnt(2)
	s_barrier
	s_add_i32 m0, s21, 0x18000
	s_nop 0
	global_load_lds_dwordx4 v132, s[12:13]
	s_add_i32 m0, s21, 0x1a000
	v_lshl_add_u64 v[0:1], s[12:13], 0, v[128:129]
	s_add_u32 s12, s26, 0x80
	s_addc_u32 s13, s27, 0
	s_add_i32 s48, s21, 0x8000
	global_load_lds_dwordx4 v[0:1], off
	s_mov_b32 m0, s48
	s_add_i32 s49, s21, 0xa000
	global_load_lds_dwordx4 v134, s[12:13]
	v_lshl_add_u64 v[0:1], s[12:13], 0, v[130:131]
	s_add_u32 s12, s24, 0x40080
	s_mov_b32 m0, s49
	s_addc_u32 s13, s25, 0
	global_load_lds_dwordx4 v[0:1], off
	s_add_i32 m0, s21, 0x1c000
	s_nop 0
	global_load_lds_dwordx4 v132, s[12:13]
	s_add_i32 m0, s21, 0x1e000
	v_lshlrev_b32_e32 v3, 6, v141
	global_load_lds_dwordx4 v128, s[12:13]
	v_ashrrev_i32_e32 v0, 6, v141
	v_and_b32_e32 v1, 48, v141
	v_lshl_add_u32 v2, v0, 10, s0
	s_movk_i32 s0, 0x3c0
	v_and_or_b32 v1, v3, s0, v1
	v_lshlrev_b32_e32 v3, 2, v141
	v_and_b32_e32 v3, 32, v3
	v_add_lshl_u32 v0, v0, s1, 10
	s_waitcnt vmcnt(6)
	v_bitop3_b32 v2, v1, v2, v3 bitop3:0xde
	v_bitop3_b32 v142, v1, v0, v3 bitop3:0xde
	s_add_i32 s52, 0, 0x10000
	s_add_i32 s53, 0, 0x14000
	s_sext_i32_i16 s55, s2
	s_mov_b32 s50, 0
	s_waitcnt lgkmcnt(0)
	s_ashr_i32 s51, s45, 31
	v_mov_b64_e32 v[136:137], 0xb00
	v_mov_b64_e32 v[138:139], 0xaff
	v_add_u32_e32 v143, s52, v142
	v_add_u32_e32 v144, s53, v142
	v_add_u32_e32 v145, 0, v2
	s_movk_i32 s54, 0x1600
	s_barrier
	s_branch .LBB0_1527

; #define PG8_STAGE(bufoff, gbase, voff) do { const char* _gb = (const char*)(gbase); asm volatile("" : "+s"(_gb));     \
;         _Pragma("unroll") for (int _i = 0; _i < 2; ++_i) \
;         __builtin_amdgcn_global_load_lds((const unsigned*)(_gb + (voff)[_i]), (LAS unsigned*)(lds + (bufoff) + ldsw + _i * 8192), 16, 0, 0); } while (0)
; #define PG8_LDA(dst, b, h) do { _Pragma("unroll") for (int m = 0; m < 4; ++m) _Pragma("unroll") for (int k = 0; k < 2; ++k) dst[m][k] = *(const LAS bf16x8*)(lds + PG8_SA(b, h) + aoff + m * 2048 + k * 1024); } while (0)
; #define PG8_LDB(dst, b, h) do { _Pragma("unroll") for (int n = 0; n < 2; ++n) _Pragma("unroll") for (int k = 0; k < 2; ++k) dst[n][k] = *(const LAS bf16x8*)(lds + PG8_SB(b, h) + boff + n * 2048 + k * 1024); } while (0)
; #define PG8_MMA(ai, bj, At, Bt) do { __builtin_amdgcn_s_setprio(1); _Pragma("unroll") for (int m = 0; m < 4; ++m) _Pragma("unroll") for (int n = 0; n < 2; ++n) _Pragma("unroll") for (int k = 0; k < 2; ++k) \
;         acc[ai][bj][m][n] = __builtin_amdgcn_mfma_f32_16x16x32_bf16(Bt[n][k], At[m][k], acc[ai][bj][m][n], 0, 0, 0); __builtin_amdgcn_s_setprio(0); } while (0)
; #define PG8_WAIT_V(n) asm volatile("s_waitcnt vmcnt(" #n ")" ::: "memory")
; #define PG8_WAIT_L(n) asm volatile("s_waitcnt lgkmcnt(" #n ")" ::: "memory")
; #define PG8_BAR __builtin_amdgcn_s_barrier()
; template <class Epi>
; __device__ __forceinline__ void gemm_phase(LAS unsigned char* lds, const int wid, const Gemm g, const Epi& E) {
;     ...
;             const bool last = (t == nt - 2);
;             const char* a1 = PG8_AP(cA, t + 1);
;             const char* a2 = last ? PG8_AP(nA, 0) : PG8_AP(cA, t + 2); const char* b2 = last ? PG8_BP(nB, 0) : PG8_BP(cB, t + 2);
;             const char* a3 = last ? PG8_AP(nA, 1) : PG8_AP(cA, t + 3); const char* b3 = last ? PG8_BP(nB, 1) : PG8_BP(cB, t + 3);
;             PG8_LDB(B0, 0, 0); PG8_LDB(B1, 0, 1); PG8_SCHED; PG8_LDA(At, 0, 0); PG8_STAGE(PG8_SA(1, 1), a1 + hstepA, voffA);
;             PG8_WAIT_V(8); PG8_WAIT_L(0); PG8_BAR; PG8_MMA(0, 0, At, B0); PG8_MMA(0, 1, At, B1); PG8_BAR; PG8_SCHED;
;             PG8_LDA(At, 0, 1); PG8_STAGE(PG8_SB(0, 0), b2, voffB); PG8_STAGE(PG8_SB(0, 1), b2 + hstepB, voffB); PG8_STAGE(PG8_SA(0, 0), a2, voffA);
;             PG8_WAIT_V(8); PG8_WAIT_L(0); PG8_BAR; PG8_MMA(1, 0, At, B0); PG8_MMA(1, 1, At, B1); PG8_BAR; PG8_SCHED;
.LBB0_1530:
	ds_read_b128 v[146:149], v143
	ds_read_b128 v[150:153], v143 offset:1024
	ds_read_b128 v[154:157], v143 offset:2048
	ds_read_b128 v[158:161], v143 offset:3072
	ds_read_b128 v[162:165], v144
	ds_read_b128 v[166:169], v144 offset:1024
	ds_read_b128 v[170:173], v144 offset:2048
	ds_read_b128 v[174:177], v144 offset:3072
	s_add_u32 s0, s24, 0xfffc0080
	s_addc_u32 s1, s25, -1
	s_add_u32 s26, s62, 0xffffff80
	s_addc_u32 s27, s63, -1
	s_add_u32 s30, s24, 0xfffc0100
	s_addc_u32 s31, s25, -1
	s_add_i32 s68, s52, s23
	s_add_i32 m0, s21, 0xc000
	s_add_i32 s65, s21, 0xe000
	s_add_i32 s69, s68, 0x2000
	s_cmp_eq_u32 s64, 12
	s_cselect_b32 s29, s15, s1
	s_cselect_b32 s28, s56, s0
	s_cselect_b32 s67, s13, s27
	s_cselect_b32 s66, s57, s26
	s_cselect_b32 s27, s59, s31
	s_cselect_b32 s26, s58, s30
	s_mov_b64 s[30:31], s[24:25]
	ds_read_b128 v[178:181], v145
	ds_read_b128 v[182:185], v145 offset:1024
	ds_read_b128 v[186:189], v145 offset:2048
	ds_read_b128 v[190:193], v145 offset:3072
	ds_read_b128 v[194:197], v145 offset:4096
	ds_read_b128 v[198:201], v145 offset:5120
	ds_read_b128 v[206:209], v145 offset:6144
	ds_read_b128 v[210:213], v145 offset:7168
	s_nop 0
	global_load_lds_dwordx4 v134, s[30:31]
	s_mov_b32 m0, s65
	s_nop 0
	global_load_lds_dwordx4 v130, s[30:31]
	s_waitcnt vmcnt(8)
	s_waitcnt lgkmcnt(0)
	s_barrier
	s_setprio 1
	s_waitcnt lgkmcnt(0)
	v_mfma_f32_16x16x32_bf16 v[124:127], v[146:149], v[178:181], v[124:127]
	v_mfma_f32_16x16x32_bf16 v[120:123], v[154:157], v[178:181], v[120:123]
	v_mfma_f32_16x16x32_bf16 v[108:111], v[146:149], v[186:189], v[108:111]
	v_mfma_f32_16x16x32_bf16 v[104:107], v[154:157], v[186:189], v[104:107]
	v_mfma_f32_16x16x32_bf16 v[92:95], v[146:149], v[194:197], v[92:95]
	v_mfma_f32_16x16x32_bf16 v[88:91], v[154:157], v[194:197], v[88:91]
	v_mfma_f32_16x16x32_bf16 v[76:79], v[146:149], v[206:209], v[76:79]
	v_mfma_f32_16x16x32_bf16 v[72:75], v[154:157], v[206:209], v[72:75]
	v_mfma_f32_16x16x32_bf16 v[124:127], v[150:153], v[182:185], v[124:127]
	v_mfma_f32_16x16x32_bf16 v[120:123], v[158:161], v[182:185], v[120:123]
	v_mfma_f32_16x16x32_bf16 v[108:111], v[150:153], v[190:193], v[108:111]
	v_mfma_f32_16x16x32_bf16 v[104:107], v[158:161], v[190:193], v[104:107]
	v_mfma_f32_16x16x32_bf16 v[92:95], v[150:153], v[198:201], v[92:95]
	v_mfma_f32_16x16x32_bf16 v[88:91], v[158:161], v[198:201], v[88:91]
	v_mfma_f32_16x16x32_bf16 v[76:79], v[150:153], v[210:213], v[76:79]
	v_mfma_f32_16x16x32_bf16 v[72:75], v[158:161], v[210:213], v[72:75]
	s_setprio 0
	s_setprio 1
	v_mfma_f32_16x16x32_bf16 v[116:119], v[162:165], v[178:181], v[116:119]
	v_mfma_f32_16x16x32_bf16 v[112:115], v[170:173], v[178:181], v[112:115]
	v_mfma_f32_16x16x32_bf16 v[100:103], v[162:165], v[186:189], v[100:103]
	v_mfma_f32_16x16x32_bf16 v[96:99], v[170:173], v[186:189], v[96:99]
	v_mfma_f32_16x16x32_bf16 v[84:87], v[162:165], v[194:197], v[84:87]
	v_mfma_f32_16x16x32_bf16 v[80:83], v[170:173], v[194:197], v[80:83]
	v_mfma_f32_16x16x32_bf16 v[68:71], v[162:165], v[206:209], v[68:71]
	v_mfma_f32_16x16x32_bf16 v[64:67], v[170:173], v[206:209], v[64:67]
	v_mfma_f32_16x16x32_bf16 v[116:119], v[166:169], v[182:185], v[116:119]
	v_mfma_f32_16x16x32_bf16 v[112:115], v[174:177], v[182:185], v[112:115]
	v_mfma_f32_16x16x32_bf16 v[100:103], v[166:169], v[190:193], v[100:103]
	v_mfma_f32_16x16x32_bf16 v[96:99], v[174:177], v[190:193], v[96:99]
	v_mfma_f32_16x16x32_bf16 v[84:87], v[166:169], v[198:201], v[84:87]
	v_mfma_f32_16x16x32_bf16 v[80:83], v[174:177], v[198:201], v[80:83]
	v_mfma_f32_16x16x32_bf16 v[68:71], v[166:169], v[210:213], v[68:71]
	v_mfma_f32_16x16x32_bf16 v[64:67], v[174:177], v[210:213], v[64:67]
	s_setprio 0
	s_barrier
	s_mov_b64 s[30:31], s[66:67]
	s_mov_b32 m0, s68
	ds_read_b128 v[178:181], v145 offset:16384
	ds_read_b128 v[182:185], v145 offset:17408
	ds_read_b128 v[186:189], v145 offset:18432
	ds_read_b128 v[190:193], v145 offset:19456
	ds_read_b128 v[194:197], v145 offset:20480
	ds_read_b128 v[198:201], v145 offset:21504
	ds_read_b128 v[206:209], v145 offset:22528
	ds_read_b128 v[210:213], v145 offset:23552
	s_nop 0
	global_load_lds_dwordx4 v132, s[30:31]
	v_lshl_add_u64 v[202:203], s[30:31], 0, v[128:129]
	s_cselect_b32 s31, s61, s63
	s_cselect_b32 s30, s60, s62
	s_add_u32 s66, s66, 0x40000
	s_mov_b32 m0, s69
	s_addc_u32 s67, s67, 0
	s_add_i32 s0, s53, s23
	global_load_lds_dwordx4 v[202:203], off
	s_mov_b32 m0, s0
	s_nop 0
	global_load_lds_dwordx4 v132, s[66:67]
	v_lshl_add_u64 v[202:203], s[66:67], 0, v[128:129]
	s_add_i32 m0, s0, 0x2000
	s_mov_b64 s[66:67], s[28:29]
	global_load_lds_dwordx4 v[202:203], off
	s_mov_b32 m0, s21
	s_nop 0
	global_load_lds_dwordx4 v134, s[66:67]
	s_mov_b32 m0, s42
	s_nop 0
	global_load_lds_dwordx4 v130, s[66:67]
	s_waitcnt vmcnt(8)
	s_waitcnt lgkmcnt(0)
	s_barrier
; #define PG8_STAGE(bufoff, gbase, voff) do { const char* _gb = (const char*)(gbase); asm volatile("" : "+s"(_gb));     \
;         _Pragma("unroll") for (int _i = 0; _i < 2; ++_i) \
;         __builtin_amdgcn_global_load_lds((const unsigned*)(_gb + (voff)[_i]), (LAS unsigned*)(lds + (bufoff) + ldsw + _i * 8192), 16, 0, 0); } while (0)
; #define PG8_LDA(dst, b, h) do { _Pragma("unroll") for (int m = 0; m < 4; ++m) _Pragma("unroll") for (int k = 0; k < 2; ++k) dst[m][k] = *(const LAS bf16x8*)(lds + PG8_SA(b, h) + aoff + m * 2048 + k * 1024); } while (0)
; #define PG8_LDB(dst, b, h) do { _Pragma("unroll") for (int n = 0; n < 2; ++n) _Pragma("unroll") for (int k = 0; k < 2; ++k) dst[n][k] = *(const LAS bf16x8*)(lds + PG8_SB(b, h) + boff + n * 2048 + k * 1024); } while (0)
; #define PG8_MMA(ai, bj, At, Bt) do { __builtin_amdgcn_s_setprio(1); _Pragma("unroll") for (int m = 0; m < 4; ++m) _Pragma("unroll") for (int n = 0; n < 2; ++n) _Pragma("unroll") for (int k = 0; k < 2; ++k) \
;         acc[ai][bj][m][n] = __builtin_amdgcn_mfma_f32_16x16x32_bf16(Bt[n][k], At[m][k], acc[ai][bj][m][n], 0, 0, 0); __builtin_amdgcn_s_setprio(0); } while (0)
; #define PG8_WAIT_V(n) asm volatile("s_waitcnt vmcnt(" #n ")" ::: "memory")
; #define PG8_WAIT_L(n) asm volatile("s_waitcnt lgkmcnt(" #n ")" ::: "memory")
; #define PG8_BAR __builtin_amdgcn_s_barrier()
; #define PG8_SCHED __builtin_amdgcn_sched_barrier(0)
; template <class Epi>
; __device__ __forceinline__ void gemm_phase(LAS unsigned char* lds, const int wid, const Gemm g, const Epi& E) {
;     ...
;             PG8_WAIT_V(8); PG8_WAIT_L(0); PG8_BAR; PG8_MMA(1, 0, At, B0); PG8_MMA(1, 1, At, B1); PG8_BAR; PG8_SCHED;
;             PG8_LDB(B0, 1, 0); PG8_LDB(B1, 1, 1); PG8_SCHED; PG8_LDA(At, 1, 0); PG8_STAGE(PG8_SA(0, 1), a2 + hstepA, voffA);
;             PG8_WAIT_V(8); PG8_WAIT_L(0); PG8_BAR; PG8_MMA(0, 0, At, B0); PG8_MMA(0, 1, At, B1); PG8_BAR; PG8_SCHED;
	s_setprio 1
	s_waitcnt lgkmcnt(0)
	v_mfma_f32_16x16x32_bf16 v[60:63], v[146:149], v[178:181], v[60:63]
	v_mfma_f32_16x16x32_bf16 v[56:59], v[154:157], v[178:181], v[56:59]
	v_mfma_f32_16x16x32_bf16 v[44:47], v[146:149], v[186:189], v[44:47]
	v_mfma_f32_16x16x32_bf16 v[40:43], v[154:157], v[186:189], v[40:43]
	v_mfma_f32_16x16x32_bf16 v[28:31], v[146:149], v[194:197], v[28:31]
	v_mfma_f32_16x16x32_bf16 v[24:27], v[154:157], v[194:197], v[24:27]
	v_mfma_f32_16x16x32_bf16 v[12:15], v[146:149], v[206:209], v[12:15]
	v_mfma_f32_16x16x32_bf16 v[8:11], v[154:157], v[206:209], v[8:11]
	v_mfma_f32_16x16x32_bf16 v[60:63], v[150:153], v[182:185], v[60:63]
	v_mfma_f32_16x16x32_bf16 v[56:59], v[158:161], v[182:185], v[56:59]
	v_mfma_f32_16x16x32_bf16 v[44:47], v[150:153], v[190:193], v[44:47]
	v_mfma_f32_16x16x32_bf16 v[40:43], v[158:161], v[190:193], v[40:43]
	v_mfma_f32_16x16x32_bf16 v[28:31], v[150:153], v[198:201], v[28:31]
	v_mfma_f32_16x16x32_bf16 v[24:27], v[158:161], v[198:201], v[24:27]
	v_mfma_f32_16x16x32_bf16 v[12:15], v[150:153], v[210:213], v[12:15]
	v_mfma_f32_16x16x32_bf16 v[8:11], v[158:161], v[210:213], v[8:11]
	s_setprio 0
	s_setprio 1
	v_mfma_f32_16x16x32_bf16 v[52:55], v[162:165], v[178:181], v[52:55]
	v_mfma_f32_16x16x32_bf16 v[48:51], v[170:173], v[178:181], v[48:51]
	v_mfma_f32_16x16x32_bf16 v[36:39], v[162:165], v[186:189], v[36:39]
	v_mfma_f32_16x16x32_bf16 v[32:35], v[170:173], v[186:189], v[32:35]
	v_mfma_f32_16x16x32_bf16 v[20:23], v[162:165], v[194:197], v[20:23]
	v_mfma_f32_16x16x32_bf16 v[16:19], v[170:173], v[194:197], v[16:19]
	v_mfma_f32_16x16x32_bf16 v[4:7], v[162:165], v[206:209], v[4:7]
	v_mfma_f32_16x16x32_bf16 v[0:3], v[170:173], v[206:209], v[0:3]
	v_mfma_f32_16x16x32_bf16 v[52:55], v[166:169], v[182:185], v[52:55]
	v_mfma_f32_16x16x32_bf16 v[48:51], v[174:177], v[182:185], v[48:51]
	v_mfma_f32_16x16x32_bf16 v[36:39], v[166:169], v[190:193], v[36:39]
	v_mfma_f32_16x16x32_bf16 v[32:35], v[174:177], v[190:193], v[32:35]
	v_mfma_f32_16x16x32_bf16 v[20:23], v[166:169], v[198:201], v[20:23]
	v_mfma_f32_16x16x32_bf16 v[16:19], v[174:177], v[198:201], v[16:19]
	v_mfma_f32_16x16x32_bf16 v[4:7], v[166:169], v[210:213], v[4:7]
	v_mfma_f32_16x16x32_bf16 v[0:3], v[174:177], v[210:213], v[0:3]
	s_setprio 0
	s_barrier
	s_add_i32 s0, 0, 0x18000
	s_add_i32 s1, 0, 0x1c000
	v_add_u32_e32 v158, s0, v142
	v_add_u32_e32 v174, s1, v142
	ds_read_b128 v[146:149], v158
	ds_read_b128 v[150:153], v158 offset:1024
	ds_read_b128 v[154:157], v158 offset:2048
	ds_read_b128 v[158:161], v158 offset:3072
	ds_read_b128 v[162:165], v174
	ds_read_b128 v[166:169], v174 offset:1024
	ds_read_b128 v[170:173], v174 offset:2048
	ds_read_b128 v[174:177], v174 offset:3072
	s_add_u32 s28, s28, 0x40000
	s_addc_u32 s29, s29, 0
	s_mov_b32 m0, s43
	ds_read_b128 v[178:181], v145 offset:32768
	ds_read_b128 v[182:185], v145 offset:33792
	ds_read_b128 v[186:189], v145 offset:34816
	ds_read_b128 v[190:193], v145 offset:35840
	ds_read_b128 v[194:197], v145 offset:36864
	ds_read_b128 v[198:201], v145 offset:37888
	ds_read_b128 v[206:209], v145 offset:38912
	ds_read_b128 v[210:213], v145 offset:39936
	s_nop 0
	global_load_lds_dwordx4 v134, s[28:29]
	s_mov_b32 m0, s44
	s_nop 0
	global_load_lds_dwordx4 v130, s[28:29]
	s_waitcnt vmcnt(8)
	s_waitcnt lgkmcnt(0)
	s_barrier
	s_setprio 1
	s_waitcnt lgkmcnt(0)
	v_mfma_f32_16x16x32_bf16 v[124:127], v[146:149], v[178:181], v[124:127]
	v_mfma_f32_16x16x32_bf16 v[120:123], v[154:157], v[178:181], v[120:123]
	v_mfma_f32_16x16x32_bf16 v[108:111], v[146:149], v[186:189], v[108:111]
	v_mfma_f32_16x16x32_bf16 v[104:107], v[154:157], v[186:189], v[104:107]
	v_mfma_f32_16x16x32_bf16 v[92:95], v[146:149], v[194:197], v[92:95]
	v_mfma_f32_16x16x32_bf16 v[88:91], v[154:157], v[194:197], v[88:91]
	v_mfma_f32_16x16x32_bf16 v[76:79], v[146:149], v[206:209], v[76:79]
	v_mfma_f32_16x16x32_bf16 v[72:75], v[154:157], v[206:209], v[72:75]
	v_mfma_f32_16x16x32_bf16 v[124:127], v[150:153], v[182:185], v[124:127]
	v_mfma_f32_16x16x32_bf16 v[120:123], v[158:161], v[182:185], v[120:123]
	v_mfma_f32_16x16x32_bf16 v[108:111], v[150:153], v[190:193], v[108:111]
	v_mfma_f32_16x16x32_bf16 v[104:107], v[158:161], v[190:193], v[104:107]
	v_mfma_f32_16x16x32_bf16 v[92:95], v[150:153], v[198:201], v[92:95]
	v_mfma_f32_16x16x32_bf16 v[88:91], v[158:161], v[198:201], v[88:91]
	v_mfma_f32_16x16x32_bf16 v[76:79], v[150:153], v[210:213], v[76:79]
	v_mfma_f32_16x16x32_bf16 v[72:75], v[158:161], v[210:213], v[72:75]
	s_setprio 0
	s_setprio 1
	v_mfma_f32_16x16x32_bf16 v[116:119], v[162:165], v[178:181], v[116:119]
	v_mfma_f32_16x16x32_bf16 v[112:115], v[170:173], v[178:181], v[112:115]
	v_mfma_f32_16x16x32_bf16 v[100:103], v[162:165], v[186:189], v[100:103]
	v_mfma_f32_16x16x32_bf16 v[96:99], v[170:173], v[186:189], v[96:99]
	v_mfma_f32_16x16x32_bf16 v[84:87], v[162:165], v[194:197], v[84:87]
	v_mfma_f32_16x16x32_bf16 v[80:83], v[170:173], v[194:197], v[80:83]
	v_mfma_f32_16x16x32_bf16 v[68:71], v[162:165], v[206:209], v[68:71]
	v_mfma_f32_16x16x32_bf16 v[64:67], v[170:173], v[206:209], v[64:67]
	v_mfma_f32_16x16x32_bf16 v[116:119], v[166:169], v[182:185], v[116:119]
	v_mfma_f32_16x16x32_bf16 v[112:115], v[174:177], v[182:185], v[112:115]
	v_mfma_f32_16x16x32_bf16 v[100:103], v[166:169], v[190:193], v[100:103]
	v_mfma_f32_16x16x32_bf16 v[96:99], v[174:177], v[190:193], v[96:99]
	v_mfma_f32_16x16x32_bf16 v[84:87], v[166:169], v[198:201], v[84:87]
	v_mfma_f32_16x16x32_bf16 v[80:83], v[174:177], v[198:201], v[80:83]
	v_mfma_f32_16x16x32_bf16 v[68:71], v[166:169], v[210:213], v[68:71]
	v_mfma_f32_16x16x32_bf16 v[64:67], v[174:177], v[210:213], v[64:67]
	s_setprio 0
	s_barrier
; #define PG8_STAGE(bufoff, gbase, voff) do { const char* _gb = (const char*)(gbase); asm volatile("" : "+s"(_gb));     \
;         _Pragma("unroll") for (int _i = 0; _i < 2; ++_i) \
;         __builtin_amdgcn_global_load_lds((const unsigned*)(_gb + (voff)[_i]), (LAS unsigned*)(lds + (bufoff) + ldsw + _i * 8192), 16, 0, 0); } while (0)
; #define PG8_LDA(dst, b, h) do { _Pragma("unroll") for (int m = 0; m < 4; ++m) _Pragma("unroll") for (int k = 0; k < 2; ++k) dst[m][k] = *(const LAS bf16x8*)(lds + PG8_SA(b, h) + aoff + m * 2048 + k * 1024); } while (0)
; #define PG8_MMA(ai, bj, At, Bt) do { __builtin_amdgcn_s_setprio(1); _Pragma("unroll") for (int m = 0; m < 4; ++m) _Pragma("unroll") for (int n = 0; n < 2; ++n) _Pragma("unroll") for (int k = 0; k < 2; ++k) \
;         acc[ai][bj][m][n] = __builtin_amdgcn_mfma_f32_16x16x32_bf16(Bt[n][k], At[m][k], acc[ai][bj][m][n], 0, 0, 0); __builtin_amdgcn_s_setprio(0); } while (0)
; #define PG8_WAIT_V(n) asm volatile("s_waitcnt vmcnt(" #n ")" ::: "memory")
; #define PG8_WAIT_L(n) asm volatile("s_waitcnt lgkmcnt(" #n ")" ::: "memory")
; #define PG8_BAR __builtin_amdgcn_s_barrier()
; #define PG8_SCHED __builtin_amdgcn_sched_barrier(0)
; template <class Epi>
; __device__ __forceinline__ void gemm_phase(LAS unsigned char* lds, const int wid, const Gemm g, const Epi& E) {
;     ...
;             PG8_WAIT_V(8); PG8_WAIT_L(0); PG8_BAR; PG8_MMA(0, 0, At, B0); PG8_MMA(0, 1, At, B1); PG8_BAR; PG8_SCHED;
;             PG8_LDA(At, 1, 1); PG8_STAGE(PG8_SB(1, 0), b3, voffB); PG8_STAGE(PG8_SB(1, 1), b3 + hstepB, voffB); PG8_STAGE(PG8_SA(1, 0), a3, voffA);
;             PG8_WAIT_V(8); PG8_WAIT_L(0); PG8_BAR; PG8_MMA(1, 0, At, B0); PG8_MMA(1, 1, At, B1); PG8_BAR; PG8_SCHED;
;         }
;         if (wr == 0) PG8_BAR;
	s_mov_b64 s[28:29], s[30:31]
	s_add_i32 s0, s0, s23
	ds_read_b128 v[178:181], v145 offset:49152
	ds_read_b128 v[182:185], v145 offset:50176
	ds_read_b128 v[186:189], v145 offset:51200
	ds_read_b128 v[190:193], v145 offset:52224
	ds_read_b128 v[194:197], v145 offset:53248
	ds_read_b128 v[198:201], v145 offset:54272
	ds_read_b128 v[206:209], v145 offset:55296
	ds_read_b128 v[210:213], v145 offset:56320
	s_mov_b32 m0, s0
	s_nop 0
	global_load_lds_dwordx4 v132, s[28:29]
	s_add_i32 m0, s0, 0x2000
	v_lshl_add_u64 v[202:203], s[28:29], 0, v[128:129]
	s_add_u32 s28, s30, 0x40000
	s_addc_u32 s29, s31, 0
	s_add_i32 s0, s1, s23
	global_load_lds_dwordx4 v[202:203], off
	s_mov_b32 m0, s0
	s_nop 0
	global_load_lds_dwordx4 v132, s[28:29]
	s_add_i32 m0, s0, 0x2000
	s_nop 0
	global_load_lds_dwordx4 v128, s[28:29]
	s_mov_b32 m0, s48
	s_nop 0
	global_load_lds_dwordx4 v134, s[26:27]
	s_mov_b32 m0, s49
	s_nop 0
	global_load_lds_dwordx4 v130, s[26:27]
	s_waitcnt vmcnt(8)
	s_waitcnt lgkmcnt(0)
	s_barrier
	s_setprio 1
	s_waitcnt lgkmcnt(0)
	v_mfma_f32_16x16x32_bf16 v[60:63], v[146:149], v[178:181], v[60:63]
	v_mfma_f32_16x16x32_bf16 v[56:59], v[154:157], v[178:181], v[56:59]
	v_mfma_f32_16x16x32_bf16 v[44:47], v[146:149], v[186:189], v[44:47]
	v_mfma_f32_16x16x32_bf16 v[40:43], v[154:157], v[186:189], v[40:43]
	v_mfma_f32_16x16x32_bf16 v[28:31], v[146:149], v[194:197], v[28:31]
	v_mfma_f32_16x16x32_bf16 v[24:27], v[154:157], v[194:197], v[24:27]
	v_mfma_f32_16x16x32_bf16 v[12:15], v[146:149], v[206:209], v[12:15]
	v_mfma_f32_16x16x32_bf16 v[8:11], v[154:157], v[206:209], v[8:11]
	v_mfma_f32_16x16x32_bf16 v[60:63], v[150:153], v[182:185], v[60:63]
	v_mfma_f32_16x16x32_bf16 v[56:59], v[158:161], v[182:185], v[56:59]
	v_mfma_f32_16x16x32_bf16 v[44:47], v[150:153], v[190:193], v[44:47]
	v_mfma_f32_16x16x32_bf16 v[40:43], v[158:161], v[190:193], v[40:43]
	v_mfma_f32_16x16x32_bf16 v[28:31], v[150:153], v[198:201], v[28:31]
	v_mfma_f32_16x16x32_bf16 v[24:27], v[158:161], v[198:201], v[24:27]
	v_mfma_f32_16x16x32_bf16 v[12:15], v[150:153], v[210:213], v[12:15]
	v_mfma_f32_16x16x32_bf16 v[8:11], v[158:161], v[210:213], v[8:11]
	s_setprio 0
	s_setprio 1
	v_mfma_f32_16x16x32_bf16 v[52:55], v[162:165], v[178:181], v[52:55]
	v_mfma_f32_16x16x32_bf16 v[48:51], v[170:173], v[178:181], v[48:51]
	v_mfma_f32_16x16x32_bf16 v[36:39], v[162:165], v[186:189], v[36:39]
	v_mfma_f32_16x16x32_bf16 v[32:35], v[170:173], v[186:189], v[32:35]
	v_mfma_f32_16x16x32_bf16 v[20:23], v[162:165], v[194:197], v[20:23]
	v_mfma_f32_16x16x32_bf16 v[16:19], v[170:173], v[194:197], v[16:19]
	v_mfma_f32_16x16x32_bf16 v[4:7], v[162:165], v[206:209], v[4:7]
	v_mfma_f32_16x16x32_bf16 v[0:3], v[170:173], v[206:209], v[0:3]
	v_mfma_f32_16x16x32_bf16 v[52:55], v[166:169], v[182:185], v[52:55]
	v_mfma_f32_16x16x32_bf16 v[48:51], v[174:177], v[182:185], v[48:51]
	v_mfma_f32_16x16x32_bf16 v[36:39], v[166:169], v[190:193], v[36:39]
	v_mfma_f32_16x16x32_bf16 v[32:35], v[174:177], v[190:193], v[32:35]
	v_mfma_f32_16x16x32_bf16 v[20:23], v[166:169], v[198:201], v[20:23]
	v_mfma_f32_16x16x32_bf16 v[16:19], v[174:177], v[198:201], v[16:19]
	v_mfma_f32_16x16x32_bf16 v[4:7], v[166:169], v[210:213], v[4:7]
	v_mfma_f32_16x16x32_bf16 v[0:3], v[174:177], v[210:213], v[0:3]
	s_setprio 0
	s_barrier
	s_add_i32 s64, s64, 2
	s_add_u32 s62, s62, 0x100
	s_addc_u32 s63, s63, 0
	s_add_u32 s24, s24, 0x100
	s_addc_u32 s25, s25, 0
	s_cmp_gt_u32 s64, 13
	s_cbranch_scc0 .LBB0_1530
	s_and_b64 vcc, exec, s[8:9]
	s_cbranch_vccz .LBB0_1533
	s_barrier

; #define PG8_STAGE(bufoff, gbase, voff) do { const char* _gb = (const char*)(gbase); asm volatile("" : "+s"(_gb));     \
;         _Pragma("unroll") for (int _i = 0; _i < 2; ++_i) \
;         __builtin_amdgcn_global_load_lds((const unsigned*)(_gb + (voff)[_i]), (LAS unsigned*)(lds + (bufoff) + ldsw + _i * 8192), 16, 0, 0); } while (0)
; #define PG8_WAIT_V(n) asm volatile("s_waitcnt vmcnt(" #n ")" ::: "memory")
; #define PG8_BAR __builtin_amdgcn_s_barrier()
; template <class Epi>
; __device__ __forceinline__ void gemm_phase(LAS unsigned char* lds, const int wid, const Gemm g, const Epi& E) {
;     ...
;     const char* cA = PG8_UA(cur); const char* cB = PG8_UB(cur);
;     PG8_STAGE(PG8_SB(0, 0), PG8_BP(cB, 0), voffB); PG8_STAGE(PG8_SB(0, 1), PG8_BP(cB, 0) + hstepB, voffB); PG8_STAGE(PG8_SA(0, 0), PG8_AP(cA, 0), voffA); PG8_STAGE(PG8_SA(0, 1), PG8_AP(cA, 0) + hstepA, voffA);
;     if (wr == 1) PG8_BAR;
;     PG8_WAIT_V(2); PG8_BAR;
;     PG8_STAGE(PG8_SB(1, 0), PG8_BP(cB, 1), voffB); PG8_STAGE(PG8_SA(1, 0), PG8_AP(cA, 1), voffA); PG8_STAGE(PG8_SB(1, 1), PG8_BP(cB, 1) + hstepB, voffB);
;     PG8_WAIT_V(6); PG8_BAR;
;     for (;;) {
;         const bool has_next = S.next(ui + 1, nxt);
;         const char* nA = has_next ? PG8_UA(nxt) : cA; const char* nB = has_next ? PG8_UB(nxt) : cB;
.LBB0_1590:
	s_lshl_b32 s1, s33, 5
	s_and_b32 s51, s1, 0x60
	s_lshl_b32 s50, s10, 6
	s_lshl_b32 s0, s10, 13
	s_lshr_b32 s1, s51, 3
	s_cmp_lt_u32 s33, 4
	s_cselect_b64 s[10:11], -1, 0
	s_add_u32 s12, s12, 0x5800000
	s_addc_u32 s13, s13, 0
	s_add_u32 s14, s14, 0x5800000
	s_addc_u32 s15, s15, 0
	s_add_u32 s2, s28, 0x80
	s_addc_u32 s3, s29, 0
	s_waitcnt vmcnt(2)
	s_barrier
	s_add_i32 m0, s45, 0x18000
	s_nop 0
	global_load_lds_dwordx4 v132, s[2:3]
	s_add_i32 m0, s45, 0x1a000
	v_lshl_add_u64 v[0:1], s[2:3], 0, v[128:129]
	s_add_u32 s2, s30, 0x80
	s_addc_u32 s3, s31, 0
	s_add_i32 s52, s45, 0x8000
	global_load_lds_dwordx4 v[0:1], off
	s_mov_b32 m0, s52
	s_add_i32 s53, s45, 0xa000
	global_load_lds_dwordx4 v134, s[2:3]
	v_lshl_add_u64 v[0:1], s[2:3], 0, v[130:131]
	s_add_u32 s2, s28, 0xb0080
	s_mov_b32 m0, s53
	s_addc_u32 s3, s29, 0
	global_load_lds_dwordx4 v[0:1], off
	s_add_i32 m0, s45, 0x1c000
	s_nop 0
	global_load_lds_dwordx4 v132, s[2:3]
	s_add_i32 m0, s45, 0x1e000
	v_lshlrev_b32_e32 v3, 6, v147
	global_load_lds_dwordx4 v128, s[2:3]
	v_ashrrev_i32_e32 v0, 6, v147
	v_and_b32_e32 v1, 48, v147
	v_lshl_add_u32 v2, v0, 10, s0
	s_movk_i32 s0, 0x3c0
	v_and_or_b32 v1, v3, s0, v1
	v_lshlrev_b32_e32 v3, 2, v147
	v_and_b32_e32 v3, 32, v3
	v_add_lshl_u32 v0, v0, s1, 10
	s_waitcnt vmcnt(6)
	v_bitop3_b32 v2, v1, v2, v3 bitop3:0xde
	v_bitop3_b32 v148, v1, v0, v3 bitop3:0xde
	s_add_i32 s56, 0, 0x10000
	s_add_i32 s57, 0, 0x14000
	s_sext_i32_i8 s61, s16
	s_mov_b32 s54, 0
	s_waitcnt lgkmcnt(0)
	s_ashr_i32 s55, s49, 31
	v_mov_b64_e32 v[136:137], 0x200
	v_mov_b64_e32 v[138:139], 0x1ff
	v_add_u32_e32 v149, s56, v148
	v_add_u32_e32 v150, s57, v148
	v_add_u32_e32 v151, 0, v2
	s_mov_b64 s[16:17], 0x40000
	s_mov_b64 s[18:19], 0x48000
	s_mov_b64 s[20:21], 0x50000
	s_mov_b64 s[24:25], 0x58000
	s_barrier
	s_branch .LBB0_1593

; #define PG8_STAGE(bufoff, gbase, voff) do { const char* _gb = (const char*)(gbase); asm volatile("" : "+s"(_gb));     \
;         _Pragma("unroll") for (int _i = 0; _i < 2; ++_i) \
;         __builtin_amdgcn_global_load_lds((const unsigned*)(_gb + (voff)[_i]), (LAS unsigned*)(lds + (bufoff) + ldsw + _i * 8192), 16, 0, 0); } while (0)
; #define PG8_LDA(dst, b, h) do { _Pragma("unroll") for (int m = 0; m < 4; ++m) _Pragma("unroll") for (int k = 0; k < 2; ++k) dst[m][k] = *(const LAS bf16x8*)(lds + PG8_SA(b, h) + aoff + m * 2048 + k * 1024); } while (0)
; #define PG8_LDB(dst, b, h) do { _Pragma("unroll") for (int n = 0; n < 2; ++n) _Pragma("unroll") for (int k = 0; k < 2; ++k) dst[n][k] = *(const LAS bf16x8*)(lds + PG8_SB(b, h) + boff + n * 2048 + k * 1024); } while (0)
; #define PG8_MMA(ai, bj, At, Bt) do { __builtin_amdgcn_s_setprio(1); _Pragma("unroll") for (int m = 0; m < 4; ++m) _Pragma("unroll") for (int n = 0; n < 2; ++n) _Pragma("unroll") for (int k = 0; k < 2; ++k) \
;         acc[ai][bj][m][n] = __builtin_amdgcn_mfma_f32_16x16x32_bf16(Bt[n][k], At[m][k], acc[ai][bj][m][n], 0, 0, 0); __builtin_amdgcn_s_setprio(0); } while (0)
; #define PG8_WAIT_V(n) asm volatile("s_waitcnt vmcnt(" #n ")" ::: "memory")
; #define PG8_WAIT_L(n) asm volatile("s_waitcnt lgkmcnt(" #n ")" ::: "memory")
; #define PG8_BAR __builtin_amdgcn_s_barrier()
; template <class Epi>
; __device__ __forceinline__ void gemm_phase(LAS unsigned char* lds, const int wid, const Gemm g, const Epi& E) {
;     ...
;             const bool last = (t == nt - 2);
;             const char* a1 = PG8_AP(cA, t + 1);
;             const char* a2 = last ? PG8_AP(nA, 0) : PG8_AP(cA, t + 2); const char* b2 = last ? PG8_BP(nB, 0) : PG8_BP(cB, t + 2);
;             const char* a3 = last ? PG8_AP(nA, 1) : PG8_AP(cA, t + 3); const char* b3 = last ? PG8_BP(nB, 1) : PG8_BP(cB, t + 3);
;             PG8_LDB(B0, 0, 0); PG8_LDB(B1, 0, 1); PG8_SCHED; PG8_LDA(At, 0, 0); PG8_STAGE(PG8_SA(1, 1), a1 + hstepA, voffA);
;             PG8_WAIT_V(8); PG8_WAIT_L(0); PG8_BAR; PG8_MMA(0, 0, At, B0); PG8_MMA(0, 1, At, B1); PG8_BAR; PG8_SCHED;
;             PG8_LDA(At, 0, 1); PG8_STAGE(PG8_SB(0, 0), b2, voffB); PG8_STAGE(PG8_SB(0, 1), b2 + hstepB, voffB); PG8_STAGE(PG8_SA(0, 0), a2, voffA);
;             PG8_WAIT_V(8); PG8_WAIT_L(0); PG8_BAR; PG8_MMA(1, 0, At, B0); PG8_MMA(1, 1, At, B1); PG8_BAR; PG8_SCHED;
.LBB0_1604:
	ds_read_b128 v[140:143], v149
	ds_read_b128 v[152:155], v149 offset:1024
	ds_read_b128 v[156:159], v149 offset:2048
	ds_read_b128 v[160:163], v149 offset:3072
	ds_read_b128 v[164:167], v150
	ds_read_b128 v[168:171], v150 offset:1024
	ds_read_b128 v[172:175], v150 offset:2048
	ds_read_b128 v[176:179], v150 offset:3072
	s_add_u32 s0, s28, 0xfff50080
	s_addc_u32 s1, s29, -1
	s_add_u32 s30, s66, 0xffffff80
	s_addc_u32 s31, s67, -1
	s_add_u32 s38, s28, 0xfff50100
	s_addc_u32 s39, s29, -1
	s_add_i32 s72, s56, s23
	s_add_i32 m0, s45, 0xc000
	s_add_i32 s69, s45, 0xe000
	s_add_i32 s73, s72, 0x2000
	s_cmp_eq_u32 s68, 40
	s_cselect_b32 s35, s5, s1
	s_cselect_b32 s34, s4, s0
	s_cselect_b32 s71, s27, s31
	s_cselect_b32 s70, s26, s30
	s_cselect_b32 s31, s63, s39
	s_cselect_b32 s30, s62, s38
	s_mov_b64 s[38:39], s[28:29]
	ds_read_b128 v[180:183], v151
	ds_read_b128 v[184:187], v151 offset:1024
	ds_read_b128 v[188:191], v151 offset:2048
	ds_read_b128 v[192:195], v151 offset:3072
	ds_read_b128 v[196:199], v151 offset:4096
	ds_read_b128 v[200:203], v151 offset:5120
	ds_read_b128 v[206:209], v151 offset:6144
	ds_read_b128 v[210:213], v151 offset:7168
	s_nop 0
	global_load_lds_dwordx4 v134, s[38:39]
	s_mov_b32 m0, s69
	s_nop 0
	global_load_lds_dwordx4 v130, s[38:39]
	s_waitcnt vmcnt(8)
	s_waitcnt lgkmcnt(0)
	s_barrier
	s_setprio 1
	s_waitcnt lgkmcnt(0)
	v_mfma_f32_16x16x32_bf16 v[124:127], v[140:143], v[180:183], v[124:127]
	v_mfma_f32_16x16x32_bf16 v[120:123], v[156:159], v[180:183], v[120:123]
	v_mfma_f32_16x16x32_bf16 v[108:111], v[140:143], v[188:191], v[108:111]
	v_mfma_f32_16x16x32_bf16 v[104:107], v[156:159], v[188:191], v[104:107]
	v_mfma_f32_16x16x32_bf16 v[92:95], v[140:143], v[196:199], v[92:95]
	v_mfma_f32_16x16x32_bf16 v[88:91], v[156:159], v[196:199], v[88:91]
	v_mfma_f32_16x16x32_bf16 v[76:79], v[140:143], v[206:209], v[76:79]
	v_mfma_f32_16x16x32_bf16 v[72:75], v[156:159], v[206:209], v[72:75]
	v_mfma_f32_16x16x32_bf16 v[124:127], v[152:155], v[184:187], v[124:127]
	v_mfma_f32_16x16x32_bf16 v[120:123], v[160:163], v[184:187], v[120:123]
	v_mfma_f32_16x16x32_bf16 v[108:111], v[152:155], v[192:195], v[108:111]
	v_mfma_f32_16x16x32_bf16 v[104:107], v[160:163], v[192:195], v[104:107]
	v_mfma_f32_16x16x32_bf16 v[92:95], v[152:155], v[200:203], v[92:95]
	v_mfma_f32_16x16x32_bf16 v[88:91], v[160:163], v[200:203], v[88:91]
	v_mfma_f32_16x16x32_bf16 v[76:79], v[152:155], v[210:213], v[76:79]
	v_mfma_f32_16x16x32_bf16 v[72:75], v[160:163], v[210:213], v[72:75]
	s_setprio 0
	s_setprio 1
	v_mfma_f32_16x16x32_bf16 v[116:119], v[164:167], v[180:183], v[116:119]
	v_mfma_f32_16x16x32_bf16 v[112:115], v[172:175], v[180:183], v[112:115]
	v_mfma_f32_16x16x32_bf16 v[100:103], v[164:167], v[188:191], v[100:103]
	v_mfma_f32_16x16x32_bf16 v[96:99], v[172:175], v[188:191], v[96:99]
	v_mfma_f32_16x16x32_bf16 v[84:87], v[164:167], v[196:199], v[84:87]
	v_mfma_f32_16x16x32_bf16 v[80:83], v[172:175], v[196:199], v[80:83]
	v_mfma_f32_16x16x32_bf16 v[68:71], v[164:167], v[206:209], v[68:71]
	v_mfma_f32_16x16x32_bf16 v[64:67], v[172:175], v[206:209], v[64:67]
	v_mfma_f32_16x16x32_bf16 v[116:119], v[168:171], v[184:187], v[116:119]
	v_mfma_f32_16x16x32_bf16 v[112:115], v[176:179], v[184:187], v[112:115]
	v_mfma_f32_16x16x32_bf16 v[100:103], v[168:171], v[192:195], v[100:103]
	v_mfma_f32_16x16x32_bf16 v[96:99], v[176:179], v[192:195], v[96:99]
	v_mfma_f32_16x16x32_bf16 v[84:87], v[168:171], v[200:203], v[84:87]
	v_mfma_f32_16x16x32_bf16 v[80:83], v[176:179], v[200:203], v[80:83]
	v_mfma_f32_16x16x32_bf16 v[68:71], v[168:171], v[210:213], v[68:71]
	v_mfma_f32_16x16x32_bf16 v[64:67], v[176:179], v[210:213], v[64:67]
	s_setprio 0
	s_barrier
	s_mov_b64 s[38:39], s[70:71]
	s_mov_b32 m0, s72
	ds_read_b128 v[180:183], v151 offset:16384
	ds_read_b128 v[184:187], v151 offset:17408
	ds_read_b128 v[188:191], v151 offset:18432
	ds_read_b128 v[192:195], v151 offset:19456
	ds_read_b128 v[196:199], v151 offset:20480
	ds_read_b128 v[200:203], v151 offset:21504
	ds_read_b128 v[206:209], v151 offset:22528
	ds_read_b128 v[210:213], v151 offset:23552
	s_nop 0
	global_load_lds_dwordx4 v132, s[38:39]
	v_lshl_add_u64 v[144:145], s[38:39], 0, v[128:129]
	s_cselect_b32 s39, s65, s67
	s_cselect_b32 s38, s64, s66
	s_add_u32 s70, s70, 0xb0000
	s_mov_b32 m0, s73
	s_addc_u32 s71, s71, 0
	s_add_i32 s0, s57, s23
	global_load_lds_dwordx4 v[144:145], off
	s_mov_b32 m0, s0
	s_nop 0
	global_load_lds_dwordx4 v132, s[70:71]
	v_lshl_add_u64 v[144:145], s[70:71], 0, v[128:129]
	s_add_i32 m0, s0, 0x2000
	s_mov_b64 s[70:71], s[34:35]
	global_load_lds_dwordx4 v[144:145], off
	s_mov_b32 m0, s45
	s_nop 0
	global_load_lds_dwordx4 v134, s[70:71]
	s_mov_b32 m0, s46
	s_nop 0
	global_load_lds_dwordx4 v130, s[70:71]
	s_waitcnt vmcnt(8)
	s_waitcnt lgkmcnt(0)
	s_barrier
; #define PG8_STAGE(bufoff, gbase, voff) do { const char* _gb = (const char*)(gbase); asm volatile("" : "+s"(_gb));     \
;         _Pragma("unroll") for (int _i = 0; _i < 2; ++_i) \
;         __builtin_amdgcn_global_load_lds((const unsigned*)(_gb + (voff)[_i]), (LAS unsigned*)(lds + (bufoff) + ldsw + _i * 8192), 16, 0, 0); } while (0)
; #define PG8_LDA(dst, b, h) do { _Pragma("unroll") for (int m = 0; m < 4; ++m) _Pragma("unroll") for (int k = 0; k < 2; ++k) dst[m][k] = *(const LAS bf16x8*)(lds + PG8_SA(b, h) + aoff + m * 2048 + k * 1024); } while (0)
; #define PG8_LDB(dst, b, h) do { _Pragma("unroll") for (int n = 0; n < 2; ++n) _Pragma("unroll") for (int k = 0; k < 2; ++k) dst[n][k] = *(const LAS bf16x8*)(lds + PG8_SB(b, h) + boff + n * 2048 + k * 1024); } while (0)
; #define PG8_MMA(ai, bj, At, Bt) do { __builtin_amdgcn_s_setprio(1); _Pragma("unroll") for (int m = 0; m < 4; ++m) _Pragma("unroll") for (int n = 0; n < 2; ++n) _Pragma("unroll") for (int k = 0; k < 2; ++k) \
;         acc[ai][bj][m][n] = __builtin_amdgcn_mfma_f32_16x16x32_bf16(Bt[n][k], At[m][k], acc[ai][bj][m][n], 0, 0, 0); __builtin_amdgcn_s_setprio(0); } while (0)
; #define PG8_WAIT_V(n) asm volatile("s_waitcnt vmcnt(" #n ")" ::: "memory")
; #define PG8_WAIT_L(n) asm volatile("s_waitcnt lgkmcnt(" #n ")" ::: "memory")
; #define PG8_BAR __builtin_amdgcn_s_barrier()
; #define PG8_SCHED __builtin_amdgcn_sched_barrier(0)
; template <class Epi>
; __device__ __forceinline__ void gemm_phase(LAS unsigned char* lds, const int wid, const Gemm g, const Epi& E) {
;     ...
;             PG8_WAIT_V(8); PG8_WAIT_L(0); PG8_BAR; PG8_MMA(1, 0, At, B0); PG8_MMA(1, 1, At, B1); PG8_BAR; PG8_SCHED;
;             PG8_LDB(B0, 1, 0); PG8_LDB(B1, 1, 1); PG8_SCHED; PG8_LDA(At, 1, 0); PG8_STAGE(PG8_SA(0, 1), a2 + hstepA, voffA);
;             PG8_WAIT_V(8); PG8_WAIT_L(0); PG8_BAR; PG8_MMA(0, 0, At, B0); PG8_MMA(0, 1, At, B1); PG8_BAR; PG8_SCHED;
	s_setprio 1
	s_waitcnt lgkmcnt(0)
	v_mfma_f32_16x16x32_bf16 v[60:63], v[140:143], v[180:183], v[60:63]
	v_mfma_f32_16x16x32_bf16 v[56:59], v[156:159], v[180:183], v[56:59]
	v_mfma_f32_16x16x32_bf16 v[44:47], v[140:143], v[188:191], v[44:47]
	v_mfma_f32_16x16x32_bf16 v[40:43], v[156:159], v[188:191], v[40:43]
	v_mfma_f32_16x16x32_bf16 v[28:31], v[140:143], v[196:199], v[28:31]
	v_mfma_f32_16x16x32_bf16 v[24:27], v[156:159], v[196:199], v[24:27]
	v_mfma_f32_16x16x32_bf16 v[12:15], v[140:143], v[206:209], v[12:15]
	v_mfma_f32_16x16x32_bf16 v[8:11], v[156:159], v[206:209], v[8:11]
	v_mfma_f32_16x16x32_bf16 v[60:63], v[152:155], v[184:187], v[60:63]
	v_mfma_f32_16x16x32_bf16 v[56:59], v[160:163], v[184:187], v[56:59]
	v_mfma_f32_16x16x32_bf16 v[44:47], v[152:155], v[192:195], v[44:47]
	v_mfma_f32_16x16x32_bf16 v[40:43], v[160:163], v[192:195], v[40:43]
	v_mfma_f32_16x16x32_bf16 v[28:31], v[152:155], v[200:203], v[28:31]
	v_mfma_f32_16x16x32_bf16 v[24:27], v[160:163], v[200:203], v[24:27]
	v_mfma_f32_16x16x32_bf16 v[12:15], v[152:155], v[210:213], v[12:15]
	v_mfma_f32_16x16x32_bf16 v[8:11], v[160:163], v[210:213], v[8:11]
	s_setprio 0
	s_setprio 1
	v_mfma_f32_16x16x32_bf16 v[52:55], v[164:167], v[180:183], v[52:55]
	v_mfma_f32_16x16x32_bf16 v[48:51], v[172:175], v[180:183], v[48:51]
	v_mfma_f32_16x16x32_bf16 v[36:39], v[164:167], v[188:191], v[36:39]
	v_mfma_f32_16x16x32_bf16 v[32:35], v[172:175], v[188:191], v[32:35]
	v_mfma_f32_16x16x32_bf16 v[20:23], v[164:167], v[196:199], v[20:23]
	v_mfma_f32_16x16x32_bf16 v[16:19], v[172:175], v[196:199], v[16:19]
	v_mfma_f32_16x16x32_bf16 v[4:7], v[164:167], v[206:209], v[4:7]
	v_mfma_f32_16x16x32_bf16 v[0:3], v[172:175], v[206:209], v[0:3]
	v_mfma_f32_16x16x32_bf16 v[52:55], v[168:171], v[184:187], v[52:55]
	v_mfma_f32_16x16x32_bf16 v[48:51], v[176:179], v[184:187], v[48:51]
	v_mfma_f32_16x16x32_bf16 v[36:39], v[168:171], v[192:195], v[36:39]
	v_mfma_f32_16x16x32_bf16 v[32:35], v[176:179], v[192:195], v[32:35]
	v_mfma_f32_16x16x32_bf16 v[20:23], v[168:171], v[200:203], v[20:23]
	v_mfma_f32_16x16x32_bf16 v[16:19], v[176:179], v[200:203], v[16:19]
	v_mfma_f32_16x16x32_bf16 v[4:7], v[168:171], v[210:213], v[4:7]
	v_mfma_f32_16x16x32_bf16 v[0:3], v[176:179], v[210:213], v[0:3]
	s_setprio 0
	s_barrier
	s_add_i32 s0, 0, 0x18000
	v_add_u32_e32 v144, s0, v148
	s_add_i32 s1, 0, 0x1c000
	ds_read_b128 v[140:143], v144
	ds_read_b128 v[152:155], v144 offset:1024
	ds_read_b128 v[156:159], v144 offset:2048
	ds_read_b128 v[160:163], v144 offset:3072
	v_add_u32_e32 v144, s1, v148
	ds_read_b128 v[164:167], v144
	ds_read_b128 v[168:171], v144 offset:1024
	ds_read_b128 v[172:175], v144 offset:2048
	ds_read_b128 v[176:179], v144 offset:3072
	s_add_u32 s34, s34, 0xb0000
	s_addc_u32 s35, s35, 0
	s_mov_b32 m0, s47
	ds_read_b128 v[180:183], v151 offset:32768
	ds_read_b128 v[184:187], v151 offset:33792
	ds_read_b128 v[188:191], v151 offset:34816
	ds_read_b128 v[192:195], v151 offset:35840
	ds_read_b128 v[196:199], v151 offset:36864
	ds_read_b128 v[200:203], v151 offset:37888
	ds_read_b128 v[206:209], v151 offset:38912
	ds_read_b128 v[210:213], v151 offset:39936
	s_nop 0
	global_load_lds_dwordx4 v134, s[34:35]
	s_mov_b32 m0, s48
	s_nop 0
	global_load_lds_dwordx4 v130, s[34:35]
	s_waitcnt vmcnt(8)
	s_waitcnt lgkmcnt(0)
	s_barrier
	s_setprio 1
	s_waitcnt lgkmcnt(0)
	v_mfma_f32_16x16x32_bf16 v[124:127], v[140:143], v[180:183], v[124:127]
	v_mfma_f32_16x16x32_bf16 v[120:123], v[156:159], v[180:183], v[120:123]
	v_mfma_f32_16x16x32_bf16 v[108:111], v[140:143], v[188:191], v[108:111]
	v_mfma_f32_16x16x32_bf16 v[104:107], v[156:159], v[188:191], v[104:107]
	v_mfma_f32_16x16x32_bf16 v[92:95], v[140:143], v[196:199], v[92:95]
	v_mfma_f32_16x16x32_bf16 v[88:91], v[156:159], v[196:199], v[88:91]
	v_mfma_f32_16x16x32_bf16 v[76:79], v[140:143], v[206:209], v[76:79]
	v_mfma_f32_16x16x32_bf16 v[72:75], v[156:159], v[206:209], v[72:75]
	v_mfma_f32_16x16x32_bf16 v[124:127], v[152:155], v[184:187], v[124:127]
	v_mfma_f32_16x16x32_bf16 v[120:123], v[160:163], v[184:187], v[120:123]
	v_mfma_f32_16x16x32_bf16 v[108:111], v[152:155], v[192:195], v[108:111]
	v_mfma_f32_16x16x32_bf16 v[104:107], v[160:163], v[192:195], v[104:107]
	v_mfma_f32_16x16x32_bf16 v[92:95], v[152:155], v[200:203], v[92:95]
	v_mfma_f32_16x16x32_bf16 v[88:91], v[160:163], v[200:203], v[88:91]
	v_mfma_f32_16x16x32_bf16 v[76:79], v[152:155], v[210:213], v[76:79]
	v_mfma_f32_16x16x32_bf16 v[72:75], v[160:163], v[210:213], v[72:75]
	s_setprio 0
	s_setprio 1
	v_mfma_f32_16x16x32_bf16 v[116:119], v[164:167], v[180:183], v[116:119]
	v_mfma_f32_16x16x32_bf16 v[112:115], v[172:175], v[180:183], v[112:115]
	v_mfma_f32_16x16x32_bf16 v[100:103], v[164:167], v[188:191], v[100:103]
	v_mfma_f32_16x16x32_bf16 v[96:99], v[172:175], v[188:191], v[96:99]
	v_mfma_f32_16x16x32_bf16 v[84:87], v[164:167], v[196:199], v[84:87]
	v_mfma_f32_16x16x32_bf16 v[80:83], v[172:175], v[196:199], v[80:83]
	v_mfma_f32_16x16x32_bf16 v[68:71], v[164:167], v[206:209], v[68:71]
	v_mfma_f32_16x16x32_bf16 v[64:67], v[172:175], v[206:209], v[64:67]
	v_mfma_f32_16x16x32_bf16 v[116:119], v[168:171], v[184:187], v[116:119]
	v_mfma_f32_16x16x32_bf16 v[112:115], v[176:179], v[184:187], v[112:115]
	v_mfma_f32_16x16x32_bf16 v[100:103], v[168:171], v[192:195], v[100:103]
	v_mfma_f32_16x16x32_bf16 v[96:99], v[176:179], v[192:195], v[96:99]
	v_mfma_f32_16x16x32_bf16 v[84:87], v[168:171], v[200:203], v[84:87]
	v_mfma_f32_16x16x32_bf16 v[80:83], v[176:179], v[200:203], v[80:83]
	v_mfma_f32_16x16x32_bf16 v[68:71], v[168:171], v[210:213], v[68:71]
	v_mfma_f32_16x16x32_bf16 v[64:67], v[176:179], v[210:213], v[64:67]
	s_setprio 0
	s_barrier
; #define PG8_STAGE(bufoff, gbase, voff) do { const char* _gb = (const char*)(gbase); asm volatile("" : "+s"(_gb));     \
;         _Pragma("unroll") for (int _i = 0; _i < 2; ++_i) \
;         __builtin_amdgcn_global_load_lds((const unsigned*)(_gb + (voff)[_i]), (LAS unsigned*)(lds + (bufoff) + ldsw + _i * 8192), 16, 0, 0); } while (0)
; #define PG8_LDA(dst, b, h) do { _Pragma("unroll") for (int m = 0; m < 4; ++m) _Pragma("unroll") for (int k = 0; k < 2; ++k) dst[m][k] = *(const LAS bf16x8*)(lds + PG8_SA(b, h) + aoff + m * 2048 + k * 1024); } while (0)
; #define PG8_MMA(ai, bj, At, Bt) do { __builtin_amdgcn_s_setprio(1); _Pragma("unroll") for (int m = 0; m < 4; ++m) _Pragma("unroll") for (int n = 0; n < 2; ++n) _Pragma("unroll") for (int k = 0; k < 2; ++k) \
;         acc[ai][bj][m][n] = __builtin_amdgcn_mfma_f32_16x16x32_bf16(Bt[n][k], At[m][k], acc[ai][bj][m][n], 0, 0, 0); __builtin_amdgcn_s_setprio(0); } while (0)
; #define PG8_WAIT_V(n) asm volatile("s_waitcnt vmcnt(" #n ")" ::: "memory")
; #define PG8_WAIT_L(n) asm volatile("s_waitcnt lgkmcnt(" #n ")" ::: "memory")
; #define PG8_BAR __builtin_amdgcn_s_barrier()
; #define PG8_SCHED __builtin_amdgcn_sched_barrier(0)
; template <class Epi>
; __device__ __forceinline__ void gemm_phase(LAS unsigned char* lds, const int wid, const Gemm g, const Epi& E) {
;     ...
;             PG8_WAIT_V(8); PG8_WAIT_L(0); PG8_BAR; PG8_MMA(0, 0, At, B0); PG8_MMA(0, 1, At, B1); PG8_BAR; PG8_SCHED;
;             PG8_LDA(At, 1, 1); PG8_STAGE(PG8_SB(1, 0), b3, voffB); PG8_STAGE(PG8_SB(1, 1), b3 + hstepB, voffB); PG8_STAGE(PG8_SA(1, 0), a3, voffA);
;             PG8_WAIT_V(8); PG8_WAIT_L(0); PG8_BAR; PG8_MMA(1, 0, At, B0); PG8_MMA(1, 1, At, B1); PG8_BAR; PG8_SCHED;
;         }
;         if (wr == 0) PG8_BAR;
	s_mov_b64 s[34:35], s[38:39]
	s_add_i32 s0, s0, s23
	ds_read_b128 v[180:183], v151 offset:49152
	ds_read_b128 v[184:187], v151 offset:50176
	ds_read_b128 v[188:191], v151 offset:51200
	ds_read_b128 v[192:195], v151 offset:52224
	ds_read_b128 v[196:199], v151 offset:53248
	ds_read_b128 v[200:203], v151 offset:54272
	ds_read_b128 v[206:209], v151 offset:55296
	ds_read_b128 v[210:213], v151 offset:56320
	s_mov_b32 m0, s0
	s_nop 0
	global_load_lds_dwordx4 v132, s[34:35]
	s_add_i32 m0, s0, 0x2000
	v_lshl_add_u64 v[144:145], s[34:35], 0, v[128:129]
	s_add_u32 s34, s38, 0xb0000
	s_addc_u32 s35, s39, 0
	s_add_i32 s0, s1, s23
	global_load_lds_dwordx4 v[144:145], off
	s_mov_b32 m0, s0
	s_nop 0
	global_load_lds_dwordx4 v132, s[34:35]
	s_add_i32 m0, s0, 0x2000
	s_nop 0
	global_load_lds_dwordx4 v128, s[34:35]
	s_mov_b32 m0, s52
	s_nop 0
	global_load_lds_dwordx4 v134, s[30:31]
	s_mov_b32 m0, s53
	s_nop 0
	global_load_lds_dwordx4 v130, s[30:31]
	s_waitcnt vmcnt(8)
	s_waitcnt lgkmcnt(0)
	s_barrier
	s_setprio 1
	s_waitcnt lgkmcnt(0)
	v_mfma_f32_16x16x32_bf16 v[60:63], v[140:143], v[180:183], v[60:63]
	v_mfma_f32_16x16x32_bf16 v[56:59], v[156:159], v[180:183], v[56:59]
	v_mfma_f32_16x16x32_bf16 v[44:47], v[140:143], v[188:191], v[44:47]
	v_mfma_f32_16x16x32_bf16 v[40:43], v[156:159], v[188:191], v[40:43]
	v_mfma_f32_16x16x32_bf16 v[28:31], v[140:143], v[196:199], v[28:31]
	v_mfma_f32_16x16x32_bf16 v[24:27], v[156:159], v[196:199], v[24:27]
	v_mfma_f32_16x16x32_bf16 v[12:15], v[140:143], v[206:209], v[12:15]
	v_mfma_f32_16x16x32_bf16 v[8:11], v[156:159], v[206:209], v[8:11]
	v_mfma_f32_16x16x32_bf16 v[60:63], v[152:155], v[184:187], v[60:63]
	v_mfma_f32_16x16x32_bf16 v[56:59], v[160:163], v[184:187], v[56:59]
	v_mfma_f32_16x16x32_bf16 v[44:47], v[152:155], v[192:195], v[44:47]
	v_mfma_f32_16x16x32_bf16 v[40:43], v[160:163], v[192:195], v[40:43]
	v_mfma_f32_16x16x32_bf16 v[28:31], v[152:155], v[200:203], v[28:31]
	v_mfma_f32_16x16x32_bf16 v[24:27], v[160:163], v[200:203], v[24:27]
	v_mfma_f32_16x16x32_bf16 v[12:15], v[152:155], v[210:213], v[12:15]
	v_mfma_f32_16x16x32_bf16 v[8:11], v[160:163], v[210:213], v[8:11]
	s_setprio 0
	s_setprio 1
	v_mfma_f32_16x16x32_bf16 v[52:55], v[164:167], v[180:183], v[52:55]
	v_mfma_f32_16x16x32_bf16 v[48:51], v[172:175], v[180:183], v[48:51]
	v_mfma_f32_16x16x32_bf16 v[36:39], v[164:167], v[188:191], v[36:39]
	v_mfma_f32_16x16x32_bf16 v[32:35], v[172:175], v[188:191], v[32:35]
	v_mfma_f32_16x16x32_bf16 v[20:23], v[164:167], v[196:199], v[20:23]
	v_mfma_f32_16x16x32_bf16 v[16:19], v[172:175], v[196:199], v[16:19]
	v_mfma_f32_16x16x32_bf16 v[4:7], v[164:167], v[206:209], v[4:7]
	v_mfma_f32_16x16x32_bf16 v[0:3], v[172:175], v[206:209], v[0:3]
	v_mfma_f32_16x16x32_bf16 v[52:55], v[168:171], v[184:187], v[52:55]
	v_mfma_f32_16x16x32_bf16 v[48:51], v[176:179], v[184:187], v[48:51]
	v_mfma_f32_16x16x32_bf16 v[36:39], v[168:171], v[192:195], v[36:39]
	v_mfma_f32_16x16x32_bf16 v[32:35], v[176:179], v[192:195], v[32:35]
	v_mfma_f32_16x16x32_bf16 v[20:23], v[168:171], v[200:203], v[20:23]
	v_mfma_f32_16x16x32_bf16 v[16:19], v[176:179], v[200:203], v[16:19]
	v_mfma_f32_16x16x32_bf16 v[4:7], v[168:171], v[210:213], v[4:7]
	v_mfma_f32_16x16x32_bf16 v[0:3], v[176:179], v[210:213], v[0:3]
	s_setprio 0
	s_barrier
	s_add_i32 s68, s68, 2
	s_add_u32 s66, s66, 0x100
	s_addc_u32 s67, s67, 0
	s_add_u32 s28, s28, 0x100
	s_addc_u32 s29, s29, 0
	s_cmp_gt_u32 s68, 41
	s_cbranch_scc0 .LBB0_1604
	s_and_b64 vcc, exec, s[10:11]
	s_cbranch_vccz .LBB0_1607
	s_barrier

; #define PG8_STAGE(bufoff, gbase, voff) do { const char* _gb = (const char*)(gbase); asm volatile("" : "+s"(_gb));     \
;         _Pragma("unroll") for (int _i = 0; _i < 2; ++_i) \
;         __builtin_amdgcn_global_load_lds((const unsigned*)(_gb + (voff)[_i]), (LAS unsigned*)(lds + (bufoff) + ldsw + _i * 8192), 16, 0, 0); } while (0)
; #define PG8_WAIT_V(n) asm volatile("s_waitcnt vmcnt(" #n ")" ::: "memory")
; #define PG8_BAR __builtin_amdgcn_s_barrier()
; template <class Epi>
; __device__ __forceinline__ void gemm_phase(LAS unsigned char* lds, const int wid, const Gemm g, const Epi& E) {
;     ...
;     const char* cA = PG8_UA(cur); const char* cB = PG8_UB(cur);
;     PG8_STAGE(PG8_SB(0, 0), PG8_BP(cB, 0), voffB); PG8_STAGE(PG8_SB(0, 1), PG8_BP(cB, 0) + hstepB, voffB); PG8_STAGE(PG8_SA(0, 0), PG8_AP(cA, 0), voffA); PG8_STAGE(PG8_SA(0, 1), PG8_AP(cA, 0) + hstepA, voffA);
;     if (wr == 1) PG8_BAR;
;     PG8_WAIT_V(2); PG8_BAR;
;     PG8_STAGE(PG8_SB(1, 0), PG8_BP(cB, 1), voffB); PG8_STAGE(PG8_SA(1, 0), PG8_AP(cA, 1), voffA); PG8_STAGE(PG8_SB(1, 1), PG8_BP(cB, 1) + hstepB, voffB);
;     PG8_WAIT_V(6); PG8_BAR;
;     for (;;) {
;         const bool has_next = S.next(ui + 1, nxt);
;         const char* nA = has_next ? PG8_UA(nxt) : cA; const char* nB = has_next ? PG8_UB(nxt) : cB;
.LBB0_1745:
	s_and_b32 s0, s33, 3
	s_lshl_b32 s56, s14, 6
	s_lshl_b32 s57, s0, 5
	s_cmp_lt_u32 s33, 4
	s_cselect_b64 s[10:11], -1, 0
	s_lshl_b32 s58, s0, 6
	s_add_u32 s12, s12, 0x9800000
	s_addc_u32 s13, s13, 0
	s_add_u32 s2, s34, 0x80
	s_addc_u32 s3, s35, 0
	s_waitcnt vmcnt(2)
	s_barrier
	s_add_i32 m0, s31, 0x18000
	s_nop 0
	global_load_lds_dwordx4 v146, s[2:3]
	s_add_i32 m0, s31, 0x1a000
	v_lshl_add_u64 v[2:3], s[2:3], 0, v[150:151]
	s_add_u32 s2, s38, 0x80
	s_addc_u32 s3, s39, 0
	s_add_i32 s59, s31, 0x8000
	global_load_lds_dwordx4 v[2:3], off
	s_mov_b32 m0, s59
	s_add_i32 s60, s31, 0xa000
	global_load_lds_dwordx4 v144, s[2:3]
	v_lshl_add_u64 v[2:3], s[2:3], 0, v[148:149]
	s_add_u32 s2, s34, 0x40080
	s_mov_b32 m0, s60
	s_addc_u32 s3, s35, 0
	global_load_lds_dwordx4 v[2:3], off
	s_add_i32 m0, s31, 0x1c000
	s_nop 0
	global_load_lds_dwordx4 v146, s[2:3]
	s_add_i32 m0, s31, 0x1e000
	v_xor_b32_e32 v1, 16, v162
	global_load_lds_dwordx4 v150, s[2:3]
	v_and_b32_e32 v2, 64, v162
	v_add_u32_e32 v2, 64, v2
	v_cmp_lt_i32_e32 vcc, v1, v2
	v_lshlrev_b32_e32 v3, 6, v163
	s_movk_i32 s1, 0x3c0
	v_cndmask_b32_e32 v1, v162, v1, vcc
	v_lshlrev_b32_e32 v164, 2, v1
	v_xor_b32_e32 v1, 32, v162
	v_cmp_lt_i32_e32 vcc, v1, v2
	v_and_b32_e32 v0, 0xfffffc00, v0
	v_lshl_add_u32 v2, s14, 13, v0
	v_cndmask_b32_e32 v1, v162, v1, vcc
	v_lshlrev_b32_e32 v165, 2, v1
	v_and_b32_e32 v1, 48, v163
	v_and_or_b32 v1, v3, s1, v1
	v_lshlrev_b32_e32 v3, 2, v163
	v_and_b32_e32 v3, 32, v3
	v_lshl_add_u32 v0, s0, 12, v0
	s_waitcnt vmcnt(6)
	v_bitop3_b32 v2, v1, v2, v3 bitop3:0xde
	v_bitop3_b32 v166, v1, v0, v3 bitop3:0xde
	s_add_i32 s63, 0, 0x10000
	s_add_i32 s64, 0, 0x14000
	s_waitcnt lgkmcnt(0)
	s_ashr_i32 s61, s46, 31
	v_mov_b64_e32 v[152:153], 0x500
	v_mov_b64_e32 v[154:155], 0x4ff
	s_movk_i32 s62, 0xa1
	v_add_u32_e32 v167, s63, v166
	v_add_u32_e32 v168, s64, v166
	v_add_u32_e32 v169, 0, v2
	s_mov_b64 s[14:15], 0x100
	s_movk_i32 s65, 0x1400
	s_mov_b32 s16, 0x3c800000
	s_mov_b32 s18, 0x358637bd
	s_mov_b32 s66, 0x800000
	v_mov_b32_e32 v170, 0x3e38aa3b
	s_barrier
	s_branch .LBB0_1748

; #define PG8_STAGE(bufoff, gbase, voff) do { const char* _gb = (const char*)(gbase); asm volatile("" : "+s"(_gb));     \
;         _Pragma("unroll") for (int _i = 0; _i < 2; ++_i) \
;         __builtin_amdgcn_global_load_lds((const unsigned*)(_gb + (voff)[_i]), (LAS unsigned*)(lds + (bufoff) + ldsw + _i * 8192), 16, 0, 0); } while (0)
; #define PG8_LDA(dst, b, h) do { _Pragma("unroll") for (int m = 0; m < 4; ++m) _Pragma("unroll") for (int k = 0; k < 2; ++k) dst[m][k] = *(const LAS bf16x8*)(lds + PG8_SA(b, h) + aoff + m * 2048 + k * 1024); } while (0)
; #define PG8_LDB(dst, b, h) do { _Pragma("unroll") for (int n = 0; n < 2; ++n) _Pragma("unroll") for (int k = 0; k < 2; ++k) dst[n][k] = *(const LAS bf16x8*)(lds + PG8_SB(b, h) + boff + n * 2048 + k * 1024); } while (0)
; #define PG8_MMA(ai, bj, At, Bt) do { __builtin_amdgcn_s_setprio(1); _Pragma("unroll") for (int m = 0; m < 4; ++m) _Pragma("unroll") for (int n = 0; n < 2; ++n) _Pragma("unroll") for (int k = 0; k < 2; ++k) \
;         acc[ai][bj][m][n] = __builtin_amdgcn_mfma_f32_16x16x32_bf16(Bt[n][k], At[m][k], acc[ai][bj][m][n], 0, 0, 0); __builtin_amdgcn_s_setprio(0); } while (0)
; #define PG8_WAIT_V(n) asm volatile("s_waitcnt vmcnt(" #n ")" ::: "memory")
; #define PG8_WAIT_L(n) asm volatile("s_waitcnt lgkmcnt(" #n ")" ::: "memory")
; #define PG8_BAR __builtin_amdgcn_s_barrier()
; template <class Epi>
; __device__ __forceinline__ void gemm_phase(LAS unsigned char* lds, const int wid, const Gemm g, const Epi& E) {
;     ...
;             const bool last = (t == nt - 2);
;             const char* a1 = PG8_AP(cA, t + 1);
;             const char* a2 = last ? PG8_AP(nA, 0) : PG8_AP(cA, t + 2); const char* b2 = last ? PG8_BP(nB, 0) : PG8_BP(cB, t + 2);
;             const char* a3 = last ? PG8_AP(nA, 1) : PG8_AP(cA, t + 3); const char* b3 = last ? PG8_BP(nB, 1) : PG8_BP(cB, t + 3);
;             PG8_LDB(B0, 0, 0); PG8_LDB(B1, 0, 1); PG8_SCHED; PG8_LDA(At, 0, 0); PG8_STAGE(PG8_SA(1, 1), a1 + hstepA, voffA);
;             PG8_WAIT_V(8); PG8_WAIT_L(0); PG8_BAR; PG8_MMA(0, 0, At, B0); PG8_MMA(0, 1, At, B1); PG8_BAR; PG8_SCHED;
;             PG8_LDA(At, 0, 1); PG8_STAGE(PG8_SB(0, 0), b2, voffB); PG8_STAGE(PG8_SB(0, 1), b2 + hstepB, voffB); PG8_STAGE(PG8_SA(0, 0), a2, voffA);
;             PG8_WAIT_V(8); PG8_WAIT_L(0); PG8_BAR; PG8_MMA(1, 0, At, B0); PG8_MMA(1, 1, At, B1); PG8_BAR; PG8_SCHED;
.LBB0_1751:
	ds_read_b128 v[128:131], v167
	ds_read_b128 v[132:135], v167 offset:1024
	ds_read_b128 v[136:139], v167 offset:2048
	ds_read_b128 v[140:143], v167 offset:3072
	ds_read_b128 v[156:159], v168
	ds_read_b128 v[172:175], v168 offset:1024
	ds_read_b128 v[176:179], v168 offset:2048
	ds_read_b128 v[180:183], v168 offset:3072
	s_add_u32 s0, s34, 0xfffc0080
	s_addc_u32 s1, s35, -1
	s_add_u32 s38, s72, 0xffffff80
	s_addc_u32 s39, s73, -1
	s_add_u32 s42, s34, 0xfffc0100
	s_addc_u32 s43, s35, -1
	s_add_i32 s78, s63, s47
	s_add_i32 m0, s31, 0xc000
	s_add_i32 s75, s31, 0xe000
	s_add_i32 s79, s78, 0x2000
	s_cmp_eq_u32 s74, 12
	s_cselect_b32 s41, s5, s1
	s_cselect_b32 s40, s25, s0
	s_cselect_b32 s77, s21, s39
	s_cselect_b32 s76, s67, s38
	s_cselect_b32 s39, s69, s43
	s_cselect_b32 s38, s68, s42
	s_mov_b64 s[42:43], s[34:35]
	ds_read_b128 v[184:187], v169
	ds_read_b128 v[188:191], v169 offset:1024
	ds_read_b128 v[192:195], v169 offset:2048
	ds_read_b128 v[196:199], v169 offset:3072
	ds_read_b128 v[200:203], v169 offset:4096
	ds_read_b128 v[206:209], v169 offset:5120
	ds_read_b128 v[210:213], v169 offset:6144
	ds_read_b128 v[214:217], v169 offset:7168
	s_nop 0
	global_load_lds_dwordx4 v144, s[42:43]
	s_mov_b32 m0, s75
	s_nop 0
	global_load_lds_dwordx4 v148, s[42:43]
	s_waitcnt vmcnt(8)
	s_waitcnt lgkmcnt(0)
	s_barrier
	s_setprio 1
	s_waitcnt lgkmcnt(0)
	v_mfma_f32_16x16x32_bf16 v[124:127], v[128:131], v[184:187], v[124:127]
	v_mfma_f32_16x16x32_bf16 v[120:123], v[136:139], v[184:187], v[120:123]
	v_mfma_f32_16x16x32_bf16 v[108:111], v[128:131], v[192:195], v[108:111]
	v_mfma_f32_16x16x32_bf16 v[104:107], v[136:139], v[192:195], v[104:107]
	v_mfma_f32_16x16x32_bf16 v[92:95], v[128:131], v[200:203], v[92:95]
	v_mfma_f32_16x16x32_bf16 v[88:91], v[136:139], v[200:203], v[88:91]
	v_mfma_f32_16x16x32_bf16 v[80:83], v[128:131], v[210:213], v[80:83]
	v_mfma_f32_16x16x32_bf16 v[72:75], v[136:139], v[210:213], v[72:75]
	v_mfma_f32_16x16x32_bf16 v[124:127], v[132:135], v[188:191], v[124:127]
	v_mfma_f32_16x16x32_bf16 v[120:123], v[140:143], v[188:191], v[120:123]
	v_mfma_f32_16x16x32_bf16 v[108:111], v[132:135], v[196:199], v[108:111]
	v_mfma_f32_16x16x32_bf16 v[104:107], v[140:143], v[196:199], v[104:107]
	v_mfma_f32_16x16x32_bf16 v[92:95], v[132:135], v[206:209], v[92:95]
	v_mfma_f32_16x16x32_bf16 v[88:91], v[140:143], v[206:209], v[88:91]
	v_mfma_f32_16x16x32_bf16 v[80:83], v[132:135], v[214:217], v[80:83]
	v_mfma_f32_16x16x32_bf16 v[72:75], v[140:143], v[214:217], v[72:75]
	s_setprio 0
	s_setprio 1
	v_mfma_f32_16x16x32_bf16 v[116:119], v[156:159], v[184:187], v[116:119]
	v_mfma_f32_16x16x32_bf16 v[112:115], v[176:179], v[184:187], v[112:115]
	v_mfma_f32_16x16x32_bf16 v[100:103], v[156:159], v[192:195], v[100:103]
	v_mfma_f32_16x16x32_bf16 v[96:99], v[176:179], v[192:195], v[96:99]
	v_mfma_f32_16x16x32_bf16 v[84:87], v[156:159], v[200:203], v[84:87]
	v_mfma_f32_16x16x32_bf16 v[76:79], v[176:179], v[200:203], v[76:79]
	v_mfma_f32_16x16x32_bf16 v[68:71], v[156:159], v[210:213], v[68:71]
	v_mfma_f32_16x16x32_bf16 v[64:67], v[176:179], v[210:213], v[64:67]
	v_mfma_f32_16x16x32_bf16 v[116:119], v[172:175], v[188:191], v[116:119]
	v_mfma_f32_16x16x32_bf16 v[112:115], v[180:183], v[188:191], v[112:115]
	v_mfma_f32_16x16x32_bf16 v[100:103], v[172:175], v[196:199], v[100:103]
	v_mfma_f32_16x16x32_bf16 v[96:99], v[180:183], v[196:199], v[96:99]
	v_mfma_f32_16x16x32_bf16 v[84:87], v[172:175], v[206:209], v[84:87]
	v_mfma_f32_16x16x32_bf16 v[76:79], v[180:183], v[206:209], v[76:79]
	v_mfma_f32_16x16x32_bf16 v[68:71], v[172:175], v[214:217], v[68:71]
	v_mfma_f32_16x16x32_bf16 v[64:67], v[180:183], v[214:217], v[64:67]
	s_setprio 0
	s_barrier
	s_mov_b64 s[42:43], s[76:77]
	s_mov_b32 m0, s78
	ds_read_b128 v[184:187], v169 offset:16384
	ds_read_b128 v[188:191], v169 offset:17408
	ds_read_b128 v[192:195], v169 offset:18432
	ds_read_b128 v[196:199], v169 offset:19456
	ds_read_b128 v[200:203], v169 offset:20480
	ds_read_b128 v[206:209], v169 offset:21504
	ds_read_b128 v[210:213], v169 offset:22528
	ds_read_b128 v[214:217], v169 offset:23552
	s_nop 0
	global_load_lds_dwordx4 v146, s[42:43]
	v_lshl_add_u64 v[160:161], s[42:43], 0, v[150:151]
	s_cselect_b32 s43, s71, s73
	s_cselect_b32 s42, s70, s72
	s_add_u32 s76, s76, 0x40000
	s_mov_b32 m0, s79
	s_addc_u32 s77, s77, 0
	s_add_i32 s0, s64, s47
	global_load_lds_dwordx4 v[160:161], off
	s_mov_b32 m0, s0
	s_nop 0
	global_load_lds_dwordx4 v146, s[76:77]
	v_lshl_add_u64 v[160:161], s[76:77], 0, v[150:151]
	s_add_i32 m0, s0, 0x2000
	s_mov_b64 s[76:77], s[40:41]
	global_load_lds_dwordx4 v[160:161], off
	s_mov_b32 m0, s31
	s_nop 0
	global_load_lds_dwordx4 v144, s[76:77]
	s_mov_b32 m0, s52
	s_nop 0
	global_load_lds_dwordx4 v148, s[76:77]
	s_waitcnt vmcnt(8)
	s_waitcnt lgkmcnt(0)
	s_barrier
; #define PG8_STAGE(bufoff, gbase, voff) do { const char* _gb = (const char*)(gbase); asm volatile("" : "+s"(_gb));     \
;         _Pragma("unroll") for (int _i = 0; _i < 2; ++_i) \
;         __builtin_amdgcn_global_load_lds((const unsigned*)(_gb + (voff)[_i]), (LAS unsigned*)(lds + (bufoff) + ldsw + _i * 8192), 16, 0, 0); } while (0)
; #define PG8_LDA(dst, b, h) do { _Pragma("unroll") for (int m = 0; m < 4; ++m) _Pragma("unroll") for (int k = 0; k < 2; ++k) dst[m][k] = *(const LAS bf16x8*)(lds + PG8_SA(b, h) + aoff + m * 2048 + k * 1024); } while (0)
; #define PG8_LDB(dst, b, h) do { _Pragma("unroll") for (int n = 0; n < 2; ++n) _Pragma("unroll") for (int k = 0; k < 2; ++k) dst[n][k] = *(const LAS bf16x8*)(lds + PG8_SB(b, h) + boff + n * 2048 + k * 1024); } while (0)
; #define PG8_MMA(ai, bj, At, Bt) do { __builtin_amdgcn_s_setprio(1); _Pragma("unroll") for (int m = 0; m < 4; ++m) _Pragma("unroll") for (int n = 0; n < 2; ++n) _Pragma("unroll") for (int k = 0; k < 2; ++k) \
;         acc[ai][bj][m][n] = __builtin_amdgcn_mfma_f32_16x16x32_bf16(Bt[n][k], At[m][k], acc[ai][bj][m][n], 0, 0, 0); __builtin_amdgcn_s_setprio(0); } while (0)
; #define PG8_WAIT_V(n) asm volatile("s_waitcnt vmcnt(" #n ")" ::: "memory")
; #define PG8_WAIT_L(n) asm volatile("s_waitcnt lgkmcnt(" #n ")" ::: "memory")
; #define PG8_BAR __builtin_amdgcn_s_barrier()
; #define PG8_SCHED __builtin_amdgcn_sched_barrier(0)
; template <class Epi>
; __device__ __forceinline__ void gemm_phase(LAS unsigned char* lds, const int wid, const Gemm g, const Epi& E) {
;     ...
;             PG8_WAIT_V(8); PG8_WAIT_L(0); PG8_BAR; PG8_MMA(1, 0, At, B0); PG8_MMA(1, 1, At, B1); PG8_BAR; PG8_SCHED;
;             PG8_LDB(B0, 1, 0); PG8_LDB(B1, 1, 1); PG8_SCHED; PG8_LDA(At, 1, 0); PG8_STAGE(PG8_SA(0, 1), a2 + hstepA, voffA);
;             PG8_WAIT_V(8); PG8_WAIT_L(0); PG8_BAR; PG8_MMA(0, 0, At, B0); PG8_MMA(0, 1, At, B1); PG8_BAR; PG8_SCHED;
	s_setprio 1
	s_waitcnt lgkmcnt(0)
	v_mfma_f32_16x16x32_bf16 v[60:63], v[128:131], v[184:187], v[60:63]
	v_mfma_f32_16x16x32_bf16 v[56:59], v[136:139], v[184:187], v[56:59]
	v_mfma_f32_16x16x32_bf16 v[48:51], v[128:131], v[192:195], v[48:51]
	v_mfma_f32_16x16x32_bf16 v[40:43], v[136:139], v[192:195], v[40:43]
	v_mfma_f32_16x16x32_bf16 v[28:31], v[128:131], v[200:203], v[28:31]
	v_mfma_f32_16x16x32_bf16 v[24:27], v[136:139], v[200:203], v[24:27]
	v_mfma_f32_16x16x32_bf16 v[16:19], v[128:131], v[210:213], v[16:19]
	v_mfma_f32_16x16x32_bf16 v[8:11], v[136:139], v[210:213], v[8:11]
	v_mfma_f32_16x16x32_bf16 v[60:63], v[132:135], v[188:191], v[60:63]
	v_mfma_f32_16x16x32_bf16 v[56:59], v[140:143], v[188:191], v[56:59]
	v_mfma_f32_16x16x32_bf16 v[48:51], v[132:135], v[196:199], v[48:51]
	v_mfma_f32_16x16x32_bf16 v[40:43], v[140:143], v[196:199], v[40:43]
	v_mfma_f32_16x16x32_bf16 v[28:31], v[132:135], v[206:209], v[28:31]
	v_mfma_f32_16x16x32_bf16 v[24:27], v[140:143], v[206:209], v[24:27]
	v_mfma_f32_16x16x32_bf16 v[16:19], v[132:135], v[214:217], v[16:19]
	v_mfma_f32_16x16x32_bf16 v[8:11], v[140:143], v[214:217], v[8:11]
	s_setprio 0
	s_setprio 1
	v_mfma_f32_16x16x32_bf16 v[52:55], v[156:159], v[184:187], v[52:55]
	v_mfma_f32_16x16x32_bf16 v[44:47], v[176:179], v[184:187], v[44:47]
	v_mfma_f32_16x16x32_bf16 v[36:39], v[156:159], v[192:195], v[36:39]
	v_mfma_f32_16x16x32_bf16 v[32:35], v[176:179], v[192:195], v[32:35]
	v_mfma_f32_16x16x32_bf16 v[20:23], v[156:159], v[200:203], v[20:23]
	v_mfma_f32_16x16x32_bf16 v[12:15], v[176:179], v[200:203], v[12:15]
	v_mfma_f32_16x16x32_bf16 v[4:7], v[156:159], v[210:213], v[4:7]
	v_mfma_f32_16x16x32_bf16 v[0:3], v[176:179], v[210:213], v[0:3]
	v_mfma_f32_16x16x32_bf16 v[52:55], v[172:175], v[188:191], v[52:55]
	v_mfma_f32_16x16x32_bf16 v[44:47], v[180:183], v[188:191], v[44:47]
	v_mfma_f32_16x16x32_bf16 v[36:39], v[172:175], v[196:199], v[36:39]
	v_mfma_f32_16x16x32_bf16 v[32:35], v[180:183], v[196:199], v[32:35]
	v_mfma_f32_16x16x32_bf16 v[20:23], v[172:175], v[206:209], v[20:23]
	v_mfma_f32_16x16x32_bf16 v[12:15], v[180:183], v[206:209], v[12:15]
	v_mfma_f32_16x16x32_bf16 v[4:7], v[172:175], v[214:217], v[4:7]
	v_mfma_f32_16x16x32_bf16 v[0:3], v[180:183], v[214:217], v[0:3]
	s_setprio 0
	s_barrier
	s_add_i32 s0, 0, 0x18000
	s_add_i32 s1, 0, 0x1c000
	v_add_u32_e32 v140, s0, v166
	v_add_u32_e32 v160, s1, v166
	ds_read_b128 v[128:131], v140
	ds_read_b128 v[132:135], v140 offset:1024
	ds_read_b128 v[136:139], v140 offset:2048
	ds_read_b128 v[140:143], v140 offset:3072
	ds_read_b128 v[156:159], v160
	ds_read_b128 v[172:175], v160 offset:1024
	ds_read_b128 v[176:179], v160 offset:2048
	ds_read_b128 v[180:183], v160 offset:3072
	s_add_u32 s40, s40, 0x40000
	s_addc_u32 s41, s41, 0
	s_mov_b32 m0, s53
	ds_read_b128 v[184:187], v169 offset:32768
	ds_read_b128 v[188:191], v169 offset:33792
	ds_read_b128 v[192:195], v169 offset:34816
	ds_read_b128 v[196:199], v169 offset:35840
	ds_read_b128 v[200:203], v169 offset:36864
	ds_read_b128 v[206:209], v169 offset:37888
	ds_read_b128 v[210:213], v169 offset:38912
	ds_read_b128 v[214:217], v169 offset:39936
	s_nop 0
	global_load_lds_dwordx4 v144, s[40:41]
	s_mov_b32 m0, s54
	s_nop 0
	global_load_lds_dwordx4 v148, s[40:41]
	s_waitcnt vmcnt(8)
	s_waitcnt lgkmcnt(0)
	s_barrier
	s_setprio 1
	s_waitcnt lgkmcnt(0)
	v_mfma_f32_16x16x32_bf16 v[124:127], v[128:131], v[184:187], v[124:127]
	v_mfma_f32_16x16x32_bf16 v[120:123], v[136:139], v[184:187], v[120:123]
	v_mfma_f32_16x16x32_bf16 v[108:111], v[128:131], v[192:195], v[108:111]
	v_mfma_f32_16x16x32_bf16 v[104:107], v[136:139], v[192:195], v[104:107]
	v_mfma_f32_16x16x32_bf16 v[92:95], v[128:131], v[200:203], v[92:95]
	v_mfma_f32_16x16x32_bf16 v[88:91], v[136:139], v[200:203], v[88:91]
	v_mfma_f32_16x16x32_bf16 v[80:83], v[128:131], v[210:213], v[80:83]
	v_mfma_f32_16x16x32_bf16 v[72:75], v[136:139], v[210:213], v[72:75]
	v_mfma_f32_16x16x32_bf16 v[124:127], v[132:135], v[188:191], v[124:127]
	v_mfma_f32_16x16x32_bf16 v[120:123], v[140:143], v[188:191], v[120:123]
	v_mfma_f32_16x16x32_bf16 v[108:111], v[132:135], v[196:199], v[108:111]
	v_mfma_f32_16x16x32_bf16 v[104:107], v[140:143], v[196:199], v[104:107]
	v_mfma_f32_16x16x32_bf16 v[92:95], v[132:135], v[206:209], v[92:95]
	v_mfma_f32_16x16x32_bf16 v[88:91], v[140:143], v[206:209], v[88:91]
	v_mfma_f32_16x16x32_bf16 v[80:83], v[132:135], v[214:217], v[80:83]
	v_mfma_f32_16x16x32_bf16 v[72:75], v[140:143], v[214:217], v[72:75]
	s_setprio 0
	s_setprio 1
	v_mfma_f32_16x16x32_bf16 v[116:119], v[156:159], v[184:187], v[116:119]
	v_mfma_f32_16x16x32_bf16 v[112:115], v[176:179], v[184:187], v[112:115]
	v_mfma_f32_16x16x32_bf16 v[100:103], v[156:159], v[192:195], v[100:103]
	v_mfma_f32_16x16x32_bf16 v[96:99], v[176:179], v[192:195], v[96:99]
	v_mfma_f32_16x16x32_bf16 v[84:87], v[156:159], v[200:203], v[84:87]
	v_mfma_f32_16x16x32_bf16 v[76:79], v[176:179], v[200:203], v[76:79]
	v_mfma_f32_16x16x32_bf16 v[68:71], v[156:159], v[210:213], v[68:71]
	v_mfma_f32_16x16x32_bf16 v[64:67], v[176:179], v[210:213], v[64:67]
	v_mfma_f32_16x16x32_bf16 v[116:119], v[172:175], v[188:191], v[116:119]
	v_mfma_f32_16x16x32_bf16 v[112:115], v[180:183], v[188:191], v[112:115]
	v_mfma_f32_16x16x32_bf16 v[100:103], v[172:175], v[196:199], v[100:103]
	v_mfma_f32_16x16x32_bf16 v[96:99], v[180:183], v[196:199], v[96:99]
	v_mfma_f32_16x16x32_bf16 v[84:87], v[172:175], v[206:209], v[84:87]
	v_mfma_f32_16x16x32_bf16 v[76:79], v[180:183], v[206:209], v[76:79]
	v_mfma_f32_16x16x32_bf16 v[68:71], v[172:175], v[214:217], v[68:71]
	v_mfma_f32_16x16x32_bf16 v[64:67], v[180:183], v[214:217], v[64:67]
	s_setprio 0
	s_barrier
; #define PG8_STAGE(bufoff, gbase, voff) do { const char* _gb = (const char*)(gbase); asm volatile("" : "+s"(_gb));     \
;         _Pragma("unroll") for (int _i = 0; _i < 2; ++_i) \
;         __builtin_amdgcn_global_load_lds((const unsigned*)(_gb + (voff)[_i]), (LAS unsigned*)(lds + (bufoff) + ldsw + _i * 8192), 16, 0, 0); } while (0)
; #define PG8_LDA(dst, b, h) do { _Pragma("unroll") for (int m = 0; m < 4; ++m) _Pragma("unroll") for (int k = 0; k < 2; ++k) dst[m][k] = *(const LAS bf16x8*)(lds + PG8_SA(b, h) + aoff + m * 2048 + k * 1024); } while (0)
; #define PG8_MMA(ai, bj, At, Bt) do { __builtin_amdgcn_s_setprio(1); _Pragma("unroll") for (int m = 0; m < 4; ++m) _Pragma("unroll") for (int n = 0; n < 2; ++n) _Pragma("unroll") for (int k = 0; k < 2; ++k) \
;         acc[ai][bj][m][n] = __builtin_amdgcn_mfma_f32_16x16x32_bf16(Bt[n][k], At[m][k], acc[ai][bj][m][n], 0, 0, 0); __builtin_amdgcn_s_setprio(0); } while (0)
; #define PG8_WAIT_V(n) asm volatile("s_waitcnt vmcnt(" #n ")" ::: "memory")
; #define PG8_WAIT_L(n) asm volatile("s_waitcnt lgkmcnt(" #n ")" ::: "memory")
; #define PG8_BAR __builtin_amdgcn_s_barrier()
; #define PG8_SCHED __builtin_amdgcn_sched_barrier(0)
; template <class Epi>
; __device__ __forceinline__ void gemm_phase(LAS unsigned char* lds, const int wid, const Gemm g, const Epi& E) {
;     ...
;             PG8_WAIT_V(8); PG8_WAIT_L(0); PG8_BAR; PG8_MMA(0, 0, At, B0); PG8_MMA(0, 1, At, B1); PG8_BAR; PG8_SCHED;
;             PG8_LDA(At, 1, 1); PG8_STAGE(PG8_SB(1, 0), b3, voffB); PG8_STAGE(PG8_SB(1, 1), b3 + hstepB, voffB); PG8_STAGE(PG8_SA(1, 0), a3, voffA);
;             PG8_WAIT_V(8); PG8_WAIT_L(0); PG8_BAR; PG8_MMA(1, 0, At, B0); PG8_MMA(1, 1, At, B1); PG8_BAR; PG8_SCHED;
;         }
;         if (wr == 0) PG8_BAR;
	s_mov_b64 s[40:41], s[42:43]
	s_add_i32 s0, s0, s47
	ds_read_b128 v[184:187], v169 offset:49152
	ds_read_b128 v[188:191], v169 offset:50176
	ds_read_b128 v[192:195], v169 offset:51200
	ds_read_b128 v[196:199], v169 offset:52224
	ds_read_b128 v[200:203], v169 offset:53248
	ds_read_b128 v[206:209], v169 offset:54272
	ds_read_b128 v[210:213], v169 offset:55296
	ds_read_b128 v[214:217], v169 offset:56320
	s_mov_b32 m0, s0
	s_nop 0
	global_load_lds_dwordx4 v146, s[40:41]
	s_add_i32 m0, s0, 0x2000
	v_lshl_add_u64 v[160:161], s[40:41], 0, v[150:151]
	s_add_u32 s40, s42, 0x40000
	s_addc_u32 s41, s43, 0
	s_add_i32 s0, s1, s47
	global_load_lds_dwordx4 v[160:161], off
	s_mov_b32 m0, s0
	s_nop 0
	global_load_lds_dwordx4 v146, s[40:41]
	s_add_i32 m0, s0, 0x2000
	s_nop 0
	global_load_lds_dwordx4 v150, s[40:41]
	s_mov_b32 m0, s59
	s_nop 0
	global_load_lds_dwordx4 v144, s[38:39]
	s_mov_b32 m0, s60
	s_nop 0
	global_load_lds_dwordx4 v148, s[38:39]
	s_waitcnt vmcnt(8)
	s_waitcnt lgkmcnt(0)
	s_barrier
	s_setprio 1
	s_waitcnt lgkmcnt(0)
	v_mfma_f32_16x16x32_bf16 v[60:63], v[128:131], v[184:187], v[60:63]
	v_mfma_f32_16x16x32_bf16 v[56:59], v[136:139], v[184:187], v[56:59]
	v_mfma_f32_16x16x32_bf16 v[48:51], v[128:131], v[192:195], v[48:51]
	v_mfma_f32_16x16x32_bf16 v[40:43], v[136:139], v[192:195], v[40:43]
	v_mfma_f32_16x16x32_bf16 v[28:31], v[128:131], v[200:203], v[28:31]
	v_mfma_f32_16x16x32_bf16 v[24:27], v[136:139], v[200:203], v[24:27]
	v_mfma_f32_16x16x32_bf16 v[16:19], v[128:131], v[210:213], v[16:19]
	v_mfma_f32_16x16x32_bf16 v[8:11], v[136:139], v[210:213], v[8:11]
	v_mfma_f32_16x16x32_bf16 v[60:63], v[132:135], v[188:191], v[60:63]
	v_mfma_f32_16x16x32_bf16 v[56:59], v[140:143], v[188:191], v[56:59]
	v_mfma_f32_16x16x32_bf16 v[48:51], v[132:135], v[196:199], v[48:51]
	v_mfma_f32_16x16x32_bf16 v[40:43], v[140:143], v[196:199], v[40:43]
	v_mfma_f32_16x16x32_bf16 v[28:31], v[132:135], v[206:209], v[28:31]
	v_mfma_f32_16x16x32_bf16 v[24:27], v[140:143], v[206:209], v[24:27]
	v_mfma_f32_16x16x32_bf16 v[16:19], v[132:135], v[214:217], v[16:19]
	v_mfma_f32_16x16x32_bf16 v[8:11], v[140:143], v[214:217], v[8:11]
	s_setprio 0
	s_setprio 1
	v_mfma_f32_16x16x32_bf16 v[52:55], v[156:159], v[184:187], v[52:55]
	v_mfma_f32_16x16x32_bf16 v[44:47], v[176:179], v[184:187], v[44:47]
	v_mfma_f32_16x16x32_bf16 v[36:39], v[156:159], v[192:195], v[36:39]
	v_mfma_f32_16x16x32_bf16 v[32:35], v[176:179], v[192:195], v[32:35]
	v_mfma_f32_16x16x32_bf16 v[20:23], v[156:159], v[200:203], v[20:23]
	v_mfma_f32_16x16x32_bf16 v[12:15], v[176:179], v[200:203], v[12:15]
	v_mfma_f32_16x16x32_bf16 v[4:7], v[156:159], v[210:213], v[4:7]
	v_mfma_f32_16x16x32_bf16 v[0:3], v[176:179], v[210:213], v[0:3]
	v_mfma_f32_16x16x32_bf16 v[52:55], v[172:175], v[188:191], v[52:55]
	v_mfma_f32_16x16x32_bf16 v[44:47], v[180:183], v[188:191], v[44:47]
	v_mfma_f32_16x16x32_bf16 v[36:39], v[172:175], v[196:199], v[36:39]
	v_mfma_f32_16x16x32_bf16 v[32:35], v[180:183], v[196:199], v[32:35]
	v_mfma_f32_16x16x32_bf16 v[20:23], v[172:175], v[206:209], v[20:23]
	v_mfma_f32_16x16x32_bf16 v[12:15], v[180:183], v[206:209], v[12:15]
	v_mfma_f32_16x16x32_bf16 v[4:7], v[172:175], v[214:217], v[4:7]
	v_mfma_f32_16x16x32_bf16 v[0:3], v[180:183], v[214:217], v[0:3]
	s_setprio 0
	s_barrier
	s_add_i32 s74, s74, 2
	s_add_u32 s72, s72, 0x100
	s_addc_u32 s73, s73, 0
	s_add_u32 s34, s34, 0x100
	s_addc_u32 s35, s35, 0
	s_cmp_gt_u32 s74, 13
	s_cbranch_scc0 .LBB0_1751
	s_and_b64 vcc, exec, s[10:11]
	s_cbranch_vccz .LBB0_1754
	s_barrier

; #define PG8_STAGE(bufoff, gbase, voff) do { const char* _gb = (const char*)(gbase); asm volatile("" : "+s"(_gb));     \
;         _Pragma("unroll") for (int _i = 0; _i < 2; ++_i) \
;         __builtin_amdgcn_global_load_lds((const unsigned*)(_gb + (voff)[_i]), (LAS unsigned*)(lds + (bufoff) + ldsw + _i * 8192), 16, 0, 0); } while (0)
; #define PG8_WAIT_V(n) asm volatile("s_waitcnt vmcnt(" #n ")" ::: "memory")
; #define PG8_BAR __builtin_amdgcn_s_barrier()
; template <class Epi>
; __device__ __forceinline__ void gemm_phase(LAS unsigned char* lds, const int wid, const Gemm g, const Epi& E) {
;     ...
;     const char* cA = PG8_UA(cur); const char* cB = PG8_UB(cur);
;     PG8_STAGE(PG8_SB(0, 0), PG8_BP(cB, 0), voffB); PG8_STAGE(PG8_SB(0, 1), PG8_BP(cB, 0) + hstepB, voffB); PG8_STAGE(PG8_SA(0, 0), PG8_AP(cA, 0), voffA); PG8_STAGE(PG8_SA(0, 1), PG8_AP(cA, 0) + hstepA, voffA);
;     if (wr == 1) PG8_BAR;
;     PG8_WAIT_V(2); PG8_BAR;
;     PG8_STAGE(PG8_SB(1, 0), PG8_BP(cB, 1), voffB); PG8_STAGE(PG8_SA(1, 0), PG8_AP(cA, 1), voffA); PG8_STAGE(PG8_SB(1, 1), PG8_BP(cB, 1) + hstepB, voffB);
;     PG8_WAIT_V(6); PG8_BAR;
;     for (;;) {
;         const bool has_next = S.next(ui + 1, nxt);
;         const char* nA = has_next ? PG8_UA(nxt) : cA; const char* nB = has_next ? PG8_UB(nxt) : cB;
.LBB0_2467:
	s_add_u32 s73, s4, 0x9800000
	s_addc_u32 s74, s5, 0
	s_add_u32 s18, s6, 0x1d800000
	s_addc_u32 s19, s7, 0
	s_add_u32 s4, s50, 0x80
	s_addc_u32 s5, s51, 0
	s_waitcnt vmcnt(2)
	s_barrier
	s_add_i32 m0, s21, 0x18000
	s_nop 0
	global_load_lds_dwordx4 v130, s[4:5]
	s_add_i32 m0, s21, 0x1a000
	v_lshl_add_u64 v[0:1], s[4:5], 0, v[134:135]
	s_add_u32 s4, s52, 0x80
	s_addc_u32 s5, s53, 0
	s_add_i32 s75, s21, 0x8000
	global_load_lds_dwordx4 v[0:1], off
	s_mov_b32 m0, s75
	s_add_i32 s76, s21, 0xa000
	global_load_lds_dwordx4 v128, s[4:5]
	v_lshl_add_u64 v[0:1], s[4:5], 0, v[132:133]
	s_add_u32 s4, s50, 0x40080
	s_mov_b32 m0, s76
	s_addc_u32 s5, s51, 0
	global_load_lds_dwordx4 v[0:1], off
	s_add_i32 m0, s21, 0x1c000
	s_nop 0
	global_load_lds_dwordx4 v130, s[4:5]
	s_add_i32 m0, s21, 0x1e000
	v_ashrrev_i32_e32 v2, 6, v155
	global_load_lds_dwordx4 v134, s[4:5]
	v_and_b32_e32 v0, 15, v155
	v_or_b32_e32 v1, s60, v0
	v_lshlrev_b32_e32 v3, 6, v1
	v_and_b32_e32 v4, 48, v155
	s_movk_i32 s0, 0x3c0
	v_lshlrev_b32_e32 v1, 2, v1
	v_and_or_b32 v3, v3, s0, v4
	v_lshl_add_u32 v5, v2, 10, s57
	v_and_b32_e32 v1, 32, v1
	v_bitop3_b32 v1, v3, v5, v1 bitop3:0xde
	v_lshlrev_b32_e32 v3, 2, v155
	v_lshl_or_b32 v0, v0, 6, v4
	v_add_lshl_u32 v2, v2, s56, 10
	v_and_b32_e32 v3, 32, v3
	s_waitcnt vmcnt(6)
	v_bitop3_b32 v156, v0, v2, v3 bitop3:0xde
	s_add_i32 s78, 0, 0x10000
	s_add_i32 s79, 0, 0x14000
	s_waitcnt lgkmcnt(0)
	s_ashr_i32 s77, s58, 31
	v_mov_b64_e32 v[136:137], 0x400
	v_mov_b64_e32 v[138:139], 0x3ff
	v_add_u32_e32 v157, s78, v156
	v_add_u32_e32 v158, s79, v156
	v_add_u32_e32 v159, 0, v1
	s_movk_i32 s80, 0xa0
	s_movk_i32 s81, 0xffbf
	s_mov_b64 s[24:25], 0x20000
	s_mov_b64 s[26:27], 0x24000
	s_mov_b64 s[28:29], 0x28000
	s_mov_b64 s[30:31], 0x2c000
	s_mov_b32 s82, 0x40000
	s_mov_b64 s[34:35], 0x48000
	s_mov_b32 s83, 0x48000
	s_mov_b64 s[38:39], 0x50000
	s_mov_b32 s84, 0x50000
	s_mov_b64 s[40:41], 0x58000
	s_barrier
	s_branch .LBB0_2470

; #define PG8_STAGE(bufoff, gbase, voff) do { const char* _gb = (const char*)(gbase); asm volatile("" : "+s"(_gb));     \
;         _Pragma("unroll") for (int _i = 0; _i < 2; ++_i) \
;         __builtin_amdgcn_global_load_lds((const unsigned*)(_gb + (voff)[_i]), (LAS unsigned*)(lds + (bufoff) + ldsw + _i * 8192), 16, 0, 0); } while (0)
; #define PG8_LDA(dst, b, h) do { _Pragma("unroll") for (int m = 0; m < 4; ++m) _Pragma("unroll") for (int k = 0; k < 2; ++k) dst[m][k] = *(const LAS bf16x8*)(lds + PG8_SA(b, h) + aoff + m * 2048 + k * 1024); } while (0)
; #define PG8_LDB(dst, b, h) do { _Pragma("unroll") for (int n = 0; n < 2; ++n) _Pragma("unroll") for (int k = 0; k < 2; ++k) dst[n][k] = *(const LAS bf16x8*)(lds + PG8_SB(b, h) + boff + n * 2048 + k * 1024); } while (0)
; #define PG8_MMA(ai, bj, At, Bt) do { __builtin_amdgcn_s_setprio(1); _Pragma("unroll") for (int m = 0; m < 4; ++m) _Pragma("unroll") for (int n = 0; n < 2; ++n) _Pragma("unroll") for (int k = 0; k < 2; ++k) \
;         acc[ai][bj][m][n] = __builtin_amdgcn_mfma_f32_16x16x32_bf16(Bt[n][k], At[m][k], acc[ai][bj][m][n], 0, 0, 0); __builtin_amdgcn_s_setprio(0); } while (0)
; #define PG8_WAIT_V(n) asm volatile("s_waitcnt vmcnt(" #n ")" ::: "memory")
; #define PG8_WAIT_L(n) asm volatile("s_waitcnt lgkmcnt(" #n ")" ::: "memory")
; #define PG8_BAR __builtin_amdgcn_s_barrier()
; template <class Epi>
; __device__ __forceinline__ void gemm_phase(LAS unsigned char* lds, const int wid, const Gemm g, const Epi& E) {
;     ...
;             const bool last = (t == nt - 2);
;             const char* a1 = PG8_AP(cA, t + 1);
;             const char* a2 = last ? PG8_AP(nA, 0) : PG8_AP(cA, t + 2); const char* b2 = last ? PG8_BP(nB, 0) : PG8_BP(cB, t + 2);
;             const char* a3 = last ? PG8_AP(nA, 1) : PG8_AP(cA, t + 3); const char* b3 = last ? PG8_BP(nB, 1) : PG8_BP(cB, t + 3);
;             PG8_LDB(B0, 0, 0); PG8_LDB(B1, 0, 1); PG8_SCHED; PG8_LDA(At, 0, 0); PG8_STAGE(PG8_SA(1, 1), a1 + hstepA, voffA);
;             PG8_WAIT_V(8); PG8_WAIT_L(0); PG8_BAR; PG8_MMA(0, 0, At, B0); PG8_MMA(0, 1, At, B1); PG8_BAR; PG8_SCHED;
;             PG8_LDA(At, 0, 1); PG8_STAGE(PG8_SB(0, 0), b2, voffB); PG8_STAGE(PG8_SB(0, 1), b2 + hstepB, voffB); PG8_STAGE(PG8_SA(0, 0), a2, voffA);
;             PG8_WAIT_V(8); PG8_WAIT_L(0); PG8_BAR; PG8_MMA(1, 0, At, B0); PG8_MMA(1, 1, At, B1); PG8_BAR; PG8_SCHED;
.LBB0_2479:
	ds_read_b128 v[140:143], v157
	ds_read_b128 v[144:147], v157 offset:1024
	ds_read_b128 v[148:151], v157 offset:2048
	ds_read_b128 v[160:163], v157 offset:3072
	ds_read_b128 v[164:167], v158
	ds_read_b128 v[168:171], v158 offset:1024
	ds_read_b128 v[172:175], v158 offset:2048
	ds_read_b128 v[176:179], v158 offset:3072
	s_add_u32 s0, s6, 0xfffc0080
	s_addc_u32 s1, s7, -1
	s_add_u32 s50, s88, 0xffffff80
	s_addc_u32 s51, s89, -1
	s_add_u32 s54, s6, 0xfffc0100
	s_addc_u32 s55, s7, -1
	s_add_i32 s94, s78, s59
	s_add_i32 m0, s21, 0xc000
	s_add_i32 s91, s21, 0xe000
	s_add_i32 s95, s94, 0x2000
	s_cmp_eq_u32 s90, 12
	s_cselect_b32 s53, s47, s1
	s_cselect_b32 s52, s46, s0
	s_cselect_b32 s93, s9, s51
	s_cselect_b32 s92, s43, s50
	s_cselect_b32 s51, s85, s55
	s_cselect_b32 s50, s45, s54
	s_mov_b64 s[54:55], s[6:7]
	ds_read_b128 v[180:183], v159
	ds_read_b128 v[184:187], v159 offset:1024
	ds_read_b128 v[188:191], v159 offset:2048
	ds_read_b128 v[192:195], v159 offset:3072
	ds_read_b128 v[196:199], v159 offset:4096
	ds_read_b128 v[200:203], v159 offset:5120
	ds_read_b128 v[206:209], v159 offset:6144
	ds_read_b128 v[210:213], v159 offset:7168
	s_nop 0
	global_load_lds_dwordx4 v128, s[54:55]
	s_mov_b32 m0, s91
	s_nop 0
	global_load_lds_dwordx4 v132, s[54:55]
	s_waitcnt vmcnt(8)
	s_waitcnt lgkmcnt(0)
	s_barrier
	s_setprio 1
	s_waitcnt lgkmcnt(0)
	v_mfma_f32_16x16x32_bf16 v[124:127], v[140:143], v[180:183], v[124:127]
	v_mfma_f32_16x16x32_bf16 v[120:123], v[148:151], v[180:183], v[120:123]
	v_mfma_f32_16x16x32_bf16 v[116:119], v[140:143], v[188:191], v[116:119]
	v_mfma_f32_16x16x32_bf16 v[112:115], v[148:151], v[188:191], v[112:115]
	v_mfma_f32_16x16x32_bf16 v[100:103], v[140:143], v[196:199], v[100:103]
	v_mfma_f32_16x16x32_bf16 v[96:99], v[148:151], v[196:199], v[96:99]
	v_mfma_f32_16x16x32_bf16 v[84:87], v[140:143], v[206:209], v[84:87]
	v_mfma_f32_16x16x32_bf16 v[80:83], v[148:151], v[206:209], v[80:83]
	v_mfma_f32_16x16x32_bf16 v[124:127], v[144:147], v[184:187], v[124:127]
	v_mfma_f32_16x16x32_bf16 v[120:123], v[160:163], v[184:187], v[120:123]
	v_mfma_f32_16x16x32_bf16 v[116:119], v[144:147], v[192:195], v[116:119]
	v_mfma_f32_16x16x32_bf16 v[112:115], v[160:163], v[192:195], v[112:115]
	v_mfma_f32_16x16x32_bf16 v[100:103], v[144:147], v[200:203], v[100:103]
	v_mfma_f32_16x16x32_bf16 v[96:99], v[160:163], v[200:203], v[96:99]
	v_mfma_f32_16x16x32_bf16 v[84:87], v[144:147], v[210:213], v[84:87]
	v_mfma_f32_16x16x32_bf16 v[80:83], v[160:163], v[210:213], v[80:83]
	s_setprio 0
	s_setprio 1
	v_mfma_f32_16x16x32_bf16 v[108:111], v[164:167], v[180:183], v[108:111]
	v_mfma_f32_16x16x32_bf16 v[104:107], v[172:175], v[180:183], v[104:107]
	v_mfma_f32_16x16x32_bf16 v[92:95], v[164:167], v[188:191], v[92:95]
	v_mfma_f32_16x16x32_bf16 v[88:91], v[172:175], v[188:191], v[88:91]
	v_mfma_f32_16x16x32_bf16 v[76:79], v[164:167], v[196:199], v[76:79]
	v_mfma_f32_16x16x32_bf16 v[72:75], v[172:175], v[196:199], v[72:75]
	v_mfma_f32_16x16x32_bf16 v[68:71], v[164:167], v[206:209], v[68:71]
	v_mfma_f32_16x16x32_bf16 v[64:67], v[172:175], v[206:209], v[64:67]
	v_mfma_f32_16x16x32_bf16 v[108:111], v[168:171], v[184:187], v[108:111]
	v_mfma_f32_16x16x32_bf16 v[104:107], v[176:179], v[184:187], v[104:107]
	v_mfma_f32_16x16x32_bf16 v[92:95], v[168:171], v[192:195], v[92:95]
	v_mfma_f32_16x16x32_bf16 v[88:91], v[176:179], v[192:195], v[88:91]
	v_mfma_f32_16x16x32_bf16 v[76:79], v[168:171], v[200:203], v[76:79]
	v_mfma_f32_16x16x32_bf16 v[72:75], v[176:179], v[200:203], v[72:75]
	v_mfma_f32_16x16x32_bf16 v[68:71], v[168:171], v[210:213], v[68:71]
	v_mfma_f32_16x16x32_bf16 v[64:67], v[176:179], v[210:213], v[64:67]
	s_setprio 0
	s_barrier
	s_mov_b64 s[54:55], s[92:93]
	s_mov_b32 m0, s94
	ds_read_b128 v[180:183], v159 offset:16384
	ds_read_b128 v[184:187], v159 offset:17408
	ds_read_b128 v[188:191], v159 offset:18432
	ds_read_b128 v[192:195], v159 offset:19456
	ds_read_b128 v[196:199], v159 offset:20480
	ds_read_b128 v[200:203], v159 offset:21504
	ds_read_b128 v[206:209], v159 offset:22528
	ds_read_b128 v[210:213], v159 offset:23552
	s_nop 0
	global_load_lds_dwordx4 v130, s[54:55]
	v_lshl_add_u64 v[152:153], s[54:55], 0, v[134:135]
	s_cselect_b32 s55, s87, s89
	s_cselect_b32 s54, s86, s88
	s_add_u32 s92, s92, 0x40000
	s_mov_b32 m0, s95
	s_addc_u32 s93, s93, 0
	s_add_i32 s0, s79, s59
	global_load_lds_dwordx4 v[152:153], off
	s_mov_b32 m0, s0
	s_nop 0
	global_load_lds_dwordx4 v130, s[92:93]
	v_lshl_add_u64 v[152:153], s[92:93], 0, v[134:135]
	s_add_i32 m0, s0, 0x2000
	s_mov_b64 s[92:93], s[52:53]
	global_load_lds_dwordx4 v[152:153], off
	s_mov_b32 m0, s21
	s_nop 0
	global_load_lds_dwordx4 v128, s[92:93]
	s_mov_b32 m0, s69
	s_nop 0
	global_load_lds_dwordx4 v132, s[92:93]
	s_waitcnt vmcnt(8)
	s_waitcnt lgkmcnt(0)
	s_barrier
; #define PG8_STAGE(bufoff, gbase, voff) do { const char* _gb = (const char*)(gbase); asm volatile("" : "+s"(_gb));     \
;         _Pragma("unroll") for (int _i = 0; _i < 2; ++_i) \
;         __builtin_amdgcn_global_load_lds((const unsigned*)(_gb + (voff)[_i]), (LAS unsigned*)(lds + (bufoff) + ldsw + _i * 8192), 16, 0, 0); } while (0)
; #define PG8_LDA(dst, b, h) do { _Pragma("unroll") for (int m = 0; m < 4; ++m) _Pragma("unroll") for (int k = 0; k < 2; ++k) dst[m][k] = *(const LAS bf16x8*)(lds + PG8_SA(b, h) + aoff + m * 2048 + k * 1024); } while (0)
; #define PG8_LDB(dst, b, h) do { _Pragma("unroll") for (int n = 0; n < 2; ++n) _Pragma("unroll") for (int k = 0; k < 2; ++k) dst[n][k] = *(const LAS bf16x8*)(lds + PG8_SB(b, h) + boff + n * 2048 + k * 1024); } while (0)
; #define PG8_MMA(ai, bj, At, Bt) do { __builtin_amdgcn_s_setprio(1); _Pragma("unroll") for (int m = 0; m < 4; ++m) _Pragma("unroll") for (int n = 0; n < 2; ++n) _Pragma("unroll") for (int k = 0; k < 2; ++k) \
;         acc[ai][bj][m][n] = __builtin_amdgcn_mfma_f32_16x16x32_bf16(Bt[n][k], At[m][k], acc[ai][bj][m][n], 0, 0, 0); __builtin_amdgcn_s_setprio(0); } while (0)
; #define PG8_WAIT_V(n) asm volatile("s_waitcnt vmcnt(" #n ")" ::: "memory")
; #define PG8_WAIT_L(n) asm volatile("s_waitcnt lgkmcnt(" #n ")" ::: "memory")
; #define PG8_BAR __builtin_amdgcn_s_barrier()
; #define PG8_SCHED __builtin_amdgcn_sched_barrier(0)
; template <class Epi>
; __device__ __forceinline__ void gemm_phase(LAS unsigned char* lds, const int wid, const Gemm g, const Epi& E) {
;     ...
;             PG8_WAIT_V(8); PG8_WAIT_L(0); PG8_BAR; PG8_MMA(1, 0, At, B0); PG8_MMA(1, 1, At, B1); PG8_BAR; PG8_SCHED;
;             PG8_LDB(B0, 1, 0); PG8_LDB(B1, 1, 1); PG8_SCHED; PG8_LDA(At, 1, 0); PG8_STAGE(PG8_SA(0, 1), a2 + hstepA, voffA);
;             PG8_WAIT_V(8); PG8_WAIT_L(0); PG8_BAR; PG8_MMA(0, 0, At, B0); PG8_MMA(0, 1, At, B1); PG8_BAR; PG8_SCHED;
	s_setprio 1
	s_waitcnt lgkmcnt(0)
	v_mfma_f32_16x16x32_bf16 v[60:63], v[140:143], v[180:183], v[60:63]
	v_mfma_f32_16x16x32_bf16 v[56:59], v[148:151], v[180:183], v[56:59]
	v_mfma_f32_16x16x32_bf16 v[52:55], v[140:143], v[188:191], v[52:55]
	v_mfma_f32_16x16x32_bf16 v[48:51], v[148:151], v[188:191], v[48:51]
	v_mfma_f32_16x16x32_bf16 v[36:39], v[140:143], v[196:199], v[36:39]
	v_mfma_f32_16x16x32_bf16 v[32:35], v[148:151], v[196:199], v[32:35]
	v_mfma_f32_16x16x32_bf16 v[20:23], v[140:143], v[206:209], v[20:23]
	v_mfma_f32_16x16x32_bf16 v[16:19], v[148:151], v[206:209], v[16:19]
	v_mfma_f32_16x16x32_bf16 v[60:63], v[144:147], v[184:187], v[60:63]
	v_mfma_f32_16x16x32_bf16 v[56:59], v[160:163], v[184:187], v[56:59]
	v_mfma_f32_16x16x32_bf16 v[52:55], v[144:147], v[192:195], v[52:55]
	v_mfma_f32_16x16x32_bf16 v[48:51], v[160:163], v[192:195], v[48:51]
	v_mfma_f32_16x16x32_bf16 v[36:39], v[144:147], v[200:203], v[36:39]
	v_mfma_f32_16x16x32_bf16 v[32:35], v[160:163], v[200:203], v[32:35]
	v_mfma_f32_16x16x32_bf16 v[20:23], v[144:147], v[210:213], v[20:23]
	v_mfma_f32_16x16x32_bf16 v[16:19], v[160:163], v[210:213], v[16:19]
	s_setprio 0
	s_setprio 1
	v_mfma_f32_16x16x32_bf16 v[44:47], v[164:167], v[180:183], v[44:47]
	v_mfma_f32_16x16x32_bf16 v[40:43], v[172:175], v[180:183], v[40:43]
	v_mfma_f32_16x16x32_bf16 v[28:31], v[164:167], v[188:191], v[28:31]
	v_mfma_f32_16x16x32_bf16 v[24:27], v[172:175], v[188:191], v[24:27]
	v_mfma_f32_16x16x32_bf16 v[12:15], v[164:167], v[196:199], v[12:15]
	v_mfma_f32_16x16x32_bf16 v[8:11], v[172:175], v[196:199], v[8:11]
	v_mfma_f32_16x16x32_bf16 v[4:7], v[164:167], v[206:209], v[4:7]
	v_mfma_f32_16x16x32_bf16 v[0:3], v[172:175], v[206:209], v[0:3]
	v_mfma_f32_16x16x32_bf16 v[44:47], v[168:171], v[184:187], v[44:47]
	v_mfma_f32_16x16x32_bf16 v[40:43], v[176:179], v[184:187], v[40:43]
	v_mfma_f32_16x16x32_bf16 v[28:31], v[168:171], v[192:195], v[28:31]
	v_mfma_f32_16x16x32_bf16 v[24:27], v[176:179], v[192:195], v[24:27]
	v_mfma_f32_16x16x32_bf16 v[12:15], v[168:171], v[200:203], v[12:15]
	v_mfma_f32_16x16x32_bf16 v[8:11], v[176:179], v[200:203], v[8:11]
	v_mfma_f32_16x16x32_bf16 v[4:7], v[168:171], v[210:213], v[4:7]
	v_mfma_f32_16x16x32_bf16 v[0:3], v[176:179], v[210:213], v[0:3]
	s_setprio 0
	s_barrier
	s_add_i32 s0, 0, 0x18000
	v_add_u32_e32 v152, s0, v156
	s_add_i32 s1, 0, 0x1c000
	ds_read_b128 v[140:143], v152
	ds_read_b128 v[144:147], v152 offset:1024
	ds_read_b128 v[148:151], v152 offset:2048
	ds_read_b128 v[160:163], v152 offset:3072
	v_add_u32_e32 v152, s1, v156
	ds_read_b128 v[164:167], v152
	ds_read_b128 v[168:171], v152 offset:1024
	ds_read_b128 v[172:175], v152 offset:2048
	ds_read_b128 v[176:179], v152 offset:3072
	s_add_u32 s52, s52, 0x40000
	s_addc_u32 s53, s53, 0
	s_mov_b32 m0, s70
	ds_read_b128 v[180:183], v159 offset:32768
	ds_read_b128 v[184:187], v159 offset:33792
	ds_read_b128 v[188:191], v159 offset:34816
	ds_read_b128 v[192:195], v159 offset:35840
	ds_read_b128 v[196:199], v159 offset:36864
	ds_read_b128 v[200:203], v159 offset:37888
	ds_read_b128 v[206:209], v159 offset:38912
	ds_read_b128 v[210:213], v159 offset:39936
	s_nop 0
	global_load_lds_dwordx4 v128, s[52:53]
	s_mov_b32 m0, s71
	s_nop 0
	global_load_lds_dwordx4 v132, s[52:53]
	s_waitcnt vmcnt(8)
	s_waitcnt lgkmcnt(0)
	s_barrier
	s_setprio 1
	s_waitcnt lgkmcnt(0)
	v_mfma_f32_16x16x32_bf16 v[124:127], v[140:143], v[180:183], v[124:127]
	v_mfma_f32_16x16x32_bf16 v[120:123], v[148:151], v[180:183], v[120:123]
	v_mfma_f32_16x16x32_bf16 v[116:119], v[140:143], v[188:191], v[116:119]
	v_mfma_f32_16x16x32_bf16 v[112:115], v[148:151], v[188:191], v[112:115]
	v_mfma_f32_16x16x32_bf16 v[100:103], v[140:143], v[196:199], v[100:103]
	v_mfma_f32_16x16x32_bf16 v[96:99], v[148:151], v[196:199], v[96:99]
	v_mfma_f32_16x16x32_bf16 v[84:87], v[140:143], v[206:209], v[84:87]
	v_mfma_f32_16x16x32_bf16 v[80:83], v[148:151], v[206:209], v[80:83]
	v_mfma_f32_16x16x32_bf16 v[124:127], v[144:147], v[184:187], v[124:127]
	v_mfma_f32_16x16x32_bf16 v[120:123], v[160:163], v[184:187], v[120:123]
	v_mfma_f32_16x16x32_bf16 v[116:119], v[144:147], v[192:195], v[116:119]
	v_mfma_f32_16x16x32_bf16 v[112:115], v[160:163], v[192:195], v[112:115]
	v_mfma_f32_16x16x32_bf16 v[100:103], v[144:147], v[200:203], v[100:103]
	v_mfma_f32_16x16x32_bf16 v[96:99], v[160:163], v[200:203], v[96:99]
	v_mfma_f32_16x16x32_bf16 v[84:87], v[144:147], v[210:213], v[84:87]
	v_mfma_f32_16x16x32_bf16 v[80:83], v[160:163], v[210:213], v[80:83]
	s_setprio 0
	s_setprio 1
	v_mfma_f32_16x16x32_bf16 v[108:111], v[164:167], v[180:183], v[108:111]
	v_mfma_f32_16x16x32_bf16 v[104:107], v[172:175], v[180:183], v[104:107]
	v_mfma_f32_16x16x32_bf16 v[92:95], v[164:167], v[188:191], v[92:95]
	v_mfma_f32_16x16x32_bf16 v[88:91], v[172:175], v[188:191], v[88:91]
	v_mfma_f32_16x16x32_bf16 v[76:79], v[164:167], v[196:199], v[76:79]
	v_mfma_f32_16x16x32_bf16 v[72:75], v[172:175], v[196:199], v[72:75]
	v_mfma_f32_16x16x32_bf16 v[68:71], v[164:167], v[206:209], v[68:71]
	v_mfma_f32_16x16x32_bf16 v[64:67], v[172:175], v[206:209], v[64:67]
	v_mfma_f32_16x16x32_bf16 v[108:111], v[168:171], v[184:187], v[108:111]
	v_mfma_f32_16x16x32_bf16 v[104:107], v[176:179], v[184:187], v[104:107]
	v_mfma_f32_16x16x32_bf16 v[92:95], v[168:171], v[192:195], v[92:95]
	v_mfma_f32_16x16x32_bf16 v[88:91], v[176:179], v[192:195], v[88:91]
	v_mfma_f32_16x16x32_bf16 v[76:79], v[168:171], v[200:203], v[76:79]
	v_mfma_f32_16x16x32_bf16 v[72:75], v[176:179], v[200:203], v[72:75]
	v_mfma_f32_16x16x32_bf16 v[68:71], v[168:171], v[210:213], v[68:71]
	v_mfma_f32_16x16x32_bf16 v[64:67], v[176:179], v[210:213], v[64:67]
	s_setprio 0
	s_barrier
; #define PG8_STAGE(bufoff, gbase, voff) do { const char* _gb = (const char*)(gbase); asm volatile("" : "+s"(_gb));     \
;         _Pragma("unroll") for (int _i = 0; _i < 2; ++_i) \
;         __builtin_amdgcn_global_load_lds((const unsigned*)(_gb + (voff)[_i]), (LAS unsigned*)(lds + (bufoff) + ldsw + _i * 8192), 16, 0, 0); } while (0)
; #define PG8_LDA(dst, b, h) do { _Pragma("unroll") for (int m = 0; m < 4; ++m) _Pragma("unroll") for (int k = 0; k < 2; ++k) dst[m][k] = *(const LAS bf16x8*)(lds + PG8_SA(b, h) + aoff + m * 2048 + k * 1024); } while (0)
; #define PG8_MMA(ai, bj, At, Bt) do { __builtin_amdgcn_s_setprio(1); _Pragma("unroll") for (int m = 0; m < 4; ++m) _Pragma("unroll") for (int n = 0; n < 2; ++n) _Pragma("unroll") for (int k = 0; k < 2; ++k) \
;         acc[ai][bj][m][n] = __builtin_amdgcn_mfma_f32_16x16x32_bf16(Bt[n][k], At[m][k], acc[ai][bj][m][n], 0, 0, 0); __builtin_amdgcn_s_setprio(0); } while (0)
; #define PG8_WAIT_V(n) asm volatile("s_waitcnt vmcnt(" #n ")" ::: "memory")
; #define PG8_WAIT_L(n) asm volatile("s_waitcnt lgkmcnt(" #n ")" ::: "memory")
; #define PG8_BAR __builtin_amdgcn_s_barrier()
; #define PG8_SCHED __builtin_amdgcn_sched_barrier(0)
; template <class Epi>
; __device__ __forceinline__ void gemm_phase(LAS unsigned char* lds, const int wid, const Gemm g, const Epi& E) {
;     ...
;             PG8_WAIT_V(8); PG8_WAIT_L(0); PG8_BAR; PG8_MMA(0, 0, At, B0); PG8_MMA(0, 1, At, B1); PG8_BAR; PG8_SCHED;
;             PG8_LDA(At, 1, 1); PG8_STAGE(PG8_SB(1, 0), b3, voffB); PG8_STAGE(PG8_SB(1, 1), b3 + hstepB, voffB); PG8_STAGE(PG8_SA(1, 0), a3, voffA);
;             PG8_WAIT_V(8); PG8_WAIT_L(0); PG8_BAR; PG8_MMA(1, 0, At, B0); PG8_MMA(1, 1, At, B1); PG8_BAR; PG8_SCHED;
;         }
;         if (wr == 0) PG8_BAR;
	s_mov_b64 s[52:53], s[54:55]
	s_add_i32 s0, s0, s59
	ds_read_b128 v[180:183], v159 offset:49152
	ds_read_b128 v[184:187], v159 offset:50176
	ds_read_b128 v[188:191], v159 offset:51200
	ds_read_b128 v[192:195], v159 offset:52224
	ds_read_b128 v[196:199], v159 offset:53248
	ds_read_b128 v[200:203], v159 offset:54272
	ds_read_b128 v[206:209], v159 offset:55296
	ds_read_b128 v[210:213], v159 offset:56320
	s_mov_b32 m0, s0
	s_nop 0
	global_load_lds_dwordx4 v130, s[52:53]
	s_add_i32 m0, s0, 0x2000
	v_lshl_add_u64 v[152:153], s[52:53], 0, v[134:135]
	s_add_u32 s52, s54, 0x40000
	s_addc_u32 s53, s55, 0
	s_add_i32 s0, s1, s59
	global_load_lds_dwordx4 v[152:153], off
	s_mov_b32 m0, s0
	s_nop 0
	global_load_lds_dwordx4 v130, s[52:53]
	s_add_i32 m0, s0, 0x2000
	s_nop 0
	global_load_lds_dwordx4 v134, s[52:53]
	s_mov_b32 m0, s75
	s_nop 0
	global_load_lds_dwordx4 v128, s[50:51]
	s_mov_b32 m0, s76
	s_nop 0
	global_load_lds_dwordx4 v132, s[50:51]
	s_waitcnt vmcnt(8)
	s_waitcnt lgkmcnt(0)
	s_barrier
	s_setprio 1
	s_waitcnt lgkmcnt(0)
	v_mfma_f32_16x16x32_bf16 v[60:63], v[140:143], v[180:183], v[60:63]
	v_mfma_f32_16x16x32_bf16 v[56:59], v[148:151], v[180:183], v[56:59]
	v_mfma_f32_16x16x32_bf16 v[52:55], v[140:143], v[188:191], v[52:55]
	v_mfma_f32_16x16x32_bf16 v[48:51], v[148:151], v[188:191], v[48:51]
	v_mfma_f32_16x16x32_bf16 v[36:39], v[140:143], v[196:199], v[36:39]
	v_mfma_f32_16x16x32_bf16 v[32:35], v[148:151], v[196:199], v[32:35]
	v_mfma_f32_16x16x32_bf16 v[20:23], v[140:143], v[206:209], v[20:23]
	v_mfma_f32_16x16x32_bf16 v[16:19], v[148:151], v[206:209], v[16:19]
	v_mfma_f32_16x16x32_bf16 v[60:63], v[144:147], v[184:187], v[60:63]
	v_mfma_f32_16x16x32_bf16 v[56:59], v[160:163], v[184:187], v[56:59]
	v_mfma_f32_16x16x32_bf16 v[52:55], v[144:147], v[192:195], v[52:55]
	v_mfma_f32_16x16x32_bf16 v[48:51], v[160:163], v[192:195], v[48:51]
	v_mfma_f32_16x16x32_bf16 v[36:39], v[144:147], v[200:203], v[36:39]
	v_mfma_f32_16x16x32_bf16 v[32:35], v[160:163], v[200:203], v[32:35]
	v_mfma_f32_16x16x32_bf16 v[20:23], v[144:147], v[210:213], v[20:23]
	v_mfma_f32_16x16x32_bf16 v[16:19], v[160:163], v[210:213], v[16:19]
	s_setprio 0
	s_setprio 1
	v_mfma_f32_16x16x32_bf16 v[44:47], v[164:167], v[180:183], v[44:47]
	v_mfma_f32_16x16x32_bf16 v[40:43], v[172:175], v[180:183], v[40:43]
	v_mfma_f32_16x16x32_bf16 v[28:31], v[164:167], v[188:191], v[28:31]
	v_mfma_f32_16x16x32_bf16 v[24:27], v[172:175], v[188:191], v[24:27]
	v_mfma_f32_16x16x32_bf16 v[12:15], v[164:167], v[196:199], v[12:15]
	v_mfma_f32_16x16x32_bf16 v[8:11], v[172:175], v[196:199], v[8:11]
	v_mfma_f32_16x16x32_bf16 v[4:7], v[164:167], v[206:209], v[4:7]
	v_mfma_f32_16x16x32_bf16 v[0:3], v[172:175], v[206:209], v[0:3]
	v_mfma_f32_16x16x32_bf16 v[44:47], v[168:171], v[184:187], v[44:47]
	v_mfma_f32_16x16x32_bf16 v[40:43], v[176:179], v[184:187], v[40:43]
	v_mfma_f32_16x16x32_bf16 v[28:31], v[168:171], v[192:195], v[28:31]
	v_mfma_f32_16x16x32_bf16 v[24:27], v[176:179], v[192:195], v[24:27]
	v_mfma_f32_16x16x32_bf16 v[12:15], v[168:171], v[200:203], v[12:15]
	v_mfma_f32_16x16x32_bf16 v[8:11], v[176:179], v[200:203], v[8:11]
	v_mfma_f32_16x16x32_bf16 v[4:7], v[168:171], v[210:213], v[4:7]
	v_mfma_f32_16x16x32_bf16 v[0:3], v[176:179], v[210:213], v[0:3]
	s_setprio 0
	s_barrier
	s_add_i32 s90, s90, 2
	s_add_u32 s88, s88, 0x100
	s_addc_u32 s89, s89, 0
	s_add_u32 s6, s6, 0x100
	s_addc_u32 s7, s7, 0
	s_cmp_gt_u32 s90, 13
	s_cbranch_scc0 .LBB0_2479
	s_and_b64 vcc, exec, s[12:13]
	s_cbranch_vccz .LBB0_2482
	s_barrier

; #define PG8_STAGE(bufoff, gbase, voff) do { const char* _gb = (const char*)(gbase); asm volatile("" : "+s"(_gb));     \
;         _Pragma("unroll") for (int _i = 0; _i < 2; ++_i) \
;         __builtin_amdgcn_global_load_lds((const unsigned*)(_gb + (voff)[_i]), (LAS unsigned*)(lds + (bufoff) + ldsw + _i * 8192), 16, 0, 0); } while (0)
; #define PG8_WAIT_V(n) asm volatile("s_waitcnt vmcnt(" #n ")" ::: "memory")
; #define PG8_BAR __builtin_amdgcn_s_barrier()
; template <class Epi>
; __device__ __forceinline__ void gemm_phase(LAS unsigned char* lds, const int wid, const Gemm g, const Epi& E) {
;     ...
;     const char* cA = PG8_UA(cur); const char* cB = PG8_UB(cur);
;     PG8_STAGE(PG8_SB(0, 0), PG8_BP(cB, 0), voffB); PG8_STAGE(PG8_SB(0, 1), PG8_BP(cB, 0) + hstepB, voffB); PG8_STAGE(PG8_SA(0, 0), PG8_AP(cA, 0), voffA); PG8_STAGE(PG8_SA(0, 1), PG8_AP(cA, 0) + hstepA, voffA);
;     if (wr == 1) PG8_BAR;
;     PG8_WAIT_V(2); PG8_BAR;
;     PG8_STAGE(PG8_SB(1, 0), PG8_BP(cB, 1), voffB); PG8_STAGE(PG8_SA(1, 0), PG8_AP(cA, 1), voffA); PG8_STAGE(PG8_SB(1, 1), PG8_BP(cB, 1) + hstepB, voffB);
;     PG8_WAIT_V(6); PG8_BAR;
;     for (;;) {
;         const bool has_next = S.next(ui + 1, nxt);
;         const char* nA = has_next ? PG8_UA(nxt) : cA; const char* nB = has_next ? PG8_UB(nxt) : cB;
.LBB0_2591:
	s_add_u32 s71, s6, 0x9800000
	s_addc_u32 s72, s7, 0
	s_add_u32 s14, s18, 0x1d800000
	s_addc_u32 s15, s19, 0
	s_add_u32 s4, s48, 0x80
	s_addc_u32 s5, s49, 0
	s_waitcnt vmcnt(2)
	s_barrier
	s_add_i32 m0, s17, 0x18000
	s_nop 0
	global_load_lds_dwordx4 v130, s[4:5]
	s_add_i32 m0, s17, 0x1a000
	v_lshl_add_u64 v[0:1], s[4:5], 0, v[134:135]
	s_add_u32 s4, s50, 0x880
	s_addc_u32 s5, s51, 0
	s_add_i32 s73, s17, 0x8000
	global_load_lds_dwordx4 v[0:1], off
	s_mov_b32 m0, s73
	s_add_i32 s74, s17, 0xa000
	global_load_lds_dwordx4 v128, s[4:5]
	v_lshl_add_u64 v[0:1], s[4:5], 0, v[132:133]
	s_add_u32 s4, s48, 0x80080
	s_mov_b32 m0, s74
	s_addc_u32 s5, s49, 0
	global_load_lds_dwordx4 v[0:1], off
	s_add_i32 m0, s17, 0x1c000
	s_nop 0
	global_load_lds_dwordx4 v130, s[4:5]
	s_add_i32 m0, s17, 0x1e000
	v_ashrrev_i32_e32 v2, 6, v155
	global_load_lds_dwordx4 v134, s[4:5]
	v_and_b32_e32 v0, 15, v155
	v_or_b32_e32 v1, s60, v0
	v_lshlrev_b32_e32 v3, 6, v1
	v_and_b32_e32 v4, 48, v155
	s_movk_i32 s0, 0x3c0
	v_lshlrev_b32_e32 v1, 2, v1
	v_and_or_b32 v3, v3, s0, v4
	v_lshl_add_u32 v5, v2, 10, s57
	v_and_b32_e32 v1, 32, v1
	v_bitop3_b32 v1, v3, v5, v1 bitop3:0xde
	v_lshlrev_b32_e32 v3, 2, v155
	v_lshl_or_b32 v0, v0, 6, v4
	v_add_lshl_u32 v2, v2, s56, 10
	v_and_b32_e32 v3, 32, v3
	s_waitcnt vmcnt(6)
	v_bitop3_b32 v156, v0, v2, v3 bitop3:0xde
	s_add_i32 s78, 0, 0x10000
	s_add_i32 s79, 0, 0x14000
	s_ashr_i32 s75, s58, 31
	v_mov_b64_e32 v[136:137], 0x300
	v_mov_b64_e32 v[138:139], 0x2ff
	s_movk_i32 s76, 0x61
	s_movk_i32 s77, 0x800
	v_add_u32_e32 v157, s78, v156
	v_add_u32_e32 v158, s79, v156
	v_add_u32_e32 v159, 0, v1
	s_mov_b64 s[18:19], 0x40000
	s_movk_i32 s80, 0xa0
	s_movk_i32 s81, 0xffbf
	s_mov_b64 s[20:21], 0x20000
	s_mov_b64 s[24:25], 0x24000
	s_mov_b64 s[26:27], 0x28000
	s_mov_b64 s[28:29], 0x2c000
	s_brev_b32 s82, 64
	s_mov_b32 s83, 0x40000
	s_mov_b64 s[30:31], 0x48000
	s_mov_b32 s84, 0x48000
	s_mov_b64 s[34:35], 0x50000
	s_mov_b32 s85, 0x50000
	s_mov_b64 s[38:39], 0x58000
	s_barrier
	s_branch .LBB0_2594

; #define PG8_STAGE(bufoff, gbase, voff) do { const char* _gb = (const char*)(gbase); asm volatile("" : "+s"(_gb));     \
;         _Pragma("unroll") for (int _i = 0; _i < 2; ++_i) \
;         __builtin_amdgcn_global_load_lds((const unsigned*)(_gb + (voff)[_i]), (LAS unsigned*)(lds + (bufoff) + ldsw + _i * 8192), 16, 0, 0); } while (0)
; #define PG8_LDA(dst, b, h) do { _Pragma("unroll") for (int m = 0; m < 4; ++m) _Pragma("unroll") for (int k = 0; k < 2; ++k) dst[m][k] = *(const LAS bf16x8*)(lds + PG8_SA(b, h) + aoff + m * 2048 + k * 1024); } while (0)
; #define PG8_LDB(dst, b, h) do { _Pragma("unroll") for (int n = 0; n < 2; ++n) _Pragma("unroll") for (int k = 0; k < 2; ++k) dst[n][k] = *(const LAS bf16x8*)(lds + PG8_SB(b, h) + boff + n * 2048 + k * 1024); } while (0)
; #define PG8_MMA(ai, bj, At, Bt) do { __builtin_amdgcn_s_setprio(1); _Pragma("unroll") for (int m = 0; m < 4; ++m) _Pragma("unroll") for (int n = 0; n < 2; ++n) _Pragma("unroll") for (int k = 0; k < 2; ++k) \
;         acc[ai][bj][m][n] = __builtin_amdgcn_mfma_f32_16x16x32_bf16(Bt[n][k], At[m][k], acc[ai][bj][m][n], 0, 0, 0); __builtin_amdgcn_s_setprio(0); } while (0)
; #define PG8_WAIT_V(n) asm volatile("s_waitcnt vmcnt(" #n ")" ::: "memory")
; #define PG8_WAIT_L(n) asm volatile("s_waitcnt lgkmcnt(" #n ")" ::: "memory")
; #define PG8_BAR __builtin_amdgcn_s_barrier()
; template <class Epi>
; __device__ __forceinline__ void gemm_phase(LAS unsigned char* lds, const int wid, const Gemm g, const Epi& E) {
;     ...
;             const bool last = (t == nt - 2);
;             const char* a1 = PG8_AP(cA, t + 1);
;             const char* a2 = last ? PG8_AP(nA, 0) : PG8_AP(cA, t + 2); const char* b2 = last ? PG8_BP(nB, 0) : PG8_BP(cB, t + 2);
;             const char* a3 = last ? PG8_AP(nA, 1) : PG8_AP(cA, t + 3); const char* b3 = last ? PG8_BP(nB, 1) : PG8_BP(cB, t + 3);
;             PG8_LDB(B0, 0, 0); PG8_LDB(B1, 0, 1); PG8_SCHED; PG8_LDA(At, 0, 0); PG8_STAGE(PG8_SA(1, 1), a1 + hstepA, voffA);
;             PG8_WAIT_V(8); PG8_WAIT_L(0); PG8_BAR; PG8_MMA(0, 0, At, B0); PG8_MMA(0, 1, At, B1); PG8_BAR; PG8_SCHED;
;             PG8_LDA(At, 0, 1); PG8_STAGE(PG8_SB(0, 0), b2, voffB); PG8_STAGE(PG8_SB(0, 1), b2 + hstepB, voffB); PG8_STAGE(PG8_SA(0, 0), a2, voffA);
;             PG8_WAIT_V(8); PG8_WAIT_L(0); PG8_BAR; PG8_MMA(1, 0, At, B0); PG8_MMA(1, 1, At, B1); PG8_BAR; PG8_SCHED;
.LBB0_2599:
	s_add_i32 s91, s91, 2
	s_cmp_lt_u32 s91, 16
	s_cselect_b32 s0, 0, -1
	s_cselect_b32 s1, s77, 0xfffff800
	s_cmp_lt_u32 s91, 14
	s_cselect_b32 s53, s77, 0xfffff800
	s_cselect_b32 s52, 0, -1
	s_add_u32 s53, s53, s6
	s_addc_u32 s52, s52, s7
	s_add_u32 s53, s50, s53
	s_addc_u32 s52, s51, s52
	s_add_u32 s53, s53, 0x100
	s_addc_u32 s52, s52, 0
	s_add_u32 s54, s48, s6
	s_addc_u32 s55, s49, s7
	s_add_u32 s92, s54, 0x100
	s_addc_u32 s93, s55, 0
	s_cmp_lt_u32 s91, 13
	s_cselect_b32 s57, s77, 0xfffff800
	s_cselect_b32 s56, 0, -1
	s_add_u32 s57, s57, s6
	s_addc_u32 s56, s56, s7
	s_add_u32 s57, s50, s57
	s_addc_u32 s56, s51, s56
	s_add_u32 s94, s57, 0x180
	s_addc_u32 s95, s56, 0
	ds_read_b128 v[140:143], v157
	ds_read_b128 v[144:147], v157 offset:1024
	ds_read_b128 v[148:151], v157 offset:2048
	ds_read_b128 v[160:163], v157 offset:3072
	ds_read_b128 v[164:167], v158
	ds_read_b128 v[168:171], v158 offset:1024
	ds_read_b128 v[172:175], v158 offset:2048
	ds_read_b128 v[176:179], v158 offset:3072
	s_add_u32 s96, s54, 0x180
	s_addc_u32 s97, s55, 0
	s_add_u32 s1, s1, s6
	s_addc_u32 s0, s0, s7
	s_add_u32 s1, s50, s1
	s_addc_u32 s0, s51, s0
	s_add_u32 s56, s1, 0x40080
	s_addc_u32 s57, s0, 0
	s_add_i32 s1, s78, s59
	s_add_i32 m0, s17, 0xc000
	s_add_i32 s0, s17, 0xe000
	s_add_i32 vcc_lo, s1, 0x2000
	s_cmpk_eq_i32 s6, 0xf00
	s_cselect_b32 s55, s86, s52
	s_cselect_b32 s54, s43, s53
	s_cselect_b32 s93, s9, s93
	s_cselect_b32 s92, s41, s92
	s_cselect_b32 s53, s88, s95
	s_cselect_b32 s52, s87, s94
	ds_read_b128 v[180:183], v159
	ds_read_b128 v[184:187], v159 offset:1024
	ds_read_b128 v[188:191], v159 offset:2048
	ds_read_b128 v[192:195], v159 offset:3072
	ds_read_b128 v[196:199], v159 offset:4096
	ds_read_b128 v[200:203], v159 offset:5120
	ds_read_b128 v[206:209], v159 offset:6144
	ds_read_b128 v[210:213], v159 offset:7168
	s_nop 0
	global_load_lds_dwordx4 v128, s[56:57]
	s_mov_b32 m0, s0
	s_nop 0
	global_load_lds_dwordx4 v132, s[56:57]
	s_waitcnt vmcnt(8)
	s_waitcnt lgkmcnt(0)
	s_barrier
	s_setprio 1
	s_waitcnt lgkmcnt(0)
	v_mfma_f32_16x16x32_bf16 v[124:127], v[140:143], v[180:183], v[124:127]
	v_mfma_f32_16x16x32_bf16 v[120:123], v[148:151], v[180:183], v[120:123]
	v_mfma_f32_16x16x32_bf16 v[116:119], v[140:143], v[188:191], v[116:119]
	v_mfma_f32_16x16x32_bf16 v[112:115], v[148:151], v[188:191], v[112:115]
	v_mfma_f32_16x16x32_bf16 v[100:103], v[140:143], v[196:199], v[100:103]
	v_mfma_f32_16x16x32_bf16 v[96:99], v[148:151], v[196:199], v[96:99]
	v_mfma_f32_16x16x32_bf16 v[84:87], v[140:143], v[206:209], v[84:87]
	v_mfma_f32_16x16x32_bf16 v[80:83], v[148:151], v[206:209], v[80:83]
	v_mfma_f32_16x16x32_bf16 v[124:127], v[144:147], v[184:187], v[124:127]
	v_mfma_f32_16x16x32_bf16 v[120:123], v[160:163], v[184:187], v[120:123]
	v_mfma_f32_16x16x32_bf16 v[116:119], v[144:147], v[192:195], v[116:119]
	v_mfma_f32_16x16x32_bf16 v[112:115], v[160:163], v[192:195], v[112:115]
	v_mfma_f32_16x16x32_bf16 v[100:103], v[144:147], v[200:203], v[100:103]
	v_mfma_f32_16x16x32_bf16 v[96:99], v[160:163], v[200:203], v[96:99]
	v_mfma_f32_16x16x32_bf16 v[84:87], v[144:147], v[210:213], v[84:87]
	v_mfma_f32_16x16x32_bf16 v[80:83], v[160:163], v[210:213], v[80:83]
	s_setprio 0
	s_setprio 1
	v_mfma_f32_16x16x32_bf16 v[108:111], v[164:167], v[180:183], v[108:111]
	v_mfma_f32_16x16x32_bf16 v[104:107], v[172:175], v[180:183], v[104:107]
	v_mfma_f32_16x16x32_bf16 v[92:95], v[164:167], v[188:191], v[92:95]
	v_mfma_f32_16x16x32_bf16 v[88:91], v[172:175], v[188:191], v[88:91]
	v_mfma_f32_16x16x32_bf16 v[76:79], v[164:167], v[196:199], v[76:79]
	v_mfma_f32_16x16x32_bf16 v[72:75], v[172:175], v[196:199], v[72:75]
	v_mfma_f32_16x16x32_bf16 v[68:71], v[164:167], v[206:209], v[68:71]
	v_mfma_f32_16x16x32_bf16 v[64:67], v[172:175], v[206:209], v[64:67]
	v_mfma_f32_16x16x32_bf16 v[108:111], v[168:171], v[184:187], v[108:111]
	v_mfma_f32_16x16x32_bf16 v[104:107], v[176:179], v[184:187], v[104:107]
	v_mfma_f32_16x16x32_bf16 v[92:95], v[168:171], v[192:195], v[92:95]
	v_mfma_f32_16x16x32_bf16 v[88:91], v[176:179], v[192:195], v[88:91]
	v_mfma_f32_16x16x32_bf16 v[76:79], v[168:171], v[200:203], v[76:79]
	v_mfma_f32_16x16x32_bf16 v[72:75], v[176:179], v[200:203], v[72:75]
	v_mfma_f32_16x16x32_bf16 v[68:71], v[168:171], v[210:213], v[68:71]
	v_mfma_f32_16x16x32_bf16 v[64:67], v[176:179], v[210:213], v[64:67]
	s_setprio 0
	s_barrier
	s_mov_b64 s[56:57], s[92:93]
	s_mov_b32 m0, s1
	ds_read_b128 v[180:183], v159 offset:16384
	ds_read_b128 v[184:187], v159 offset:17408
	ds_read_b128 v[188:191], v159 offset:18432
	ds_read_b128 v[192:195], v159 offset:19456
	ds_read_b128 v[196:199], v159 offset:20480
	ds_read_b128 v[200:203], v159 offset:21504
	ds_read_b128 v[206:209], v159 offset:22528
	ds_read_b128 v[210:213], v159 offset:23552
	s_nop 0
	global_load_lds_dwordx4 v130, s[56:57]
	v_lshl_add_u64 v[152:153], s[56:57], 0, v[134:135]
	s_cselect_b32 s57, s90, s97
	s_cselect_b32 s56, s89, s96
	s_add_u32 s92, s92, 0x80000
	s_mov_b32 m0, vcc_lo
	s_addc_u32 s93, s93, 0
	s_add_i32 s0, s79, s59
	global_load_lds_dwordx4 v[152:153], off
	s_mov_b32 m0, s0
	s_nop 0
	global_load_lds_dwordx4 v130, s[92:93]
	v_lshl_add_u64 v[152:153], s[92:93], 0, v[134:135]
	s_add_i32 m0, s0, 0x2000
	s_mov_b64 s[92:93], s[54:55]
	global_load_lds_dwordx4 v[152:153], off
	s_mov_b32 m0, s17
	s_nop 0
	global_load_lds_dwordx4 v128, s[92:93]
	s_mov_b32 m0, s67
	s_nop 0
	global_load_lds_dwordx4 v132, s[92:93]
	s_waitcnt vmcnt(8)
	s_waitcnt lgkmcnt(0)
	s_barrier
; #define PG8_STAGE(bufoff, gbase, voff) do { const char* _gb = (const char*)(gbase); asm volatile("" : "+s"(_gb));     \
;         _Pragma("unroll") for (int _i = 0; _i < 2; ++_i) \
;         __builtin_amdgcn_global_load_lds((const unsigned*)(_gb + (voff)[_i]), (LAS unsigned*)(lds + (bufoff) + ldsw + _i * 8192), 16, 0, 0); } while (0)
; #define PG8_LDA(dst, b, h) do { _Pragma("unroll") for (int m = 0; m < 4; ++m) _Pragma("unroll") for (int k = 0; k < 2; ++k) dst[m][k] = *(const LAS bf16x8*)(lds + PG8_SA(b, h) + aoff + m * 2048 + k * 1024); } while (0)
; #define PG8_LDB(dst, b, h) do { _Pragma("unroll") for (int n = 0; n < 2; ++n) _Pragma("unroll") for (int k = 0; k < 2; ++k) dst[n][k] = *(const LAS bf16x8*)(lds + PG8_SB(b, h) + boff + n * 2048 + k * 1024); } while (0)
; #define PG8_MMA(ai, bj, At, Bt) do { __builtin_amdgcn_s_setprio(1); _Pragma("unroll") for (int m = 0; m < 4; ++m) _Pragma("unroll") for (int n = 0; n < 2; ++n) _Pragma("unroll") for (int k = 0; k < 2; ++k) \
;         acc[ai][bj][m][n] = __builtin_amdgcn_mfma_f32_16x16x32_bf16(Bt[n][k], At[m][k], acc[ai][bj][m][n], 0, 0, 0); __builtin_amdgcn_s_setprio(0); } while (0)
; #define PG8_WAIT_V(n) asm volatile("s_waitcnt vmcnt(" #n ")" ::: "memory")
; #define PG8_WAIT_L(n) asm volatile("s_waitcnt lgkmcnt(" #n ")" ::: "memory")
; #define PG8_BAR __builtin_amdgcn_s_barrier()
; #define PG8_SCHED __builtin_amdgcn_sched_barrier(0)
; template <class Epi>
; __device__ __forceinline__ void gemm_phase(LAS unsigned char* lds, const int wid, const Gemm g, const Epi& E) {
;     ...
;             PG8_WAIT_V(8); PG8_WAIT_L(0); PG8_BAR; PG8_MMA(1, 0, At, B0); PG8_MMA(1, 1, At, B1); PG8_BAR; PG8_SCHED;
;             PG8_LDB(B0, 1, 0); PG8_LDB(B1, 1, 1); PG8_SCHED; PG8_LDA(At, 1, 0); PG8_STAGE(PG8_SA(0, 1), a2 + hstepA, voffA);
;             PG8_WAIT_V(8); PG8_WAIT_L(0); PG8_BAR; PG8_MMA(0, 0, At, B0); PG8_MMA(0, 1, At, B1); PG8_BAR; PG8_SCHED;
	s_setprio 1
	s_waitcnt lgkmcnt(0)
	v_mfma_f32_16x16x32_bf16 v[60:63], v[140:143], v[180:183], v[60:63]
	v_mfma_f32_16x16x32_bf16 v[56:59], v[148:151], v[180:183], v[56:59]
	v_mfma_f32_16x16x32_bf16 v[52:55], v[140:143], v[188:191], v[52:55]
	v_mfma_f32_16x16x32_bf16 v[48:51], v[148:151], v[188:191], v[48:51]
	v_mfma_f32_16x16x32_bf16 v[36:39], v[140:143], v[196:199], v[36:39]
	v_mfma_f32_16x16x32_bf16 v[32:35], v[148:151], v[196:199], v[32:35]
	v_mfma_f32_16x16x32_bf16 v[20:23], v[140:143], v[206:209], v[20:23]
	v_mfma_f32_16x16x32_bf16 v[16:19], v[148:151], v[206:209], v[16:19]
	v_mfma_f32_16x16x32_bf16 v[60:63], v[144:147], v[184:187], v[60:63]
	v_mfma_f32_16x16x32_bf16 v[56:59], v[160:163], v[184:187], v[56:59]
	v_mfma_f32_16x16x32_bf16 v[52:55], v[144:147], v[192:195], v[52:55]
	v_mfma_f32_16x16x32_bf16 v[48:51], v[160:163], v[192:195], v[48:51]
	v_mfma_f32_16x16x32_bf16 v[36:39], v[144:147], v[200:203], v[36:39]
	v_mfma_f32_16x16x32_bf16 v[32:35], v[160:163], v[200:203], v[32:35]
	v_mfma_f32_16x16x32_bf16 v[20:23], v[144:147], v[210:213], v[20:23]
	v_mfma_f32_16x16x32_bf16 v[16:19], v[160:163], v[210:213], v[16:19]
	s_setprio 0
	s_setprio 1
	v_mfma_f32_16x16x32_bf16 v[44:47], v[164:167], v[180:183], v[44:47]
	v_mfma_f32_16x16x32_bf16 v[40:43], v[172:175], v[180:183], v[40:43]
	v_mfma_f32_16x16x32_bf16 v[28:31], v[164:167], v[188:191], v[28:31]
	v_mfma_f32_16x16x32_bf16 v[24:27], v[172:175], v[188:191], v[24:27]
	v_mfma_f32_16x16x32_bf16 v[12:15], v[164:167], v[196:199], v[12:15]
	v_mfma_f32_16x16x32_bf16 v[8:11], v[172:175], v[196:199], v[8:11]
	v_mfma_f32_16x16x32_bf16 v[4:7], v[164:167], v[206:209], v[4:7]
	v_mfma_f32_16x16x32_bf16 v[0:3], v[172:175], v[206:209], v[0:3]
	v_mfma_f32_16x16x32_bf16 v[44:47], v[168:171], v[184:187], v[44:47]
	v_mfma_f32_16x16x32_bf16 v[40:43], v[176:179], v[184:187], v[40:43]
	v_mfma_f32_16x16x32_bf16 v[28:31], v[168:171], v[192:195], v[28:31]
	v_mfma_f32_16x16x32_bf16 v[24:27], v[176:179], v[192:195], v[24:27]
	v_mfma_f32_16x16x32_bf16 v[12:15], v[168:171], v[200:203], v[12:15]
	v_mfma_f32_16x16x32_bf16 v[8:11], v[176:179], v[200:203], v[8:11]
	v_mfma_f32_16x16x32_bf16 v[4:7], v[168:171], v[210:213], v[4:7]
	v_mfma_f32_16x16x32_bf16 v[0:3], v[176:179], v[210:213], v[0:3]
	s_setprio 0
	s_barrier
	s_add_i32 s0, 0, 0x18000
	v_add_u32_e32 v152, s0, v156
	s_add_i32 s1, 0, 0x1c000
	ds_read_b128 v[140:143], v152
	ds_read_b128 v[144:147], v152 offset:1024
	ds_read_b128 v[148:151], v152 offset:2048
	ds_read_b128 v[160:163], v152 offset:3072
	v_add_u32_e32 v152, s1, v156
	ds_read_b128 v[164:167], v152
	ds_read_b128 v[168:171], v152 offset:1024
	ds_read_b128 v[172:175], v152 offset:2048
	ds_read_b128 v[176:179], v152 offset:3072
	s_add_u32 s54, s54, 0x40000
	s_addc_u32 s55, s55, 0
	s_mov_b32 m0, s68
	ds_read_b128 v[180:183], v159 offset:32768
	ds_read_b128 v[184:187], v159 offset:33792
	ds_read_b128 v[188:191], v159 offset:34816
	ds_read_b128 v[192:195], v159 offset:35840
	ds_read_b128 v[196:199], v159 offset:36864
	ds_read_b128 v[200:203], v159 offset:37888
	ds_read_b128 v[206:209], v159 offset:38912
	ds_read_b128 v[210:213], v159 offset:39936
	s_nop 0
	global_load_lds_dwordx4 v128, s[54:55]
	s_mov_b32 m0, s69
	s_nop 0
	global_load_lds_dwordx4 v132, s[54:55]
	s_waitcnt vmcnt(8)
	s_waitcnt lgkmcnt(0)
	s_barrier
	s_setprio 1
	s_waitcnt lgkmcnt(0)
	v_mfma_f32_16x16x32_bf16 v[124:127], v[140:143], v[180:183], v[124:127]
	v_mfma_f32_16x16x32_bf16 v[120:123], v[148:151], v[180:183], v[120:123]
	v_mfma_f32_16x16x32_bf16 v[116:119], v[140:143], v[188:191], v[116:119]
	v_mfma_f32_16x16x32_bf16 v[112:115], v[148:151], v[188:191], v[112:115]
	v_mfma_f32_16x16x32_bf16 v[100:103], v[140:143], v[196:199], v[100:103]
	v_mfma_f32_16x16x32_bf16 v[96:99], v[148:151], v[196:199], v[96:99]
	v_mfma_f32_16x16x32_bf16 v[84:87], v[140:143], v[206:209], v[84:87]
	v_mfma_f32_16x16x32_bf16 v[80:83], v[148:151], v[206:209], v[80:83]
	v_mfma_f32_16x16x32_bf16 v[124:127], v[144:147], v[184:187], v[124:127]
	v_mfma_f32_16x16x32_bf16 v[120:123], v[160:163], v[184:187], v[120:123]
	v_mfma_f32_16x16x32_bf16 v[116:119], v[144:147], v[192:195], v[116:119]
	v_mfma_f32_16x16x32_bf16 v[112:115], v[160:163], v[192:195], v[112:115]
	v_mfma_f32_16x16x32_bf16 v[100:103], v[144:147], v[200:203], v[100:103]
	v_mfma_f32_16x16x32_bf16 v[96:99], v[160:163], v[200:203], v[96:99]
	v_mfma_f32_16x16x32_bf16 v[84:87], v[144:147], v[210:213], v[84:87]
	v_mfma_f32_16x16x32_bf16 v[80:83], v[160:163], v[210:213], v[80:83]
	s_setprio 0
	s_setprio 1
	v_mfma_f32_16x16x32_bf16 v[108:111], v[164:167], v[180:183], v[108:111]
	v_mfma_f32_16x16x32_bf16 v[104:107], v[172:175], v[180:183], v[104:107]
	v_mfma_f32_16x16x32_bf16 v[92:95], v[164:167], v[188:191], v[92:95]
	v_mfma_f32_16x16x32_bf16 v[88:91], v[172:175], v[188:191], v[88:91]
	v_mfma_f32_16x16x32_bf16 v[76:79], v[164:167], v[196:199], v[76:79]
	v_mfma_f32_16x16x32_bf16 v[72:75], v[172:175], v[196:199], v[72:75]
	v_mfma_f32_16x16x32_bf16 v[68:71], v[164:167], v[206:209], v[68:71]
	v_mfma_f32_16x16x32_bf16 v[64:67], v[172:175], v[206:209], v[64:67]
	v_mfma_f32_16x16x32_bf16 v[108:111], v[168:171], v[184:187], v[108:111]
	v_mfma_f32_16x16x32_bf16 v[104:107], v[176:179], v[184:187], v[104:107]
	v_mfma_f32_16x16x32_bf16 v[92:95], v[168:171], v[192:195], v[92:95]
	v_mfma_f32_16x16x32_bf16 v[88:91], v[176:179], v[192:195], v[88:91]
	v_mfma_f32_16x16x32_bf16 v[76:79], v[168:171], v[200:203], v[76:79]
	v_mfma_f32_16x16x32_bf16 v[72:75], v[176:179], v[200:203], v[72:75]
	v_mfma_f32_16x16x32_bf16 v[68:71], v[168:171], v[210:213], v[68:71]
	v_mfma_f32_16x16x32_bf16 v[64:67], v[176:179], v[210:213], v[64:67]
	s_setprio 0
	s_barrier
; #define PG8_STAGE(bufoff, gbase, voff) do { const char* _gb = (const char*)(gbase); asm volatile("" : "+s"(_gb));     \
;         _Pragma("unroll") for (int _i = 0; _i < 2; ++_i) \
;         __builtin_amdgcn_global_load_lds((const unsigned*)(_gb + (voff)[_i]), (LAS unsigned*)(lds + (bufoff) + ldsw + _i * 8192), 16, 0, 0); } while (0)
; #define PG8_LDA(dst, b, h) do { _Pragma("unroll") for (int m = 0; m < 4; ++m) _Pragma("unroll") for (int k = 0; k < 2; ++k) dst[m][k] = *(const LAS bf16x8*)(lds + PG8_SA(b, h) + aoff + m * 2048 + k * 1024); } while (0)
; #define PG8_MMA(ai, bj, At, Bt) do { __builtin_amdgcn_s_setprio(1); _Pragma("unroll") for (int m = 0; m < 4; ++m) _Pragma("unroll") for (int n = 0; n < 2; ++n) _Pragma("unroll") for (int k = 0; k < 2; ++k) \
;         acc[ai][bj][m][n] = __builtin_amdgcn_mfma_f32_16x16x32_bf16(Bt[n][k], At[m][k], acc[ai][bj][m][n], 0, 0, 0); __builtin_amdgcn_s_setprio(0); } while (0)
; #define PG8_WAIT_V(n) asm volatile("s_waitcnt vmcnt(" #n ")" ::: "memory")
; #define PG8_WAIT_L(n) asm volatile("s_waitcnt lgkmcnt(" #n ")" ::: "memory")
; #define PG8_BAR __builtin_amdgcn_s_barrier()
; #define PG8_SCHED __builtin_amdgcn_sched_barrier(0)
; template <class Epi>
; __device__ __forceinline__ void gemm_phase(LAS unsigned char* lds, const int wid, const Gemm g, const Epi& E) {
;     ...
;             PG8_WAIT_V(8); PG8_WAIT_L(0); PG8_BAR; PG8_MMA(0, 0, At, B0); PG8_MMA(0, 1, At, B1); PG8_BAR; PG8_SCHED;
;             PG8_LDA(At, 1, 1); PG8_STAGE(PG8_SB(1, 0), b3, voffB); PG8_STAGE(PG8_SB(1, 1), b3 + hstepB, voffB); PG8_STAGE(PG8_SA(1, 0), a3, voffA);
;             PG8_WAIT_V(8); PG8_WAIT_L(0); PG8_BAR; PG8_MMA(1, 0, At, B0); PG8_MMA(1, 1, At, B1); PG8_BAR; PG8_SCHED;
;         }
;         if (wr == 0) PG8_BAR;
	s_mov_b64 s[54:55], s[56:57]
	s_add_i32 s0, s0, s59
	ds_read_b128 v[180:183], v159 offset:49152
	ds_read_b128 v[184:187], v159 offset:50176
	ds_read_b128 v[188:191], v159 offset:51200
	ds_read_b128 v[192:195], v159 offset:52224
	ds_read_b128 v[196:199], v159 offset:53248
	ds_read_b128 v[200:203], v159 offset:54272
	ds_read_b128 v[206:209], v159 offset:55296
	ds_read_b128 v[210:213], v159 offset:56320
	s_mov_b32 m0, s0
	s_nop 0
	global_load_lds_dwordx4 v130, s[54:55]
	s_add_i32 m0, s0, 0x2000
	v_lshl_add_u64 v[152:153], s[54:55], 0, v[134:135]
	s_add_u32 s54, s56, 0x80000
	s_addc_u32 s55, s57, 0
	s_add_i32 s0, s1, s59
	global_load_lds_dwordx4 v[152:153], off
	s_mov_b32 m0, s0
	s_nop 0
	global_load_lds_dwordx4 v130, s[54:55]
	s_add_i32 m0, s0, 0x2000
	s_nop 0
	global_load_lds_dwordx4 v134, s[54:55]
	s_mov_b32 m0, s73
	s_nop 0
	global_load_lds_dwordx4 v128, s[52:53]
	s_mov_b32 m0, s74
	s_nop 0
	global_load_lds_dwordx4 v132, s[52:53]
	s_waitcnt vmcnt(8)
	s_waitcnt lgkmcnt(0)
	s_barrier
	s_setprio 1
	s_waitcnt lgkmcnt(0)
	v_mfma_f32_16x16x32_bf16 v[60:63], v[140:143], v[180:183], v[60:63]
	v_mfma_f32_16x16x32_bf16 v[56:59], v[148:151], v[180:183], v[56:59]
	v_mfma_f32_16x16x32_bf16 v[52:55], v[140:143], v[188:191], v[52:55]
	v_mfma_f32_16x16x32_bf16 v[48:51], v[148:151], v[188:191], v[48:51]
	v_mfma_f32_16x16x32_bf16 v[36:39], v[140:143], v[196:199], v[36:39]
	v_mfma_f32_16x16x32_bf16 v[32:35], v[148:151], v[196:199], v[32:35]
	v_mfma_f32_16x16x32_bf16 v[20:23], v[140:143], v[206:209], v[20:23]
	v_mfma_f32_16x16x32_bf16 v[16:19], v[148:151], v[206:209], v[16:19]
	v_mfma_f32_16x16x32_bf16 v[60:63], v[144:147], v[184:187], v[60:63]
	v_mfma_f32_16x16x32_bf16 v[56:59], v[160:163], v[184:187], v[56:59]
	v_mfma_f32_16x16x32_bf16 v[52:55], v[144:147], v[192:195], v[52:55]
	v_mfma_f32_16x16x32_bf16 v[48:51], v[160:163], v[192:195], v[48:51]
	v_mfma_f32_16x16x32_bf16 v[36:39], v[144:147], v[200:203], v[36:39]
	v_mfma_f32_16x16x32_bf16 v[32:35], v[160:163], v[200:203], v[32:35]
	v_mfma_f32_16x16x32_bf16 v[20:23], v[144:147], v[210:213], v[20:23]
	v_mfma_f32_16x16x32_bf16 v[16:19], v[160:163], v[210:213], v[16:19]
	s_setprio 0
	s_setprio 1
	v_mfma_f32_16x16x32_bf16 v[44:47], v[164:167], v[180:183], v[44:47]
	v_mfma_f32_16x16x32_bf16 v[40:43], v[172:175], v[180:183], v[40:43]
	v_mfma_f32_16x16x32_bf16 v[28:31], v[164:167], v[188:191], v[28:31]
	v_mfma_f32_16x16x32_bf16 v[24:27], v[172:175], v[188:191], v[24:27]
	v_mfma_f32_16x16x32_bf16 v[12:15], v[164:167], v[196:199], v[12:15]
	v_mfma_f32_16x16x32_bf16 v[8:11], v[172:175], v[196:199], v[8:11]
	v_mfma_f32_16x16x32_bf16 v[4:7], v[164:167], v[206:209], v[4:7]
	v_mfma_f32_16x16x32_bf16 v[0:3], v[172:175], v[206:209], v[0:3]
	v_mfma_f32_16x16x32_bf16 v[44:47], v[168:171], v[184:187], v[44:47]
	v_mfma_f32_16x16x32_bf16 v[40:43], v[176:179], v[184:187], v[40:43]
	v_mfma_f32_16x16x32_bf16 v[28:31], v[168:171], v[192:195], v[28:31]
	v_mfma_f32_16x16x32_bf16 v[24:27], v[176:179], v[192:195], v[24:27]
	v_mfma_f32_16x16x32_bf16 v[12:15], v[168:171], v[200:203], v[12:15]
	v_mfma_f32_16x16x32_bf16 v[8:11], v[176:179], v[200:203], v[8:11]
	v_mfma_f32_16x16x32_bf16 v[4:7], v[168:171], v[210:213], v[4:7]
	v_mfma_f32_16x16x32_bf16 v[0:3], v[176:179], v[210:213], v[0:3]
	s_setprio 0
	s_barrier
	s_add_u32 s6, s6, 0x100
	s_addc_u32 s7, s7, 0
	s_cmp_gt_u32 s91, 29
	s_cbranch_scc0 .LBB0_2599
	s_and_b64 vcc, exec, s[12:13]
	s_cbranch_vccz .LBB0_2602
	s_barrier

; #define PG8_STAGE(bufoff, gbase, voff) do { const char* _gb = (const char*)(gbase); asm volatile("" : "+s"(_gb));     \
;         _Pragma("unroll") for (int _i = 0; _i < 2; ++_i) \
;         __builtin_amdgcn_global_load_lds((const unsigned*)(_gb + (voff)[_i]), (LAS unsigned*)(lds + (bufoff) + ldsw + _i * 8192), 16, 0, 0); } while (0)
; #define PG8_WAIT_V(n) asm volatile("s_waitcnt vmcnt(" #n ")" ::: "memory")
; #define PG8_BAR __builtin_amdgcn_s_barrier()
; template <class Epi>
; __device__ __forceinline__ void gemm_phase(LAS unsigned char* lds, const int wid, const Gemm g, const Epi& E) {
;     ...
;     for (int i = 0; i < 2; ++i) { int R, C; stage_rc(tid * 16 + i * 8192, R, C); const int Rb = Epi::PERM ? ((R & ~31) + perm32(R & 31)) : R;
;         voffA[i] = (unsigned)(R * g.lda + C) * 2u; voffB[i] = (unsigned)(Rb * g.ldb + C) * 2u; }
;     const size_t kstep = (size_t)(BK * 2);
;     const size_t hstepA = (size_t)HALF * g.lda * 2, hstepB = (size_t)HALF * g.ldb * 2;
;     const unsigned ldsw = (unsigned)wid * 1024u;
;     const int aoff = lds_byte(wr * 64 + fr, fq * 8), boff = lds_byte(wc * 32 + fr, fq * 8);
;     ...
;     const char* cA = PG8_UA(cur); const char* cB = PG8_UB(cur);
;     PG8_STAGE(PG8_SB(0, 0), PG8_BP(cB, 0), voffB); PG8_STAGE(PG8_SB(0, 1), PG8_BP(cB, 0) + hstepB, voffB); PG8_STAGE(PG8_SA(0, 0), PG8_AP(cA, 0), voffA); PG8_STAGE(PG8_SA(0, 1), PG8_AP(cA, 0) + hstepA, voffA);
;     if (wr == 1) PG8_BAR;
;     PG8_WAIT_V(2); PG8_BAR;
;     PG8_STAGE(PG8_SB(1, 0), PG8_BP(cB, 1), voffB); PG8_STAGE(PG8_SA(1, 0), PG8_AP(cA, 1), voffA); PG8_STAGE(PG8_SB(1, 1), PG8_BP(cB, 1) + hstepB, voffB);
;     PG8_WAIT_V(6); PG8_BAR;
.LBB0_2761:
	s_lshl_b32 s1, s33, 5
	s_and_b32 s58, s1, 0x60
	s_lshl_b32 s57, s14, 6
	s_lshl_b32 s0, s14, 13
	s_lshr_b32 s1, s58, 3
	s_cmp_lt_u32 s33, 4
	s_cselect_b64 s[14:15], -1, 0
	s_add_u32 s59, s18, 0x15800000
	s_addc_u32 s60, s19, 0
	s_add_u32 s2, s40, 0x80
	s_addc_u32 s3, s41, 0
	s_waitcnt vmcnt(2)
	s_barrier
	s_add_i32 m0, s52, 0x18000
	s_nop 0
	global_load_lds_dwordx4 v138, s[2:3]
	s_add_i32 m0, s52, 0x1a000
	v_lshl_add_u64 v[0:1], s[2:3], 0, v[142:143]
	s_add_u32 s2, s42, 0x80
	s_addc_u32 s3, s43, 0
	s_add_i32 s61, s52, 0x8000
	global_load_lds_dwordx4 v[0:1], off
	s_mov_b32 m0, s61
	s_add_i32 s62, s52, 0xa000
	global_load_lds_dwordx4 v136, s[2:3]
	v_lshl_add_u64 v[0:1], s[2:3], 0, v[140:141]
	s_add_u32 s2, s40, 0x18080
	s_mov_b32 m0, s62
	s_addc_u32 s3, s41, 0
	global_load_lds_dwordx4 v[0:1], off
	s_add_i32 m0, s52, 0x1c000
	s_nop 0
	global_load_lds_dwordx4 v138, s[2:3]
	s_add_i32 m0, s52, 0x1e000
	v_lshlrev_b32_e32 v3, 6, v161
	global_load_lds_dwordx4 v142, s[2:3]
	v_ashrrev_i32_e32 v0, 6, v161
	v_and_b32_e32 v1, 48, v161
	v_lshl_add_u32 v2, v0, 10, s0
	s_movk_i32 s0, 0x3c0
	v_and_or_b32 v1, v3, s0, v1
	v_lshlrev_b32_e32 v3, 2, v161
	s_waitcnt lgkmcnt(0)
	s_ashr_i32 s63, s46, 31
	v_and_b32_e32 v3, 32, v3
	v_add_lshl_u32 v0, v0, s1, 10
	s_waitcnt vmcnt(6)
	s_add_u32 s18, s18, 0x11800000
	v_bitop3_b32 v2, v1, v2, v3 bitop3:0xde
	v_bitop3_b32 v162, v1, v0, v3 bitop3:0xde
	s_addc_u32 s19, s19, 0
	s_add_i32 s65, 0, 0x10000
	s_add_i32 s66, 0, 0x14000
	s_mov_b64 s[16:17], 0x80
	v_mov_b64_e32 v[144:145], 0x600
	v_mov_b64_e32 v[146:147], 0x5ff
	s_movk_i32 s64, 0xc1
	v_add_u32_e32 v163, s65, v162
	v_add_u32_e32 v164, s66, v162
	v_add_u32_e32 v165, 0, v2
	s_movk_i32 s67, 0xa0
	s_brev_b32 s68, 64
	s_mov_b64 s[20:21], 0x24000
	s_mov_b64 s[24:25], 0x28000
	s_mov_b64 s[26:27], 0x2c000
	v_mov_b32_e32 v166, 0x3f1b4598
	s_barrier
	s_branch .LBB0_2764

; #define PG8_STAGE(bufoff, gbase, voff) do { const char* _gb = (const char*)(gbase); asm volatile("" : "+s"(_gb));     \
;         _Pragma("unroll") for (int _i = 0; _i < 2; ++_i) \
;         __builtin_amdgcn_global_load_lds((const unsigned*)(_gb + (voff)[_i]), (LAS unsigned*)(lds + (bufoff) + ldsw + _i * 8192), 16, 0, 0); } while (0)
; #define PG8_LDA(dst, b, h) do { _Pragma("unroll") for (int m = 0; m < 4; ++m) _Pragma("unroll") for (int k = 0; k < 2; ++k) dst[m][k] = *(const LAS bf16x8*)(lds + PG8_SA(b, h) + aoff + m * 2048 + k * 1024); } while (0)
; #define PG8_LDB(dst, b, h) do { _Pragma("unroll") for (int n = 0; n < 2; ++n) _Pragma("unroll") for (int k = 0; k < 2; ++k) dst[n][k] = *(const LAS bf16x8*)(lds + PG8_SB(b, h) + boff + n * 2048 + k * 1024); } while (0)
; #define PG8_MMA(ai, bj, At, Bt) do { __builtin_amdgcn_s_setprio(1); _Pragma("unroll") for (int m = 0; m < 4; ++m) _Pragma("unroll") for (int n = 0; n < 2; ++n) _Pragma("unroll") for (int k = 0; k < 2; ++k) \
;         acc[ai][bj][m][n] = __builtin_amdgcn_mfma_f32_16x16x32_bf16(Bt[n][k], At[m][k], acc[ai][bj][m][n], 0, 0, 0); __builtin_amdgcn_s_setprio(0); } while (0)
; #define PG8_WAIT_V(n) asm volatile("s_waitcnt vmcnt(" #n ")" ::: "memory")
; #define PG8_WAIT_L(n) asm volatile("s_waitcnt lgkmcnt(" #n ")" ::: "memory")
; #define PG8_BAR __builtin_amdgcn_s_barrier()
; template <class Epi>
; __device__ __forceinline__ void gemm_phase(LAS unsigned char* lds, const int wid, const Gemm g, const Epi& E) {
;     ...
;             const bool last = (t == nt - 2);
;             const char* a1 = PG8_AP(cA, t + 1);
;             const char* a2 = last ? PG8_AP(nA, 0) : PG8_AP(cA, t + 2); const char* b2 = last ? PG8_BP(nB, 0) : PG8_BP(cB, t + 2);
;             const char* a3 = last ? PG8_AP(nA, 1) : PG8_AP(cA, t + 3); const char* b3 = last ? PG8_BP(nB, 1) : PG8_BP(cB, t + 3);
;             PG8_LDB(B0, 0, 0); PG8_LDB(B1, 0, 1); PG8_SCHED; PG8_LDA(At, 0, 0); PG8_STAGE(PG8_SA(1, 1), a1 + hstepA, voffA);
;             PG8_WAIT_V(8); PG8_WAIT_L(0); PG8_BAR; PG8_MMA(0, 0, At, B0); PG8_MMA(0, 1, At, B1); PG8_BAR; PG8_SCHED;
;             PG8_LDA(At, 0, 1); PG8_STAGE(PG8_SB(0, 0), b2, voffB); PG8_STAGE(PG8_SB(0, 1), b2 + hstepB, voffB); PG8_STAGE(PG8_SA(0, 0), a2, voffA);
;             PG8_WAIT_V(8); PG8_WAIT_L(0); PG8_BAR; PG8_MMA(1, 0, At, B0); PG8_MMA(1, 1, At, B1); PG8_BAR; PG8_SCHED;
.LBB0_2769:
	ds_read_b128 v[104:107], v163
	ds_read_b128 v[108:111], v163 offset:1024
	ds_read_b128 v[148:151], v163 offset:2048
	ds_read_b128 v[152:155], v163 offset:3072
	ds_read_b128 v[156:159], v164
	ds_read_b128 v[168:171], v164 offset:1024
	ds_read_b128 v[172:175], v164 offset:2048
	ds_read_b128 v[176:179], v164 offset:3072
	s_add_u32 s0, s4, 0xfffe0080
	s_addc_u32 s1, s5, -1
	s_add_u32 s40, s75, 0xffffff80
	s_addc_u32 s41, s76, -1
	s_add_u32 s44, s4, 0xfffe0100
	s_addc_u32 s45, s5, -1
	s_add_i32 s81, s65, s47
	s_add_i32 m0, s52, 0xc000
	s_add_i32 s80, s52, 0xe000
	s_add_i32 s82, s81, 0x2000
	s_cmp_eq_u32 s77, 2
	s_cselect_b32 s43, s29, s1
	s_cselect_b32 s42, s39, s0
	s_cselect_b32 s79, s31, s41
	s_cselect_b32 s78, s30, s40
	s_cselect_b32 s41, s72, s45
	s_cselect_b32 s40, s71, s44
	s_mov_b64 s[44:45], s[4:5]
	ds_read_b128 v[180:183], v165
	ds_read_b128 v[184:187], v165 offset:1024
	ds_read_b128 v[188:191], v165 offset:2048
	ds_read_b128 v[192:195], v165 offset:3072
	ds_read_b128 v[196:199], v165 offset:4096
	ds_read_b128 v[200:203], v165 offset:5120
	ds_read_b128 v[206:209], v165 offset:6144
	ds_read_b128 v[210:213], v165 offset:7168
	s_nop 0
	global_load_lds_dwordx4 v136, s[44:45]
	s_mov_b32 m0, s80
	s_nop 0
	global_load_lds_dwordx4 v140, s[44:45]
	s_waitcnt vmcnt(8)
	s_waitcnt lgkmcnt(0)
	s_barrier
	s_setprio 1
	s_waitcnt lgkmcnt(0)
	v_mfma_f32_16x16x32_bf16 v[132:135], v[104:107], v[180:183], v[132:135]
	v_mfma_f32_16x16x32_bf16 v[128:131], v[148:151], v[180:183], v[128:131]
	v_mfma_f32_16x16x32_bf16 v[124:127], v[104:107], v[188:191], v[124:127]
	v_mfma_f32_16x16x32_bf16 v[120:123], v[148:151], v[188:191], v[120:123]
	v_mfma_f32_16x16x32_bf16 v[116:119], v[104:107], v[196:199], v[116:119]
	v_mfma_f32_16x16x32_bf16 v[112:115], v[148:151], v[196:199], v[112:115]
	v_mfma_f32_16x16x32_bf16 v[100:103], v[104:107], v[206:209], v[100:103]
	v_mfma_f32_16x16x32_bf16 v[96:99], v[148:151], v[206:209], v[96:99]
	v_mfma_f32_16x16x32_bf16 v[132:135], v[108:111], v[184:187], v[132:135]
	v_mfma_f32_16x16x32_bf16 v[128:131], v[152:155], v[184:187], v[128:131]
	v_mfma_f32_16x16x32_bf16 v[124:127], v[108:111], v[192:195], v[124:127]
	v_mfma_f32_16x16x32_bf16 v[120:123], v[152:155], v[192:195], v[120:123]
	v_mfma_f32_16x16x32_bf16 v[116:119], v[108:111], v[200:203], v[116:119]
	v_mfma_f32_16x16x32_bf16 v[112:115], v[152:155], v[200:203], v[112:115]
	v_mfma_f32_16x16x32_bf16 v[100:103], v[108:111], v[210:213], v[100:103]
	v_mfma_f32_16x16x32_bf16 v[96:99], v[152:155], v[210:213], v[96:99]
	s_setprio 0
	s_setprio 1
	v_mfma_f32_16x16x32_bf16 v[60:63], v[156:159], v[180:183], v[60:63]
	v_mfma_f32_16x16x32_bf16 v[56:59], v[172:175], v[180:183], v[56:59]
	v_mfma_f32_16x16x32_bf16 v[52:55], v[156:159], v[188:191], v[52:55]
	v_mfma_f32_16x16x32_bf16 v[48:51], v[172:175], v[188:191], v[48:51]
	v_mfma_f32_16x16x32_bf16 v[44:47], v[156:159], v[196:199], v[44:47]
	v_mfma_f32_16x16x32_bf16 v[40:43], v[172:175], v[196:199], v[40:43]
	v_mfma_f32_16x16x32_bf16 v[36:39], v[156:159], v[206:209], v[36:39]
	v_mfma_f32_16x16x32_bf16 v[32:35], v[172:175], v[206:209], v[32:35]
	v_mfma_f32_16x16x32_bf16 v[60:63], v[168:171], v[184:187], v[60:63]
	v_mfma_f32_16x16x32_bf16 v[56:59], v[176:179], v[184:187], v[56:59]
	v_mfma_f32_16x16x32_bf16 v[52:55], v[168:171], v[192:195], v[52:55]
	v_mfma_f32_16x16x32_bf16 v[48:51], v[176:179], v[192:195], v[48:51]
	v_mfma_f32_16x16x32_bf16 v[44:47], v[168:171], v[200:203], v[44:47]
	v_mfma_f32_16x16x32_bf16 v[40:43], v[176:179], v[200:203], v[40:43]
	v_mfma_f32_16x16x32_bf16 v[36:39], v[168:171], v[210:213], v[36:39]
	v_mfma_f32_16x16x32_bf16 v[32:35], v[176:179], v[210:213], v[32:35]
	s_setprio 0
	s_barrier
	s_mov_b64 s[44:45], s[78:79]
	s_mov_b32 m0, s81
	ds_read_b128 v[180:183], v165 offset:16384
	ds_read_b128 v[184:187], v165 offset:17408
	ds_read_b128 v[188:191], v165 offset:18432
	ds_read_b128 v[192:195], v165 offset:19456
	ds_read_b128 v[196:199], v165 offset:20480
	ds_read_b128 v[200:203], v165 offset:21504
	ds_read_b128 v[206:209], v165 offset:22528
	ds_read_b128 v[210:213], v165 offset:23552
	s_nop 0
	global_load_lds_dwordx4 v138, s[44:45]
	v_lshl_add_u64 v[204:205], s[44:45], 0, v[142:143]
	s_cselect_b32 s45, s74, s76
	s_cselect_b32 s44, s73, s75
	s_add_u32 s78, s78, 0x18000
	s_mov_b32 m0, s82
	s_addc_u32 s79, s79, 0
	s_add_i32 s0, s66, s47
	global_load_lds_dwordx4 v[204:205], off
	s_mov_b32 m0, s0
	s_nop 0
	global_load_lds_dwordx4 v138, s[78:79]
	v_lshl_add_u64 v[204:205], s[78:79], 0, v[142:143]
	s_add_i32 m0, s0, 0x2000
	s_mov_b64 s[78:79], s[42:43]
	global_load_lds_dwordx4 v[204:205], off
	s_mov_b32 m0, s52
	s_nop 0
	global_load_lds_dwordx4 v136, s[78:79]
	s_mov_b32 m0, s53
	s_nop 0
	global_load_lds_dwordx4 v140, s[78:79]
	s_waitcnt vmcnt(8)
	s_waitcnt lgkmcnt(0)
	s_barrier
; #define PG8_STAGE(bufoff, gbase, voff) do { const char* _gb = (const char*)(gbase); asm volatile("" : "+s"(_gb));     \
;         _Pragma("unroll") for (int _i = 0; _i < 2; ++_i) \
;         __builtin_amdgcn_global_load_lds((const unsigned*)(_gb + (voff)[_i]), (LAS unsigned*)(lds + (bufoff) + ldsw + _i * 8192), 16, 0, 0); } while (0)
; #define PG8_LDA(dst, b, h) do { _Pragma("unroll") for (int m = 0; m < 4; ++m) _Pragma("unroll") for (int k = 0; k < 2; ++k) dst[m][k] = *(const LAS bf16x8*)(lds + PG8_SA(b, h) + aoff + m * 2048 + k * 1024); } while (0)
; #define PG8_LDB(dst, b, h) do { _Pragma("unroll") for (int n = 0; n < 2; ++n) _Pragma("unroll") for (int k = 0; k < 2; ++k) dst[n][k] = *(const LAS bf16x8*)(lds + PG8_SB(b, h) + boff + n * 2048 + k * 1024); } while (0)
; #define PG8_MMA(ai, bj, At, Bt) do { __builtin_amdgcn_s_setprio(1); _Pragma("unroll") for (int m = 0; m < 4; ++m) _Pragma("unroll") for (int n = 0; n < 2; ++n) _Pragma("unroll") for (int k = 0; k < 2; ++k) \
;         acc[ai][bj][m][n] = __builtin_amdgcn_mfma_f32_16x16x32_bf16(Bt[n][k], At[m][k], acc[ai][bj][m][n], 0, 0, 0); __builtin_amdgcn_s_setprio(0); } while (0)
; #define PG8_WAIT_V(n) asm volatile("s_waitcnt vmcnt(" #n ")" ::: "memory")
; #define PG8_WAIT_L(n) asm volatile("s_waitcnt lgkmcnt(" #n ")" ::: "memory")
; #define PG8_BAR __builtin_amdgcn_s_barrier()
; #define PG8_SCHED __builtin_amdgcn_sched_barrier(0)
; template <class Epi>
; __device__ __forceinline__ void gemm_phase(LAS unsigned char* lds, const int wid, const Gemm g, const Epi& E) {
;     ...
;             PG8_WAIT_V(8); PG8_WAIT_L(0); PG8_BAR; PG8_MMA(1, 0, At, B0); PG8_MMA(1, 1, At, B1); PG8_BAR; PG8_SCHED;
;             PG8_LDB(B0, 1, 0); PG8_LDB(B1, 1, 1); PG8_SCHED; PG8_LDA(At, 1, 0); PG8_STAGE(PG8_SA(0, 1), a2 + hstepA, voffA);
;             PG8_WAIT_V(8); PG8_WAIT_L(0); PG8_BAR; PG8_MMA(0, 0, At, B0); PG8_MMA(0, 1, At, B1); PG8_BAR; PG8_SCHED;
	s_setprio 1
	s_waitcnt lgkmcnt(0)
	v_mfma_f32_16x16x32_bf16 v[92:95], v[104:107], v[180:183], v[92:95]
	v_mfma_f32_16x16x32_bf16 v[88:91], v[148:151], v[180:183], v[88:91]
	v_mfma_f32_16x16x32_bf16 v[84:87], v[104:107], v[188:191], v[84:87]
	v_mfma_f32_16x16x32_bf16 v[80:83], v[148:151], v[188:191], v[80:83]
	v_mfma_f32_16x16x32_bf16 v[76:79], v[104:107], v[196:199], v[76:79]
	v_mfma_f32_16x16x32_bf16 v[72:75], v[148:151], v[196:199], v[72:75]
	v_mfma_f32_16x16x32_bf16 v[68:71], v[104:107], v[206:209], v[68:71]
	v_mfma_f32_16x16x32_bf16 v[64:67], v[148:151], v[206:209], v[64:67]
	v_mfma_f32_16x16x32_bf16 v[92:95], v[108:111], v[184:187], v[92:95]
	v_mfma_f32_16x16x32_bf16 v[88:91], v[152:155], v[184:187], v[88:91]
	v_mfma_f32_16x16x32_bf16 v[84:87], v[108:111], v[192:195], v[84:87]
	v_mfma_f32_16x16x32_bf16 v[80:83], v[152:155], v[192:195], v[80:83]
	v_mfma_f32_16x16x32_bf16 v[76:79], v[108:111], v[200:203], v[76:79]
	v_mfma_f32_16x16x32_bf16 v[72:75], v[152:155], v[200:203], v[72:75]
	v_mfma_f32_16x16x32_bf16 v[68:71], v[108:111], v[210:213], v[68:71]
	v_mfma_f32_16x16x32_bf16 v[64:67], v[152:155], v[210:213], v[64:67]
	s_setprio 0
	s_setprio 1
	v_mfma_f32_16x16x32_bf16 v[28:31], v[156:159], v[180:183], v[28:31]
	v_mfma_f32_16x16x32_bf16 v[24:27], v[172:175], v[180:183], v[24:27]
	v_mfma_f32_16x16x32_bf16 v[20:23], v[156:159], v[188:191], v[20:23]
	v_mfma_f32_16x16x32_bf16 v[16:19], v[172:175], v[188:191], v[16:19]
	v_mfma_f32_16x16x32_bf16 v[12:15], v[156:159], v[196:199], v[12:15]
	v_mfma_f32_16x16x32_bf16 v[8:11], v[172:175], v[196:199], v[8:11]
	v_mfma_f32_16x16x32_bf16 v[4:7], v[156:159], v[206:209], v[4:7]
	v_mfma_f32_16x16x32_bf16 v[0:3], v[172:175], v[206:209], v[0:3]
	v_mfma_f32_16x16x32_bf16 v[28:31], v[168:171], v[184:187], v[28:31]
	v_mfma_f32_16x16x32_bf16 v[24:27], v[176:179], v[184:187], v[24:27]
	v_mfma_f32_16x16x32_bf16 v[20:23], v[168:171], v[192:195], v[20:23]
	v_mfma_f32_16x16x32_bf16 v[16:19], v[176:179], v[192:195], v[16:19]
	v_mfma_f32_16x16x32_bf16 v[12:15], v[168:171], v[200:203], v[12:15]
	v_mfma_f32_16x16x32_bf16 v[8:11], v[176:179], v[200:203], v[8:11]
	v_mfma_f32_16x16x32_bf16 v[4:7], v[168:171], v[210:213], v[4:7]
	v_mfma_f32_16x16x32_bf16 v[0:3], v[176:179], v[210:213], v[0:3]
	s_setprio 0
	s_barrier
	s_add_i32 s0, 0, 0x18000
	s_add_i32 s1, 0, 0x1c000
	v_add_u32_e32 v152, s0, v162
	v_add_u32_e32 v167, s1, v162
	ds_read_b128 v[104:107], v152
	ds_read_b128 v[108:111], v152 offset:1024
	ds_read_b128 v[148:151], v152 offset:2048
	ds_read_b128 v[152:155], v152 offset:3072
	ds_read_b128 v[156:159], v167
	ds_read_b128 v[168:171], v167 offset:1024
	ds_read_b128 v[172:175], v167 offset:2048
	ds_read_b128 v[176:179], v167 offset:3072
	s_add_u32 s42, s42, 0x20000
	s_addc_u32 s43, s43, 0
	s_mov_b32 m0, s54
	ds_read_b128 v[180:183], v165 offset:32768
	ds_read_b128 v[184:187], v165 offset:33792
	ds_read_b128 v[188:191], v165 offset:34816
	ds_read_b128 v[192:195], v165 offset:35840
	ds_read_b128 v[196:199], v165 offset:36864
	ds_read_b128 v[200:203], v165 offset:37888
	ds_read_b128 v[206:209], v165 offset:38912
	ds_read_b128 v[210:213], v165 offset:39936
	s_nop 0
	global_load_lds_dwordx4 v136, s[42:43]
	s_mov_b32 m0, s55
	s_nop 0
	global_load_lds_dwordx4 v140, s[42:43]
	s_waitcnt vmcnt(8)
	s_waitcnt lgkmcnt(0)
	s_barrier
	s_setprio 1
	s_waitcnt lgkmcnt(0)
	v_mfma_f32_16x16x32_bf16 v[132:135], v[104:107], v[180:183], v[132:135]
	v_mfma_f32_16x16x32_bf16 v[128:131], v[148:151], v[180:183], v[128:131]
	v_mfma_f32_16x16x32_bf16 v[124:127], v[104:107], v[188:191], v[124:127]
	v_mfma_f32_16x16x32_bf16 v[120:123], v[148:151], v[188:191], v[120:123]
	v_mfma_f32_16x16x32_bf16 v[116:119], v[104:107], v[196:199], v[116:119]
	v_mfma_f32_16x16x32_bf16 v[112:115], v[148:151], v[196:199], v[112:115]
	v_mfma_f32_16x16x32_bf16 v[100:103], v[104:107], v[206:209], v[100:103]
	v_mfma_f32_16x16x32_bf16 v[96:99], v[148:151], v[206:209], v[96:99]
	v_mfma_f32_16x16x32_bf16 v[132:135], v[108:111], v[184:187], v[132:135]
	v_mfma_f32_16x16x32_bf16 v[128:131], v[152:155], v[184:187], v[128:131]
	v_mfma_f32_16x16x32_bf16 v[124:127], v[108:111], v[192:195], v[124:127]
	v_mfma_f32_16x16x32_bf16 v[120:123], v[152:155], v[192:195], v[120:123]
	v_mfma_f32_16x16x32_bf16 v[116:119], v[108:111], v[200:203], v[116:119]
	v_mfma_f32_16x16x32_bf16 v[112:115], v[152:155], v[200:203], v[112:115]
	v_mfma_f32_16x16x32_bf16 v[100:103], v[108:111], v[210:213], v[100:103]
	v_mfma_f32_16x16x32_bf16 v[96:99], v[152:155], v[210:213], v[96:99]
	s_setprio 0
	s_setprio 1
	v_mfma_f32_16x16x32_bf16 v[60:63], v[156:159], v[180:183], v[60:63]
	v_mfma_f32_16x16x32_bf16 v[56:59], v[172:175], v[180:183], v[56:59]
	v_mfma_f32_16x16x32_bf16 v[52:55], v[156:159], v[188:191], v[52:55]
	v_mfma_f32_16x16x32_bf16 v[48:51], v[172:175], v[188:191], v[48:51]
	v_mfma_f32_16x16x32_bf16 v[44:47], v[156:159], v[196:199], v[44:47]
	v_mfma_f32_16x16x32_bf16 v[40:43], v[172:175], v[196:199], v[40:43]
	v_mfma_f32_16x16x32_bf16 v[36:39], v[156:159], v[206:209], v[36:39]
	v_mfma_f32_16x16x32_bf16 v[32:35], v[172:175], v[206:209], v[32:35]
	v_mfma_f32_16x16x32_bf16 v[60:63], v[168:171], v[184:187], v[60:63]
	v_mfma_f32_16x16x32_bf16 v[56:59], v[176:179], v[184:187], v[56:59]
	v_mfma_f32_16x16x32_bf16 v[52:55], v[168:171], v[192:195], v[52:55]
	v_mfma_f32_16x16x32_bf16 v[48:51], v[176:179], v[192:195], v[48:51]
	v_mfma_f32_16x16x32_bf16 v[44:47], v[168:171], v[200:203], v[44:47]
	v_mfma_f32_16x16x32_bf16 v[40:43], v[176:179], v[200:203], v[40:43]
	v_mfma_f32_16x16x32_bf16 v[36:39], v[168:171], v[210:213], v[36:39]
	v_mfma_f32_16x16x32_bf16 v[32:35], v[176:179], v[210:213], v[32:35]
	s_setprio 0
	s_barrier
; #define PG8_STAGE(bufoff, gbase, voff) do { const char* _gb = (const char*)(gbase); asm volatile("" : "+s"(_gb));     \
;         _Pragma("unroll") for (int _i = 0; _i < 2; ++_i) \
;         __builtin_amdgcn_global_load_lds((const unsigned*)(_gb + (voff)[_i]), (LAS unsigned*)(lds + (bufoff) + ldsw + _i * 8192), 16, 0, 0); } while (0)
; #define PG8_LDA(dst, b, h) do { _Pragma("unroll") for (int m = 0; m < 4; ++m) _Pragma("unroll") for (int k = 0; k < 2; ++k) dst[m][k] = *(const LAS bf16x8*)(lds + PG8_SA(b, h) + aoff + m * 2048 + k * 1024); } while (0)
; #define PG8_MMA(ai, bj, At, Bt) do { __builtin_amdgcn_s_setprio(1); _Pragma("unroll") for (int m = 0; m < 4; ++m) _Pragma("unroll") for (int n = 0; n < 2; ++n) _Pragma("unroll") for (int k = 0; k < 2; ++k) \
;         acc[ai][bj][m][n] = __builtin_amdgcn_mfma_f32_16x16x32_bf16(Bt[n][k], At[m][k], acc[ai][bj][m][n], 0, 0, 0); __builtin_amdgcn_s_setprio(0); } while (0)
; #define PG8_WAIT_V(n) asm volatile("s_waitcnt vmcnt(" #n ")" ::: "memory")
; #define PG8_WAIT_L(n) asm volatile("s_waitcnt lgkmcnt(" #n ")" ::: "memory")
; #define PG8_BAR __builtin_amdgcn_s_barrier()
; #define PG8_SCHED __builtin_amdgcn_sched_barrier(0)
; template <class Epi>
; __device__ __forceinline__ void gemm_phase(LAS unsigned char* lds, const int wid, const Gemm g, const Epi& E) {
;     ...
;             PG8_LDA(At, 1, 1); PG8_STAGE(PG8_SB(1, 0), b3, voffB); PG8_STAGE(PG8_SB(1, 1), b3 + hstepB, voffB); PG8_STAGE(PG8_SA(1, 0), a3, voffA);
;             PG8_WAIT_V(8); PG8_WAIT_L(0); PG8_BAR; PG8_MMA(1, 0, At, B0); PG8_MMA(1, 1, At, B1); PG8_BAR; PG8_SCHED;
;         }
	s_mov_b64 s[42:43], s[44:45]
	s_add_i32 s0, s0, s47
	ds_read_b128 v[180:183], v165 offset:49152
	ds_read_b128 v[184:187], v165 offset:50176
	ds_read_b128 v[188:191], v165 offset:51200
	ds_read_b128 v[192:195], v165 offset:52224
	ds_read_b128 v[196:199], v165 offset:53248
	ds_read_b128 v[200:203], v165 offset:54272
	ds_read_b128 v[206:209], v165 offset:55296
	ds_read_b128 v[210:213], v165 offset:56320
	s_mov_b32 m0, s0
	s_nop 0
	global_load_lds_dwordx4 v138, s[42:43]
	s_add_i32 m0, s0, 0x2000
	v_lshl_add_u64 v[204:205], s[42:43], 0, v[142:143]
	s_add_u32 s42, s44, 0x18000
	s_addc_u32 s43, s45, 0
	s_add_i32 s0, s1, s47
	global_load_lds_dwordx4 v[204:205], off
	s_mov_b32 m0, s0
	s_nop 0
	global_load_lds_dwordx4 v138, s[42:43]
	s_add_i32 m0, s0, 0x2000
	s_nop 0
	global_load_lds_dwordx4 v142, s[42:43]
	s_mov_b32 m0, s61
	s_nop 0
	global_load_lds_dwordx4 v136, s[40:41]
	s_mov_b32 m0, s62
	s_nop 0
	global_load_lds_dwordx4 v140, s[40:41]
	s_waitcnt vmcnt(8)
	s_waitcnt lgkmcnt(0)
	s_barrier
	s_setprio 1
	s_waitcnt lgkmcnt(0)
	v_mfma_f32_16x16x32_bf16 v[92:95], v[104:107], v[180:183], v[92:95]
	v_mfma_f32_16x16x32_bf16 v[88:91], v[148:151], v[180:183], v[88:91]
	v_mfma_f32_16x16x32_bf16 v[84:87], v[104:107], v[188:191], v[84:87]
	v_mfma_f32_16x16x32_bf16 v[80:83], v[148:151], v[188:191], v[80:83]
	v_mfma_f32_16x16x32_bf16 v[76:79], v[104:107], v[196:199], v[76:79]
	v_mfma_f32_16x16x32_bf16 v[72:75], v[148:151], v[196:199], v[72:75]
	v_mfma_f32_16x16x32_bf16 v[68:71], v[104:107], v[206:209], v[68:71]
	v_mfma_f32_16x16x32_bf16 v[64:67], v[148:151], v[206:209], v[64:67]
	v_mfma_f32_16x16x32_bf16 v[92:95], v[108:111], v[184:187], v[92:95]
	v_mfma_f32_16x16x32_bf16 v[88:91], v[152:155], v[184:187], v[88:91]
	v_mfma_f32_16x16x32_bf16 v[84:87], v[108:111], v[192:195], v[84:87]
	v_mfma_f32_16x16x32_bf16 v[80:83], v[152:155], v[192:195], v[80:83]
	v_mfma_f32_16x16x32_bf16 v[76:79], v[108:111], v[200:203], v[76:79]
	v_mfma_f32_16x16x32_bf16 v[72:75], v[152:155], v[200:203], v[72:75]
	v_mfma_f32_16x16x32_bf16 v[68:71], v[108:111], v[210:213], v[68:71]
	v_mfma_f32_16x16x32_bf16 v[64:67], v[152:155], v[210:213], v[64:67]
	s_setprio 0
	s_setprio 1
	v_mfma_f32_16x16x32_bf16 v[28:31], v[156:159], v[180:183], v[28:31]
	v_mfma_f32_16x16x32_bf16 v[24:27], v[172:175], v[180:183], v[24:27]
	v_mfma_f32_16x16x32_bf16 v[20:23], v[156:159], v[188:191], v[20:23]
	v_mfma_f32_16x16x32_bf16 v[16:19], v[172:175], v[188:191], v[16:19]
	v_mfma_f32_16x16x32_bf16 v[12:15], v[156:159], v[196:199], v[12:15]
	v_mfma_f32_16x16x32_bf16 v[8:11], v[172:175], v[196:199], v[8:11]
	v_mfma_f32_16x16x32_bf16 v[4:7], v[156:159], v[206:209], v[4:7]
	v_mfma_f32_16x16x32_bf16 v[0:3], v[172:175], v[206:209], v[0:3]
	v_mfma_f32_16x16x32_bf16 v[28:31], v[168:171], v[184:187], v[28:31]
	v_mfma_f32_16x16x32_bf16 v[24:27], v[176:179], v[184:187], v[24:27]
	v_mfma_f32_16x16x32_bf16 v[20:23], v[168:171], v[192:195], v[20:23]
	v_mfma_f32_16x16x32_bf16 v[16:19], v[176:179], v[192:195], v[16:19]
	v_mfma_f32_16x16x32_bf16 v[12:15], v[168:171], v[200:203], v[12:15]
	v_mfma_f32_16x16x32_bf16 v[8:11], v[176:179], v[200:203], v[8:11]
	v_mfma_f32_16x16x32_bf16 v[4:7], v[168:171], v[210:213], v[4:7]
	v_mfma_f32_16x16x32_bf16 v[0:3], v[176:179], v[210:213], v[0:3]
	s_setprio 0
	s_barrier
	s_add_i32 s77, s77, 2
	s_add_u32 s75, s75, 0x100
	s_addc_u32 s76, s76, 0
	s_add_u32 s4, s4, 0x100
	s_addc_u32 s5, s5, 0
	s_cmp_gt_u32 s77, 3
	s_cbranch_scc0 .LBB0_2769
	s_and_b64 vcc, exec, s[14:15]
	s_cbranch_vccz .LBB0_2772
	s_barrier

; #define PG8_STAGE(bufoff, gbase, voff) do { const char* _gb = (const char*)(gbase); asm volatile("" : "+s"(_gb));     \
;         _Pragma("unroll") for (int _i = 0; _i < 2; ++_i) \
;         __builtin_amdgcn_global_load_lds((const unsigned*)(_gb + (voff)[_i]), (LAS unsigned*)(lds + (bufoff) + ldsw + _i * 8192), 16, 0, 0); } while (0)
; #define PG8_WAIT_V(n) asm volatile("s_waitcnt vmcnt(" #n ")" ::: "memory")
; #define PG8_BAR __builtin_amdgcn_s_barrier()
; template <class Epi>
; __device__ __forceinline__ void gemm_phase(LAS unsigned char* lds, const int wid, const Gemm g, const Epi& E) {
;     ...
;     const char* cA = PG8_UA(cur); const char* cB = PG8_UB(cur);
;     PG8_STAGE(PG8_SB(0, 0), PG8_BP(cB, 0), voffB); PG8_STAGE(PG8_SB(0, 1), PG8_BP(cB, 0) + hstepB, voffB); PG8_STAGE(PG8_SA(0, 0), PG8_AP(cA, 0), voffA); PG8_STAGE(PG8_SA(0, 1), PG8_AP(cA, 0) + hstepA, voffA);
;     if (wr == 1) PG8_BAR;
;     PG8_WAIT_V(2); PG8_BAR;
;     PG8_STAGE(PG8_SB(1, 0), PG8_BP(cB, 1), voffB); PG8_STAGE(PG8_SA(1, 0), PG8_AP(cA, 1), voffA); PG8_STAGE(PG8_SB(1, 1), PG8_BP(cB, 1) + hstepB, voffB);
;     PG8_WAIT_V(6); PG8_BAR;
;     __device__ __forceinline__ void operator()(const Acc& acc, const Unit& u, int wr, int wc, int fr, int fq) const {
;     ...
;                 s += __shfl_xor(s, 16); s += __shfl_xor(s, 32);
;                 const float mean = s * (1.f / 64.f);
;                 float q = 0.f;
; #pragma unroll
;                 for (int bj = 0; bj < 2; ++bj)
; #pragma unroll
;                     for (int n = 0; n < 2; ++n) { y[bj][n] = y[bj][n] - mean; q += (y[bj][n][0] * y[bj][n][0] + y[bj][n][1] * y[bj][n][1]) + (y[bj][n][2] * y[bj][n][2] + y[bj][n][3] * y[bj][n][3]); }
;                 q += __shfl_xor(q, 16); q += __shfl_xor(q, 32);
;                 const float rs = rsqrtf(q * (1.f / 64.f) + 64e-5f);
.LBB0_2962:
	s_and_b32 s70, s33, 3
	s_lshl_b32 s71, s3, 6
	s_cmp_lt_u32 s33, 4
	s_cselect_b64 s[8:9], -1, 0
	s_add_u32 s10, s12, 0x1700000
	s_addc_u32 s11, s13, 0
	s_add_u32 s12, s14, 0x11800000
	s_addc_u32 s13, s15, 0
	s_add_u32 s14, s16, 0x100000
	s_addc_u32 s15, s17, 0
	s_add_u32 s16, s18, 0x1000
	s_addc_u32 s17, s19, 0
	s_add_u32 s18, s20, 0x1000
	s_addc_u32 s19, s21, 0
	s_add_u32 s20, s24, 0x15800000
	s_addc_u32 s21, s25, 0
	s_add_u32 s24, s38, 0x80
	s_addc_u32 s25, s39, 0
	s_waitcnt vmcnt(2)
	s_barrier
	s_add_i32 m0, s65, 0x18000
	s_nop 0
	global_load_lds_dwordx4 v132, s[24:25]
	s_add_i32 m0, s65, 0x1a000
	v_lshl_add_u64 v[2:3], s[24:25], 0, v[128:129]
	s_add_u32 s24, s40, 0x80
	s_addc_u32 s25, s41, 0
	s_add_i32 s72, s65, 0x8000
	global_load_lds_dwordx4 v[2:3], off
	s_mov_b32 m0, s72
	s_add_i32 s73, s65, 0xa000
	global_load_lds_dwordx4 v134, s[24:25]
	v_lshl_add_u64 v[2:3], s[24:25], 0, v[130:131]
	s_add_u32 s24, s38, 0x10080
	s_mov_b32 m0, s73
	s_addc_u32 s25, s39, 0
	global_load_lds_dwordx4 v[2:3], off
	s_add_i32 m0, s65, 0x1c000
	s_nop 0
	global_load_lds_dwordx4 v132, s[24:25]
	s_add_i32 m0, s65, 0x1e000
	v_xor_b32_e32 v1, 16, v152
	global_load_lds_dwordx4 v128, s[24:25]
	v_and_b32_e32 v2, 64, v152
	v_add_u32_e32 v2, 64, v2
	v_cmp_lt_i32_e32 vcc, v1, v2
	v_lshlrev_b32_e32 v3, 6, v153
	s_movk_i32 s0, 0x3c0
	v_cndmask_b32_e32 v1, v152, v1, vcc
	v_lshlrev_b32_e32 v154, 2, v1
	v_xor_b32_e32 v1, 32, v152
	v_cmp_lt_i32_e32 vcc, v1, v2
	v_and_b32_e32 v0, 0xfffffc00, v0
	v_lshl_add_u32 v2, s3, 13, v0
	v_cndmask_b32_e32 v1, v152, v1, vcc
	v_lshlrev_b32_e32 v155, 2, v1
	v_and_b32_e32 v1, 48, v153
	v_and_or_b32 v1, v3, s0, v1
	v_lshlrev_b32_e32 v3, 2, v153
	v_and_b32_e32 v3, 32, v3
	v_lshl_add_u32 v0, s70, 12, v0
	s_waitcnt vmcnt(6)
	v_bitop3_b32 v2, v1, v2, v3 bitop3:0xde
	v_bitop3_b32 v156, v1, v0, v3 bitop3:0xde
	s_add_i32 s76, 0, 0x10000
	s_add_i32 s77, 0, 0x14000
	s_sext_i32_i8 s35, s2
	s_mov_b32 s74, 0
	s_waitcnt lgkmcnt(0)
	s_ashr_i32 s75, s69, 31
	v_mov_b64_e32 v[136:137], 0x200
	v_mov_b64_e32 v[138:139], 0x1ff
	v_add_u32_e32 v157, s76, v156
	v_add_u32_e32 v158, s77, v156
	v_add_u32_e32 v159, 0, v2
	v_mov_b32_e32 v160, 0x3a27c5ac
	s_mov_b32 s78, 0x800000
	s_barrier
	s_branch .LBB0_2965

; #define PG8_STAGE(bufoff, gbase, voff) do { const char* _gb = (const char*)(gbase); asm volatile("" : "+s"(_gb));     \
;         _Pragma("unroll") for (int _i = 0; _i < 2; ++_i) \
;         __builtin_amdgcn_global_load_lds((const unsigned*)(_gb + (voff)[_i]), (LAS unsigned*)(lds + (bufoff) + ldsw + _i * 8192), 16, 0, 0); } while (0)
; #define PG8_LDA(dst, b, h) do { _Pragma("unroll") for (int m = 0; m < 4; ++m) _Pragma("unroll") for (int k = 0; k < 2; ++k) dst[m][k] = *(const LAS bf16x8*)(lds + PG8_SA(b, h) + aoff + m * 2048 + k * 1024); } while (0)
; #define PG8_LDB(dst, b, h) do { _Pragma("unroll") for (int n = 0; n < 2; ++n) _Pragma("unroll") for (int k = 0; k < 2; ++k) dst[n][k] = *(const LAS bf16x8*)(lds + PG8_SB(b, h) + boff + n * 2048 + k * 1024); } while (0)
; #define PG8_MMA(ai, bj, At, Bt) do { __builtin_amdgcn_s_setprio(1); _Pragma("unroll") for (int m = 0; m < 4; ++m) _Pragma("unroll") for (int n = 0; n < 2; ++n) _Pragma("unroll") for (int k = 0; k < 2; ++k) \
;         acc[ai][bj][m][n] = __builtin_amdgcn_mfma_f32_16x16x32_bf16(Bt[n][k], At[m][k], acc[ai][bj][m][n], 0, 0, 0); __builtin_amdgcn_s_setprio(0); } while (0)
; #define PG8_WAIT_V(n) asm volatile("s_waitcnt vmcnt(" #n ")" ::: "memory")
; #define PG8_WAIT_L(n) asm volatile("s_waitcnt lgkmcnt(" #n ")" ::: "memory")
; #define PG8_BAR __builtin_amdgcn_s_barrier()
; template <class Epi>
; __device__ __forceinline__ void gemm_phase(LAS unsigned char* lds, const int wid, const Gemm g, const Epi& E) {
;     ...
;             const bool last = (t == nt - 2);
;             const char* a1 = PG8_AP(cA, t + 1);
;             const char* a2 = last ? PG8_AP(nA, 0) : PG8_AP(cA, t + 2); const char* b2 = last ? PG8_BP(nB, 0) : PG8_BP(cB, t + 2);
;             const char* a3 = last ? PG8_AP(nA, 1) : PG8_AP(cA, t + 3); const char* b3 = last ? PG8_BP(nB, 1) : PG8_BP(cB, t + 3);
;             PG8_LDB(B0, 0, 0); PG8_LDB(B1, 0, 1); PG8_SCHED; PG8_LDA(At, 0, 0); PG8_STAGE(PG8_SA(1, 1), a1 + hstepA, voffA);
;             PG8_WAIT_V(8); PG8_WAIT_L(0); PG8_BAR; PG8_MMA(0, 0, At, B0); PG8_MMA(0, 1, At, B1); PG8_BAR; PG8_SCHED;
;             PG8_LDA(At, 0, 1); PG8_STAGE(PG8_SB(0, 0), b2, voffB); PG8_STAGE(PG8_SB(0, 1), b2 + hstepB, voffB); PG8_STAGE(PG8_SA(0, 0), a2, voffA);
;             PG8_WAIT_V(8); PG8_WAIT_L(0); PG8_BAR; PG8_MMA(1, 0, At, B0); PG8_MMA(1, 1, At, B1); PG8_BAR; PG8_SCHED;
.LBB0_2972:
	s_add_u32 s0, s40, s46
	s_addc_u32 s1, s41, 0
	s_add_u32 s47, s0, 0x100
	s_addc_u32 s50, s1, 0
	s_and_b64 s[48:49], s[44:45], exec
	s_cselect_b32 s53, s27, s50
	s_cselect_b32 s52, s79, s47
	s_add_u32 s48, s38, s46
	s_addc_u32 s49, s39, 0
	s_add_u32 s50, s48, 0x100
	s_addc_u32 s51, s49, 0
	s_and_b64 s[46:47], s[44:45], exec
	s_cselect_b32 s55, s25, s51
	s_cselect_b32 s54, s80, s50
	s_add_u32 s50, s0, 0x180
	s_addc_u32 s51, s1, 0
	s_and_b64 s[46:47], s[44:45], exec
	s_cselect_b32 s46, s81, s50
	s_cselect_b32 s47, s82, s51
	s_add_u32 s48, s48, 0x180
	s_addc_u32 s49, s49, 0
	s_add_u32 s58, s0, 0x20080
	s_addc_u32 s59, s1, 0
	s_add_i32 s94, s76, s23
	s_add_i32 m0, s65, 0xc000
	s_add_i32 s0, s65, 0xe000
	s_add_i32 s91, s94, 0x2000
	ds_read_b128 v[140:143], v157
	ds_read_b128 v[144:147], v157 offset:1024
	ds_read_b128 v[148:151], v157 offset:2048
	ds_read_b128 v[162:165], v157 offset:3072
	ds_read_b128 v[166:169], v158
	ds_read_b128 v[170:173], v158 offset:1024
	ds_read_b128 v[174:177], v158 offset:2048
	ds_read_b128 v[178:181], v158 offset:3072
	s_add_u32 s56, s54, 0x10000
	s_addc_u32 s57, s55, 0
	s_add_i32 s90, s77, s23
	s_add_i32 s89, s90, 0x2000
	s_add_i32 s88, 0, 0x18000
	s_add_i32 s87, 0, 0x1c000
	s_add_u32 s50, s52, 0x20000
	s_addc_u32 s51, s53, 0
	s_and_b64 s[44:45], s[44:45], exec
	s_cselect_b32 s49, s84, s49
	s_cselect_b32 s48, s83, s48
	s_add_i32 s86, s88, s23
	s_add_i32 s85, s86, 0x2000
	s_add_u32 s44, s48, 0x10000
	s_addc_u32 s45, s49, 0
	s_add_i32 s93, s87, s23
	s_add_i32 s92, s93, 0x2000
	ds_read_b128 v[182:185], v159
	ds_read_b128 v[186:189], v159 offset:1024
	ds_read_b128 v[190:193], v159 offset:2048
	ds_read_b128 v[194:197], v159 offset:3072
	ds_read_b128 v[198:201], v159 offset:4096
	ds_read_b128 v[206:209], v159 offset:5120
	ds_read_b128 v[210:213], v159 offset:6144
	ds_read_b128 v[214:217], v159 offset:7168
	s_nop 0
	global_load_lds_dwordx4 v134, s[58:59]
	s_mov_b32 m0, s0
	s_nop 0
	global_load_lds_dwordx4 v130, s[58:59]
	s_waitcnt vmcnt(8)
	s_waitcnt lgkmcnt(0)
	s_barrier
	s_setprio 1
	s_waitcnt lgkmcnt(0)
	v_mfma_f32_16x16x32_bf16 v[124:127], v[140:143], v[182:185], v[124:127]
	v_mfma_f32_16x16x32_bf16 v[120:123], v[148:151], v[182:185], v[120:123]
	v_mfma_f32_16x16x32_bf16 v[108:111], v[140:143], v[190:193], v[108:111]
	v_mfma_f32_16x16x32_bf16 v[104:107], v[148:151], v[190:193], v[104:107]
	v_mfma_f32_16x16x32_bf16 v[92:95], v[140:143], v[198:201], v[92:95]
	v_mfma_f32_16x16x32_bf16 v[88:91], v[148:151], v[198:201], v[88:91]
	v_mfma_f32_16x16x32_bf16 v[76:79], v[140:143], v[210:213], v[76:79]
	v_mfma_f32_16x16x32_bf16 v[72:75], v[148:151], v[210:213], v[72:75]
	v_mfma_f32_16x16x32_bf16 v[124:127], v[144:147], v[186:189], v[124:127]
	v_mfma_f32_16x16x32_bf16 v[120:123], v[162:165], v[186:189], v[120:123]
	v_mfma_f32_16x16x32_bf16 v[108:111], v[144:147], v[194:197], v[108:111]
	v_mfma_f32_16x16x32_bf16 v[104:107], v[162:165], v[194:197], v[104:107]
	v_mfma_f32_16x16x32_bf16 v[92:95], v[144:147], v[206:209], v[92:95]
	v_mfma_f32_16x16x32_bf16 v[88:91], v[162:165], v[206:209], v[88:91]
	v_mfma_f32_16x16x32_bf16 v[76:79], v[144:147], v[214:217], v[76:79]
	v_mfma_f32_16x16x32_bf16 v[72:75], v[162:165], v[214:217], v[72:75]
	s_setprio 0
	s_setprio 1
	v_mfma_f32_16x16x32_bf16 v[116:119], v[166:169], v[182:185], v[116:119]
	v_mfma_f32_16x16x32_bf16 v[112:115], v[174:177], v[182:185], v[112:115]
	v_mfma_f32_16x16x32_bf16 v[100:103], v[166:169], v[190:193], v[100:103]
	v_mfma_f32_16x16x32_bf16 v[96:99], v[174:177], v[190:193], v[96:99]
	v_mfma_f32_16x16x32_bf16 v[84:87], v[166:169], v[198:201], v[84:87]
	v_mfma_f32_16x16x32_bf16 v[80:83], v[174:177], v[198:201], v[80:83]
	v_mfma_f32_16x16x32_bf16 v[68:71], v[166:169], v[210:213], v[68:71]
	v_mfma_f32_16x16x32_bf16 v[64:67], v[174:177], v[210:213], v[64:67]
	v_mfma_f32_16x16x32_bf16 v[116:119], v[170:173], v[186:189], v[116:119]
	v_mfma_f32_16x16x32_bf16 v[112:115], v[178:181], v[186:189], v[112:115]
	v_mfma_f32_16x16x32_bf16 v[100:103], v[170:173], v[194:197], v[100:103]
	v_mfma_f32_16x16x32_bf16 v[96:99], v[178:181], v[194:197], v[96:99]
	v_mfma_f32_16x16x32_bf16 v[84:87], v[170:173], v[206:209], v[84:87]
	v_mfma_f32_16x16x32_bf16 v[80:83], v[178:181], v[206:209], v[80:83]
	v_mfma_f32_16x16x32_bf16 v[68:71], v[170:173], v[214:217], v[68:71]
	v_mfma_f32_16x16x32_bf16 v[64:67], v[178:181], v[214:217], v[64:67]
	s_setprio 0
	s_barrier
	s_mov_b32 m0, s94
	ds_read_b128 v[182:185], v159 offset:16384
	ds_read_b128 v[186:189], v159 offset:17408
	ds_read_b128 v[190:193], v159 offset:18432
	ds_read_b128 v[194:197], v159 offset:19456
	ds_read_b128 v[198:201], v159 offset:20480
	ds_read_b128 v[206:209], v159 offset:21504
	ds_read_b128 v[210:213], v159 offset:22528
	ds_read_b128 v[214:217], v159 offset:23552
	s_nop 0
	global_load_lds_dwordx4 v132, s[54:55]
	s_mov_b32 m0, s91
	s_nop 0
	global_load_lds_dwordx4 v128, s[54:55]
	s_mov_b32 m0, s90
	s_nop 0
	global_load_lds_dwordx4 v132, s[56:57]
	s_mov_b32 m0, s89
	s_nop 0
	global_load_lds_dwordx4 v128, s[56:57]
	s_mov_b32 m0, s65
	s_nop 0
	global_load_lds_dwordx4 v134, s[52:53]
	s_mov_b32 m0, s66
	s_nop 0
	global_load_lds_dwordx4 v130, s[52:53]
	s_waitcnt vmcnt(8)
	s_waitcnt lgkmcnt(0)
	s_barrier
; #define PG8_STAGE(bufoff, gbase, voff) do { const char* _gb = (const char*)(gbase); asm volatile("" : "+s"(_gb));     \
;         _Pragma("unroll") for (int _i = 0; _i < 2; ++_i) \
;         __builtin_amdgcn_global_load_lds((const unsigned*)(_gb + (voff)[_i]), (LAS unsigned*)(lds + (bufoff) + ldsw + _i * 8192), 16, 0, 0); } while (0)
; #define PG8_LDA(dst, b, h) do { _Pragma("unroll") for (int m = 0; m < 4; ++m) _Pragma("unroll") for (int k = 0; k < 2; ++k) dst[m][k] = *(const LAS bf16x8*)(lds + PG8_SA(b, h) + aoff + m * 2048 + k * 1024); } while (0)
; #define PG8_LDB(dst, b, h) do { _Pragma("unroll") for (int n = 0; n < 2; ++n) _Pragma("unroll") for (int k = 0; k < 2; ++k) dst[n][k] = *(const LAS bf16x8*)(lds + PG8_SB(b, h) + boff + n * 2048 + k * 1024); } while (0)
; #define PG8_MMA(ai, bj, At, Bt) do { __builtin_amdgcn_s_setprio(1); _Pragma("unroll") for (int m = 0; m < 4; ++m) _Pragma("unroll") for (int n = 0; n < 2; ++n) _Pragma("unroll") for (int k = 0; k < 2; ++k) \
;         acc[ai][bj][m][n] = __builtin_amdgcn_mfma_f32_16x16x32_bf16(Bt[n][k], At[m][k], acc[ai][bj][m][n], 0, 0, 0); __builtin_amdgcn_s_setprio(0); } while (0)
; #define PG8_WAIT_V(n) asm volatile("s_waitcnt vmcnt(" #n ")" ::: "memory")
; #define PG8_WAIT_L(n) asm volatile("s_waitcnt lgkmcnt(" #n ")" ::: "memory")
; #define PG8_BAR __builtin_amdgcn_s_barrier()
; #define PG8_SCHED __builtin_amdgcn_sched_barrier(0)
; template <class Epi>
; __device__ __forceinline__ void gemm_phase(LAS unsigned char* lds, const int wid, const Gemm g, const Epi& E) {
;     ...
;             PG8_WAIT_V(8); PG8_WAIT_L(0); PG8_BAR; PG8_MMA(1, 0, At, B0); PG8_MMA(1, 1, At, B1); PG8_BAR; PG8_SCHED;
;             PG8_LDB(B0, 1, 0); PG8_LDB(B1, 1, 1); PG8_SCHED; PG8_LDA(At, 1, 0); PG8_STAGE(PG8_SA(0, 1), a2 + hstepA, voffA);
;             PG8_WAIT_V(8); PG8_WAIT_L(0); PG8_BAR; PG8_MMA(0, 0, At, B0); PG8_MMA(0, 1, At, B1); PG8_BAR; PG8_SCHED;
	s_setprio 1
	s_waitcnt lgkmcnt(0)
	v_mfma_f32_16x16x32_bf16 v[60:63], v[140:143], v[182:185], v[60:63]
	v_mfma_f32_16x16x32_bf16 v[56:59], v[148:151], v[182:185], v[56:59]
	v_mfma_f32_16x16x32_bf16 v[44:47], v[140:143], v[190:193], v[44:47]
	v_mfma_f32_16x16x32_bf16 v[40:43], v[148:151], v[190:193], v[40:43]
	v_mfma_f32_16x16x32_bf16 v[28:31], v[140:143], v[198:201], v[28:31]
	v_mfma_f32_16x16x32_bf16 v[24:27], v[148:151], v[198:201], v[24:27]
	v_mfma_f32_16x16x32_bf16 v[12:15], v[140:143], v[210:213], v[12:15]
	v_mfma_f32_16x16x32_bf16 v[8:11], v[148:151], v[210:213], v[8:11]
	v_mfma_f32_16x16x32_bf16 v[60:63], v[144:147], v[186:189], v[60:63]
	v_mfma_f32_16x16x32_bf16 v[56:59], v[162:165], v[186:189], v[56:59]
	v_mfma_f32_16x16x32_bf16 v[44:47], v[144:147], v[194:197], v[44:47]
	v_mfma_f32_16x16x32_bf16 v[40:43], v[162:165], v[194:197], v[40:43]
	v_mfma_f32_16x16x32_bf16 v[28:31], v[144:147], v[206:209], v[28:31]
	v_mfma_f32_16x16x32_bf16 v[24:27], v[162:165], v[206:209], v[24:27]
	v_mfma_f32_16x16x32_bf16 v[12:15], v[144:147], v[214:217], v[12:15]
	v_mfma_f32_16x16x32_bf16 v[8:11], v[162:165], v[214:217], v[8:11]
	s_setprio 0
	s_setprio 1
	v_mfma_f32_16x16x32_bf16 v[52:55], v[166:169], v[182:185], v[52:55]
	v_mfma_f32_16x16x32_bf16 v[48:51], v[174:177], v[182:185], v[48:51]
	v_mfma_f32_16x16x32_bf16 v[36:39], v[166:169], v[190:193], v[36:39]
	v_mfma_f32_16x16x32_bf16 v[32:35], v[174:177], v[190:193], v[32:35]
	v_mfma_f32_16x16x32_bf16 v[20:23], v[166:169], v[198:201], v[20:23]
	v_mfma_f32_16x16x32_bf16 v[16:19], v[174:177], v[198:201], v[16:19]
	v_mfma_f32_16x16x32_bf16 v[4:7], v[166:169], v[210:213], v[4:7]
	v_mfma_f32_16x16x32_bf16 v[0:3], v[174:177], v[210:213], v[0:3]
	v_mfma_f32_16x16x32_bf16 v[52:55], v[170:173], v[186:189], v[52:55]
	v_mfma_f32_16x16x32_bf16 v[48:51], v[178:181], v[186:189], v[48:51]
	v_mfma_f32_16x16x32_bf16 v[36:39], v[170:173], v[194:197], v[36:39]
	v_mfma_f32_16x16x32_bf16 v[32:35], v[178:181], v[194:197], v[32:35]
	v_mfma_f32_16x16x32_bf16 v[20:23], v[170:173], v[206:209], v[20:23]
	v_mfma_f32_16x16x32_bf16 v[16:19], v[178:181], v[206:209], v[16:19]
	v_mfma_f32_16x16x32_bf16 v[4:7], v[170:173], v[214:217], v[4:7]
	v_mfma_f32_16x16x32_bf16 v[0:3], v[178:181], v[214:217], v[0:3]
	s_setprio 0
	s_barrier
	v_add_u32_e32 v161, s88, v156
	ds_read_b128 v[140:143], v161
	ds_read_b128 v[144:147], v161 offset:1024
	ds_read_b128 v[148:151], v161 offset:2048
	ds_read_b128 v[162:165], v161 offset:3072
	v_add_u32_e32 v161, s87, v156
	ds_read_b128 v[166:169], v161
	ds_read_b128 v[170:173], v161 offset:1024
	ds_read_b128 v[174:177], v161 offset:2048
	ds_read_b128 v[178:181], v161 offset:3072
	s_mov_b32 m0, s67
	ds_read_b128 v[182:185], v159 offset:32768
	ds_read_b128 v[186:189], v159 offset:33792
	ds_read_b128 v[190:193], v159 offset:34816
	ds_read_b128 v[194:197], v159 offset:35840
	ds_read_b128 v[198:201], v159 offset:36864
	ds_read_b128 v[206:209], v159 offset:37888
	ds_read_b128 v[210:213], v159 offset:38912
	ds_read_b128 v[214:217], v159 offset:39936
	s_nop 0
	global_load_lds_dwordx4 v134, s[50:51]
	s_mov_b32 m0, s68
	s_nop 0
	global_load_lds_dwordx4 v130, s[50:51]
	s_waitcnt vmcnt(8)
	s_waitcnt lgkmcnt(0)
	s_barrier
	s_setprio 1
	s_waitcnt lgkmcnt(0)
	v_mfma_f32_16x16x32_bf16 v[124:127], v[140:143], v[182:185], v[124:127]
	v_mfma_f32_16x16x32_bf16 v[120:123], v[148:151], v[182:185], v[120:123]
	v_mfma_f32_16x16x32_bf16 v[108:111], v[140:143], v[190:193], v[108:111]
	v_mfma_f32_16x16x32_bf16 v[104:107], v[148:151], v[190:193], v[104:107]
	v_mfma_f32_16x16x32_bf16 v[92:95], v[140:143], v[198:201], v[92:95]
	v_mfma_f32_16x16x32_bf16 v[88:91], v[148:151], v[198:201], v[88:91]
	v_mfma_f32_16x16x32_bf16 v[76:79], v[140:143], v[210:213], v[76:79]
	v_mfma_f32_16x16x32_bf16 v[72:75], v[148:151], v[210:213], v[72:75]
	v_mfma_f32_16x16x32_bf16 v[124:127], v[144:147], v[186:189], v[124:127]
	v_mfma_f32_16x16x32_bf16 v[120:123], v[162:165], v[186:189], v[120:123]
	v_mfma_f32_16x16x32_bf16 v[108:111], v[144:147], v[194:197], v[108:111]
	v_mfma_f32_16x16x32_bf16 v[104:107], v[162:165], v[194:197], v[104:107]
	v_mfma_f32_16x16x32_bf16 v[92:95], v[144:147], v[206:209], v[92:95]
	v_mfma_f32_16x16x32_bf16 v[88:91], v[162:165], v[206:209], v[88:91]
	v_mfma_f32_16x16x32_bf16 v[76:79], v[144:147], v[214:217], v[76:79]
	v_mfma_f32_16x16x32_bf16 v[72:75], v[162:165], v[214:217], v[72:75]
	s_setprio 0
	s_setprio 1
	v_mfma_f32_16x16x32_bf16 v[116:119], v[166:169], v[182:185], v[116:119]
	v_mfma_f32_16x16x32_bf16 v[112:115], v[174:177], v[182:185], v[112:115]
	v_mfma_f32_16x16x32_bf16 v[100:103], v[166:169], v[190:193], v[100:103]
	v_mfma_f32_16x16x32_bf16 v[96:99], v[174:177], v[190:193], v[96:99]
	v_mfma_f32_16x16x32_bf16 v[84:87], v[166:169], v[198:201], v[84:87]
	v_mfma_f32_16x16x32_bf16 v[80:83], v[174:177], v[198:201], v[80:83]
	v_mfma_f32_16x16x32_bf16 v[68:71], v[166:169], v[210:213], v[68:71]
	v_mfma_f32_16x16x32_bf16 v[64:67], v[174:177], v[210:213], v[64:67]
	v_mfma_f32_16x16x32_bf16 v[116:119], v[170:173], v[186:189], v[116:119]
	v_mfma_f32_16x16x32_bf16 v[112:115], v[178:181], v[186:189], v[112:115]
	v_mfma_f32_16x16x32_bf16 v[100:103], v[170:173], v[194:197], v[100:103]
	v_mfma_f32_16x16x32_bf16 v[96:99], v[178:181], v[194:197], v[96:99]
	v_mfma_f32_16x16x32_bf16 v[84:87], v[170:173], v[206:209], v[84:87]
	v_mfma_f32_16x16x32_bf16 v[80:83], v[178:181], v[206:209], v[80:83]
	v_mfma_f32_16x16x32_bf16 v[68:71], v[170:173], v[214:217], v[68:71]
	v_mfma_f32_16x16x32_bf16 v[64:67], v[178:181], v[214:217], v[64:67]
	s_setprio 0
	s_barrier
; #define PG8_STAGE(bufoff, gbase, voff) do { const char* _gb = (const char*)(gbase); asm volatile("" : "+s"(_gb));     \
;         _Pragma("unroll") for (int _i = 0; _i < 2; ++_i) \
;         __builtin_amdgcn_global_load_lds((const unsigned*)(_gb + (voff)[_i]), (LAS unsigned*)(lds + (bufoff) + ldsw + _i * 8192), 16, 0, 0); } while (0)
; #define PG8_LDA(dst, b, h) do { _Pragma("unroll") for (int m = 0; m < 4; ++m) _Pragma("unroll") for (int k = 0; k < 2; ++k) dst[m][k] = *(const LAS bf16x8*)(lds + PG8_SA(b, h) + aoff + m * 2048 + k * 1024); } while (0)
; #define PG8_MMA(ai, bj, At, Bt) do { __builtin_amdgcn_s_setprio(1); _Pragma("unroll") for (int m = 0; m < 4; ++m) _Pragma("unroll") for (int n = 0; n < 2; ++n) _Pragma("unroll") for (int k = 0; k < 2; ++k) \
;         acc[ai][bj][m][n] = __builtin_amdgcn_mfma_f32_16x16x32_bf16(Bt[n][k], At[m][k], acc[ai][bj][m][n], 0, 0, 0); __builtin_amdgcn_s_setprio(0); } while (0)
; #define PG8_WAIT_V(n) asm volatile("s_waitcnt vmcnt(" #n ")" ::: "memory")
; #define PG8_WAIT_L(n) asm volatile("s_waitcnt lgkmcnt(" #n ")" ::: "memory")
; #define PG8_BAR __builtin_amdgcn_s_barrier()
; #define PG8_SCHED __builtin_amdgcn_sched_barrier(0)
; template <class Epi>
; __device__ __forceinline__ void gemm_phase(LAS unsigned char* lds, const int wid, const Gemm g, const Epi& E) {
;     ...
;             PG8_LDA(At, 1, 1); PG8_STAGE(PG8_SB(1, 0), b3, voffB); PG8_STAGE(PG8_SB(1, 1), b3 + hstepB, voffB); PG8_STAGE(PG8_SA(1, 0), a3, voffA);
;             PG8_WAIT_V(8); PG8_WAIT_L(0); PG8_BAR; PG8_MMA(1, 0, At, B0); PG8_MMA(1, 1, At, B1); PG8_BAR; PG8_SCHED;
;         }
	s_mov_b32 m0, s86
	ds_read_b128 v[182:185], v159 offset:49152
	ds_read_b128 v[186:189], v159 offset:50176
	ds_read_b128 v[190:193], v159 offset:51200
	ds_read_b128 v[194:197], v159 offset:52224
	ds_read_b128 v[198:201], v159 offset:53248
	ds_read_b128 v[206:209], v159 offset:54272
	ds_read_b128 v[210:213], v159 offset:55296
	ds_read_b128 v[214:217], v159 offset:56320
	s_nop 0
	global_load_lds_dwordx4 v132, s[48:49]
	s_mov_b32 m0, s85
	s_nop 0
	global_load_lds_dwordx4 v128, s[48:49]
	s_mov_b32 m0, s93
	s_nop 0
	global_load_lds_dwordx4 v132, s[44:45]
	s_mov_b32 m0, s92
	s_nop 0
	global_load_lds_dwordx4 v128, s[44:45]
	s_mov_b32 m0, s72
	s_nop 0
	global_load_lds_dwordx4 v134, s[46:47]
	s_mov_b32 m0, s73
	s_nop 0
	global_load_lds_dwordx4 v130, s[46:47]
	s_waitcnt vmcnt(8)
	s_waitcnt lgkmcnt(0)
	s_barrier
	s_setprio 1
	s_waitcnt lgkmcnt(0)
	v_mfma_f32_16x16x32_bf16 v[60:63], v[140:143], v[182:185], v[60:63]
	v_mfma_f32_16x16x32_bf16 v[56:59], v[148:151], v[182:185], v[56:59]
	v_mfma_f32_16x16x32_bf16 v[44:47], v[140:143], v[190:193], v[44:47]
	v_mfma_f32_16x16x32_bf16 v[40:43], v[148:151], v[190:193], v[40:43]
	v_mfma_f32_16x16x32_bf16 v[28:31], v[140:143], v[198:201], v[28:31]
	v_mfma_f32_16x16x32_bf16 v[24:27], v[148:151], v[198:201], v[24:27]
	v_mfma_f32_16x16x32_bf16 v[12:15], v[140:143], v[210:213], v[12:15]
	v_mfma_f32_16x16x32_bf16 v[8:11], v[148:151], v[210:213], v[8:11]
	v_mfma_f32_16x16x32_bf16 v[60:63], v[144:147], v[186:189], v[60:63]
	v_mfma_f32_16x16x32_bf16 v[56:59], v[162:165], v[186:189], v[56:59]
	v_mfma_f32_16x16x32_bf16 v[44:47], v[144:147], v[194:197], v[44:47]
	v_mfma_f32_16x16x32_bf16 v[40:43], v[162:165], v[194:197], v[40:43]
	v_mfma_f32_16x16x32_bf16 v[28:31], v[144:147], v[206:209], v[28:31]
	v_mfma_f32_16x16x32_bf16 v[24:27], v[162:165], v[206:209], v[24:27]
	v_mfma_f32_16x16x32_bf16 v[12:15], v[144:147], v[214:217], v[12:15]
	v_mfma_f32_16x16x32_bf16 v[8:11], v[162:165], v[214:217], v[8:11]
	s_setprio 0
	s_setprio 1
	v_mfma_f32_16x16x32_bf16 v[52:55], v[166:169], v[182:185], v[52:55]
	v_mfma_f32_16x16x32_bf16 v[48:51], v[174:177], v[182:185], v[48:51]
	v_mfma_f32_16x16x32_bf16 v[36:39], v[166:169], v[190:193], v[36:39]
	v_mfma_f32_16x16x32_bf16 v[32:35], v[174:177], v[190:193], v[32:35]
	v_mfma_f32_16x16x32_bf16 v[20:23], v[166:169], v[198:201], v[20:23]
	v_mfma_f32_16x16x32_bf16 v[16:19], v[174:177], v[198:201], v[16:19]
	v_mfma_f32_16x16x32_bf16 v[4:7], v[166:169], v[210:213], v[4:7]
	v_mfma_f32_16x16x32_bf16 v[0:3], v[174:177], v[210:213], v[0:3]
	v_mfma_f32_16x16x32_bf16 v[52:55], v[170:173], v[186:189], v[52:55]
	v_mfma_f32_16x16x32_bf16 v[48:51], v[178:181], v[186:189], v[48:51]
	v_mfma_f32_16x16x32_bf16 v[36:39], v[170:173], v[194:197], v[36:39]
	v_mfma_f32_16x16x32_bf16 v[32:35], v[178:181], v[194:197], v[32:35]
	v_mfma_f32_16x16x32_bf16 v[20:23], v[170:173], v[206:209], v[20:23]
	v_mfma_f32_16x16x32_bf16 v[16:19], v[178:181], v[206:209], v[16:19]
	v_mfma_f32_16x16x32_bf16 v[4:7], v[170:173], v[214:217], v[4:7]
	v_mfma_f32_16x16x32_bf16 v[0:3], v[178:181], v[214:217], v[0:3]
	s_setprio 0
	s_barrier
	s_movk_i32 s46, 0x100
	s_andn2_b64 vcc, exec, s[42:43]
	s_mov_b64 s[44:45], -1
	s_mov_b64 s[42:43], 0
	s_cbranch_vccz .LBB0_2972
	s_and_b64 vcc, exec, s[8:9]
	s_cbranch_vccz .LBB0_2975
	s_barrier

; #define PG8_STAGE(bufoff, gbase, voff) do { const char* _gb = (const char*)(gbase); asm volatile("" : "+s"(_gb));     \
;         _Pragma("unroll") for (int _i = 0; _i < 2; ++_i) \
;         __builtin_amdgcn_global_load_lds((const unsigned*)(_gb + (voff)[_i]), (LAS unsigned*)(lds + (bufoff) + ldsw + _i * 8192), 16, 0, 0); } while (0)
; #define PG8_WAIT_V(n) asm volatile("s_waitcnt vmcnt(" #n ")" ::: "memory")
; #define PG8_BAR __builtin_amdgcn_s_barrier()
; template <class Epi>
; __device__ __forceinline__ void gemm_phase(LAS unsigned char* lds, const int wid, const Gemm g, const Epi& E) {
;     ...
;     for (int i = 0; i < 2; ++i) { int R, C; stage_rc(tid * 16 + i * 8192, R, C); const int Rb = Epi::PERM ? ((R & ~31) + perm32(R & 31)) : R;
;         voffA[i] = (unsigned)(R * g.lda + C) * 2u; voffB[i] = (unsigned)(Rb * g.ldb + C) * 2u; }
;     const size_t kstep = (size_t)(BK * 2);
;     const size_t hstepA = (size_t)HALF * g.lda * 2, hstepB = (size_t)HALF * g.ldb * 2;
;     const unsigned ldsw = (unsigned)wid * 1024u;
;     const int aoff = lds_byte(wr * 64 + fr, fq * 8), boff = lds_byte(wc * 32 + fr, fq * 8);
;     ...
;     const char* cA = PG8_UA(cur); const char* cB = PG8_UB(cur);
;     PG8_STAGE(PG8_SB(0, 0), PG8_BP(cB, 0), voffB); PG8_STAGE(PG8_SB(0, 1), PG8_BP(cB, 0) + hstepB, voffB); PG8_STAGE(PG8_SA(0, 0), PG8_AP(cA, 0), voffA); PG8_STAGE(PG8_SA(0, 1), PG8_AP(cA, 0) + hstepA, voffA);
;     if (wr == 1) PG8_BAR;
;     PG8_WAIT_V(2); PG8_BAR;
;     PG8_STAGE(PG8_SB(1, 0), PG8_BP(cB, 1), voffB); PG8_STAGE(PG8_SA(1, 0), PG8_AP(cA, 1), voffA); PG8_STAGE(PG8_SB(1, 1), PG8_BP(cB, 1) + hstepB, voffB);
;     PG8_WAIT_V(6); PG8_BAR;
.LBB0_3234:
	s_lshl_b32 s0, s33, 5
	s_and_b32 s48, s0, 0x60
	s_lshl_b32 s47, s10, 6
	s_lshl_b32 s2, s10, 13
	s_lshr_b32 s3, s48, 3
	s_cmp_lt_u32 s33, 4
	s_cselect_b64 s[10:11], -1, 0
	s_add_u32 s12, s12, 0x5800000
	s_addc_u32 s13, s13, 0
	s_add_u32 s0, s26, 0x80
	s_addc_u32 s1, s27, 0
	s_waitcnt vmcnt(2)
	s_barrier
	s_add_i32 m0, s42, 0x18000
	s_nop 0
	global_load_lds_dwordx4 v132, s[0:1]
	s_add_i32 m0, s42, 0x1a000
	v_lshl_add_u64 v[0:1], s[0:1], 0, v[128:129]
	s_add_u32 s0, s28, 0x80
	s_addc_u32 s1, s29, 0
	s_add_i32 s49, s42, 0x8000
	global_load_lds_dwordx4 v[0:1], off
	s_mov_b32 m0, s49
	s_add_i32 s50, s42, 0xa000
	global_load_lds_dwordx4 v134, s[0:1]
	v_lshl_add_u64 v[0:1], s[0:1], 0, v[130:131]
	s_add_u32 s0, s26, 0xb0080
	s_mov_b32 m0, s50
	s_addc_u32 s1, s27, 0
	global_load_lds_dwordx4 v[0:1], off
	s_add_i32 m0, s42, 0x1c000
	s_nop 0
	global_load_lds_dwordx4 v132, s[0:1]
	s_add_i32 m0, s42, 0x1e000
	v_lshlrev_b32_e32 v3, 6, v147
	global_load_lds_dwordx4 v128, s[0:1]
	v_and_b32_e32 v1, 48, v147
	s_movk_i32 s0, 0x3c0
	v_ashrrev_i32_e32 v0, 6, v147
	v_and_or_b32 v1, v3, s0, v1
	v_lshlrev_b32_e32 v3, 2, v147
	v_lshl_add_u32 v2, v0, 10, s2
	v_and_b32_e32 v3, 32, v3
	v_add_lshl_u32 v0, v0, s3, 10
	s_waitcnt vmcnt(6)
	v_bitop3_b32 v2, v1, v2, v3 bitop3:0xde
	v_bitop3_b32 v148, v1, v0, v3 bitop3:0xde
	s_add_i32 s53, 0, 0x10000
	s_add_i32 s54, 0, 0x14000
	s_sext_i32_i8 s58, s14
	s_mov_b32 s51, 0
	s_waitcnt lgkmcnt(0)
	s_ashr_i32 s52, s46, 31
	v_mov_b64_e32 v[136:137], 0x200
	v_mov_b64_e32 v[138:139], 0x1ff
	v_add_u32_e32 v149, s53, v148
	v_add_u32_e32 v150, s54, v148
	v_add_u32_e32 v151, 0, v2
	s_mov_b64 s[14:15], 0x20000
	s_mov_b64 s[16:17], 0x24000
	s_mov_b64 s[18:19], 0x28000
	s_mov_b64 s[20:21], 0x2c000
	s_barrier
	s_branch .LBB0_3237

; #define PG8_STAGE(bufoff, gbase, voff) do { const char* _gb = (const char*)(gbase); asm volatile("" : "+s"(_gb));     \
;         _Pragma("unroll") for (int _i = 0; _i < 2; ++_i) \
;         __builtin_amdgcn_global_load_lds((const unsigned*)(_gb + (voff)[_i]), (LAS unsigned*)(lds + (bufoff) + ldsw + _i * 8192), 16, 0, 0); } while (0)
; #define PG8_LDA(dst, b, h) do { _Pragma("unroll") for (int m = 0; m < 4; ++m) _Pragma("unroll") for (int k = 0; k < 2; ++k) dst[m][k] = *(const LAS bf16x8*)(lds + PG8_SA(b, h) + aoff + m * 2048 + k * 1024); } while (0)
; #define PG8_LDB(dst, b, h) do { _Pragma("unroll") for (int n = 0; n < 2; ++n) _Pragma("unroll") for (int k = 0; k < 2; ++k) dst[n][k] = *(const LAS bf16x8*)(lds + PG8_SB(b, h) + boff + n * 2048 + k * 1024); } while (0)
; #define PG8_MMA(ai, bj, At, Bt) do { __builtin_amdgcn_s_setprio(1); _Pragma("unroll") for (int m = 0; m < 4; ++m) _Pragma("unroll") for (int n = 0; n < 2; ++n) _Pragma("unroll") for (int k = 0; k < 2; ++k) \
;         acc[ai][bj][m][n] = __builtin_amdgcn_mfma_f32_16x16x32_bf16(Bt[n][k], At[m][k], acc[ai][bj][m][n], 0, 0, 0); __builtin_amdgcn_s_setprio(0); } while (0)
; #define PG8_WAIT_V(n) asm volatile("s_waitcnt vmcnt(" #n ")" ::: "memory")
; #define PG8_WAIT_L(n) asm volatile("s_waitcnt lgkmcnt(" #n ")" ::: "memory")
; #define PG8_BAR __builtin_amdgcn_s_barrier()
; template <class Epi>
; __device__ __forceinline__ void gemm_phase(LAS unsigned char* lds, const int wid, const Gemm g, const Epi& E) {
;     ...
;             const bool last = (t == nt - 2);
;             const char* a1 = PG8_AP(cA, t + 1);
;             const char* a2 = last ? PG8_AP(nA, 0) : PG8_AP(cA, t + 2); const char* b2 = last ? PG8_BP(nB, 0) : PG8_BP(cB, t + 2);
;             const char* a3 = last ? PG8_AP(nA, 1) : PG8_AP(cA, t + 3); const char* b3 = last ? PG8_BP(nB, 1) : PG8_BP(cB, t + 3);
;             PG8_LDB(B0, 0, 0); PG8_LDB(B1, 0, 1); PG8_SCHED; PG8_LDA(At, 0, 0); PG8_STAGE(PG8_SA(1, 1), a1 + hstepA, voffA);
;             PG8_WAIT_V(8); PG8_WAIT_L(0); PG8_BAR; PG8_MMA(0, 0, At, B0); PG8_MMA(0, 1, At, B1); PG8_BAR; PG8_SCHED;
;             PG8_LDA(At, 0, 1); PG8_STAGE(PG8_SB(0, 0), b2, voffB); PG8_STAGE(PG8_SB(0, 1), b2 + hstepB, voffB); PG8_STAGE(PG8_SA(0, 0), a2, voffA);
;             PG8_WAIT_V(8); PG8_WAIT_L(0); PG8_BAR; PG8_MMA(1, 0, At, B0); PG8_MMA(1, 1, At, B1); PG8_BAR; PG8_SCHED;
.LBB0_3248:
	ds_read_b128 v[140:143], v149
	ds_read_b128 v[152:155], v149 offset:1024
	ds_read_b128 v[156:159], v149 offset:2048
	ds_read_b128 v[160:163], v149 offset:3072
	ds_read_b128 v[164:167], v150
	ds_read_b128 v[168:171], v150 offset:1024
	ds_read_b128 v[172:175], v150 offset:2048
	ds_read_b128 v[176:179], v150 offset:3072
	s_add_u32 s28, s26, 0xfff50080
	s_addc_u32 s29, s27, -1
	s_add_u32 s34, s63, 0xffffff80
	s_addc_u32 s35, s64, -1
	s_add_u32 s68, s26, 0xfff50100
	s_addc_u32 s69, s27, -1
	s_add_i32 s71, s53, s23
	s_add_i32 m0, s42, 0xc000
	s_add_i32 s70, s42, 0xe000
	s_add_i32 s72, s71, 0x2000
	s_cmp_eq_u32 s65, 40
	s_cselect_b32 s31, s3, s29
	s_cselect_b32 s30, s2, s28
	s_cselect_b32 s67, s25, s35
	s_cselect_b32 s66, s24, s34
	s_cselect_b32 s29, s60, s69
	s_cselect_b32 s28, s59, s68
	s_mov_b64 s[34:35], s[26:27]
	ds_read_b128 v[180:183], v151
	ds_read_b128 v[184:187], v151 offset:1024
	ds_read_b128 v[188:191], v151 offset:2048
	ds_read_b128 v[192:195], v151 offset:3072
	ds_read_b128 v[196:199], v151 offset:4096
	ds_read_b128 v[200:203], v151 offset:5120
	ds_read_b128 v[204:207], v151 offset:6144
	ds_read_b128 v[208:211], v151 offset:7168
	s_nop 0
	global_load_lds_dwordx4 v134, s[34:35]
	s_mov_b32 m0, s70
	s_nop 0
	global_load_lds_dwordx4 v130, s[34:35]
	s_waitcnt vmcnt(8)
	s_waitcnt lgkmcnt(0)
	s_barrier
	s_setprio 1
	s_waitcnt lgkmcnt(0)
	v_mfma_f32_16x16x32_bf16 v[124:127], v[140:143], v[180:183], v[124:127]
	v_mfma_f32_16x16x32_bf16 v[120:123], v[156:159], v[180:183], v[120:123]
	v_mfma_f32_16x16x32_bf16 v[108:111], v[140:143], v[188:191], v[108:111]
	v_mfma_f32_16x16x32_bf16 v[104:107], v[156:159], v[188:191], v[104:107]
	v_mfma_f32_16x16x32_bf16 v[92:95], v[140:143], v[196:199], v[92:95]
	v_mfma_f32_16x16x32_bf16 v[88:91], v[156:159], v[196:199], v[88:91]
	v_mfma_f32_16x16x32_bf16 v[76:79], v[140:143], v[204:207], v[76:79]
	v_mfma_f32_16x16x32_bf16 v[72:75], v[156:159], v[204:207], v[72:75]
	v_mfma_f32_16x16x32_bf16 v[124:127], v[152:155], v[184:187], v[124:127]
	v_mfma_f32_16x16x32_bf16 v[120:123], v[160:163], v[184:187], v[120:123]
	v_mfma_f32_16x16x32_bf16 v[108:111], v[152:155], v[192:195], v[108:111]
	v_mfma_f32_16x16x32_bf16 v[104:107], v[160:163], v[192:195], v[104:107]
	v_mfma_f32_16x16x32_bf16 v[92:95], v[152:155], v[200:203], v[92:95]
	v_mfma_f32_16x16x32_bf16 v[88:91], v[160:163], v[200:203], v[88:91]
	v_mfma_f32_16x16x32_bf16 v[76:79], v[152:155], v[208:211], v[76:79]
	v_mfma_f32_16x16x32_bf16 v[72:75], v[160:163], v[208:211], v[72:75]
	s_setprio 0
	s_setprio 1
	v_mfma_f32_16x16x32_bf16 v[116:119], v[164:167], v[180:183], v[116:119]
	v_mfma_f32_16x16x32_bf16 v[112:115], v[172:175], v[180:183], v[112:115]
	v_mfma_f32_16x16x32_bf16 v[100:103], v[164:167], v[188:191], v[100:103]
	v_mfma_f32_16x16x32_bf16 v[96:99], v[172:175], v[188:191], v[96:99]
	v_mfma_f32_16x16x32_bf16 v[84:87], v[164:167], v[196:199], v[84:87]
	v_mfma_f32_16x16x32_bf16 v[80:83], v[172:175], v[196:199], v[80:83]
	v_mfma_f32_16x16x32_bf16 v[68:71], v[164:167], v[204:207], v[68:71]
	v_mfma_f32_16x16x32_bf16 v[64:67], v[172:175], v[204:207], v[64:67]
	v_mfma_f32_16x16x32_bf16 v[116:119], v[168:171], v[184:187], v[116:119]
	v_mfma_f32_16x16x32_bf16 v[112:115], v[176:179], v[184:187], v[112:115]
	v_mfma_f32_16x16x32_bf16 v[100:103], v[168:171], v[192:195], v[100:103]
	v_mfma_f32_16x16x32_bf16 v[96:99], v[176:179], v[192:195], v[96:99]
	v_mfma_f32_16x16x32_bf16 v[84:87], v[168:171], v[200:203], v[84:87]
	v_mfma_f32_16x16x32_bf16 v[80:83], v[176:179], v[200:203], v[80:83]
	v_mfma_f32_16x16x32_bf16 v[68:71], v[168:171], v[208:211], v[68:71]
	v_mfma_f32_16x16x32_bf16 v[64:67], v[176:179], v[208:211], v[64:67]
	s_setprio 0
	s_barrier
	s_mov_b64 s[34:35], s[66:67]
	s_mov_b32 m0, s71
	ds_read_b128 v[180:183], v151 offset:16384
	ds_read_b128 v[184:187], v151 offset:17408
	ds_read_b128 v[188:191], v151 offset:18432
	ds_read_b128 v[192:195], v151 offset:19456
	ds_read_b128 v[196:199], v151 offset:20480
	ds_read_b128 v[200:203], v151 offset:21504
	ds_read_b128 v[204:207], v151 offset:22528
	ds_read_b128 v[208:211], v151 offset:23552
	s_nop 0
	global_load_lds_dwordx4 v132, s[34:35]
	v_lshl_add_u64 v[144:145], s[34:35], 0, v[128:129]
	s_cselect_b32 s35, s62, s64
	s_cselect_b32 s34, s61, s63
	s_add_u32 s66, s66, 0xb0000
	s_mov_b32 m0, s72
	s_addc_u32 s67, s67, 0
	s_add_i32 s68, s54, s23
	global_load_lds_dwordx4 v[144:145], off
	s_mov_b32 m0, s68
	s_nop 0
	global_load_lds_dwordx4 v132, s[66:67]
	v_lshl_add_u64 v[144:145], s[66:67], 0, v[128:129]
	s_add_i32 m0, s68, 0x2000
	s_mov_b64 s[66:67], s[30:31]
	global_load_lds_dwordx4 v[144:145], off
	s_mov_b32 m0, s42
	s_nop 0
	global_load_lds_dwordx4 v134, s[66:67]
	s_mov_b32 m0, s43
	s_nop 0
	global_load_lds_dwordx4 v130, s[66:67]
	s_waitcnt vmcnt(8)
	s_waitcnt lgkmcnt(0)
	s_barrier
; #define PG8_STAGE(bufoff, gbase, voff) do { const char* _gb = (const char*)(gbase); asm volatile("" : "+s"(_gb));     \
;         _Pragma("unroll") for (int _i = 0; _i < 2; ++_i) \
;         __builtin_amdgcn_global_load_lds((const unsigned*)(_gb + (voff)[_i]), (LAS unsigned*)(lds + (bufoff) + ldsw + _i * 8192), 16, 0, 0); } while (0)
; #define PG8_LDA(dst, b, h) do { _Pragma("unroll") for (int m = 0; m < 4; ++m) _Pragma("unroll") for (int k = 0; k < 2; ++k) dst[m][k] = *(const LAS bf16x8*)(lds + PG8_SA(b, h) + aoff + m * 2048 + k * 1024); } while (0)
; #define PG8_LDB(dst, b, h) do { _Pragma("unroll") for (int n = 0; n < 2; ++n) _Pragma("unroll") for (int k = 0; k < 2; ++k) dst[n][k] = *(const LAS bf16x8*)(lds + PG8_SB(b, h) + boff + n * 2048 + k * 1024); } while (0)
; #define PG8_MMA(ai, bj, At, Bt) do { __builtin_amdgcn_s_setprio(1); _Pragma("unroll") for (int m = 0; m < 4; ++m) _Pragma("unroll") for (int n = 0; n < 2; ++n) _Pragma("unroll") for (int k = 0; k < 2; ++k) \
;         acc[ai][bj][m][n] = __builtin_amdgcn_mfma_f32_16x16x32_bf16(Bt[n][k], At[m][k], acc[ai][bj][m][n], 0, 0, 0); __builtin_amdgcn_s_setprio(0); } while (0)
; #define PG8_WAIT_V(n) asm volatile("s_waitcnt vmcnt(" #n ")" ::: "memory")
; #define PG8_WAIT_L(n) asm volatile("s_waitcnt lgkmcnt(" #n ")" ::: "memory")
; #define PG8_BAR __builtin_amdgcn_s_barrier()
; #define PG8_SCHED __builtin_amdgcn_sched_barrier(0)
; template <class Epi>
; __device__ __forceinline__ void gemm_phase(LAS unsigned char* lds, const int wid, const Gemm g, const Epi& E) {
;     ...
;             PG8_WAIT_V(8); PG8_WAIT_L(0); PG8_BAR; PG8_MMA(1, 0, At, B0); PG8_MMA(1, 1, At, B1); PG8_BAR; PG8_SCHED;
;             PG8_LDB(B0, 1, 0); PG8_LDB(B1, 1, 1); PG8_SCHED; PG8_LDA(At, 1, 0); PG8_STAGE(PG8_SA(0, 1), a2 + hstepA, voffA);
;             PG8_WAIT_V(8); PG8_WAIT_L(0); PG8_BAR; PG8_MMA(0, 0, At, B0); PG8_MMA(0, 1, At, B1); PG8_BAR; PG8_SCHED;
	s_setprio 1
	s_waitcnt lgkmcnt(0)
	v_mfma_f32_16x16x32_bf16 v[60:63], v[140:143], v[180:183], v[60:63]
	v_mfma_f32_16x16x32_bf16 v[56:59], v[156:159], v[180:183], v[56:59]
	v_mfma_f32_16x16x32_bf16 v[44:47], v[140:143], v[188:191], v[44:47]
	v_mfma_f32_16x16x32_bf16 v[40:43], v[156:159], v[188:191], v[40:43]
	v_mfma_f32_16x16x32_bf16 v[28:31], v[140:143], v[196:199], v[28:31]
	v_mfma_f32_16x16x32_bf16 v[24:27], v[156:159], v[196:199], v[24:27]
	v_mfma_f32_16x16x32_bf16 v[12:15], v[140:143], v[204:207], v[12:15]
	v_mfma_f32_16x16x32_bf16 v[8:11], v[156:159], v[204:207], v[8:11]
	v_mfma_f32_16x16x32_bf16 v[60:63], v[152:155], v[184:187], v[60:63]
	v_mfma_f32_16x16x32_bf16 v[56:59], v[160:163], v[184:187], v[56:59]
	v_mfma_f32_16x16x32_bf16 v[44:47], v[152:155], v[192:195], v[44:47]
	v_mfma_f32_16x16x32_bf16 v[40:43], v[160:163], v[192:195], v[40:43]
	v_mfma_f32_16x16x32_bf16 v[28:31], v[152:155], v[200:203], v[28:31]
	v_mfma_f32_16x16x32_bf16 v[24:27], v[160:163], v[200:203], v[24:27]
	v_mfma_f32_16x16x32_bf16 v[12:15], v[152:155], v[208:211], v[12:15]
	v_mfma_f32_16x16x32_bf16 v[8:11], v[160:163], v[208:211], v[8:11]
	s_setprio 0
	s_setprio 1
	v_mfma_f32_16x16x32_bf16 v[52:55], v[164:167], v[180:183], v[52:55]
	v_mfma_f32_16x16x32_bf16 v[48:51], v[172:175], v[180:183], v[48:51]
	v_mfma_f32_16x16x32_bf16 v[36:39], v[164:167], v[188:191], v[36:39]
	v_mfma_f32_16x16x32_bf16 v[32:35], v[172:175], v[188:191], v[32:35]
	v_mfma_f32_16x16x32_bf16 v[20:23], v[164:167], v[196:199], v[20:23]
	v_mfma_f32_16x16x32_bf16 v[16:19], v[172:175], v[196:199], v[16:19]
	v_mfma_f32_16x16x32_bf16 v[4:7], v[164:167], v[204:207], v[4:7]
	v_mfma_f32_16x16x32_bf16 v[0:3], v[172:175], v[204:207], v[0:3]
	v_mfma_f32_16x16x32_bf16 v[52:55], v[168:171], v[184:187], v[52:55]
	v_mfma_f32_16x16x32_bf16 v[48:51], v[176:179], v[184:187], v[48:51]
	v_mfma_f32_16x16x32_bf16 v[36:39], v[168:171], v[192:195], v[36:39]
	v_mfma_f32_16x16x32_bf16 v[32:35], v[176:179], v[192:195], v[32:35]
	v_mfma_f32_16x16x32_bf16 v[20:23], v[168:171], v[200:203], v[20:23]
	v_mfma_f32_16x16x32_bf16 v[16:19], v[176:179], v[200:203], v[16:19]
	v_mfma_f32_16x16x32_bf16 v[4:7], v[168:171], v[208:211], v[4:7]
	v_mfma_f32_16x16x32_bf16 v[0:3], v[176:179], v[208:211], v[0:3]
	s_setprio 0
	s_barrier
	s_add_i32 s66, 0, 0x18000
	v_add_u32_e32 v144, s66, v148
	s_add_i32 s67, 0, 0x1c000
	ds_read_b128 v[140:143], v144
	ds_read_b128 v[152:155], v144 offset:1024
	ds_read_b128 v[156:159], v144 offset:2048
	ds_read_b128 v[160:163], v144 offset:3072
	v_add_u32_e32 v144, s67, v148
	ds_read_b128 v[164:167], v144
	ds_read_b128 v[168:171], v144 offset:1024
	ds_read_b128 v[172:175], v144 offset:2048
	ds_read_b128 v[176:179], v144 offset:3072
	s_add_u32 s30, s30, 0xb0000
	s_addc_u32 s31, s31, 0
	s_mov_b32 m0, s44
	ds_read_b128 v[180:183], v151 offset:32768
	ds_read_b128 v[184:187], v151 offset:33792
	ds_read_b128 v[188:191], v151 offset:34816
	ds_read_b128 v[192:195], v151 offset:35840
	ds_read_b128 v[196:199], v151 offset:36864
	ds_read_b128 v[200:203], v151 offset:37888
	ds_read_b128 v[204:207], v151 offset:38912
	ds_read_b128 v[208:211], v151 offset:39936
	s_nop 0
	global_load_lds_dwordx4 v134, s[30:31]
	s_mov_b32 m0, s45
	s_nop 0
	global_load_lds_dwordx4 v130, s[30:31]
	s_waitcnt vmcnt(8)
	s_waitcnt lgkmcnt(0)
	s_barrier
	s_setprio 1
	s_waitcnt lgkmcnt(0)
	v_mfma_f32_16x16x32_bf16 v[124:127], v[140:143], v[180:183], v[124:127]
	v_mfma_f32_16x16x32_bf16 v[120:123], v[156:159], v[180:183], v[120:123]
	v_mfma_f32_16x16x32_bf16 v[108:111], v[140:143], v[188:191], v[108:111]
	v_mfma_f32_16x16x32_bf16 v[104:107], v[156:159], v[188:191], v[104:107]
	v_mfma_f32_16x16x32_bf16 v[92:95], v[140:143], v[196:199], v[92:95]
	v_mfma_f32_16x16x32_bf16 v[88:91], v[156:159], v[196:199], v[88:91]
	v_mfma_f32_16x16x32_bf16 v[76:79], v[140:143], v[204:207], v[76:79]
	v_mfma_f32_16x16x32_bf16 v[72:75], v[156:159], v[204:207], v[72:75]
	v_mfma_f32_16x16x32_bf16 v[124:127], v[152:155], v[184:187], v[124:127]
	v_mfma_f32_16x16x32_bf16 v[120:123], v[160:163], v[184:187], v[120:123]
	v_mfma_f32_16x16x32_bf16 v[108:111], v[152:155], v[192:195], v[108:111]
	v_mfma_f32_16x16x32_bf16 v[104:107], v[160:163], v[192:195], v[104:107]
	v_mfma_f32_16x16x32_bf16 v[92:95], v[152:155], v[200:203], v[92:95]
	v_mfma_f32_16x16x32_bf16 v[88:91], v[160:163], v[200:203], v[88:91]
	v_mfma_f32_16x16x32_bf16 v[76:79], v[152:155], v[208:211], v[76:79]
	v_mfma_f32_16x16x32_bf16 v[72:75], v[160:163], v[208:211], v[72:75]
	s_setprio 0
	s_setprio 1
	v_mfma_f32_16x16x32_bf16 v[116:119], v[164:167], v[180:183], v[116:119]
	v_mfma_f32_16x16x32_bf16 v[112:115], v[172:175], v[180:183], v[112:115]
	v_mfma_f32_16x16x32_bf16 v[100:103], v[164:167], v[188:191], v[100:103]
	v_mfma_f32_16x16x32_bf16 v[96:99], v[172:175], v[188:191], v[96:99]
	v_mfma_f32_16x16x32_bf16 v[84:87], v[164:167], v[196:199], v[84:87]
	v_mfma_f32_16x16x32_bf16 v[80:83], v[172:175], v[196:199], v[80:83]
	v_mfma_f32_16x16x32_bf16 v[68:71], v[164:167], v[204:207], v[68:71]
	v_mfma_f32_16x16x32_bf16 v[64:67], v[172:175], v[204:207], v[64:67]
	v_mfma_f32_16x16x32_bf16 v[116:119], v[168:171], v[184:187], v[116:119]
	v_mfma_f32_16x16x32_bf16 v[112:115], v[176:179], v[184:187], v[112:115]
	v_mfma_f32_16x16x32_bf16 v[100:103], v[168:171], v[192:195], v[100:103]
	v_mfma_f32_16x16x32_bf16 v[96:99], v[176:179], v[192:195], v[96:99]
	v_mfma_f32_16x16x32_bf16 v[84:87], v[168:171], v[200:203], v[84:87]
	v_mfma_f32_16x16x32_bf16 v[80:83], v[176:179], v[200:203], v[80:83]
	v_mfma_f32_16x16x32_bf16 v[68:71], v[168:171], v[208:211], v[68:71]
	v_mfma_f32_16x16x32_bf16 v[64:67], v[176:179], v[208:211], v[64:67]
	s_setprio 0
	s_barrier
; #define PG8_STAGE(bufoff, gbase, voff) do { const char* _gb = (const char*)(gbase); asm volatile("" : "+s"(_gb));     \
;         _Pragma("unroll") for (int _i = 0; _i < 2; ++_i) \
;         __builtin_amdgcn_global_load_lds((const unsigned*)(_gb + (voff)[_i]), (LAS unsigned*)(lds + (bufoff) + ldsw + _i * 8192), 16, 0, 0); } while (0)
; #define PG8_LDA(dst, b, h) do { _Pragma("unroll") for (int m = 0; m < 4; ++m) _Pragma("unroll") for (int k = 0; k < 2; ++k) dst[m][k] = *(const LAS bf16x8*)(lds + PG8_SA(b, h) + aoff + m * 2048 + k * 1024); } while (0)
; #define PG8_MMA(ai, bj, At, Bt) do { __builtin_amdgcn_s_setprio(1); _Pragma("unroll") for (int m = 0; m < 4; ++m) _Pragma("unroll") for (int n = 0; n < 2; ++n) _Pragma("unroll") for (int k = 0; k < 2; ++k) \
;         acc[ai][bj][m][n] = __builtin_amdgcn_mfma_f32_16x16x32_bf16(Bt[n][k], At[m][k], acc[ai][bj][m][n], 0, 0, 0); __builtin_amdgcn_s_setprio(0); } while (0)
; #define PG8_WAIT_V(n) asm volatile("s_waitcnt vmcnt(" #n ")" ::: "memory")
; #define PG8_WAIT_L(n) asm volatile("s_waitcnt lgkmcnt(" #n ")" ::: "memory")
; #define PG8_BAR __builtin_amdgcn_s_barrier()
; #define PG8_SCHED __builtin_amdgcn_sched_barrier(0)
; template <class Epi>
; __device__ __forceinline__ void gemm_phase(LAS unsigned char* lds, const int wid, const Gemm g, const Epi& E) {
;     ...
;             PG8_LDA(At, 1, 1); PG8_STAGE(PG8_SB(1, 0), b3, voffB); PG8_STAGE(PG8_SB(1, 1), b3 + hstepB, voffB); PG8_STAGE(PG8_SA(1, 0), a3, voffA);
;             PG8_WAIT_V(8); PG8_WAIT_L(0); PG8_BAR; PG8_MMA(1, 0, At, B0); PG8_MMA(1, 1, At, B1); PG8_BAR; PG8_SCHED;
;         }
	s_mov_b64 s[30:31], s[34:35]
	s_add_i32 s66, s66, s23
	ds_read_b128 v[180:183], v151 offset:49152
	ds_read_b128 v[184:187], v151 offset:50176
	ds_read_b128 v[188:191], v151 offset:51200
	ds_read_b128 v[192:195], v151 offset:52224
	ds_read_b128 v[196:199], v151 offset:53248
	ds_read_b128 v[200:203], v151 offset:54272
	ds_read_b128 v[204:207], v151 offset:55296
	ds_read_b128 v[208:211], v151 offset:56320
	s_mov_b32 m0, s66
	s_nop 0
	global_load_lds_dwordx4 v132, s[30:31]
	s_add_i32 m0, s66, 0x2000
	v_lshl_add_u64 v[144:145], s[30:31], 0, v[128:129]
	s_add_u32 s30, s34, 0xb0000
	s_addc_u32 s31, s35, 0
	s_add_i32 s34, s67, s23
	global_load_lds_dwordx4 v[144:145], off
	s_mov_b32 m0, s34
	s_nop 0
	global_load_lds_dwordx4 v132, s[30:31]
	s_add_i32 m0, s34, 0x2000
	s_nop 0
	global_load_lds_dwordx4 v128, s[30:31]
	s_mov_b32 m0, s49
	s_nop 0
	global_load_lds_dwordx4 v134, s[28:29]
	s_mov_b32 m0, s50
	s_nop 0
	global_load_lds_dwordx4 v130, s[28:29]
	s_waitcnt vmcnt(8)
	s_waitcnt lgkmcnt(0)
	s_barrier
	s_setprio 1
	s_waitcnt lgkmcnt(0)
	v_mfma_f32_16x16x32_bf16 v[60:63], v[140:143], v[180:183], v[60:63]
	v_mfma_f32_16x16x32_bf16 v[56:59], v[156:159], v[180:183], v[56:59]
	v_mfma_f32_16x16x32_bf16 v[44:47], v[140:143], v[188:191], v[44:47]
	v_mfma_f32_16x16x32_bf16 v[40:43], v[156:159], v[188:191], v[40:43]
	v_mfma_f32_16x16x32_bf16 v[28:31], v[140:143], v[196:199], v[28:31]
	v_mfma_f32_16x16x32_bf16 v[24:27], v[156:159], v[196:199], v[24:27]
	v_mfma_f32_16x16x32_bf16 v[12:15], v[140:143], v[204:207], v[12:15]
	v_mfma_f32_16x16x32_bf16 v[8:11], v[156:159], v[204:207], v[8:11]
	v_mfma_f32_16x16x32_bf16 v[60:63], v[152:155], v[184:187], v[60:63]
	v_mfma_f32_16x16x32_bf16 v[56:59], v[160:163], v[184:187], v[56:59]
	v_mfma_f32_16x16x32_bf16 v[44:47], v[152:155], v[192:195], v[44:47]
	v_mfma_f32_16x16x32_bf16 v[40:43], v[160:163], v[192:195], v[40:43]
	v_mfma_f32_16x16x32_bf16 v[28:31], v[152:155], v[200:203], v[28:31]
	v_mfma_f32_16x16x32_bf16 v[24:27], v[160:163], v[200:203], v[24:27]
	v_mfma_f32_16x16x32_bf16 v[12:15], v[152:155], v[208:211], v[12:15]
	v_mfma_f32_16x16x32_bf16 v[8:11], v[160:163], v[208:211], v[8:11]
	s_setprio 0
	s_setprio 1
	v_mfma_f32_16x16x32_bf16 v[52:55], v[164:167], v[180:183], v[52:55]
	v_mfma_f32_16x16x32_bf16 v[48:51], v[172:175], v[180:183], v[48:51]
	v_mfma_f32_16x16x32_bf16 v[36:39], v[164:167], v[188:191], v[36:39]
	v_mfma_f32_16x16x32_bf16 v[32:35], v[172:175], v[188:191], v[32:35]
	v_mfma_f32_16x16x32_bf16 v[20:23], v[164:167], v[196:199], v[20:23]
	v_mfma_f32_16x16x32_bf16 v[16:19], v[172:175], v[196:199], v[16:19]
	v_mfma_f32_16x16x32_bf16 v[4:7], v[164:167], v[204:207], v[4:7]
	v_mfma_f32_16x16x32_bf16 v[0:3], v[172:175], v[204:207], v[0:3]
	v_mfma_f32_16x16x32_bf16 v[52:55], v[168:171], v[184:187], v[52:55]
	v_mfma_f32_16x16x32_bf16 v[48:51], v[176:179], v[184:187], v[48:51]
	v_mfma_f32_16x16x32_bf16 v[36:39], v[168:171], v[192:195], v[36:39]
	v_mfma_f32_16x16x32_bf16 v[32:35], v[176:179], v[192:195], v[32:35]
	v_mfma_f32_16x16x32_bf16 v[20:23], v[168:171], v[200:203], v[20:23]
	v_mfma_f32_16x16x32_bf16 v[16:19], v[176:179], v[200:203], v[16:19]
	v_mfma_f32_16x16x32_bf16 v[4:7], v[168:171], v[208:211], v[4:7]
	v_mfma_f32_16x16x32_bf16 v[0:3], v[176:179], v[208:211], v[0:3]
	s_setprio 0
	s_barrier
	s_add_i32 s65, s65, 2
	s_add_u32 s63, s63, 0x100
	s_addc_u32 s64, s64, 0
	s_add_u32 s26, s26, 0x100
	s_addc_u32 s27, s27, 0
	s_cmp_gt_u32 s65, 41
	s_cbranch_scc0 .LBB0_3248
	s_and_b64 vcc, exec, s[10:11]
	s_cbranch_vccz .LBB0_3251
	s_barrier
